# context-row GEMM tiles: operands through wave-private LDS staging (full 128-byte lines per DMA piece); S5 table builder moved to waves without a context row; last-layer S5 pass 3 skips the context chu
# speedup vs baseline: 1.4523x; 1.0174x over previous
.Lcg_k6:
	v_lshrrev_b32_e32 v129, 3, v133
	v_and_b32_e32 v128, 7, v133
	v_xor_b32_e32 v128, v128, v129
	v_lshlrev_b32_e32 v128, 4, v128
	v_mul_u32_u24_e32 v129, 0x800, v129
	v_add_u32_e32 v128, v128, v129
	s_lshl_b32 s30, s24, 14
	v_and_b32_e32 v131, 7, v134
	v_or_b32_e32 v129, 0, v135
	v_xor_b32_e32 v129, v129, v131
	v_lshlrev_b32_e32 v129, 4, v129
	v_lshl_add_u32 v129, v134, 7, v129
	v_add_u32_e32 v129, s30, v129
	v_or_b32_e32 v130, 4, v135
	v_xor_b32_e32 v130, v130, v131
	v_lshlrev_b32_e32 v130, 4, v130
	v_lshl_add_u32 v130, v134, 7, v130
	v_add_u32_e32 v130, s30, v130
	s_mov_b32 s14, 0
.Lcg_tile_k6:
	s_lshr_b32 s16, s69, 4
	s_and_b32 s17, s69, 15
	s_mul_i32 s25, s24, 0x100
	s_mul_i32 s26, s16, 0x20000
	s_add_u32 s26, s26, s25
	s_add_u32 s26, s26, 0x3c00000
	s_add_u32 s10, s4, s26
	s_addc_u32 s11, s5, 0
	s_mul_i32 s26, s17, 0x20000
	s_add_u32 s26, s26, s25
	s_add_u32 s26, s26, 0x1000000
	s_add_u32 s12, s4, s26
	s_addc_u32 s13, s5, 0
	s_add_u32 s26, s10, 0x0
	s_addc_u32 s27, s11, 0
	s_add_i32 m0, s30, 0x0
	s_nop 0
	global_load_lds_dwordx4 v128, s[26:27]
	s_add_u32 s26, s10, 0x4000
	s_addc_u32 s27, s11, 0
	s_add_i32 m0, s30, 0x400
	s_nop 0
	global_load_lds_dwordx4 v128, s[26:27]
	s_add_u32 s26, s10, 0x8000
	s_addc_u32 s27, s11, 0
	s_add_i32 m0, s30, 0x800
	s_nop 0
	global_load_lds_dwordx4 v128, s[26:27]
	s_add_u32 s26, s10, 0xc000
	s_addc_u32 s27, s11, 0
	s_add_i32 m0, s30, 0xc00
	s_nop 0
	global_load_lds_dwordx4 v128, s[26:27]
	s_add_u32 s26, s10, 0x10000
	s_addc_u32 s27, s11, 0
	s_add_i32 m0, s30, 0x1000
	s_nop 0
	global_load_lds_dwordx4 v128, s[26:27]
	s_add_u32 s26, s10, 0x14000
	s_addc_u32 s27, s11, 0
	s_add_i32 m0, s30, 0x1400
	s_nop 0
	global_load_lds_dwordx4 v128, s[26:27]
	s_add_u32 s26, s10, 0x18000
	s_addc_u32 s27, s11, 0
	s_add_i32 m0, s30, 0x1800
	s_nop 0
	global_load_lds_dwordx4 v128, s[26:27]
	s_add_u32 s26, s10, 0x1c000
	s_addc_u32 s27, s11, 0
	s_add_i32 m0, s30, 0x1c00
	s_nop 0
	global_load_lds_dwordx4 v128, s[26:27]
	s_add_u32 s26, s12, 0x0
	s_addc_u32 s27, s13, 0
	s_add_i32 m0, s30, 0x2000
	s_nop 0
	global_load_lds_dwordx4 v128, s[26:27]
	s_add_u32 s26, s12, 0x4000
	s_addc_u32 s27, s13, 0
	s_add_i32 m0, s30, 0x2400
	s_nop 0
	global_load_lds_dwordx4 v128, s[26:27]
	s_add_u32 s26, s12, 0x8000
	s_addc_u32 s27, s13, 0
	s_add_i32 m0, s30, 0x2800
	s_nop 0
	global_load_lds_dwordx4 v128, s[26:27]
	s_add_u32 s26, s12, 0xc000
	s_addc_u32 s27, s13, 0
	s_add_i32 m0, s30, 0x2c00
	s_nop 0
	global_load_lds_dwordx4 v128, s[26:27]
	s_add_u32 s26, s12, 0x10000
	s_addc_u32 s27, s13, 0
	s_add_i32 m0, s30, 0x3000
	s_nop 0
	global_load_lds_dwordx4 v128, s[26:27]
	s_add_u32 s26, s12, 0x14000
	s_addc_u32 s27, s13, 0
	s_add_i32 m0, s30, 0x3400
	s_nop 0
	global_load_lds_dwordx4 v128, s[26:27]
	s_add_u32 s26, s12, 0x18000
	s_addc_u32 s27, s13, 0
	s_add_i32 m0, s30, 0x3800
	s_nop 0
	global_load_lds_dwordx4 v128, s[26:27]
	s_add_u32 s26, s12, 0x1c000
	s_addc_u32 s27, s13, 0
	s_add_i32 m0, s30, 0x3c00
	s_nop 0
	global_load_lds_dwordx4 v128, s[26:27]
	s_waitcnt vmcnt(0)
	ds_read_b128 v[64:67], v129 offset:0
	ds_read_b128 v[68:71], v129 offset:2048
	ds_read_b128 v[72:75], v129 offset:4096
	ds_read_b128 v[76:79], v129 offset:6144
	ds_read_b128 v[80:83], v129 offset:8192
	ds_read_b128 v[84:87], v129 offset:10240
	ds_read_b128 v[88:91], v129 offset:12288
	ds_read_b128 v[92:95], v129 offset:14336
	ds_read_b128 v[96:99], v130 offset:0
	ds_read_b128 v[100:103], v130 offset:2048
	ds_read_b128 v[104:107], v130 offset:4096
	ds_read_b128 v[108:111], v130 offset:6144
	ds_read_b128 v[112:115], v130 offset:8192
	ds_read_b128 v[116:119], v130 offset:10240
	ds_read_b128 v[120:123], v130 offset:12288
	ds_read_b128 v[124:127], v130 offset:14336
	s_waitcnt lgkmcnt(0)
	s_add_u32 s26, s10, 0x80
	s_addc_u32 s27, s11, 0
	s_add_i32 m0, s30, 0x0
	s_nop 0
	global_load_lds_dwordx4 v128, s[26:27]
	s_add_u32 s26, s10, 0x4080
	s_addc_u32 s27, s11, 0
	s_add_i32 m0, s30, 0x400
	s_nop 0
	global_load_lds_dwordx4 v128, s[26:27]
	s_add_u32 s26, s10, 0x8080
	s_addc_u32 s27, s11, 0
	s_add_i32 m0, s30, 0x800
	s_nop 0
	global_load_lds_dwordx4 v128, s[26:27]
	s_add_u32 s26, s10, 0xc080
	s_addc_u32 s27, s11, 0
	s_add_i32 m0, s30, 0xc00
	s_nop 0
	global_load_lds_dwordx4 v128, s[26:27]
	s_add_u32 s26, s10, 0x10080
	s_addc_u32 s27, s11, 0
	s_add_i32 m0, s30, 0x1000
	s_nop 0
	global_load_lds_dwordx4 v128, s[26:27]
	s_add_u32 s26, s10, 0x14080
	s_addc_u32 s27, s11, 0
	s_add_i32 m0, s30, 0x1400
	s_nop 0
	global_load_lds_dwordx4 v128, s[26:27]
	s_add_u32 s26, s10, 0x18080
	s_addc_u32 s27, s11, 0
	s_add_i32 m0, s30, 0x1800
	s_nop 0
	global_load_lds_dwordx4 v128, s[26:27]
	s_add_u32 s26, s10, 0x1c080
	s_addc_u32 s27, s11, 0
	s_add_i32 m0, s30, 0x1c00
	s_nop 0
	global_load_lds_dwordx4 v128, s[26:27]
	s_add_u32 s26, s12, 0x80
	s_addc_u32 s27, s13, 0
	s_add_i32 m0, s30, 0x2000
	s_nop 0
	global_load_lds_dwordx4 v128, s[26:27]
	s_add_u32 s26, s12, 0x4080
	s_addc_u32 s27, s13, 0
	s_add_i32 m0, s30, 0x2400
	s_nop 0
	global_load_lds_dwordx4 v128, s[26:27]
	s_add_u32 s26, s12, 0x8080
	s_addc_u32 s27, s13, 0
	s_add_i32 m0, s30, 0x2800
	s_nop 0
	global_load_lds_dwordx4 v128, s[26:27]
	s_add_u32 s26, s12, 0xc080
	s_addc_u32 s27, s13, 0
	s_add_i32 m0, s30, 0x2c00
	s_nop 0
	global_load_lds_dwordx4 v128, s[26:27]
	s_add_u32 s26, s12, 0x10080
	s_addc_u32 s27, s13, 0
	s_add_i32 m0, s30, 0x3000
	s_nop 0
	global_load_lds_dwordx4 v128, s[26:27]
	s_add_u32 s26, s12, 0x14080
	s_addc_u32 s27, s13, 0
	s_add_i32 m0, s30, 0x3400
	s_nop 0
	global_load_lds_dwordx4 v128, s[26:27]
	s_add_u32 s26, s12, 0x18080
	s_addc_u32 s27, s13, 0
	s_add_i32 m0, s30, 0x3800
	s_nop 0
	global_load_lds_dwordx4 v128, s[26:27]
	s_add_u32 s26, s12, 0x1c080
	s_addc_u32 s27, s13, 0
	s_add_i32 m0, s30, 0x3c00
	s_nop 0
	global_load_lds_dwordx4 v128, s[26:27]
	v_mfma_f32_16x16x32_bf16 v[0:3], v[80:83], v[64:67], 0
	v_mfma_f32_16x16x32_bf16 v[4:7], v[84:87], v[64:67], 0
	v_mfma_f32_16x16x32_bf16 v[8:11], v[88:91], v[64:67], 0
	v_mfma_f32_16x16x32_bf16 v[12:15], v[92:95], v[64:67], 0
	v_mfma_f32_16x16x32_bf16 v[16:19], v[80:83], v[68:71], 0
	v_mfma_f32_16x16x32_bf16 v[20:23], v[84:87], v[68:71], 0
	v_mfma_f32_16x16x32_bf16 v[24:27], v[88:91], v[68:71], 0
	v_mfma_f32_16x16x32_bf16 v[28:31], v[92:95], v[68:71], 0
	v_mfma_f32_16x16x32_bf16 v[32:35], v[80:83], v[72:75], 0
	v_mfma_f32_16x16x32_bf16 v[36:39], v[84:87], v[72:75], 0
	v_mfma_f32_16x16x32_bf16 v[40:43], v[88:91], v[72:75], 0
	v_mfma_f32_16x16x32_bf16 v[44:47], v[92:95], v[72:75], 0
	v_mfma_f32_16x16x32_bf16 v[48:51], v[80:83], v[76:79], 0
	v_mfma_f32_16x16x32_bf16 v[52:55], v[84:87], v[76:79], 0
	v_mfma_f32_16x16x32_bf16 v[56:59], v[88:91], v[76:79], 0
	v_mfma_f32_16x16x32_bf16 v[60:63], v[92:95], v[76:79], 0
	v_mfma_f32_16x16x32_bf16 v[0:3], v[112:115], v[96:99], v[0:3]
	v_mfma_f32_16x16x32_bf16 v[4:7], v[116:119], v[96:99], v[4:7]
	v_mfma_f32_16x16x32_bf16 v[8:11], v[120:123], v[96:99], v[8:11]
	v_mfma_f32_16x16x32_bf16 v[12:15], v[124:127], v[96:99], v[12:15]
	v_mfma_f32_16x16x32_bf16 v[16:19], v[112:115], v[100:103], v[16:19]
	v_mfma_f32_16x16x32_bf16 v[20:23], v[116:119], v[100:103], v[20:23]
	v_mfma_f32_16x16x32_bf16 v[24:27], v[120:123], v[100:103], v[24:27]
	v_mfma_f32_16x16x32_bf16 v[28:31], v[124:127], v[100:103], v[28:31]
	v_mfma_f32_16x16x32_bf16 v[32:35], v[112:115], v[104:107], v[32:35]
	v_mfma_f32_16x16x32_bf16 v[36:39], v[116:119], v[104:107], v[36:39]
	v_mfma_f32_16x16x32_bf16 v[40:43], v[120:123], v[104:107], v[40:43]
	v_mfma_f32_16x16x32_bf16 v[44:47], v[124:127], v[104:107], v[44:47]
	v_mfma_f32_16x16x32_bf16 v[48:51], v[112:115], v[108:111], v[48:51]
	v_mfma_f32_16x16x32_bf16 v[52:55], v[116:119], v[108:111], v[52:55]
	v_mfma_f32_16x16x32_bf16 v[56:59], v[120:123], v[108:111], v[56:59]
	v_mfma_f32_16x16x32_bf16 v[60:63], v[124:127], v[108:111], v[60:63]
	s_waitcnt vmcnt(0)
	ds_read_b128 v[64:67], v129 offset:0
	ds_read_b128 v[68:71], v129 offset:2048
	ds_read_b128 v[72:75], v129 offset:4096
	ds_read_b128 v[76:79], v129 offset:6144
	ds_read_b128 v[80:83], v129 offset:8192
	ds_read_b128 v[84:87], v129 offset:10240
	ds_read_b128 v[88:91], v129 offset:12288
	ds_read_b128 v[92:95], v129 offset:14336
	ds_read_b128 v[96:99], v130 offset:0
	ds_read_b128 v[100:103], v130 offset:2048
	ds_read_b128 v[104:107], v130 offset:4096
	ds_read_b128 v[108:111], v130 offset:6144
	ds_read_b128 v[112:115], v130 offset:8192
	ds_read_b128 v[116:119], v130 offset:10240
	ds_read_b128 v[120:123], v130 offset:12288
	ds_read_b128 v[124:127], v130 offset:14336
	s_waitcnt lgkmcnt(0)
	v_mfma_f32_16x16x32_bf16 v[0:3], v[80:83], v[64:67], v[0:3]
	v_mfma_f32_16x16x32_bf16 v[4:7], v[84:87], v[64:67], v[4:7]
	v_mfma_f32_16x16x32_bf16 v[8:11], v[88:91], v[64:67], v[8:11]
	v_mfma_f32_16x16x32_bf16 v[12:15], v[92:95], v[64:67], v[12:15]
	v_mfma_f32_16x16x32_bf16 v[16:19], v[80:83], v[68:71], v[16:19]
	v_mfma_f32_16x16x32_bf16 v[20:23], v[84:87], v[68:71], v[20:23]
	v_mfma_f32_16x16x32_bf16 v[24:27], v[88:91], v[68:71], v[24:27]
	v_mfma_f32_16x16x32_bf16 v[28:31], v[92:95], v[68:71], v[28:31]
	v_mfma_f32_16x16x32_bf16 v[32:35], v[80:83], v[72:75], v[32:35]
	v_mfma_f32_16x16x32_bf16 v[36:39], v[84:87], v[72:75], v[36:39]
	v_mfma_f32_16x16x32_bf16 v[40:43], v[88:91], v[72:75], v[40:43]
	v_mfma_f32_16x16x32_bf16 v[44:47], v[92:95], v[72:75], v[44:47]
	v_mfma_f32_16x16x32_bf16 v[48:51], v[80:83], v[76:79], v[48:51]
	v_mfma_f32_16x16x32_bf16 v[52:55], v[84:87], v[76:79], v[52:55]
	v_mfma_f32_16x16x32_bf16 v[56:59], v[88:91], v[76:79], v[56:59]
	v_mfma_f32_16x16x32_bf16 v[60:63], v[92:95], v[76:79], v[60:63]
	v_mfma_f32_16x16x32_bf16 v[0:3], v[112:115], v[96:99], v[0:3]
	v_mfma_f32_16x16x32_bf16 v[4:7], v[116:119], v[96:99], v[4:7]
	v_mfma_f32_16x16x32_bf16 v[8:11], v[120:123], v[96:99], v[8:11]
	v_mfma_f32_16x16x32_bf16 v[12:15], v[124:127], v[96:99], v[12:15]
	v_mfma_f32_16x16x32_bf16 v[16:19], v[112:115], v[100:103], v[16:19]
	v_mfma_f32_16x16x32_bf16 v[20:23], v[116:119], v[100:103], v[20:23]
	v_mfma_f32_16x16x32_bf16 v[24:27], v[120:123], v[100:103], v[24:27]
	v_mfma_f32_16x16x32_bf16 v[28:31], v[124:127], v[100:103], v[28:31]
	v_mfma_f32_16x16x32_bf16 v[32:35], v[112:115], v[104:107], v[32:35]
	v_mfma_f32_16x16x32_bf16 v[36:39], v[116:119], v[104:107], v[36:39]
	v_mfma_f32_16x16x32_bf16 v[40:43], v[120:123], v[104:107], v[40:43]
	v_mfma_f32_16x16x32_bf16 v[44:47], v[124:127], v[104:107], v[44:47]
	v_mfma_f32_16x16x32_bf16 v[48:51], v[112:115], v[108:111], v[48:51]
	v_mfma_f32_16x16x32_bf16 v[52:55], v[116:119], v[108:111], v[52:55]
	v_mfma_f32_16x16x32_bf16 v[56:59], v[120:123], v[108:111], v[56:59]
	v_mfma_f32_16x16x32_bf16 v[60:63], v[124:127], v[108:111], v[60:63]
	v_lshlrev_b32_e32 v170, 14, v132
	v_lshl_add_u32 v170, v133, 4, v170
	s_nop 7
	ds_write_b128 v170, v[0:3] offset:0
	ds_write_b128 v170, v[4:7] offset:1024
	ds_write_b128 v170, v[8:11] offset:2048
	ds_write_b128 v170, v[12:15] offset:3072
	ds_write_b128 v170, v[16:19] offset:4096
	ds_write_b128 v170, v[20:23] offset:5120
	ds_write_b128 v170, v[24:27] offset:6144
	ds_write_b128 v170, v[28:31] offset:7168
	ds_write_b128 v170, v[32:35] offset:8192
	ds_write_b128 v170, v[36:39] offset:9216
	ds_write_b128 v170, v[40:43] offset:10240
	ds_write_b128 v170, v[44:47] offset:11264
	ds_write_b128 v170, v[48:51] offset:12288
	ds_write_b128 v170, v[52:55] offset:13312
	ds_write_b128 v170, v[56:59] offset:14336
	ds_write_b128 v170, v[60:63] offset:15360
	s_lshr_b32 s25, s24, 1
	s_lshl_b32 s25, s25, 4
	s_lshl_b32 s26, s16, 6
	s_add_i32 s25, s25, s26
	s_and_b32 s26, s24, 1
	s_lshl_b32 s26, s26, 5
	s_lshl_b32 s27, s17, 6
	s_add_i32 s26, s26, s27
	v_add_u32_e32 v171, s25, v134
	v_lshl_add_u32 v172, v135, 2, s26
	v_lshlrev_b32_e32 v173, 10, v171
	v_add_lshl_u32 v173, v173, v172, 2
	v_readlane_b32 s18, v247, 10
	v_readlane_b32 s19, v247, 11
	s_add_u32 s20, s4, 0x3800000
	s_addc_u32 s21, s5, 0
	v_lshlrev_b32_e32 v174, 2, v172
	s_add_u32 s22, s4, 0x223320
	s_addc_u32 s23, s5, 0
	s_add_u32 s28, s4, 0x1a000
	s_addc_u32 s29, s5, 0
	s_nop 2
	global_load_dwordx4 v[176:179], v173, s[18:19] offset:0
	global_load_dwordx4 v[64:67], v174, s[22:23] offset:0
	global_load_dwordx4 v[72:75], v174, s[28:29] offset:0
	global_load_dwordx4 v[180:183], v173, s[18:19] offset:64
	global_load_dwordx4 v[68:71], v174, s[22:23] offset:64
	global_load_dwordx4 v[76:79], v174, s[28:29] offset:64
	s_waitcnt lgkmcnt(0)
	s_barrier
	v_lshlrev_b32_e32 v175, 11, v132
	v_lshl_add_u32 v175, v133, 4, v175
	v_add_u32_e32 v100, 0x4000, v175
	v_add_u32_e32 v101, 0x8000, v175
	v_add_u32_e32 v102, 0xc000, v175
	v_add_u32_e32 v103, 0x10000, v175
	v_add_u32_e32 v166, 0x14000, v175
	v_add_u32_e32 v167, 0x18000, v175
	v_add_u32_e32 v168, 0x1c000, v175
	ds_read_b128 v[80:83], v175 offset:0
	ds_read_b128 v[0:3], v100 offset:0
	ds_read_b128 v[4:7], v101 offset:0
	ds_read_b128 v[8:11], v102 offset:0
	ds_read_b128 v[12:15], v103 offset:0
	ds_read_b128 v[16:19], v166 offset:0
	ds_read_b128 v[20:23], v167 offset:0
	ds_read_b128 v[24:27], v168 offset:0
	s_waitcnt lgkmcnt(0)
	ds_read_b128 v[96:99], v175 offset:1024
	ds_read_b128 v[138:141], v100 offset:1024
	ds_read_b128 v[142:145], v101 offset:1024
	ds_read_b128 v[146:149], v102 offset:1024
	ds_read_b128 v[150:153], v103 offset:1024
	ds_read_b128 v[154:157], v166 offset:1024
	ds_read_b128 v[158:161], v167 offset:1024
	ds_read_b128 v[162:165], v168 offset:1024
	s_waitcnt lgkmcnt(0)
	v_add_f32_e32 v80, v80, v0
	v_add_f32_e32 v81, v81, v1
	v_add_f32_e32 v82, v82, v2
	v_add_f32_e32 v83, v83, v3
	v_add_f32_e32 v80, v80, v4
	v_add_f32_e32 v81, v81, v5
	v_add_f32_e32 v82, v82, v6
	v_add_f32_e32 v83, v83, v7
	v_add_f32_e32 v80, v80, v8
	v_add_f32_e32 v81, v81, v9
	v_add_f32_e32 v82, v82, v10
	v_add_f32_e32 v83, v83, v11
	v_add_f32_e32 v80, v80, v12
	v_add_f32_e32 v81, v81, v13
	v_add_f32_e32 v82, v82, v14
	v_add_f32_e32 v83, v83, v15
	v_add_f32_e32 v80, v80, v16
	v_add_f32_e32 v81, v81, v17
	v_add_f32_e32 v82, v82, v18
	v_add_f32_e32 v83, v83, v19
	v_add_f32_e32 v80, v80, v20
	v_add_f32_e32 v81, v81, v21
	v_add_f32_e32 v82, v82, v22
	v_add_f32_e32 v83, v83, v23
	v_add_f32_e32 v80, v80, v24
	v_add_f32_e32 v81, v81, v25
	v_add_f32_e32 v82, v82, v26
	v_add_f32_e32 v83, v83, v27
	v_add_f32_e32 v96, v96, v138
	v_add_f32_e32 v97, v97, v139
	v_add_f32_e32 v98, v98, v140
	v_add_f32_e32 v99, v99, v141
	v_add_f32_e32 v96, v96, v142
	v_add_f32_e32 v97, v97, v143
	v_add_f32_e32 v98, v98, v144
	v_add_f32_e32 v99, v99, v145
	v_add_f32_e32 v96, v96, v146
	v_add_f32_e32 v97, v97, v147
	v_add_f32_e32 v98, v98, v148
	v_add_f32_e32 v99, v99, v149
	v_add_f32_e32 v96, v96, v150
	v_add_f32_e32 v97, v97, v151
	v_add_f32_e32 v98, v98, v152
	v_add_f32_e32 v99, v99, v153
	v_add_f32_e32 v96, v96, v154
	v_add_f32_e32 v97, v97, v155
	v_add_f32_e32 v98, v98, v156
	v_add_f32_e32 v99, v99, v157
	v_add_f32_e32 v96, v96, v158
	v_add_f32_e32 v97, v97, v159
	v_add_f32_e32 v98, v98, v160
	v_add_f32_e32 v99, v99, v161
	v_add_f32_e32 v96, v96, v162
	v_add_f32_e32 v97, v97, v163
	v_add_f32_e32 v98, v98, v164
	v_add_f32_e32 v99, v99, v165
	s_waitcnt vmcnt(0)
	v_add_f32_e32 v80, v80, v64
	v_add_f32_e32 v81, v81, v65
	v_add_f32_e32 v82, v82, v66
	v_add_f32_e32 v83, v83, v67
	v_fma_f32 v80, v72, v80, v176
	v_fma_f32 v81, v73, v81, v177
	v_fma_f32 v82, v74, v82, v178
	v_fma_f32 v83, v75, v83, v179
	global_store_dwordx4 v173, v[80:83], s[20:21] offset:0
	v_add_f32_e32 v96, v96, v68
	v_add_f32_e32 v97, v97, v69
	v_add_f32_e32 v98, v98, v70
	v_add_f32_e32 v99, v99, v71
	v_fma_f32 v96, v76, v96, v180
	v_fma_f32 v97, v77, v97, v181
	v_fma_f32 v98, v78, v98, v182
	v_fma_f32 v99, v79, v99, v183
	global_store_dwordx4 v173, v[96:99], s[20:21] offset:64
	s_barrier
	s_branch .Lcg_done

.Lcg_tile_k5:
	s_lshl_b32 s15, s69, 2
	s_add_i32 s15, s15, s14
	s_lshr_b32 s16, s15, 6
	s_and_b32 s17, s15, 63
	s_mul_i32 s25, s24, 0x100
	s_mul_i32 s26, s16, 0x20000
	s_add_u32 s26, s26, s25
	s_add_u32 s26, s26, 0x3c00000
	s_add_u32 s10, s4, s26
	s_addc_u32 s11, s5, 0
	s_mul_i32 s26, s17, 0x20000
	s_add_u32 s26, s26, s25
	s_add_u32 s26, s26, 0x1200000
	s_add_u32 s12, s4, s26
	s_addc_u32 s13, s5, 0
	s_add_u32 s26, s10, 0x0
	s_addc_u32 s27, s11, 0
	s_add_i32 m0, s30, 0x0
	s_nop 0
	global_load_lds_dwordx4 v128, s[26:27]
	s_add_u32 s26, s10, 0x4000
	s_addc_u32 s27, s11, 0
	s_add_i32 m0, s30, 0x400
	s_nop 0
	global_load_lds_dwordx4 v128, s[26:27]
	s_add_u32 s26, s10, 0x8000
	s_addc_u32 s27, s11, 0
	s_add_i32 m0, s30, 0x800
	s_nop 0
	global_load_lds_dwordx4 v128, s[26:27]
	s_add_u32 s26, s10, 0xc000
	s_addc_u32 s27, s11, 0
	s_add_i32 m0, s30, 0xc00
	s_nop 0
	global_load_lds_dwordx4 v128, s[26:27]
	s_add_u32 s26, s10, 0x10000
	s_addc_u32 s27, s11, 0
	s_add_i32 m0, s30, 0x1000
	s_nop 0
	global_load_lds_dwordx4 v128, s[26:27]
	s_add_u32 s26, s10, 0x14000
	s_addc_u32 s27, s11, 0
	s_add_i32 m0, s30, 0x1400
	s_nop 0
	global_load_lds_dwordx4 v128, s[26:27]
	s_add_u32 s26, s10, 0x18000
	s_addc_u32 s27, s11, 0
	s_add_i32 m0, s30, 0x1800
	s_nop 0
	global_load_lds_dwordx4 v128, s[26:27]
	s_add_u32 s26, s10, 0x1c000
	s_addc_u32 s27, s11, 0
	s_add_i32 m0, s30, 0x1c00
	s_nop 0
	global_load_lds_dwordx4 v128, s[26:27]
	s_add_u32 s26, s12, 0x0
	s_addc_u32 s27, s13, 0
	s_add_i32 m0, s30, 0x2000
	s_nop 0
	global_load_lds_dwordx4 v128, s[26:27]
	s_add_u32 s26, s12, 0x4000
	s_addc_u32 s27, s13, 0
	s_add_i32 m0, s30, 0x2400
	s_nop 0
	global_load_lds_dwordx4 v128, s[26:27]
	s_add_u32 s26, s12, 0x8000
	s_addc_u32 s27, s13, 0
	s_add_i32 m0, s30, 0x2800
	s_nop 0
	global_load_lds_dwordx4 v128, s[26:27]
	s_add_u32 s26, s12, 0xc000
	s_addc_u32 s27, s13, 0
	s_add_i32 m0, s30, 0x2c00
	s_nop 0
	global_load_lds_dwordx4 v128, s[26:27]
	s_add_u32 s26, s12, 0x10000
	s_addc_u32 s27, s13, 0
	s_add_i32 m0, s30, 0x3000
	s_nop 0
	global_load_lds_dwordx4 v128, s[26:27]
	s_add_u32 s26, s12, 0x14000
	s_addc_u32 s27, s13, 0
	s_add_i32 m0, s30, 0x3400
	s_nop 0
	global_load_lds_dwordx4 v128, s[26:27]
	s_add_u32 s26, s12, 0x18000
	s_addc_u32 s27, s13, 0
	s_add_i32 m0, s30, 0x3800
	s_nop 0
	global_load_lds_dwordx4 v128, s[26:27]
	s_add_u32 s26, s12, 0x1c000
	s_addc_u32 s27, s13, 0
	s_add_i32 m0, s30, 0x3c00
	s_nop 0
	global_load_lds_dwordx4 v128, s[26:27]
	s_waitcnt vmcnt(0)
	ds_read_b128 v[64:67], v129 offset:0
	ds_read_b128 v[68:71], v129 offset:2048
	ds_read_b128 v[72:75], v129 offset:4096
	ds_read_b128 v[76:79], v129 offset:6144
	ds_read_b128 v[80:83], v129 offset:8192
	ds_read_b128 v[84:87], v129 offset:10240
	ds_read_b128 v[88:91], v129 offset:12288
	ds_read_b128 v[92:95], v129 offset:14336
	ds_read_b128 v[96:99], v130 offset:0
	ds_read_b128 v[100:103], v130 offset:2048
	ds_read_b128 v[104:107], v130 offset:4096
	ds_read_b128 v[108:111], v130 offset:6144
	ds_read_b128 v[112:115], v130 offset:8192
	ds_read_b128 v[116:119], v130 offset:10240
	ds_read_b128 v[120:123], v130 offset:12288
	ds_read_b128 v[124:127], v130 offset:14336
	s_add_u32 s26, s10, 0x80
	s_addc_u32 s27, s11, 0
	s_add_i32 m0, s30, 0x0
	s_nop 0
	global_load_lds_dwordx4 v128, s[26:27]
	s_add_u32 s26, s10, 0x4080
	s_addc_u32 s27, s11, 0
	s_add_i32 m0, s30, 0x400
	s_nop 0
	global_load_lds_dwordx4 v128, s[26:27]
	s_add_u32 s26, s10, 0x8080
	s_addc_u32 s27, s11, 0
	s_add_i32 m0, s30, 0x800
	s_nop 0
	global_load_lds_dwordx4 v128, s[26:27]
	s_add_u32 s26, s10, 0xc080
	s_addc_u32 s27, s11, 0
	s_add_i32 m0, s30, 0xc00
	s_nop 0
	global_load_lds_dwordx4 v128, s[26:27]
	s_add_u32 s26, s10, 0x10080
	s_addc_u32 s27, s11, 0
	s_add_i32 m0, s30, 0x1000
	s_nop 0
	global_load_lds_dwordx4 v128, s[26:27]
	s_add_u32 s26, s10, 0x14080
	s_addc_u32 s27, s11, 0
	s_add_i32 m0, s30, 0x1400
	s_nop 0
	global_load_lds_dwordx4 v128, s[26:27]
	s_add_u32 s26, s10, 0x18080
	s_addc_u32 s27, s11, 0
	s_add_i32 m0, s30, 0x1800
	s_nop 0
	global_load_lds_dwordx4 v128, s[26:27]
	s_add_u32 s26, s10, 0x1c080
	s_addc_u32 s27, s11, 0
	s_add_i32 m0, s30, 0x1c00
	s_nop 0
	global_load_lds_dwordx4 v128, s[26:27]
	s_add_u32 s26, s12, 0x80
	s_addc_u32 s27, s13, 0
	s_add_i32 m0, s30, 0x2000
	s_nop 0
	global_load_lds_dwordx4 v128, s[26:27]
	s_add_u32 s26, s12, 0x4080
	s_addc_u32 s27, s13, 0
	s_add_i32 m0, s30, 0x2400
	s_nop 0
	global_load_lds_dwordx4 v128, s[26:27]
	s_add_u32 s26, s12, 0x8080
	s_addc_u32 s27, s13, 0
	s_add_i32 m0, s30, 0x2800
	s_nop 0
	global_load_lds_dwordx4 v128, s[26:27]
	s_add_u32 s26, s12, 0xc080
	s_addc_u32 s27, s13, 0
	s_add_i32 m0, s30, 0x2c00
	s_nop 0
	global_load_lds_dwordx4 v128, s[26:27]
	s_add_u32 s26, s12, 0x10080
	s_addc_u32 s27, s13, 0
	s_add_i32 m0, s30, 0x3000
	s_nop 0
	global_load_lds_dwordx4 v128, s[26:27]
	s_add_u32 s26, s12, 0x14080
	s_addc_u32 s27, s13, 0
	s_add_i32 m0, s30, 0x3400
	s_nop 0
	global_load_lds_dwordx4 v128, s[26:27]
	s_add_u32 s26, s12, 0x18080
	s_addc_u32 s27, s13, 0
	s_add_i32 m0, s30, 0x3800
	s_nop 0
	global_load_lds_dwordx4 v128, s[26:27]
	s_add_u32 s26, s12, 0x1c080
	s_addc_u32 s27, s13, 0
	s_add_i32 m0, s30, 0x3c00
	s_nop 0
	global_load_lds_dwordx4 v128, s[26:27]
	v_mfma_f32_16x16x32_bf16 v[0:3], v[80:83], v[64:67], 0
	v_mfma_f32_16x16x32_bf16 v[4:7], v[84:87], v[64:67], 0
	v_mfma_f32_16x16x32_bf16 v[8:11], v[88:91], v[64:67], 0
	v_mfma_f32_16x16x32_bf16 v[12:15], v[92:95], v[64:67], 0
	v_mfma_f32_16x16x32_bf16 v[16:19], v[80:83], v[68:71], 0
	v_mfma_f32_16x16x32_bf16 v[20:23], v[84:87], v[68:71], 0
	v_mfma_f32_16x16x32_bf16 v[24:27], v[88:91], v[68:71], 0
	v_mfma_f32_16x16x32_bf16 v[28:31], v[92:95], v[68:71], 0
	v_mfma_f32_16x16x32_bf16 v[32:35], v[80:83], v[72:75], 0
	v_mfma_f32_16x16x32_bf16 v[36:39], v[84:87], v[72:75], 0
	v_mfma_f32_16x16x32_bf16 v[40:43], v[88:91], v[72:75], 0
	v_mfma_f32_16x16x32_bf16 v[44:47], v[92:95], v[72:75], 0
	v_mfma_f32_16x16x32_bf16 v[48:51], v[80:83], v[76:79], 0
	v_mfma_f32_16x16x32_bf16 v[52:55], v[84:87], v[76:79], 0
	v_mfma_f32_16x16x32_bf16 v[56:59], v[88:91], v[76:79], 0
	v_mfma_f32_16x16x32_bf16 v[60:63], v[92:95], v[76:79], 0
	v_mfma_f32_16x16x32_bf16 v[0:3], v[112:115], v[96:99], v[0:3]
	v_mfma_f32_16x16x32_bf16 v[4:7], v[116:119], v[96:99], v[4:7]
	v_mfma_f32_16x16x32_bf16 v[8:11], v[120:123], v[96:99], v[8:11]
	v_mfma_f32_16x16x32_bf16 v[12:15], v[124:127], v[96:99], v[12:15]
	v_mfma_f32_16x16x32_bf16 v[16:19], v[112:115], v[100:103], v[16:19]
	v_mfma_f32_16x16x32_bf16 v[20:23], v[116:119], v[100:103], v[20:23]
	v_mfma_f32_16x16x32_bf16 v[24:27], v[120:123], v[100:103], v[24:27]
	v_mfma_f32_16x16x32_bf16 v[28:31], v[124:127], v[100:103], v[28:31]
	v_mfma_f32_16x16x32_bf16 v[32:35], v[112:115], v[104:107], v[32:35]
	v_mfma_f32_16x16x32_bf16 v[36:39], v[116:119], v[104:107], v[36:39]
	v_mfma_f32_16x16x32_bf16 v[40:43], v[120:123], v[104:107], v[40:43]
	v_mfma_f32_16x16x32_bf16 v[44:47], v[124:127], v[104:107], v[44:47]
	v_mfma_f32_16x16x32_bf16 v[48:51], v[112:115], v[108:111], v[48:51]
	v_mfma_f32_16x16x32_bf16 v[52:55], v[116:119], v[108:111], v[52:55]
	v_mfma_f32_16x16x32_bf16 v[56:59], v[120:123], v[108:111], v[56:59]
	v_mfma_f32_16x16x32_bf16 v[60:63], v[124:127], v[108:111], v[60:63]
	s_waitcnt vmcnt(0)
	ds_read_b128 v[64:67], v129 offset:0
	ds_read_b128 v[68:71], v129 offset:2048
	ds_read_b128 v[72:75], v129 offset:4096
	ds_read_b128 v[76:79], v129 offset:6144
	ds_read_b128 v[80:83], v129 offset:8192
	ds_read_b128 v[84:87], v129 offset:10240
	ds_read_b128 v[88:91], v129 offset:12288
	ds_read_b128 v[92:95], v129 offset:14336
	ds_read_b128 v[96:99], v130 offset:0
	ds_read_b128 v[100:103], v130 offset:2048
	ds_read_b128 v[104:107], v130 offset:4096
	ds_read_b128 v[108:111], v130 offset:6144
	ds_read_b128 v[112:115], v130 offset:8192
	ds_read_b128 v[116:119], v130 offset:10240
	ds_read_b128 v[120:123], v130 offset:12288
	ds_read_b128 v[124:127], v130 offset:14336
	v_mfma_f32_16x16x32_bf16 v[0:3], v[80:83], v[64:67], v[0:3]
	v_mfma_f32_16x16x32_bf16 v[4:7], v[84:87], v[64:67], v[4:7]
	v_mfma_f32_16x16x32_bf16 v[8:11], v[88:91], v[64:67], v[8:11]
	v_mfma_f32_16x16x32_bf16 v[12:15], v[92:95], v[64:67], v[12:15]
	v_mfma_f32_16x16x32_bf16 v[16:19], v[80:83], v[68:71], v[16:19]
	v_mfma_f32_16x16x32_bf16 v[20:23], v[84:87], v[68:71], v[20:23]
	v_mfma_f32_16x16x32_bf16 v[24:27], v[88:91], v[68:71], v[24:27]
	v_mfma_f32_16x16x32_bf16 v[28:31], v[92:95], v[68:71], v[28:31]
	v_mfma_f32_16x16x32_bf16 v[32:35], v[80:83], v[72:75], v[32:35]
	v_mfma_f32_16x16x32_bf16 v[36:39], v[84:87], v[72:75], v[36:39]
	v_mfma_f32_16x16x32_bf16 v[40:43], v[88:91], v[72:75], v[40:43]
	v_mfma_f32_16x16x32_bf16 v[44:47], v[92:95], v[72:75], v[44:47]
	v_mfma_f32_16x16x32_bf16 v[48:51], v[80:83], v[76:79], v[48:51]
	v_mfma_f32_16x16x32_bf16 v[52:55], v[84:87], v[76:79], v[52:55]
	v_mfma_f32_16x16x32_bf16 v[56:59], v[88:91], v[76:79], v[56:59]
	v_mfma_f32_16x16x32_bf16 v[60:63], v[92:95], v[76:79], v[60:63]
	v_mfma_f32_16x16x32_bf16 v[0:3], v[112:115], v[96:99], v[0:3]
	v_mfma_f32_16x16x32_bf16 v[4:7], v[116:119], v[96:99], v[4:7]
	v_mfma_f32_16x16x32_bf16 v[8:11], v[120:123], v[96:99], v[8:11]
	v_mfma_f32_16x16x32_bf16 v[12:15], v[124:127], v[96:99], v[12:15]
	v_mfma_f32_16x16x32_bf16 v[16:19], v[112:115], v[100:103], v[16:19]
	v_mfma_f32_16x16x32_bf16 v[20:23], v[116:119], v[100:103], v[20:23]
	v_mfma_f32_16x16x32_bf16 v[24:27], v[120:123], v[100:103], v[24:27]
	v_mfma_f32_16x16x32_bf16 v[28:31], v[124:127], v[100:103], v[28:31]
	v_mfma_f32_16x16x32_bf16 v[32:35], v[112:115], v[104:107], v[32:35]
	v_mfma_f32_16x16x32_bf16 v[36:39], v[116:119], v[104:107], v[36:39]
	v_mfma_f32_16x16x32_bf16 v[40:43], v[120:123], v[104:107], v[40:43]
	v_mfma_f32_16x16x32_bf16 v[44:47], v[124:127], v[104:107], v[44:47]
	v_mfma_f32_16x16x32_bf16 v[48:51], v[112:115], v[108:111], v[48:51]
	v_mfma_f32_16x16x32_bf16 v[52:55], v[116:119], v[108:111], v[52:55]
	v_mfma_f32_16x16x32_bf16 v[56:59], v[120:123], v[108:111], v[56:59]
	v_mfma_f32_16x16x32_bf16 v[60:63], v[124:127], v[108:111], v[60:63]
	v_lshlrev_b32_e32 v170, 14, v132
	v_lshl_add_u32 v170, v133, 4, v170
	s_nop 7
	ds_write_b128 v170, v[0:3] offset:0
	ds_write_b128 v170, v[4:7] offset:1024
	ds_write_b128 v170, v[8:11] offset:2048
	ds_write_b128 v170, v[12:15] offset:3072
	ds_write_b128 v170, v[16:19] offset:4096
	ds_write_b128 v170, v[20:23] offset:5120
	ds_write_b128 v170, v[24:27] offset:6144
	ds_write_b128 v170, v[28:31] offset:7168
	ds_write_b128 v170, v[32:35] offset:8192
	ds_write_b128 v170, v[36:39] offset:9216
	ds_write_b128 v170, v[40:43] offset:10240
	ds_write_b128 v170, v[44:47] offset:11264
	ds_write_b128 v170, v[48:51] offset:12288
	ds_write_b128 v170, v[52:55] offset:13312
	ds_write_b128 v170, v[56:59] offset:14336
	ds_write_b128 v170, v[60:63] offset:15360
	s_lshr_b32 s25, s24, 1
	s_lshl_b32 s25, s25, 4
	s_lshl_b32 s26, s16, 6
	s_add_i32 s25, s25, s26
	s_and_b32 s26, s24, 1
	s_lshl_b32 s26, s26, 5
	s_lshl_b32 s27, s17, 6
	s_add_i32 s26, s26, s27
	v_add_u32_e32 v171, s25, v134
	v_lshl_add_u32 v172, v135, 2, s26
	v_lshlrev_b32_e32 v174, 2, v172
	s_add_u32 s22, s4, 0x227320
	s_addc_u32 s23, s5, 0
	global_load_dwordx4 v[64:67], v174, s[22:23] offset:0
	global_load_dwordx4 v[68:71], v174, s[22:23] offset:64
	v_lshlrev_b32_e32 v173, 12, v171
	v_add_lshl_u32 v173, v173, v172, 1
	s_add_u32 s20, s4, 0x5e00000
	s_addc_u32 s21, s5, 0
	s_waitcnt lgkmcnt(0)
	s_barrier
	v_lshlrev_b32_e32 v175, 11, v132
	v_lshl_add_u32 v175, v133, 4, v175
	v_add_u32_e32 v100, 0x4000, v175
	v_add_u32_e32 v101, 0x8000, v175
	v_add_u32_e32 v102, 0xc000, v175
	v_add_u32_e32 v103, 0x10000, v175
	v_add_u32_e32 v166, 0x14000, v175
	v_add_u32_e32 v167, 0x18000, v175
	v_add_u32_e32 v168, 0x1c000, v175
	ds_read_b128 v[80:83], v175 offset:0
	ds_read_b128 v[0:3], v100 offset:0
	ds_read_b128 v[4:7], v101 offset:0
	ds_read_b128 v[8:11], v102 offset:0
	ds_read_b128 v[12:15], v103 offset:0
	ds_read_b128 v[16:19], v166 offset:0
	ds_read_b128 v[20:23], v167 offset:0
	ds_read_b128 v[24:27], v168 offset:0
	s_waitcnt lgkmcnt(0)
	ds_read_b128 v[96:99], v175 offset:1024
	ds_read_b128 v[138:141], v100 offset:1024
	ds_read_b128 v[142:145], v101 offset:1024
	ds_read_b128 v[146:149], v102 offset:1024
	ds_read_b128 v[150:153], v103 offset:1024
	ds_read_b128 v[154:157], v166 offset:1024
	ds_read_b128 v[158:161], v167 offset:1024
	ds_read_b128 v[162:165], v168 offset:1024
	s_waitcnt lgkmcnt(0)
	v_add_f32_e32 v80, v80, v0
	v_add_f32_e32 v81, v81, v1
	v_add_f32_e32 v82, v82, v2
	v_add_f32_e32 v83, v83, v3
	v_add_f32_e32 v80, v80, v4
	v_add_f32_e32 v81, v81, v5
	v_add_f32_e32 v82, v82, v6
	v_add_f32_e32 v83, v83, v7
	v_add_f32_e32 v80, v80, v8
	v_add_f32_e32 v81, v81, v9
	v_add_f32_e32 v82, v82, v10
	v_add_f32_e32 v83, v83, v11
	v_add_f32_e32 v80, v80, v12
	v_add_f32_e32 v81, v81, v13
	v_add_f32_e32 v82, v82, v14
	v_add_f32_e32 v83, v83, v15
	v_add_f32_e32 v80, v80, v16
	v_add_f32_e32 v81, v81, v17
	v_add_f32_e32 v82, v82, v18
	v_add_f32_e32 v83, v83, v19
	v_add_f32_e32 v80, v80, v20
	v_add_f32_e32 v81, v81, v21
	v_add_f32_e32 v82, v82, v22
	v_add_f32_e32 v83, v83, v23
	v_add_f32_e32 v80, v80, v24
	v_add_f32_e32 v81, v81, v25
	v_add_f32_e32 v82, v82, v26
	v_add_f32_e32 v83, v83, v27
	v_add_f32_e32 v96, v96, v138
	v_add_f32_e32 v97, v97, v139
	v_add_f32_e32 v98, v98, v140
	v_add_f32_e32 v99, v99, v141
	v_add_f32_e32 v96, v96, v142
	v_add_f32_e32 v97, v97, v143
	v_add_f32_e32 v98, v98, v144
	v_add_f32_e32 v99, v99, v145
	v_add_f32_e32 v96, v96, v146
	v_add_f32_e32 v97, v97, v147
	v_add_f32_e32 v98, v98, v148
	v_add_f32_e32 v99, v99, v149
	v_add_f32_e32 v96, v96, v150
	v_add_f32_e32 v97, v97, v151
	v_add_f32_e32 v98, v98, v152
	v_add_f32_e32 v99, v99, v153
	v_add_f32_e32 v96, v96, v154
	v_add_f32_e32 v97, v97, v155
	v_add_f32_e32 v98, v98, v156
	v_add_f32_e32 v99, v99, v157
	v_add_f32_e32 v96, v96, v158
	v_add_f32_e32 v97, v97, v159
	v_add_f32_e32 v98, v98, v160
	v_add_f32_e32 v99, v99, v161
	v_add_f32_e32 v96, v96, v162
	v_add_f32_e32 v97, v97, v163
	v_add_f32_e32 v98, v98, v164
	v_add_f32_e32 v99, v99, v165
	s_waitcnt vmcnt(0)
	v_add_f32_e32 v80, v80, v64
	v_max_f32_e32 v80, 0, v80
	v_mul_f32_e32 v80, v80, v80
	v_add_f32_e32 v81, v81, v65
	v_max_f32_e32 v81, 0, v81
	v_mul_f32_e32 v81, v81, v81
	v_add_f32_e32 v82, v82, v66
	v_max_f32_e32 v82, 0, v82
	v_mul_f32_e32 v82, v82, v82
	v_add_f32_e32 v83, v83, v67
	v_max_f32_e32 v83, 0, v83
	v_mul_f32_e32 v83, v83, v83
	v_cvt_pk_bf16_f32 v112, v80, v81
	v_cvt_pk_bf16_f32 v113, v82, v83
	global_store_dwordx2 v173, v[112:113], s[20:21] offset:0
	v_add_f32_e32 v96, v96, v68
	v_max_f32_e32 v96, 0, v96
	v_mul_f32_e32 v96, v96, v96
	v_add_f32_e32 v97, v97, v69
	v_max_f32_e32 v97, 0, v97
	v_mul_f32_e32 v97, v97, v97
	v_add_f32_e32 v98, v98, v70
	v_max_f32_e32 v98, 0, v98
	v_mul_f32_e32 v98, v98, v98
	v_add_f32_e32 v99, v99, v71
	v_max_f32_e32 v99, 0, v99
	v_mul_f32_e32 v99, v99, v99
	v_cvt_pk_bf16_f32 v114, v96, v97
	v_cvt_pk_bf16_f32 v115, v98, v99
	global_store_dwordx2 v173, v[114:115], s[20:21] offset:32
	s_barrier
	s_add_i32 s14, s14, 1
	s_cmp_lt_u32 s14, 4
	s_cbranch_scc1 .Lcg_tile_k5
	s_branch .Lcg_done
.Lcg_k7:
	v_lshrrev_b32_e32 v129, 3, v133
	v_and_b32_e32 v128, 7, v133
	v_xor_b32_e32 v128, v128, v129
	v_lshlrev_b32_e32 v128, 4, v128
	v_mul_u32_u24_e32 v129, 0x2000, v129
	v_add_u32_e32 v128, v128, v129
	s_lshl_b32 s30, s24, 14
	v_and_b32_e32 v131, 7, v134
	v_or_b32_e32 v129, 0, v135
	v_xor_b32_e32 v129, v129, v131
	v_lshlrev_b32_e32 v129, 4, v129
	v_lshl_add_u32 v129, v134, 7, v129
	v_add_u32_e32 v129, s30, v129
	v_or_b32_e32 v130, 4, v135
	v_xor_b32_e32 v130, v130, v131
	v_lshlrev_b32_e32 v130, 4, v130
	v_lshl_add_u32 v130, v134, 7, v130
	v_add_u32_e32 v130, s30, v130
	s_mov_b32 s14, 0
.Lcg_tile_k7:
	s_lshr_b32 s16, s69, 4
	s_and_b32 s17, s69, 15
	s_mul_i32 s25, s24, 0x400
	s_mul_i32 s26, s16, 0x80000
	s_add_u32 s26, s26, s25
	s_add_u32 s26, s26, 0x5e00000
	s_add_u32 s10, s4, s26
	s_addc_u32 s11, s5, 0
	s_mul_i32 s26, s17, 0x80000
	s_add_u32 s26, s26, s25
	s_add_u32 s26, s26, 0x1a00000
	s_add_u32 s12, s4, s26
	s_addc_u32 s13, s5, 0
	s_add_u32 s26, s10, 0x0
	s_addc_u32 s27, s11, 0
	s_add_i32 m0, s30, 0x0
	s_nop 0
	global_load_lds_dwordx4 v128, s[26:27]
	s_add_u32 s26, s10, 0x10000
	s_addc_u32 s27, s11, 0
	s_add_i32 m0, s30, 0x400
	s_nop 0
	global_load_lds_dwordx4 v128, s[26:27]
	s_add_u32 s26, s10, 0x20000
	s_addc_u32 s27, s11, 0
	s_add_i32 m0, s30, 0x800
	s_nop 0
	global_load_lds_dwordx4 v128, s[26:27]
	s_add_u32 s26, s10, 0x30000
	s_addc_u32 s27, s11, 0
	s_add_i32 m0, s30, 0xc00
	s_nop 0
	global_load_lds_dwordx4 v128, s[26:27]
	s_add_u32 s26, s10, 0x40000
	s_addc_u32 s27, s11, 0
	s_add_i32 m0, s30, 0x1000
	s_nop 0
	global_load_lds_dwordx4 v128, s[26:27]
	s_add_u32 s26, s10, 0x50000
	s_addc_u32 s27, s11, 0
	s_add_i32 m0, s30, 0x1400
	s_nop 0
	global_load_lds_dwordx4 v128, s[26:27]
	s_add_u32 s26, s10, 0x60000
	s_addc_u32 s27, s11, 0
	s_add_i32 m0, s30, 0x1800
	s_nop 0
	global_load_lds_dwordx4 v128, s[26:27]
	s_add_u32 s26, s10, 0x70000
	s_addc_u32 s27, s11, 0
	s_add_i32 m0, s30, 0x1c00
	s_nop 0
	global_load_lds_dwordx4 v128, s[26:27]
	s_add_u32 s26, s12, 0x0
	s_addc_u32 s27, s13, 0
	s_add_i32 m0, s30, 0x2000
	s_nop 0
	global_load_lds_dwordx4 v128, s[26:27]
	s_add_u32 s26, s12, 0x10000
	s_addc_u32 s27, s13, 0
	s_add_i32 m0, s30, 0x2400
	s_nop 0
	global_load_lds_dwordx4 v128, s[26:27]
	s_add_u32 s26, s12, 0x20000
	s_addc_u32 s27, s13, 0
	s_add_i32 m0, s30, 0x2800
	s_nop 0
	global_load_lds_dwordx4 v128, s[26:27]
	s_add_u32 s26, s12, 0x30000
	s_addc_u32 s27, s13, 0
	s_add_i32 m0, s30, 0x2c00
	s_nop 0
	global_load_lds_dwordx4 v128, s[26:27]
	s_add_u32 s26, s12, 0x40000
	s_addc_u32 s27, s13, 0
	s_add_i32 m0, s30, 0x3000
	s_nop 0
	global_load_lds_dwordx4 v128, s[26:27]
	s_add_u32 s26, s12, 0x50000
	s_addc_u32 s27, s13, 0
	s_add_i32 m0, s30, 0x3400
	s_nop 0
	global_load_lds_dwordx4 v128, s[26:27]
	s_add_u32 s26, s12, 0x60000
	s_addc_u32 s27, s13, 0
	s_add_i32 m0, s30, 0x3800
	s_nop 0
	global_load_lds_dwordx4 v128, s[26:27]
	s_add_u32 s26, s12, 0x70000
	s_addc_u32 s27, s13, 0
	s_add_i32 m0, s30, 0x3c00
	s_nop 0
	global_load_lds_dwordx4 v128, s[26:27]
	s_waitcnt vmcnt(0)
	ds_read_b128 v[64:67], v129 offset:0
	ds_read_b128 v[68:71], v129 offset:2048
	ds_read_b128 v[72:75], v129 offset:4096
	ds_read_b128 v[76:79], v129 offset:6144
	ds_read_b128 v[80:83], v129 offset:8192
	ds_read_b128 v[84:87], v129 offset:10240
	ds_read_b128 v[88:91], v129 offset:12288
	ds_read_b128 v[92:95], v129 offset:14336
	ds_read_b128 v[96:99], v130 offset:0
	ds_read_b128 v[100:103], v130 offset:2048
	ds_read_b128 v[104:107], v130 offset:4096
	ds_read_b128 v[108:111], v130 offset:6144
	ds_read_b128 v[112:115], v130 offset:8192
	ds_read_b128 v[116:119], v130 offset:10240
	ds_read_b128 v[120:123], v130 offset:12288
	ds_read_b128 v[124:127], v130 offset:14336
	s_add_u32 s26, s10, 0x80
	s_addc_u32 s27, s11, 0
	s_add_i32 m0, s30, 0x0
	s_nop 0
	global_load_lds_dwordx4 v128, s[26:27]
	s_add_u32 s26, s10, 0x10080
	s_addc_u32 s27, s11, 0
	s_add_i32 m0, s30, 0x400
	s_nop 0
	global_load_lds_dwordx4 v128, s[26:27]
	s_add_u32 s26, s10, 0x20080
	s_addc_u32 s27, s11, 0
	s_add_i32 m0, s30, 0x800
	s_nop 0
	global_load_lds_dwordx4 v128, s[26:27]
	s_add_u32 s26, s10, 0x30080
	s_addc_u32 s27, s11, 0
	s_add_i32 m0, s30, 0xc00
	s_nop 0
	global_load_lds_dwordx4 v128, s[26:27]
	s_add_u32 s26, s10, 0x40080
	s_addc_u32 s27, s11, 0
	s_add_i32 m0, s30, 0x1000
	s_nop 0
	global_load_lds_dwordx4 v128, s[26:27]
	s_add_u32 s26, s10, 0x50080
	s_addc_u32 s27, s11, 0
	s_add_i32 m0, s30, 0x1400
	s_nop 0
	global_load_lds_dwordx4 v128, s[26:27]
	s_add_u32 s26, s10, 0x60080
	s_addc_u32 s27, s11, 0
	s_add_i32 m0, s30, 0x1800
	s_nop 0
	global_load_lds_dwordx4 v128, s[26:27]
	s_add_u32 s26, s10, 0x70080
	s_addc_u32 s27, s11, 0
	s_add_i32 m0, s30, 0x1c00
	s_nop 0
	global_load_lds_dwordx4 v128, s[26:27]
	s_add_u32 s26, s12, 0x80
	s_addc_u32 s27, s13, 0
	s_add_i32 m0, s30, 0x2000
	s_nop 0
	global_load_lds_dwordx4 v128, s[26:27]
	s_add_u32 s26, s12, 0x10080
	s_addc_u32 s27, s13, 0
	s_add_i32 m0, s30, 0x2400
	s_nop 0
	global_load_lds_dwordx4 v128, s[26:27]
	s_add_u32 s26, s12, 0x20080
	s_addc_u32 s27, s13, 0
	s_add_i32 m0, s30, 0x2800
	s_nop 0
	global_load_lds_dwordx4 v128, s[26:27]
	s_add_u32 s26, s12, 0x30080
	s_addc_u32 s27, s13, 0
	s_add_i32 m0, s30, 0x2c00
	s_nop 0
	global_load_lds_dwordx4 v128, s[26:27]
	s_add_u32 s26, s12, 0x40080
	s_addc_u32 s27, s13, 0
	s_add_i32 m0, s30, 0x3000
	s_nop 0
	global_load_lds_dwordx4 v128, s[26:27]
	s_add_u32 s26, s12, 0x50080
	s_addc_u32 s27, s13, 0
	s_add_i32 m0, s30, 0x3400
	s_nop 0
	global_load_lds_dwordx4 v128, s[26:27]
	s_add_u32 s26, s12, 0x60080
	s_addc_u32 s27, s13, 0
	s_add_i32 m0, s30, 0x3800
	s_nop 0
	global_load_lds_dwordx4 v128, s[26:27]
	s_add_u32 s26, s12, 0x70080
	s_addc_u32 s27, s13, 0
	s_add_i32 m0, s30, 0x3c00
	s_nop 0
	global_load_lds_dwordx4 v128, s[26:27]
	v_mfma_f32_16x16x32_bf16 v[0:3], v[80:83], v[64:67], 0
	v_mfma_f32_16x16x32_bf16 v[4:7], v[84:87], v[64:67], 0
	v_mfma_f32_16x16x32_bf16 v[8:11], v[88:91], v[64:67], 0
	v_mfma_f32_16x16x32_bf16 v[12:15], v[92:95], v[64:67], 0
	v_mfma_f32_16x16x32_bf16 v[16:19], v[80:83], v[68:71], 0
	v_mfma_f32_16x16x32_bf16 v[20:23], v[84:87], v[68:71], 0
	v_mfma_f32_16x16x32_bf16 v[24:27], v[88:91], v[68:71], 0
	v_mfma_f32_16x16x32_bf16 v[28:31], v[92:95], v[68:71], 0
	v_mfma_f32_16x16x32_bf16 v[32:35], v[80:83], v[72:75], 0
	v_mfma_f32_16x16x32_bf16 v[36:39], v[84:87], v[72:75], 0
	v_mfma_f32_16x16x32_bf16 v[40:43], v[88:91], v[72:75], 0
	v_mfma_f32_16x16x32_bf16 v[44:47], v[92:95], v[72:75], 0
	v_mfma_f32_16x16x32_bf16 v[48:51], v[80:83], v[76:79], 0
	v_mfma_f32_16x16x32_bf16 v[52:55], v[84:87], v[76:79], 0
	v_mfma_f32_16x16x32_bf16 v[56:59], v[88:91], v[76:79], 0
	v_mfma_f32_16x16x32_bf16 v[60:63], v[92:95], v[76:79], 0
	v_mfma_f32_16x16x32_bf16 v[0:3], v[112:115], v[96:99], v[0:3]
	v_mfma_f32_16x16x32_bf16 v[4:7], v[116:119], v[96:99], v[4:7]
	v_mfma_f32_16x16x32_bf16 v[8:11], v[120:123], v[96:99], v[8:11]
	v_mfma_f32_16x16x32_bf16 v[12:15], v[124:127], v[96:99], v[12:15]
	v_mfma_f32_16x16x32_bf16 v[16:19], v[112:115], v[100:103], v[16:19]
	v_mfma_f32_16x16x32_bf16 v[20:23], v[116:119], v[100:103], v[20:23]
	v_mfma_f32_16x16x32_bf16 v[24:27], v[120:123], v[100:103], v[24:27]
	v_mfma_f32_16x16x32_bf16 v[28:31], v[124:127], v[100:103], v[28:31]
	v_mfma_f32_16x16x32_bf16 v[32:35], v[112:115], v[104:107], v[32:35]
	v_mfma_f32_16x16x32_bf16 v[36:39], v[116:119], v[104:107], v[36:39]
	v_mfma_f32_16x16x32_bf16 v[40:43], v[120:123], v[104:107], v[40:43]
	v_mfma_f32_16x16x32_bf16 v[44:47], v[124:127], v[104:107], v[44:47]
	v_mfma_f32_16x16x32_bf16 v[48:51], v[112:115], v[108:111], v[48:51]
	v_mfma_f32_16x16x32_bf16 v[52:55], v[116:119], v[108:111], v[52:55]
	v_mfma_f32_16x16x32_bf16 v[56:59], v[120:123], v[108:111], v[56:59]
	v_mfma_f32_16x16x32_bf16 v[60:63], v[124:127], v[108:111], v[60:63]
	s_waitcnt vmcnt(0)
	ds_read_b128 v[64:67], v129 offset:0
	ds_read_b128 v[68:71], v129 offset:2048
	ds_read_b128 v[72:75], v129 offset:4096
	ds_read_b128 v[76:79], v129 offset:6144
	ds_read_b128 v[80:83], v129 offset:8192
	ds_read_b128 v[84:87], v129 offset:10240
	ds_read_b128 v[88:91], v129 offset:12288
	ds_read_b128 v[92:95], v129 offset:14336
	ds_read_b128 v[96:99], v130 offset:0
	ds_read_b128 v[100:103], v130 offset:2048
	ds_read_b128 v[104:107], v130 offset:4096
	ds_read_b128 v[108:111], v130 offset:6144
	ds_read_b128 v[112:115], v130 offset:8192
	ds_read_b128 v[116:119], v130 offset:10240
	ds_read_b128 v[120:123], v130 offset:12288
	ds_read_b128 v[124:127], v130 offset:14336
	s_add_u32 s26, s10, 0x100
	s_addc_u32 s27, s11, 0
	s_add_i32 m0, s30, 0x0
	s_nop 0
	global_load_lds_dwordx4 v128, s[26:27]
	s_add_u32 s26, s10, 0x10100
	s_addc_u32 s27, s11, 0
	s_add_i32 m0, s30, 0x400
	s_nop 0
	global_load_lds_dwordx4 v128, s[26:27]
	s_add_u32 s26, s10, 0x20100
	s_addc_u32 s27, s11, 0
	s_add_i32 m0, s30, 0x800
	s_nop 0
	global_load_lds_dwordx4 v128, s[26:27]
	s_add_u32 s26, s10, 0x30100
	s_addc_u32 s27, s11, 0
	s_add_i32 m0, s30, 0xc00
	s_nop 0
	global_load_lds_dwordx4 v128, s[26:27]
	s_add_u32 s26, s10, 0x40100
	s_addc_u32 s27, s11, 0
	s_add_i32 m0, s30, 0x1000
	s_nop 0
	global_load_lds_dwordx4 v128, s[26:27]
	s_add_u32 s26, s10, 0x50100
	s_addc_u32 s27, s11, 0
	s_add_i32 m0, s30, 0x1400
	s_nop 0
	global_load_lds_dwordx4 v128, s[26:27]
	s_add_u32 s26, s10, 0x60100
	s_addc_u32 s27, s11, 0
	s_add_i32 m0, s30, 0x1800
	s_nop 0
	global_load_lds_dwordx4 v128, s[26:27]
	s_add_u32 s26, s10, 0x70100
	s_addc_u32 s27, s11, 0
	s_add_i32 m0, s30, 0x1c00
	s_nop 0
	global_load_lds_dwordx4 v128, s[26:27]
	s_add_u32 s26, s12, 0x100
	s_addc_u32 s27, s13, 0
	s_add_i32 m0, s30, 0x2000
	s_nop 0
	global_load_lds_dwordx4 v128, s[26:27]
	s_add_u32 s26, s12, 0x10100
	s_addc_u32 s27, s13, 0
	s_add_i32 m0, s30, 0x2400
	s_nop 0
	global_load_lds_dwordx4 v128, s[26:27]
	s_add_u32 s26, s12, 0x20100
	s_addc_u32 s27, s13, 0
	s_add_i32 m0, s30, 0x2800
	s_nop 0
	global_load_lds_dwordx4 v128, s[26:27]
	s_add_u32 s26, s12, 0x30100
	s_addc_u32 s27, s13, 0
	s_add_i32 m0, s30, 0x2c00
	s_nop 0
	global_load_lds_dwordx4 v128, s[26:27]
	s_add_u32 s26, s12, 0x40100
	s_addc_u32 s27, s13, 0
	s_add_i32 m0, s30, 0x3000
	s_nop 0
	global_load_lds_dwordx4 v128, s[26:27]
	s_add_u32 s26, s12, 0x50100
	s_addc_u32 s27, s13, 0
	s_add_i32 m0, s30, 0x3400
	s_nop 0
	global_load_lds_dwordx4 v128, s[26:27]
	s_add_u32 s26, s12, 0x60100
	s_addc_u32 s27, s13, 0
	s_add_i32 m0, s30, 0x3800
	s_nop 0
	global_load_lds_dwordx4 v128, s[26:27]
	s_add_u32 s26, s12, 0x70100
	s_addc_u32 s27, s13, 0
	s_add_i32 m0, s30, 0x3c00
	s_nop 0
	global_load_lds_dwordx4 v128, s[26:27]
	v_mfma_f32_16x16x32_bf16 v[0:3], v[80:83], v[64:67], v[0:3]
	v_mfma_f32_16x16x32_bf16 v[4:7], v[84:87], v[64:67], v[4:7]
	v_mfma_f32_16x16x32_bf16 v[8:11], v[88:91], v[64:67], v[8:11]
	v_mfma_f32_16x16x32_bf16 v[12:15], v[92:95], v[64:67], v[12:15]
	v_mfma_f32_16x16x32_bf16 v[16:19], v[80:83], v[68:71], v[16:19]
	v_mfma_f32_16x16x32_bf16 v[20:23], v[84:87], v[68:71], v[20:23]
	v_mfma_f32_16x16x32_bf16 v[24:27], v[88:91], v[68:71], v[24:27]
	v_mfma_f32_16x16x32_bf16 v[28:31], v[92:95], v[68:71], v[28:31]
	v_mfma_f32_16x16x32_bf16 v[32:35], v[80:83], v[72:75], v[32:35]
	v_mfma_f32_16x16x32_bf16 v[36:39], v[84:87], v[72:75], v[36:39]
	v_mfma_f32_16x16x32_bf16 v[40:43], v[88:91], v[72:75], v[40:43]
	v_mfma_f32_16x16x32_bf16 v[44:47], v[92:95], v[72:75], v[44:47]
	v_mfma_f32_16x16x32_bf16 v[48:51], v[80:83], v[76:79], v[48:51]
	v_mfma_f32_16x16x32_bf16 v[52:55], v[84:87], v[76:79], v[52:55]
	v_mfma_f32_16x16x32_bf16 v[56:59], v[88:91], v[76:79], v[56:59]
	v_mfma_f32_16x16x32_bf16 v[60:63], v[92:95], v[76:79], v[60:63]
	v_mfma_f32_16x16x32_bf16 v[0:3], v[112:115], v[96:99], v[0:3]
	v_mfma_f32_16x16x32_bf16 v[4:7], v[116:119], v[96:99], v[4:7]
	v_mfma_f32_16x16x32_bf16 v[8:11], v[120:123], v[96:99], v[8:11]
	v_mfma_f32_16x16x32_bf16 v[12:15], v[124:127], v[96:99], v[12:15]
	v_mfma_f32_16x16x32_bf16 v[16:19], v[112:115], v[100:103], v[16:19]
	v_mfma_f32_16x16x32_bf16 v[20:23], v[116:119], v[100:103], v[20:23]
	v_mfma_f32_16x16x32_bf16 v[24:27], v[120:123], v[100:103], v[24:27]
	v_mfma_f32_16x16x32_bf16 v[28:31], v[124:127], v[100:103], v[28:31]
	v_mfma_f32_16x16x32_bf16 v[32:35], v[112:115], v[104:107], v[32:35]
	v_mfma_f32_16x16x32_bf16 v[36:39], v[116:119], v[104:107], v[36:39]
	v_mfma_f32_16x16x32_bf16 v[40:43], v[120:123], v[104:107], v[40:43]
	v_mfma_f32_16x16x32_bf16 v[44:47], v[124:127], v[104:107], v[44:47]
	v_mfma_f32_16x16x32_bf16 v[48:51], v[112:115], v[108:111], v[48:51]
	v_mfma_f32_16x16x32_bf16 v[52:55], v[116:119], v[108:111], v[52:55]
	v_mfma_f32_16x16x32_bf16 v[56:59], v[120:123], v[108:111], v[56:59]
	v_mfma_f32_16x16x32_bf16 v[60:63], v[124:127], v[108:111], v[60:63]
	s_waitcnt vmcnt(0)
	ds_read_b128 v[64:67], v129 offset:0
	ds_read_b128 v[68:71], v129 offset:2048
	ds_read_b128 v[72:75], v129 offset:4096
	ds_read_b128 v[76:79], v129 offset:6144
	ds_read_b128 v[80:83], v129 offset:8192
	ds_read_b128 v[84:87], v129 offset:10240
	ds_read_b128 v[88:91], v129 offset:12288
	ds_read_b128 v[92:95], v129 offset:14336
	ds_read_b128 v[96:99], v130 offset:0
	ds_read_b128 v[100:103], v130 offset:2048
	ds_read_b128 v[104:107], v130 offset:4096
	ds_read_b128 v[108:111], v130 offset:6144
	ds_read_b128 v[112:115], v130 offset:8192
	ds_read_b128 v[116:119], v130 offset:10240
	ds_read_b128 v[120:123], v130 offset:12288
	ds_read_b128 v[124:127], v130 offset:14336
	s_waitcnt lgkmcnt(0)
	s_add_u32 s26, s10, 0x180
	s_addc_u32 s27, s11, 0
	s_add_i32 m0, s30, 0x0
	s_nop 0
	global_load_lds_dwordx4 v128, s[26:27]
	s_add_u32 s26, s10, 0x10180
	s_addc_u32 s27, s11, 0
	s_add_i32 m0, s30, 0x400
	s_nop 0
	global_load_lds_dwordx4 v128, s[26:27]
	s_add_u32 s26, s10, 0x20180
	s_addc_u32 s27, s11, 0
	s_add_i32 m0, s30, 0x800
	s_nop 0
	global_load_lds_dwordx4 v128, s[26:27]
	s_add_u32 s26, s10, 0x30180
	s_addc_u32 s27, s11, 0
	s_add_i32 m0, s30, 0xc00
	s_nop 0
	global_load_lds_dwordx4 v128, s[26:27]
	s_add_u32 s26, s10, 0x40180
	s_addc_u32 s27, s11, 0
	s_add_i32 m0, s30, 0x1000
	s_nop 0
	global_load_lds_dwordx4 v128, s[26:27]
	s_add_u32 s26, s10, 0x50180
	s_addc_u32 s27, s11, 0
	s_add_i32 m0, s30, 0x1400
	s_nop 0
	global_load_lds_dwordx4 v128, s[26:27]
	s_add_u32 s26, s10, 0x60180
	s_addc_u32 s27, s11, 0
	s_add_i32 m0, s30, 0x1800
	s_nop 0
	global_load_lds_dwordx4 v128, s[26:27]
	s_add_u32 s26, s10, 0x70180
	s_addc_u32 s27, s11, 0
	s_add_i32 m0, s30, 0x1c00
	s_nop 0
	global_load_lds_dwordx4 v128, s[26:27]
	s_add_u32 s26, s12, 0x180
	s_addc_u32 s27, s13, 0
	s_add_i32 m0, s30, 0x2000
	s_nop 0
	global_load_lds_dwordx4 v128, s[26:27]
	s_add_u32 s26, s12, 0x10180
	s_addc_u32 s27, s13, 0
	s_add_i32 m0, s30, 0x2400
	s_nop 0
	global_load_lds_dwordx4 v128, s[26:27]
	s_add_u32 s26, s12, 0x20180
	s_addc_u32 s27, s13, 0
	s_add_i32 m0, s30, 0x2800
	s_nop 0
	global_load_lds_dwordx4 v128, s[26:27]
	s_add_u32 s26, s12, 0x30180
	s_addc_u32 s27, s13, 0
	s_add_i32 m0, s30, 0x2c00
	s_nop 0
	global_load_lds_dwordx4 v128, s[26:27]
	s_add_u32 s26, s12, 0x40180
	s_addc_u32 s27, s13, 0
	s_add_i32 m0, s30, 0x3000
	s_nop 0
	global_load_lds_dwordx4 v128, s[26:27]
	s_add_u32 s26, s12, 0x50180
	s_addc_u32 s27, s13, 0
	s_add_i32 m0, s30, 0x3400
	s_nop 0
	global_load_lds_dwordx4 v128, s[26:27]
	s_add_u32 s26, s12, 0x60180
	s_addc_u32 s27, s13, 0
	s_add_i32 m0, s30, 0x3800
	s_nop 0
	global_load_lds_dwordx4 v128, s[26:27]
	s_add_u32 s26, s12, 0x70180
	s_addc_u32 s27, s13, 0
	s_add_i32 m0, s30, 0x3c00
	s_nop 0
	global_load_lds_dwordx4 v128, s[26:27]
	v_mfma_f32_16x16x32_bf16 v[0:3], v[80:83], v[64:67], v[0:3]
	v_mfma_f32_16x16x32_bf16 v[4:7], v[84:87], v[64:67], v[4:7]
	v_mfma_f32_16x16x32_bf16 v[8:11], v[88:91], v[64:67], v[8:11]
	v_mfma_f32_16x16x32_bf16 v[12:15], v[92:95], v[64:67], v[12:15]
	v_mfma_f32_16x16x32_bf16 v[16:19], v[80:83], v[68:71], v[16:19]
	v_mfma_f32_16x16x32_bf16 v[20:23], v[84:87], v[68:71], v[20:23]
	v_mfma_f32_16x16x32_bf16 v[24:27], v[88:91], v[68:71], v[24:27]
	v_mfma_f32_16x16x32_bf16 v[28:31], v[92:95], v[68:71], v[28:31]
	v_mfma_f32_16x16x32_bf16 v[32:35], v[80:83], v[72:75], v[32:35]
	v_mfma_f32_16x16x32_bf16 v[36:39], v[84:87], v[72:75], v[36:39]
	v_mfma_f32_16x16x32_bf16 v[40:43], v[88:91], v[72:75], v[40:43]
	v_mfma_f32_16x16x32_bf16 v[44:47], v[92:95], v[72:75], v[44:47]
	v_mfma_f32_16x16x32_bf16 v[48:51], v[80:83], v[76:79], v[48:51]
	v_mfma_f32_16x16x32_bf16 v[52:55], v[84:87], v[76:79], v[52:55]
	v_mfma_f32_16x16x32_bf16 v[56:59], v[88:91], v[76:79], v[56:59]
	v_mfma_f32_16x16x32_bf16 v[60:63], v[92:95], v[76:79], v[60:63]
	v_mfma_f32_16x16x32_bf16 v[0:3], v[112:115], v[96:99], v[0:3]
	v_mfma_f32_16x16x32_bf16 v[4:7], v[116:119], v[96:99], v[4:7]
	v_mfma_f32_16x16x32_bf16 v[8:11], v[120:123], v[96:99], v[8:11]
	v_mfma_f32_16x16x32_bf16 v[12:15], v[124:127], v[96:99], v[12:15]
	v_mfma_f32_16x16x32_bf16 v[16:19], v[112:115], v[100:103], v[16:19]
	v_mfma_f32_16x16x32_bf16 v[20:23], v[116:119], v[100:103], v[20:23]
	v_mfma_f32_16x16x32_bf16 v[24:27], v[120:123], v[100:103], v[24:27]
	v_mfma_f32_16x16x32_bf16 v[28:31], v[124:127], v[100:103], v[28:31]
	v_mfma_f32_16x16x32_bf16 v[32:35], v[112:115], v[104:107], v[32:35]
	v_mfma_f32_16x16x32_bf16 v[36:39], v[116:119], v[104:107], v[36:39]
	v_mfma_f32_16x16x32_bf16 v[40:43], v[120:123], v[104:107], v[40:43]
	v_mfma_f32_16x16x32_bf16 v[44:47], v[124:127], v[104:107], v[44:47]
	v_mfma_f32_16x16x32_bf16 v[48:51], v[112:115], v[108:111], v[48:51]
	v_mfma_f32_16x16x32_bf16 v[52:55], v[116:119], v[108:111], v[52:55]
	v_mfma_f32_16x16x32_bf16 v[56:59], v[120:123], v[108:111], v[56:59]
	v_mfma_f32_16x16x32_bf16 v[60:63], v[124:127], v[108:111], v[60:63]
	s_waitcnt vmcnt(0)
	ds_read_b128 v[64:67], v129 offset:0
	ds_read_b128 v[68:71], v129 offset:2048
	ds_read_b128 v[72:75], v129 offset:4096
	ds_read_b128 v[76:79], v129 offset:6144
	ds_read_b128 v[80:83], v129 offset:8192
	ds_read_b128 v[84:87], v129 offset:10240
	ds_read_b128 v[88:91], v129 offset:12288
	ds_read_b128 v[92:95], v129 offset:14336
	ds_read_b128 v[96:99], v130 offset:0
	ds_read_b128 v[100:103], v130 offset:2048
	ds_read_b128 v[104:107], v130 offset:4096
	ds_read_b128 v[108:111], v130 offset:6144
	ds_read_b128 v[112:115], v130 offset:8192
	ds_read_b128 v[116:119], v130 offset:10240
	ds_read_b128 v[120:123], v130 offset:12288
	ds_read_b128 v[124:127], v130 offset:14336
	s_waitcnt lgkmcnt(0)
	s_add_u32 s26, s10, 0x200
	s_addc_u32 s27, s11, 0
	s_add_i32 m0, s30, 0x0
	s_nop 0
	global_load_lds_dwordx4 v128, s[26:27]
	s_add_u32 s26, s10, 0x10200
	s_addc_u32 s27, s11, 0
	s_add_i32 m0, s30, 0x400
	s_nop 0
	global_load_lds_dwordx4 v128, s[26:27]
	s_add_u32 s26, s10, 0x20200
	s_addc_u32 s27, s11, 0
	s_add_i32 m0, s30, 0x800
	s_nop 0
	global_load_lds_dwordx4 v128, s[26:27]
	s_add_u32 s26, s10, 0x30200
	s_addc_u32 s27, s11, 0
	s_add_i32 m0, s30, 0xc00
	s_nop 0
	global_load_lds_dwordx4 v128, s[26:27]
	s_add_u32 s26, s10, 0x40200
	s_addc_u32 s27, s11, 0
	s_add_i32 m0, s30, 0x1000
	s_nop 0
	global_load_lds_dwordx4 v128, s[26:27]
	s_add_u32 s26, s10, 0x50200
	s_addc_u32 s27, s11, 0
	s_add_i32 m0, s30, 0x1400
	s_nop 0
	global_load_lds_dwordx4 v128, s[26:27]
	s_add_u32 s26, s10, 0x60200
	s_addc_u32 s27, s11, 0
	s_add_i32 m0, s30, 0x1800
	s_nop 0
	global_load_lds_dwordx4 v128, s[26:27]
	s_add_u32 s26, s10, 0x70200
	s_addc_u32 s27, s11, 0
	s_add_i32 m0, s30, 0x1c00
	s_nop 0
	global_load_lds_dwordx4 v128, s[26:27]
	s_add_u32 s26, s12, 0x200
	s_addc_u32 s27, s13, 0
	s_add_i32 m0, s30, 0x2000
	s_nop 0
	global_load_lds_dwordx4 v128, s[26:27]
	s_add_u32 s26, s12, 0x10200
	s_addc_u32 s27, s13, 0
	s_add_i32 m0, s30, 0x2400
	s_nop 0
	global_load_lds_dwordx4 v128, s[26:27]
	s_add_u32 s26, s12, 0x20200
	s_addc_u32 s27, s13, 0
	s_add_i32 m0, s30, 0x2800
	s_nop 0
	global_load_lds_dwordx4 v128, s[26:27]
	s_add_u32 s26, s12, 0x30200
	s_addc_u32 s27, s13, 0
	s_add_i32 m0, s30, 0x2c00
	s_nop 0
	global_load_lds_dwordx4 v128, s[26:27]
	s_add_u32 s26, s12, 0x40200
	s_addc_u32 s27, s13, 0
	s_add_i32 m0, s30, 0x3000
	s_nop 0
	global_load_lds_dwordx4 v128, s[26:27]
	s_add_u32 s26, s12, 0x50200
	s_addc_u32 s27, s13, 0
	s_add_i32 m0, s30, 0x3400
	s_nop 0
	global_load_lds_dwordx4 v128, s[26:27]
	s_add_u32 s26, s12, 0x60200
	s_addc_u32 s27, s13, 0
	s_add_i32 m0, s30, 0x3800
	s_nop 0
	global_load_lds_dwordx4 v128, s[26:27]
	s_add_u32 s26, s12, 0x70200
	s_addc_u32 s27, s13, 0
	s_add_i32 m0, s30, 0x3c00
	s_nop 0
	global_load_lds_dwordx4 v128, s[26:27]
	v_mfma_f32_16x16x32_bf16 v[0:3], v[80:83], v[64:67], v[0:3]
	v_mfma_f32_16x16x32_bf16 v[4:7], v[84:87], v[64:67], v[4:7]
	v_mfma_f32_16x16x32_bf16 v[8:11], v[88:91], v[64:67], v[8:11]
	v_mfma_f32_16x16x32_bf16 v[12:15], v[92:95], v[64:67], v[12:15]
	v_mfma_f32_16x16x32_bf16 v[16:19], v[80:83], v[68:71], v[16:19]
	v_mfma_f32_16x16x32_bf16 v[20:23], v[84:87], v[68:71], v[20:23]
	v_mfma_f32_16x16x32_bf16 v[24:27], v[88:91], v[68:71], v[24:27]
	v_mfma_f32_16x16x32_bf16 v[28:31], v[92:95], v[68:71], v[28:31]
	v_mfma_f32_16x16x32_bf16 v[32:35], v[80:83], v[72:75], v[32:35]
	v_mfma_f32_16x16x32_bf16 v[36:39], v[84:87], v[72:75], v[36:39]
	v_mfma_f32_16x16x32_bf16 v[40:43], v[88:91], v[72:75], v[40:43]
	v_mfma_f32_16x16x32_bf16 v[44:47], v[92:95], v[72:75], v[44:47]
	v_mfma_f32_16x16x32_bf16 v[48:51], v[80:83], v[76:79], v[48:51]
	v_mfma_f32_16x16x32_bf16 v[52:55], v[84:87], v[76:79], v[52:55]
	v_mfma_f32_16x16x32_bf16 v[56:59], v[88:91], v[76:79], v[56:59]
	v_mfma_f32_16x16x32_bf16 v[60:63], v[92:95], v[76:79], v[60:63]
	v_mfma_f32_16x16x32_bf16 v[0:3], v[112:115], v[96:99], v[0:3]
	v_mfma_f32_16x16x32_bf16 v[4:7], v[116:119], v[96:99], v[4:7]
	v_mfma_f32_16x16x32_bf16 v[8:11], v[120:123], v[96:99], v[8:11]
	v_mfma_f32_16x16x32_bf16 v[12:15], v[124:127], v[96:99], v[12:15]
	v_mfma_f32_16x16x32_bf16 v[16:19], v[112:115], v[100:103], v[16:19]
	v_mfma_f32_16x16x32_bf16 v[20:23], v[116:119], v[100:103], v[20:23]
	v_mfma_f32_16x16x32_bf16 v[24:27], v[120:123], v[100:103], v[24:27]
	v_mfma_f32_16x16x32_bf16 v[28:31], v[124:127], v[100:103], v[28:31]
	v_mfma_f32_16x16x32_bf16 v[32:35], v[112:115], v[104:107], v[32:35]
	v_mfma_f32_16x16x32_bf16 v[36:39], v[116:119], v[104:107], v[36:39]
	v_mfma_f32_16x16x32_bf16 v[40:43], v[120:123], v[104:107], v[40:43]
	v_mfma_f32_16x16x32_bf16 v[44:47], v[124:127], v[104:107], v[44:47]
	v_mfma_f32_16x16x32_bf16 v[48:51], v[112:115], v[108:111], v[48:51]
	v_mfma_f32_16x16x32_bf16 v[52:55], v[116:119], v[108:111], v[52:55]
	v_mfma_f32_16x16x32_bf16 v[56:59], v[120:123], v[108:111], v[56:59]
	v_mfma_f32_16x16x32_bf16 v[60:63], v[124:127], v[108:111], v[60:63]
	s_waitcnt vmcnt(0)
	ds_read_b128 v[64:67], v129 offset:0
	ds_read_b128 v[68:71], v129 offset:2048
	ds_read_b128 v[72:75], v129 offset:4096
	ds_read_b128 v[76:79], v129 offset:6144
	ds_read_b128 v[80:83], v129 offset:8192
	ds_read_b128 v[84:87], v129 offset:10240
	ds_read_b128 v[88:91], v129 offset:12288
	ds_read_b128 v[92:95], v129 offset:14336
	ds_read_b128 v[96:99], v130 offset:0
	ds_read_b128 v[100:103], v130 offset:2048
	ds_read_b128 v[104:107], v130 offset:4096
	ds_read_b128 v[108:111], v130 offset:6144
	ds_read_b128 v[112:115], v130 offset:8192
	ds_read_b128 v[116:119], v130 offset:10240
	ds_read_b128 v[120:123], v130 offset:12288
	ds_read_b128 v[124:127], v130 offset:14336
	s_waitcnt lgkmcnt(0)
	s_add_u32 s26, s10, 0x280
	s_addc_u32 s27, s11, 0
	s_add_i32 m0, s30, 0x0
	s_nop 0
	global_load_lds_dwordx4 v128, s[26:27]
	s_add_u32 s26, s10, 0x10280
	s_addc_u32 s27, s11, 0
	s_add_i32 m0, s30, 0x400
	s_nop 0
	global_load_lds_dwordx4 v128, s[26:27]
	s_add_u32 s26, s10, 0x20280
	s_addc_u32 s27, s11, 0
	s_add_i32 m0, s30, 0x800
	s_nop 0
	global_load_lds_dwordx4 v128, s[26:27]
	s_add_u32 s26, s10, 0x30280
	s_addc_u32 s27, s11, 0
	s_add_i32 m0, s30, 0xc00
	s_nop 0
	global_load_lds_dwordx4 v128, s[26:27]
	s_add_u32 s26, s10, 0x40280
	s_addc_u32 s27, s11, 0
	s_add_i32 m0, s30, 0x1000
	s_nop 0
	global_load_lds_dwordx4 v128, s[26:27]
	s_add_u32 s26, s10, 0x50280
	s_addc_u32 s27, s11, 0
	s_add_i32 m0, s30, 0x1400
	s_nop 0
	global_load_lds_dwordx4 v128, s[26:27]
	s_add_u32 s26, s10, 0x60280
	s_addc_u32 s27, s11, 0
	s_add_i32 m0, s30, 0x1800
	s_nop 0
	global_load_lds_dwordx4 v128, s[26:27]
	s_add_u32 s26, s10, 0x70280
	s_addc_u32 s27, s11, 0
	s_add_i32 m0, s30, 0x1c00
	s_nop 0
	global_load_lds_dwordx4 v128, s[26:27]
	s_add_u32 s26, s12, 0x280
	s_addc_u32 s27, s13, 0
	s_add_i32 m0, s30, 0x2000
	s_nop 0
	global_load_lds_dwordx4 v128, s[26:27]
	s_add_u32 s26, s12, 0x10280
	s_addc_u32 s27, s13, 0
	s_add_i32 m0, s30, 0x2400
	s_nop 0
	global_load_lds_dwordx4 v128, s[26:27]
	s_add_u32 s26, s12, 0x20280
	s_addc_u32 s27, s13, 0
	s_add_i32 m0, s30, 0x2800
	s_nop 0
	global_load_lds_dwordx4 v128, s[26:27]
	s_add_u32 s26, s12, 0x30280
	s_addc_u32 s27, s13, 0
	s_add_i32 m0, s30, 0x2c00
	s_nop 0
	global_load_lds_dwordx4 v128, s[26:27]
	s_add_u32 s26, s12, 0x40280
	s_addc_u32 s27, s13, 0
	s_add_i32 m0, s30, 0x3000
	s_nop 0
	global_load_lds_dwordx4 v128, s[26:27]
	s_add_u32 s26, s12, 0x50280
	s_addc_u32 s27, s13, 0
	s_add_i32 m0, s30, 0x3400
	s_nop 0
	global_load_lds_dwordx4 v128, s[26:27]
	s_add_u32 s26, s12, 0x60280
	s_addc_u32 s27, s13, 0
	s_add_i32 m0, s30, 0x3800
	s_nop 0
	global_load_lds_dwordx4 v128, s[26:27]
	s_add_u32 s26, s12, 0x70280
	s_addc_u32 s27, s13, 0
	s_add_i32 m0, s30, 0x3c00
	s_nop 0
	global_load_lds_dwordx4 v128, s[26:27]
	v_mfma_f32_16x16x32_bf16 v[0:3], v[80:83], v[64:67], v[0:3]
	v_mfma_f32_16x16x32_bf16 v[4:7], v[84:87], v[64:67], v[4:7]
	v_mfma_f32_16x16x32_bf16 v[8:11], v[88:91], v[64:67], v[8:11]
	v_mfma_f32_16x16x32_bf16 v[12:15], v[92:95], v[64:67], v[12:15]
	v_mfma_f32_16x16x32_bf16 v[16:19], v[80:83], v[68:71], v[16:19]
	v_mfma_f32_16x16x32_bf16 v[20:23], v[84:87], v[68:71], v[20:23]
	v_mfma_f32_16x16x32_bf16 v[24:27], v[88:91], v[68:71], v[24:27]
	v_mfma_f32_16x16x32_bf16 v[28:31], v[92:95], v[68:71], v[28:31]
	v_mfma_f32_16x16x32_bf16 v[32:35], v[80:83], v[72:75], v[32:35]
	v_mfma_f32_16x16x32_bf16 v[36:39], v[84:87], v[72:75], v[36:39]
	v_mfma_f32_16x16x32_bf16 v[40:43], v[88:91], v[72:75], v[40:43]
	v_mfma_f32_16x16x32_bf16 v[44:47], v[92:95], v[72:75], v[44:47]
	v_mfma_f32_16x16x32_bf16 v[48:51], v[80:83], v[76:79], v[48:51]
	v_mfma_f32_16x16x32_bf16 v[52:55], v[84:87], v[76:79], v[52:55]
	v_mfma_f32_16x16x32_bf16 v[56:59], v[88:91], v[76:79], v[56:59]
	v_mfma_f32_16x16x32_bf16 v[60:63], v[92:95], v[76:79], v[60:63]
	v_mfma_f32_16x16x32_bf16 v[0:3], v[112:115], v[96:99], v[0:3]
	v_mfma_f32_16x16x32_bf16 v[4:7], v[116:119], v[96:99], v[4:7]
	v_mfma_f32_16x16x32_bf16 v[8:11], v[120:123], v[96:99], v[8:11]
	v_mfma_f32_16x16x32_bf16 v[12:15], v[124:127], v[96:99], v[12:15]
	v_mfma_f32_16x16x32_bf16 v[16:19], v[112:115], v[100:103], v[16:19]
	v_mfma_f32_16x16x32_bf16 v[20:23], v[116:119], v[100:103], v[20:23]
	v_mfma_f32_16x16x32_bf16 v[24:27], v[120:123], v[100:103], v[24:27]
	v_mfma_f32_16x16x32_bf16 v[28:31], v[124:127], v[100:103], v[28:31]
	v_mfma_f32_16x16x32_bf16 v[32:35], v[112:115], v[104:107], v[32:35]
	v_mfma_f32_16x16x32_bf16 v[36:39], v[116:119], v[104:107], v[36:39]
	v_mfma_f32_16x16x32_bf16 v[40:43], v[120:123], v[104:107], v[40:43]
	v_mfma_f32_16x16x32_bf16 v[44:47], v[124:127], v[104:107], v[44:47]
	v_mfma_f32_16x16x32_bf16 v[48:51], v[112:115], v[108:111], v[48:51]
	v_mfma_f32_16x16x32_bf16 v[52:55], v[116:119], v[108:111], v[52:55]
	v_mfma_f32_16x16x32_bf16 v[56:59], v[120:123], v[108:111], v[56:59]
	v_mfma_f32_16x16x32_bf16 v[60:63], v[124:127], v[108:111], v[60:63]
	s_waitcnt vmcnt(0)
	ds_read_b128 v[64:67], v129 offset:0
	ds_read_b128 v[68:71], v129 offset:2048
	ds_read_b128 v[72:75], v129 offset:4096
	ds_read_b128 v[76:79], v129 offset:6144
	ds_read_b128 v[80:83], v129 offset:8192
	ds_read_b128 v[84:87], v129 offset:10240
	ds_read_b128 v[88:91], v129 offset:12288
	ds_read_b128 v[92:95], v129 offset:14336
	ds_read_b128 v[96:99], v130 offset:0
	ds_read_b128 v[100:103], v130 offset:2048
	ds_read_b128 v[104:107], v130 offset:4096
	ds_read_b128 v[108:111], v130 offset:6144
	ds_read_b128 v[112:115], v130 offset:8192
	ds_read_b128 v[116:119], v130 offset:10240
	ds_read_b128 v[120:123], v130 offset:12288
	ds_read_b128 v[124:127], v130 offset:14336
	s_waitcnt lgkmcnt(0)
	s_add_u32 s26, s10, 0x300
	s_addc_u32 s27, s11, 0
	s_add_i32 m0, s30, 0x0
	s_nop 0
	global_load_lds_dwordx4 v128, s[26:27]
	s_add_u32 s26, s10, 0x10300
	s_addc_u32 s27, s11, 0
	s_add_i32 m0, s30, 0x400
	s_nop 0
	global_load_lds_dwordx4 v128, s[26:27]
	s_add_u32 s26, s10, 0x20300
	s_addc_u32 s27, s11, 0
	s_add_i32 m0, s30, 0x800
	s_nop 0
	global_load_lds_dwordx4 v128, s[26:27]
	s_add_u32 s26, s10, 0x30300
	s_addc_u32 s27, s11, 0
	s_add_i32 m0, s30, 0xc00
	s_nop 0
	global_load_lds_dwordx4 v128, s[26:27]
	s_add_u32 s26, s10, 0x40300
	s_addc_u32 s27, s11, 0
	s_add_i32 m0, s30, 0x1000
	s_nop 0
	global_load_lds_dwordx4 v128, s[26:27]
	s_add_u32 s26, s10, 0x50300
	s_addc_u32 s27, s11, 0
	s_add_i32 m0, s30, 0x1400
	s_nop 0
	global_load_lds_dwordx4 v128, s[26:27]
	s_add_u32 s26, s10, 0x60300
	s_addc_u32 s27, s11, 0
	s_add_i32 m0, s30, 0x1800
	s_nop 0
	global_load_lds_dwordx4 v128, s[26:27]
	s_add_u32 s26, s10, 0x70300
	s_addc_u32 s27, s11, 0
	s_add_i32 m0, s30, 0x1c00
	s_nop 0
	global_load_lds_dwordx4 v128, s[26:27]
	s_add_u32 s26, s12, 0x300
	s_addc_u32 s27, s13, 0
	s_add_i32 m0, s30, 0x2000
	s_nop 0
	global_load_lds_dwordx4 v128, s[26:27]
	s_add_u32 s26, s12, 0x10300
	s_addc_u32 s27, s13, 0
	s_add_i32 m0, s30, 0x2400
	s_nop 0
	global_load_lds_dwordx4 v128, s[26:27]
	s_add_u32 s26, s12, 0x20300
	s_addc_u32 s27, s13, 0
	s_add_i32 m0, s30, 0x2800
	s_nop 0
	global_load_lds_dwordx4 v128, s[26:27]
	s_add_u32 s26, s12, 0x30300
	s_addc_u32 s27, s13, 0
	s_add_i32 m0, s30, 0x2c00
	s_nop 0
	global_load_lds_dwordx4 v128, s[26:27]
	s_add_u32 s26, s12, 0x40300
	s_addc_u32 s27, s13, 0
	s_add_i32 m0, s30, 0x3000
	s_nop 0
	global_load_lds_dwordx4 v128, s[26:27]
	s_add_u32 s26, s12, 0x50300
	s_addc_u32 s27, s13, 0
	s_add_i32 m0, s30, 0x3400
	s_nop 0
	global_load_lds_dwordx4 v128, s[26:27]
	s_add_u32 s26, s12, 0x60300
	s_addc_u32 s27, s13, 0
	s_add_i32 m0, s30, 0x3800
	s_nop 0
	global_load_lds_dwordx4 v128, s[26:27]
	s_add_u32 s26, s12, 0x70300
	s_addc_u32 s27, s13, 0
	s_add_i32 m0, s30, 0x3c00
	s_nop 0
	global_load_lds_dwordx4 v128, s[26:27]
	v_mfma_f32_16x16x32_bf16 v[0:3], v[80:83], v[64:67], v[0:3]
	v_mfma_f32_16x16x32_bf16 v[4:7], v[84:87], v[64:67], v[4:7]
	v_mfma_f32_16x16x32_bf16 v[8:11], v[88:91], v[64:67], v[8:11]
	v_mfma_f32_16x16x32_bf16 v[12:15], v[92:95], v[64:67], v[12:15]
	v_mfma_f32_16x16x32_bf16 v[16:19], v[80:83], v[68:71], v[16:19]
	v_mfma_f32_16x16x32_bf16 v[20:23], v[84:87], v[68:71], v[20:23]
	v_mfma_f32_16x16x32_bf16 v[24:27], v[88:91], v[68:71], v[24:27]
	v_mfma_f32_16x16x32_bf16 v[28:31], v[92:95], v[68:71], v[28:31]
	v_mfma_f32_16x16x32_bf16 v[32:35], v[80:83], v[72:75], v[32:35]
	v_mfma_f32_16x16x32_bf16 v[36:39], v[84:87], v[72:75], v[36:39]
	v_mfma_f32_16x16x32_bf16 v[40:43], v[88:91], v[72:75], v[40:43]
	v_mfma_f32_16x16x32_bf16 v[44:47], v[92:95], v[72:75], v[44:47]
	v_mfma_f32_16x16x32_bf16 v[48:51], v[80:83], v[76:79], v[48:51]
	v_mfma_f32_16x16x32_bf16 v[52:55], v[84:87], v[76:79], v[52:55]
	v_mfma_f32_16x16x32_bf16 v[56:59], v[88:91], v[76:79], v[56:59]
	v_mfma_f32_16x16x32_bf16 v[60:63], v[92:95], v[76:79], v[60:63]
	v_mfma_f32_16x16x32_bf16 v[0:3], v[112:115], v[96:99], v[0:3]
	v_mfma_f32_16x16x32_bf16 v[4:7], v[116:119], v[96:99], v[4:7]
	v_mfma_f32_16x16x32_bf16 v[8:11], v[120:123], v[96:99], v[8:11]
	v_mfma_f32_16x16x32_bf16 v[12:15], v[124:127], v[96:99], v[12:15]
	v_mfma_f32_16x16x32_bf16 v[16:19], v[112:115], v[100:103], v[16:19]
	v_mfma_f32_16x16x32_bf16 v[20:23], v[116:119], v[100:103], v[20:23]
	v_mfma_f32_16x16x32_bf16 v[24:27], v[120:123], v[100:103], v[24:27]
	v_mfma_f32_16x16x32_bf16 v[28:31], v[124:127], v[100:103], v[28:31]
	v_mfma_f32_16x16x32_bf16 v[32:35], v[112:115], v[104:107], v[32:35]
	v_mfma_f32_16x16x32_bf16 v[36:39], v[116:119], v[104:107], v[36:39]
	v_mfma_f32_16x16x32_bf16 v[40:43], v[120:123], v[104:107], v[40:43]
	v_mfma_f32_16x16x32_bf16 v[44:47], v[124:127], v[104:107], v[44:47]
	v_mfma_f32_16x16x32_bf16 v[48:51], v[112:115], v[108:111], v[48:51]
	v_mfma_f32_16x16x32_bf16 v[52:55], v[116:119], v[108:111], v[52:55]
	v_mfma_f32_16x16x32_bf16 v[56:59], v[120:123], v[108:111], v[56:59]
	v_mfma_f32_16x16x32_bf16 v[60:63], v[124:127], v[108:111], v[60:63]
	s_waitcnt vmcnt(0)
	ds_read_b128 v[64:67], v129 offset:0
	ds_read_b128 v[68:71], v129 offset:2048
	ds_read_b128 v[72:75], v129 offset:4096
	ds_read_b128 v[76:79], v129 offset:6144
	ds_read_b128 v[80:83], v129 offset:8192
	ds_read_b128 v[84:87], v129 offset:10240
	ds_read_b128 v[88:91], v129 offset:12288
	ds_read_b128 v[92:95], v129 offset:14336
	ds_read_b128 v[96:99], v130 offset:0
	ds_read_b128 v[100:103], v130 offset:2048
	ds_read_b128 v[104:107], v130 offset:4096
	ds_read_b128 v[108:111], v130 offset:6144
	ds_read_b128 v[112:115], v130 offset:8192
	ds_read_b128 v[116:119], v130 offset:10240
	ds_read_b128 v[120:123], v130 offset:12288
	ds_read_b128 v[124:127], v130 offset:14336
	s_waitcnt lgkmcnt(0)
	s_add_u32 s26, s10, 0x380
	s_addc_u32 s27, s11, 0
	s_add_i32 m0, s30, 0x0
	s_nop 0
	global_load_lds_dwordx4 v128, s[26:27]
	s_add_u32 s26, s10, 0x10380
	s_addc_u32 s27, s11, 0
	s_add_i32 m0, s30, 0x400
	s_nop 0
	global_load_lds_dwordx4 v128, s[26:27]
	s_add_u32 s26, s10, 0x20380
	s_addc_u32 s27, s11, 0
	s_add_i32 m0, s30, 0x800
	s_nop 0
	global_load_lds_dwordx4 v128, s[26:27]
	s_add_u32 s26, s10, 0x30380
	s_addc_u32 s27, s11, 0
	s_add_i32 m0, s30, 0xc00
	s_nop 0
	global_load_lds_dwordx4 v128, s[26:27]
	s_add_u32 s26, s10, 0x40380
	s_addc_u32 s27, s11, 0
	s_add_i32 m0, s30, 0x1000
	s_nop 0
	global_load_lds_dwordx4 v128, s[26:27]
	s_add_u32 s26, s10, 0x50380
	s_addc_u32 s27, s11, 0
	s_add_i32 m0, s30, 0x1400
	s_nop 0
	global_load_lds_dwordx4 v128, s[26:27]
	s_add_u32 s26, s10, 0x60380
	s_addc_u32 s27, s11, 0
	s_add_i32 m0, s30, 0x1800
	s_nop 0
	global_load_lds_dwordx4 v128, s[26:27]
	s_add_u32 s26, s10, 0x70380
	s_addc_u32 s27, s11, 0
	s_add_i32 m0, s30, 0x1c00
	s_nop 0
	global_load_lds_dwordx4 v128, s[26:27]
	s_add_u32 s26, s12, 0x380
	s_addc_u32 s27, s13, 0
	s_add_i32 m0, s30, 0x2000
	s_nop 0
	global_load_lds_dwordx4 v128, s[26:27]
	s_add_u32 s26, s12, 0x10380
	s_addc_u32 s27, s13, 0
	s_add_i32 m0, s30, 0x2400
	s_nop 0
	global_load_lds_dwordx4 v128, s[26:27]
	s_add_u32 s26, s12, 0x20380
	s_addc_u32 s27, s13, 0
	s_add_i32 m0, s30, 0x2800
	s_nop 0
	global_load_lds_dwordx4 v128, s[26:27]
	s_add_u32 s26, s12, 0x30380
	s_addc_u32 s27, s13, 0
	s_add_i32 m0, s30, 0x2c00
	s_nop 0
	global_load_lds_dwordx4 v128, s[26:27]
	s_add_u32 s26, s12, 0x40380
	s_addc_u32 s27, s13, 0
	s_add_i32 m0, s30, 0x3000
	s_nop 0
	global_load_lds_dwordx4 v128, s[26:27]
	s_add_u32 s26, s12, 0x50380
	s_addc_u32 s27, s13, 0
	s_add_i32 m0, s30, 0x3400
	s_nop 0
	global_load_lds_dwordx4 v128, s[26:27]
	s_add_u32 s26, s12, 0x60380
	s_addc_u32 s27, s13, 0
	s_add_i32 m0, s30, 0x3800
	s_nop 0
	global_load_lds_dwordx4 v128, s[26:27]
	s_add_u32 s26, s12, 0x70380
	s_addc_u32 s27, s13, 0
	s_add_i32 m0, s30, 0x3c00
	s_nop 0
	global_load_lds_dwordx4 v128, s[26:27]
	v_mfma_f32_16x16x32_bf16 v[0:3], v[80:83], v[64:67], v[0:3]
	v_mfma_f32_16x16x32_bf16 v[4:7], v[84:87], v[64:67], v[4:7]
	v_mfma_f32_16x16x32_bf16 v[8:11], v[88:91], v[64:67], v[8:11]
	v_mfma_f32_16x16x32_bf16 v[12:15], v[92:95], v[64:67], v[12:15]
	v_mfma_f32_16x16x32_bf16 v[16:19], v[80:83], v[68:71], v[16:19]
	v_mfma_f32_16x16x32_bf16 v[20:23], v[84:87], v[68:71], v[20:23]
	v_mfma_f32_16x16x32_bf16 v[24:27], v[88:91], v[68:71], v[24:27]
	v_mfma_f32_16x16x32_bf16 v[28:31], v[92:95], v[68:71], v[28:31]
	v_mfma_f32_16x16x32_bf16 v[32:35], v[80:83], v[72:75], v[32:35]
	v_mfma_f32_16x16x32_bf16 v[36:39], v[84:87], v[72:75], v[36:39]
	v_mfma_f32_16x16x32_bf16 v[40:43], v[88:91], v[72:75], v[40:43]
	v_mfma_f32_16x16x32_bf16 v[44:47], v[92:95], v[72:75], v[44:47]
	v_mfma_f32_16x16x32_bf16 v[48:51], v[80:83], v[76:79], v[48:51]
	v_mfma_f32_16x16x32_bf16 v[52:55], v[84:87], v[76:79], v[52:55]
	v_mfma_f32_16x16x32_bf16 v[56:59], v[88:91], v[76:79], v[56:59]
	v_mfma_f32_16x16x32_bf16 v[60:63], v[92:95], v[76:79], v[60:63]
	v_mfma_f32_16x16x32_bf16 v[0:3], v[112:115], v[96:99], v[0:3]
	v_mfma_f32_16x16x32_bf16 v[4:7], v[116:119], v[96:99], v[4:7]
	v_mfma_f32_16x16x32_bf16 v[8:11], v[120:123], v[96:99], v[8:11]
	v_mfma_f32_16x16x32_bf16 v[12:15], v[124:127], v[96:99], v[12:15]
	v_mfma_f32_16x16x32_bf16 v[16:19], v[112:115], v[100:103], v[16:19]
	v_mfma_f32_16x16x32_bf16 v[20:23], v[116:119], v[100:103], v[20:23]
	v_mfma_f32_16x16x32_bf16 v[24:27], v[120:123], v[100:103], v[24:27]
	v_mfma_f32_16x16x32_bf16 v[28:31], v[124:127], v[100:103], v[28:31]
	v_mfma_f32_16x16x32_bf16 v[32:35], v[112:115], v[104:107], v[32:35]
	v_mfma_f32_16x16x32_bf16 v[36:39], v[116:119], v[104:107], v[36:39]
	v_mfma_f32_16x16x32_bf16 v[40:43], v[120:123], v[104:107], v[40:43]
	v_mfma_f32_16x16x32_bf16 v[44:47], v[124:127], v[104:107], v[44:47]
	v_mfma_f32_16x16x32_bf16 v[48:51], v[112:115], v[108:111], v[48:51]
	v_mfma_f32_16x16x32_bf16 v[52:55], v[116:119], v[108:111], v[52:55]
	v_mfma_f32_16x16x32_bf16 v[56:59], v[120:123], v[108:111], v[56:59]
	v_mfma_f32_16x16x32_bf16 v[60:63], v[124:127], v[108:111], v[60:63]
	s_waitcnt vmcnt(0)
	ds_read_b128 v[64:67], v129 offset:0
	ds_read_b128 v[68:71], v129 offset:2048
	ds_read_b128 v[72:75], v129 offset:4096
	ds_read_b128 v[76:79], v129 offset:6144
	ds_read_b128 v[80:83], v129 offset:8192
	ds_read_b128 v[84:87], v129 offset:10240
	ds_read_b128 v[88:91], v129 offset:12288
	ds_read_b128 v[92:95], v129 offset:14336
	ds_read_b128 v[96:99], v130 offset:0
	ds_read_b128 v[100:103], v130 offset:2048
	ds_read_b128 v[104:107], v130 offset:4096
	ds_read_b128 v[108:111], v130 offset:6144
	ds_read_b128 v[112:115], v130 offset:8192
	ds_read_b128 v[116:119], v130 offset:10240
	ds_read_b128 v[120:123], v130 offset:12288
	ds_read_b128 v[124:127], v130 offset:14336
	s_waitcnt lgkmcnt(0)
	v_mfma_f32_16x16x32_bf16 v[0:3], v[80:83], v[64:67], v[0:3]
	v_mfma_f32_16x16x32_bf16 v[4:7], v[84:87], v[64:67], v[4:7]
	v_mfma_f32_16x16x32_bf16 v[8:11], v[88:91], v[64:67], v[8:11]
	v_mfma_f32_16x16x32_bf16 v[12:15], v[92:95], v[64:67], v[12:15]
	v_mfma_f32_16x16x32_bf16 v[16:19], v[80:83], v[68:71], v[16:19]
	v_mfma_f32_16x16x32_bf16 v[20:23], v[84:87], v[68:71], v[20:23]
	v_mfma_f32_16x16x32_bf16 v[24:27], v[88:91], v[68:71], v[24:27]
	v_mfma_f32_16x16x32_bf16 v[28:31], v[92:95], v[68:71], v[28:31]
	v_mfma_f32_16x16x32_bf16 v[32:35], v[80:83], v[72:75], v[32:35]
	v_mfma_f32_16x16x32_bf16 v[36:39], v[84:87], v[72:75], v[36:39]
	v_mfma_f32_16x16x32_bf16 v[40:43], v[88:91], v[72:75], v[40:43]
	v_mfma_f32_16x16x32_bf16 v[44:47], v[92:95], v[72:75], v[44:47]
	v_mfma_f32_16x16x32_bf16 v[48:51], v[80:83], v[76:79], v[48:51]
	v_mfma_f32_16x16x32_bf16 v[52:55], v[84:87], v[76:79], v[52:55]
	v_mfma_f32_16x16x32_bf16 v[56:59], v[88:91], v[76:79], v[56:59]
	v_mfma_f32_16x16x32_bf16 v[60:63], v[92:95], v[76:79], v[60:63]
	v_mfma_f32_16x16x32_bf16 v[0:3], v[112:115], v[96:99], v[0:3]
	v_mfma_f32_16x16x32_bf16 v[4:7], v[116:119], v[96:99], v[4:7]
	v_mfma_f32_16x16x32_bf16 v[8:11], v[120:123], v[96:99], v[8:11]
	v_mfma_f32_16x16x32_bf16 v[12:15], v[124:127], v[96:99], v[12:15]
	v_mfma_f32_16x16x32_bf16 v[16:19], v[112:115], v[100:103], v[16:19]
	v_mfma_f32_16x16x32_bf16 v[20:23], v[116:119], v[100:103], v[20:23]
	v_mfma_f32_16x16x32_bf16 v[24:27], v[120:123], v[100:103], v[24:27]
	v_mfma_f32_16x16x32_bf16 v[28:31], v[124:127], v[100:103], v[28:31]
	v_mfma_f32_16x16x32_bf16 v[32:35], v[112:115], v[104:107], v[32:35]
	v_mfma_f32_16x16x32_bf16 v[36:39], v[116:119], v[104:107], v[36:39]
	v_mfma_f32_16x16x32_bf16 v[40:43], v[120:123], v[104:107], v[40:43]
	v_mfma_f32_16x16x32_bf16 v[44:47], v[124:127], v[104:107], v[44:47]
	v_mfma_f32_16x16x32_bf16 v[48:51], v[112:115], v[108:111], v[48:51]
	v_mfma_f32_16x16x32_bf16 v[52:55], v[116:119], v[108:111], v[52:55]
	v_mfma_f32_16x16x32_bf16 v[56:59], v[120:123], v[108:111], v[56:59]
	v_mfma_f32_16x16x32_bf16 v[60:63], v[124:127], v[108:111], v[60:63]
	v_lshlrev_b32_e32 v170, 14, v132
	v_lshl_add_u32 v170, v133, 4, v170
	s_nop 7
	ds_write_b128 v170, v[0:3] offset:0
	ds_write_b128 v170, v[4:7] offset:1024
	ds_write_b128 v170, v[8:11] offset:2048
	ds_write_b128 v170, v[12:15] offset:3072
	ds_write_b128 v170, v[16:19] offset:4096
	ds_write_b128 v170, v[20:23] offset:5120
	ds_write_b128 v170, v[24:27] offset:6144
	ds_write_b128 v170, v[28:31] offset:7168
	ds_write_b128 v170, v[32:35] offset:8192
	ds_write_b128 v170, v[36:39] offset:9216
	ds_write_b128 v170, v[40:43] offset:10240
	ds_write_b128 v170, v[44:47] offset:11264
	ds_write_b128 v170, v[48:51] offset:12288
	ds_write_b128 v170, v[52:55] offset:13312
	ds_write_b128 v170, v[56:59] offset:14336
	ds_write_b128 v170, v[60:63] offset:15360
	s_lshr_b32 s25, s24, 1
	s_lshl_b32 s25, s25, 4
	s_lshl_b32 s26, s16, 6
	s_add_i32 s25, s25, s26
	s_and_b32 s26, s24, 1
	s_lshl_b32 s26, s26, 5
	s_lshl_b32 s27, s17, 6
	s_add_i32 s26, s26, s27
	v_add_u32_e32 v171, s25, v134
	v_lshl_add_u32 v172, v135, 2, s26
	v_lshlrev_b32_e32 v173, 10, v171
	v_add_lshl_u32 v173, v173, v172, 2
	s_add_u32 s18, s4, 0x3800000
	s_addc_u32 s19, s5, 0
	s_add_u32 s20, s4, 0x3800000
	s_addc_u32 s21, s5, 0
	v_lshlrev_b32_e32 v174, 2, v172
	s_add_u32 s22, s4, 0x22f320
	s_addc_u32 s23, s5, 0
	s_add_u32 s28, s4, 0x1d000
	s_addc_u32 s29, s5, 0
	s_nop 2
	global_load_dwordx4 v[176:179], v173, s[18:19] offset:0
	global_load_dwordx4 v[64:67], v174, s[22:23] offset:0
	global_load_dwordx4 v[72:75], v174, s[28:29] offset:0
	global_load_dwordx4 v[180:183], v173, s[18:19] offset:64
	global_load_dwordx4 v[68:71], v174, s[22:23] offset:64
	global_load_dwordx4 v[76:79], v174, s[28:29] offset:64
	s_waitcnt lgkmcnt(0)
	s_barrier
	v_lshlrev_b32_e32 v175, 11, v132
	v_lshl_add_u32 v175, v133, 4, v175
	v_add_u32_e32 v100, 0x4000, v175
	v_add_u32_e32 v101, 0x8000, v175
	v_add_u32_e32 v102, 0xc000, v175
	v_add_u32_e32 v103, 0x10000, v175
	v_add_u32_e32 v166, 0x14000, v175
	v_add_u32_e32 v167, 0x18000, v175
	v_add_u32_e32 v168, 0x1c000, v175
	ds_read_b128 v[80:83], v175 offset:0
	ds_read_b128 v[0:3], v100 offset:0
	ds_read_b128 v[4:7], v101 offset:0
	ds_read_b128 v[8:11], v102 offset:0
	ds_read_b128 v[12:15], v103 offset:0
	ds_read_b128 v[16:19], v166 offset:0
	ds_read_b128 v[20:23], v167 offset:0
	ds_read_b128 v[24:27], v168 offset:0
	s_waitcnt lgkmcnt(0)
	ds_read_b128 v[96:99], v175 offset:1024
	ds_read_b128 v[138:141], v100 offset:1024
	ds_read_b128 v[142:145], v101 offset:1024
	ds_read_b128 v[146:149], v102 offset:1024
	ds_read_b128 v[150:153], v103 offset:1024
	ds_read_b128 v[154:157], v166 offset:1024
	ds_read_b128 v[158:161], v167 offset:1024
	ds_read_b128 v[162:165], v168 offset:1024
	s_waitcnt lgkmcnt(0)
	v_add_f32_e32 v80, v80, v0
	v_add_f32_e32 v81, v81, v1
	v_add_f32_e32 v82, v82, v2
	v_add_f32_e32 v83, v83, v3
	v_add_f32_e32 v80, v80, v4
	v_add_f32_e32 v81, v81, v5
	v_add_f32_e32 v82, v82, v6
	v_add_f32_e32 v83, v83, v7
	v_add_f32_e32 v80, v80, v8
	v_add_f32_e32 v81, v81, v9
	v_add_f32_e32 v82, v82, v10
	v_add_f32_e32 v83, v83, v11
	v_add_f32_e32 v80, v80, v12
	v_add_f32_e32 v81, v81, v13
	v_add_f32_e32 v82, v82, v14
	v_add_f32_e32 v83, v83, v15
	v_add_f32_e32 v80, v80, v16
	v_add_f32_e32 v81, v81, v17
	v_add_f32_e32 v82, v82, v18
	v_add_f32_e32 v83, v83, v19
	v_add_f32_e32 v80, v80, v20
	v_add_f32_e32 v81, v81, v21
	v_add_f32_e32 v82, v82, v22
	v_add_f32_e32 v83, v83, v23
	v_add_f32_e32 v80, v80, v24
	v_add_f32_e32 v81, v81, v25
	v_add_f32_e32 v82, v82, v26
	v_add_f32_e32 v83, v83, v27
	v_add_f32_e32 v96, v96, v138
	v_add_f32_e32 v97, v97, v139
	v_add_f32_e32 v98, v98, v140
	v_add_f32_e32 v99, v99, v141
	v_add_f32_e32 v96, v96, v142
	v_add_f32_e32 v97, v97, v143
	v_add_f32_e32 v98, v98, v144
	v_add_f32_e32 v99, v99, v145
	v_add_f32_e32 v96, v96, v146
	v_add_f32_e32 v97, v97, v147
	v_add_f32_e32 v98, v98, v148
	v_add_f32_e32 v99, v99, v149
	v_add_f32_e32 v96, v96, v150
	v_add_f32_e32 v97, v97, v151
	v_add_f32_e32 v98, v98, v152
	v_add_f32_e32 v99, v99, v153
	v_add_f32_e32 v96, v96, v154
	v_add_f32_e32 v97, v97, v155
	v_add_f32_e32 v98, v98, v156
	v_add_f32_e32 v99, v99, v157
	v_add_f32_e32 v96, v96, v158
	v_add_f32_e32 v97, v97, v159
	v_add_f32_e32 v98, v98, v160
	v_add_f32_e32 v99, v99, v161
	v_add_f32_e32 v96, v96, v162
	v_add_f32_e32 v97, v97, v163
	v_add_f32_e32 v98, v98, v164
	v_add_f32_e32 v99, v99, v165
	s_waitcnt vmcnt(0)
	v_add_f32_e32 v80, v80, v64
	v_add_f32_e32 v81, v81, v65
	v_add_f32_e32 v82, v82, v66
	v_add_f32_e32 v83, v83, v67
	v_fma_f32 v80, v72, v80, v176
	v_fma_f32 v81, v73, v81, v177
	v_fma_f32 v82, v74, v82, v178
	v_fma_f32 v83, v75, v83, v179
	global_store_dwordx4 v173, v[80:83], s[20:21] offset:0
	v_add_f32_e32 v96, v96, v68
	v_add_f32_e32 v97, v97, v69
	v_add_f32_e32 v98, v98, v70
	v_add_f32_e32 v99, v99, v71
	v_fma_f32 v96, v76, v96, v180
	v_fma_f32 v97, v77, v97, v181
	v_fma_f32 v98, v78, v98, v182
	v_fma_f32 v99, v79, v99, v183
	global_store_dwordx4 v173, v[96:99], s[20:21] offset:64
	s_barrier
	s_branch .Lcg_done

.Lss3_top:
	s_cmp_lt_u32 s36, 0x1000
	s_cbranch_scc1 .Lss3_body
	s_cmp_eq_u32 s37, 1
	s_cbranch_scc1 .Lss3_done
	v_readlane_b32 s58, v247, 28
	s_cmp_eq_u32 s58, 1
	s_cbranch_scc1 .Lss3_done
	v_readlane_b32 s0, v245, 17
	v_readlane_b32 s1, v245, 18
	s_mov_b32 s37, 1
	s_and_b64 vcc, exec, s[0:1]
	s_cbranch_vccz .Lss3_done
	v_readlane_b32 s36, v246, 0
.Lss3_body:
	v_readlane_b32 s58, v247, 28
	s_lshr_b32 s59, s36, 6
	s_mul_i32 s59, s59, 68
	s_and_b32 s10, s36, 63
	s_add_i32 s59, s59, s10
	s_add_i32 s59, s59, 4
	s_cmp_eq_u32 s58, 1
	s_cselect_b32 s58, s59, s36
	s_mul_i32 s10, s58, 0xf0f1
	s_lshr_b32 s10, s10, 22
	s_mul_i32 s11, s10, 68
	s_sub_i32 s8, s58, s11
	s_and_b32 s7, s10, 15
	s_lshr_b32 s6, s10, 4
	s_lshl_b32 s10, s8, 6
	s_lshl_b32 s11, s6, 8
	s_add_i32 s9, s10, s11
	s_lshl_b32 s11, s6, 12
	s_add_i32 s11, s11, s10
	s_add_i32 s11, s11, 0x300
	s_cmp_lt_u32 s8, 4
	s_cselect_b32 s9, s9, s11
	v_mov_b32_e32 v0, 0
	v_mov_b32_e32 v1, 0
	v_mov_b32_e32 v2, 0
	v_mov_b32_e32 v3, 0
	v_mov_b32_e32 v4, 0
	v_mov_b32_e32 v5, 0
	v_mov_b32_e32 v6, 0
	v_mov_b32_e32 v7, 0
	v_mov_b32_e32 v8, 0
	v_mov_b32_e32 v9, 0
	v_mov_b32_e32 v10, 0
	v_mov_b32_e32 v11, 0
	v_mov_b32_e32 v12, 0
	v_mov_b32_e32 v13, 0
	v_mov_b32_e32 v14, 0
	v_mov_b32_e32 v15, 0
	v_and_b32_e32 v207, 15, v205
	v_mul_u32_u24_e32 v207, 0xe00, v207
	v_and_b32_e32 v208, 16, v205
	v_add_u32_e32 v207, v207, v208
	s_mul_i32 s18, s9, 0xe00
	s_lshl_b32 s19, s7, 5
	s_add_i32 s18, s18, s19
	s_add_u32 s18, s18, 0x5e00c00
	s_add_u32 s18, s4, s18
	s_addc_u32 s19, s5, 0
	s_mov_b32 exec_hi, 0
	global_load_dwordx4 v[0:3], v207, s[18:19]
	s_add_u32 s18, s18, 0xe000
	s_addc_u32 s19, s19, 0
	global_load_dwordx4 v[4:7], v207, s[18:19]
	s_add_u32 s18, s18, 0xe000
	s_addc_u32 s19, s19, 0
	global_load_dwordx4 v[8:11], v207, s[18:19]
	s_add_u32 s18, s18, 0xe000
	s_addc_u32 s19, s19, 0
	global_load_dwordx4 v[12:15], v207, s[18:19]
	s_mov_b64 exec, -1
	v_lshlrev_b32_e32 v134, 4, v205
	v_add_u32_e32 v208, 0x1000, v134
	v_and_b32_e32 v135, 15, v205
	v_lshlrev_b32_e32 v136, 8, v135
	v_lshlrev_b32_e32 v135, 6, v135
	v_and_b32_e32 v207, 16, v205
	v_lshl_add_u32 v135, v207, 1, v135
	v_lshrrev_b32_e32 v207, 4, v205
	v_lshl_add_u32 v136, v207, 4, v136
	v_lshlrev_b32_e32 v206, 5, v207
	v_readlane_b32 s10, v247, 28
	s_mov_b32 s11, s8
	s_lshl_b32 s16, s10, 1
	s_add_i32 s16, s16, 0
	s_lshl_b32 s16, s16, 4
	s_add_i32 s16, s16, s7
	s_lshl_b32 s17, s6, 1
	s_add_i32 s17, s17, 0
	s_lshl_b32 s17, s17, 4
	s_add_i32 s17, s17, s7
	s_mul_i32 s17, s17, 68
	s_add_i32 s17, s17, s11
	s_lshl_b32 s17, s17, 6
	s_lshl_b32 s20, s16, 13
	s_add_u32 s20, s20, 0xfd00000
	s_add_u32 s20, s4, s20
	s_addc_u32 s21, s5, 0
	s_lshl_b32 s38, s16, 12
	s_add_u32 s38, s38, 0xfd80000
	s_add_u32 s38, s4, s38
	s_addc_u32 s39, s5, 0
	s_lshl_b32 s42, s16, 15
	s_add_u32 s42, s42, 0xf900000
	s_add_u32 s42, s4, s42
	s_addc_u32 s43, s5, 0
	s_lshl_b32 s44, s17, 3
	s_add_u32 s44, s44, 0x740000
	s_add_u32 s44, s4, s44
	s_addc_u32 s45, s5, 0
	global_load_dwordx4 v[64:67], v134, s[20:21]
	global_load_dwordx4 v[72:75], v134, s[20:21] offset:1024
	s_add_u32 s20, s20, 0x800
	s_addc_u32 s21, s21, 0
	global_load_dwordx4 v[138:141], v134, s[42:43] offset:0
	global_load_dwordx4 v[142:145], v134, s[42:43] offset:1024
	global_load_dwordx4 v[146:149], v134, s[42:43] offset:2048
	global_load_dwordx4 v[150:153], v134, s[42:43] offset:3072
	global_load_dwordx4 v[154:157], v208, s[42:43] offset:0
	global_load_dwordx4 v[158:161], v208, s[42:43] offset:1024
	global_load_dwordx4 v[162:165], v208, s[42:43] offset:2048
	global_load_dwordx4 v[166:169], v208, s[42:43] offset:3072
	global_load_dwordx4 v[170:173], v206, s[44:45]
	global_load_dwordx4 v[174:177], v206, s[44:45] offset:16
	s_add_u32 s42, s42, 0x2000
	s_addc_u32 s43, s43, 0
	s_add_u32 s44, s44, 0x80
	s_addc_u32 s45, s45, 0
	s_waitcnt vmcnt(12)
	s_waitcnt vmcnt(10)
	global_load_dwordx4 v[80:83], v134, s[38:39]
	s_add_u32 s38, s38, 0x400
	s_addc_u32 s39, s39, 0
	v_mfma_f32_16x16x32_bf16 v[32:35], v[64:67], v[0:3], 0
	v_mfma_f32_16x16x32_bf16 v[36:39], v[72:75], v[0:3], 0
	v_mfma_f32_16x16x32_bf16 v[40:43], v[64:67], v[4:7], 0
	v_mfma_f32_16x16x32_bf16 v[44:47], v[72:75], v[4:7], 0
	v_mfma_f32_16x16x32_bf16 v[48:51], v[64:67], v[8:11], 0
	v_mfma_f32_16x16x32_bf16 v[52:55], v[72:75], v[8:11], 0
	v_mfma_f32_16x16x32_bf16 v[56:59], v[64:67], v[12:15], 0
	v_mfma_f32_16x16x32_bf16 v[60:63], v[72:75], v[12:15], 0
	global_load_dwordx4 v[64:67], v134, s[20:21]
	global_load_dwordx4 v[72:75], v134, s[20:21] offset:1024
	s_add_u32 s20, s20, 0x800
	s_addc_u32 s21, s21, 0
	global_load_dwordx4 v[100:103], v134, s[42:43] offset:0
	global_load_dwordx4 v[104:107], v134, s[42:43] offset:1024
	global_load_dwordx4 v[108:111], v134, s[42:43] offset:2048
	global_load_dwordx4 v[112:115], v134, s[42:43] offset:3072
	global_load_dwordx4 v[116:119], v208, s[42:43] offset:0
	global_load_dwordx4 v[120:123], v208, s[42:43] offset:1024
	global_load_dwordx4 v[124:127], v208, s[42:43] offset:2048
	global_load_dwordx4 v[128:131], v208, s[42:43] offset:3072
	global_load_dwordx4 v[178:181], v206, s[44:45]
	global_load_dwordx4 v[182:185], v206, s[44:45] offset:16
	s_add_u32 s42, s42, 0x2000
	s_addc_u32 s43, s43, 0
	s_add_u32 s44, s44, 0x80
	s_addc_u32 s45, s45, 0
	s_waitcnt vmcnt(13)
	v_mul_f32_e32 v132, v171, v157
	v_mul_f32_e32 v133, v170, v157
	v_fma_f32 v170, v170, v156, -v132
	v_fma_f32 v171, v171, v156, v133
	v_mul_f32_e32 v132, v173, v161
	v_mul_f32_e32 v133, v172, v161
	v_fma_f32 v172, v172, v160, -v132
	v_fma_f32 v173, v173, v160, v133
	v_mul_f32_e32 v132, v175, v165
	v_mul_f32_e32 v133, v174, v165
	v_fma_f32 v174, v174, v164, -v132
	v_fma_f32 v175, v175, v164, v133
	v_mul_f32_e32 v132, v177, v169
	v_mul_f32_e32 v133, v176, v169
	v_fma_f32 v176, v176, v168, -v132
	v_fma_f32 v177, v177, v168, v133
	v_mul_f32_e32 v132, v32, v139
	v_mul_f32_e32 v32, v32, v138
	v_fma_f32 v32, -v36, v139, v32
	v_fma_f32 v36, v36, v138, v132
	v_mul_f32_e32 v133, v33, v143
	v_mul_f32_e32 v33, v33, v142
	v_fma_f32 v33, -v37, v143, v33
	v_fma_f32 v37, v37, v142, v133
	v_mul_f32_e32 v132, v34, v147
	v_mul_f32_e32 v34, v34, v146
	v_fma_f32 v34, -v38, v147, v34
	v_fma_f32 v38, v38, v146, v132
	v_mul_f32_e32 v133, v35, v151
	v_mul_f32_e32 v35, v35, v150
	v_fma_f32 v35, -v39, v151, v35
	v_fma_f32 v39, v39, v150, v133
	v_add_f32_dpp v32, v32, v32 row_shr:1 row_mask:0xf bank_mask:0xf bound_ctrl:1
	v_add_f32_dpp v33, v33, v33 row_shr:1 row_mask:0xf bank_mask:0xf bound_ctrl:1
	v_add_f32_dpp v34, v34, v34 row_shr:1 row_mask:0xf bank_mask:0xf bound_ctrl:1
	v_add_f32_dpp v35, v35, v35 row_shr:1 row_mask:0xf bank_mask:0xf bound_ctrl:1
	v_add_f32_dpp v36, v36, v36 row_shr:1 row_mask:0xf bank_mask:0xf bound_ctrl:1
	v_add_f32_dpp v37, v37, v37 row_shr:1 row_mask:0xf bank_mask:0xf bound_ctrl:1
	v_add_f32_dpp v38, v38, v38 row_shr:1 row_mask:0xf bank_mask:0xf bound_ctrl:1
	v_add_f32_dpp v39, v39, v39 row_shr:1 row_mask:0xf bank_mask:0xf bound_ctrl:1
	v_add_f32_dpp v32, v32, v32 row_shr:2 row_mask:0xf bank_mask:0xf bound_ctrl:1
	v_add_f32_dpp v33, v33, v33 row_shr:2 row_mask:0xf bank_mask:0xf bound_ctrl:1
	v_add_f32_dpp v34, v34, v34 row_shr:2 row_mask:0xf bank_mask:0xf bound_ctrl:1
	v_add_f32_dpp v35, v35, v35 row_shr:2 row_mask:0xf bank_mask:0xf bound_ctrl:1
	v_add_f32_dpp v36, v36, v36 row_shr:2 row_mask:0xf bank_mask:0xf bound_ctrl:1
	v_add_f32_dpp v37, v37, v37 row_shr:2 row_mask:0xf bank_mask:0xf bound_ctrl:1
	v_add_f32_dpp v38, v38, v38 row_shr:2 row_mask:0xf bank_mask:0xf bound_ctrl:1
	v_add_f32_dpp v39, v39, v39 row_shr:2 row_mask:0xf bank_mask:0xf bound_ctrl:1
	v_add_f32_dpp v32, v32, v32 row_shr:4 row_mask:0xf bank_mask:0xf bound_ctrl:1
	v_add_f32_dpp v33, v33, v33 row_shr:4 row_mask:0xf bank_mask:0xf bound_ctrl:1
	v_add_f32_dpp v34, v34, v34 row_shr:4 row_mask:0xf bank_mask:0xf bound_ctrl:1
	v_add_f32_dpp v35, v35, v35 row_shr:4 row_mask:0xf bank_mask:0xf bound_ctrl:1
	v_add_f32_dpp v36, v36, v36 row_shr:4 row_mask:0xf bank_mask:0xf bound_ctrl:1
	v_add_f32_dpp v37, v37, v37 row_shr:4 row_mask:0xf bank_mask:0xf bound_ctrl:1
	v_add_f32_dpp v38, v38, v38 row_shr:4 row_mask:0xf bank_mask:0xf bound_ctrl:1
	v_add_f32_dpp v39, v39, v39 row_shr:4 row_mask:0xf bank_mask:0xf bound_ctrl:1
	v_add_f32_dpp v32, v32, v32 row_shr:8 row_mask:0xf bank_mask:0xf bound_ctrl:1
	v_add_f32_dpp v33, v33, v33 row_shr:8 row_mask:0xf bank_mask:0xf bound_ctrl:1
	v_add_f32_dpp v34, v34, v34 row_shr:8 row_mask:0xf bank_mask:0xf bound_ctrl:1
	v_add_f32_dpp v35, v35, v35 row_shr:8 row_mask:0xf bank_mask:0xf bound_ctrl:1
	v_add_f32_dpp v36, v36, v36 row_shr:8 row_mask:0xf bank_mask:0xf bound_ctrl:1
	v_add_f32_dpp v37, v37, v37 row_shr:8 row_mask:0xf bank_mask:0xf bound_ctrl:1
	v_add_f32_dpp v38, v38, v38 row_shr:8 row_mask:0xf bank_mask:0xf bound_ctrl:1
	v_add_f32_dpp v39, v39, v39 row_shr:8 row_mask:0xf bank_mask:0xf bound_ctrl:1
	v_mov_b32_dpp v88, v32 row_newbcast:15 row_mask:0xf bank_mask:0xf
	v_mov_b32_dpp v89, v33 row_newbcast:15 row_mask:0xf bank_mask:0xf
	v_mov_b32_dpp v90, v34 row_newbcast:15 row_mask:0xf bank_mask:0xf
	v_mov_b32_dpp v91, v35 row_newbcast:15 row_mask:0xf bank_mask:0xf
	v_mov_b32_dpp v92, v36 row_newbcast:15 row_mask:0xf bank_mask:0xf
	v_mov_b32_dpp v93, v37 row_newbcast:15 row_mask:0xf bank_mask:0xf
	v_mov_b32_dpp v94, v38 row_newbcast:15 row_mask:0xf bank_mask:0xf
	v_mov_b32_dpp v95, v39 row_newbcast:15 row_mask:0xf bank_mask:0xf
	v_add_f32_e32 v32, v32, v170
	v_add_f32_e32 v36, v36, v171
	v_add_f32_e32 v33, v33, v172
	v_add_f32_e32 v37, v37, v173
	v_add_f32_e32 v34, v34, v174
	v_add_f32_e32 v38, v38, v175
	v_add_f32_e32 v35, v35, v176
	v_add_f32_e32 v39, v39, v177
	v_mul_f32_e32 v132, v32, v141
	v_mul_f32_e32 v32, v32, v140
	v_fma_f32 v32, -v36, v141, v32
	v_fma_f32 v36, v36, v140, v132
	v_mul_f32_e32 v133, v33, v145
	v_mul_f32_e32 v33, v33, v144
	v_fma_f32 v33, -v37, v145, v33
	v_fma_f32 v37, v37, v144, v133
	v_mul_f32_e32 v132, v34, v149
	v_mul_f32_e32 v34, v34, v148
	v_fma_f32 v34, -v38, v149, v34
	v_fma_f32 v38, v38, v148, v132
	v_mul_f32_e32 v133, v35, v153
	v_mul_f32_e32 v35, v35, v152
	v_fma_f32 v35, -v39, v153, v35
	v_fma_f32 v39, v39, v152, v133
	v_add_f32_e32 v88, v88, v170
	v_add_f32_e32 v92, v92, v171
	v_mul_f32_e32 v132, v92, v155
	v_mul_f32_e32 v171, v88, v155
	v_fma_f32 v170, v88, v154, -v132
	v_fma_f32 v171, v92, v154, v171
	v_add_f32_e32 v89, v89, v172
	v_add_f32_e32 v93, v93, v173
	v_mul_f32_e32 v133, v93, v159
	v_mul_f32_e32 v173, v89, v159
	v_fma_f32 v172, v89, v158, -v133
	v_fma_f32 v173, v93, v158, v173
	v_add_f32_e32 v90, v90, v174
	v_add_f32_e32 v94, v94, v175
	v_mul_f32_e32 v132, v94, v163
	v_mul_f32_e32 v175, v90, v163
	v_fma_f32 v174, v90, v162, -v132
	v_fma_f32 v175, v94, v162, v175
	v_add_f32_e32 v91, v91, v176
	v_add_f32_e32 v95, v95, v177
	v_mul_f32_e32 v133, v95, v167
	v_mul_f32_e32 v177, v91, v167
	v_fma_f32 v176, v91, v166, -v133
	v_fma_f32 v177, v95, v166, v177
	v_mul_f32_e32 v132, v40, v139
	v_mul_f32_e32 v40, v40, v138
	v_fma_f32 v40, -v44, v139, v40
	v_fma_f32 v44, v44, v138, v132
	v_mul_f32_e32 v133, v41, v143
	v_mul_f32_e32 v41, v41, v142
	v_fma_f32 v41, -v45, v143, v41
	v_fma_f32 v45, v45, v142, v133
	v_mul_f32_e32 v132, v42, v147
	v_mul_f32_e32 v42, v42, v146
	v_fma_f32 v42, -v46, v147, v42
	v_fma_f32 v46, v46, v146, v132
	v_mul_f32_e32 v133, v43, v151
	v_mul_f32_e32 v43, v43, v150
	v_fma_f32 v43, -v47, v151, v43
	v_fma_f32 v47, v47, v150, v133
	v_add_f32_dpp v40, v40, v40 row_shr:1 row_mask:0xf bank_mask:0xf bound_ctrl:1
	v_add_f32_dpp v41, v41, v41 row_shr:1 row_mask:0xf bank_mask:0xf bound_ctrl:1
	v_add_f32_dpp v42, v42, v42 row_shr:1 row_mask:0xf bank_mask:0xf bound_ctrl:1
	v_add_f32_dpp v43, v43, v43 row_shr:1 row_mask:0xf bank_mask:0xf bound_ctrl:1
	v_add_f32_dpp v44, v44, v44 row_shr:1 row_mask:0xf bank_mask:0xf bound_ctrl:1
	v_add_f32_dpp v45, v45, v45 row_shr:1 row_mask:0xf bank_mask:0xf bound_ctrl:1
	v_add_f32_dpp v46, v46, v46 row_shr:1 row_mask:0xf bank_mask:0xf bound_ctrl:1
	v_add_f32_dpp v47, v47, v47 row_shr:1 row_mask:0xf bank_mask:0xf bound_ctrl:1
	v_add_f32_dpp v40, v40, v40 row_shr:2 row_mask:0xf bank_mask:0xf bound_ctrl:1
	v_add_f32_dpp v41, v41, v41 row_shr:2 row_mask:0xf bank_mask:0xf bound_ctrl:1
	v_add_f32_dpp v42, v42, v42 row_shr:2 row_mask:0xf bank_mask:0xf bound_ctrl:1
	v_add_f32_dpp v43, v43, v43 row_shr:2 row_mask:0xf bank_mask:0xf bound_ctrl:1
	v_add_f32_dpp v44, v44, v44 row_shr:2 row_mask:0xf bank_mask:0xf bound_ctrl:1
	v_add_f32_dpp v45, v45, v45 row_shr:2 row_mask:0xf bank_mask:0xf bound_ctrl:1
	v_add_f32_dpp v46, v46, v46 row_shr:2 row_mask:0xf bank_mask:0xf bound_ctrl:1
	v_add_f32_dpp v47, v47, v47 row_shr:2 row_mask:0xf bank_mask:0xf bound_ctrl:1
	v_add_f32_dpp v40, v40, v40 row_shr:4 row_mask:0xf bank_mask:0xf bound_ctrl:1
	v_add_f32_dpp v41, v41, v41 row_shr:4 row_mask:0xf bank_mask:0xf bound_ctrl:1
	v_add_f32_dpp v42, v42, v42 row_shr:4 row_mask:0xf bank_mask:0xf bound_ctrl:1
	v_add_f32_dpp v43, v43, v43 row_shr:4 row_mask:0xf bank_mask:0xf bound_ctrl:1
	v_add_f32_dpp v44, v44, v44 row_shr:4 row_mask:0xf bank_mask:0xf bound_ctrl:1
	v_add_f32_dpp v45, v45, v45 row_shr:4 row_mask:0xf bank_mask:0xf bound_ctrl:1
	v_add_f32_dpp v46, v46, v46 row_shr:4 row_mask:0xf bank_mask:0xf bound_ctrl:1
	v_add_f32_dpp v47, v47, v47 row_shr:4 row_mask:0xf bank_mask:0xf bound_ctrl:1
	v_add_f32_dpp v40, v40, v40 row_shr:8 row_mask:0xf bank_mask:0xf bound_ctrl:1
	v_add_f32_dpp v41, v41, v41 row_shr:8 row_mask:0xf bank_mask:0xf bound_ctrl:1
	v_add_f32_dpp v42, v42, v42 row_shr:8 row_mask:0xf bank_mask:0xf bound_ctrl:1
	v_add_f32_dpp v43, v43, v43 row_shr:8 row_mask:0xf bank_mask:0xf bound_ctrl:1
	v_add_f32_dpp v44, v44, v44 row_shr:8 row_mask:0xf bank_mask:0xf bound_ctrl:1
	v_add_f32_dpp v45, v45, v45 row_shr:8 row_mask:0xf bank_mask:0xf bound_ctrl:1
	v_add_f32_dpp v46, v46, v46 row_shr:8 row_mask:0xf bank_mask:0xf bound_ctrl:1
	v_add_f32_dpp v47, v47, v47 row_shr:8 row_mask:0xf bank_mask:0xf bound_ctrl:1
	v_mov_b32_dpp v88, v40 row_newbcast:15 row_mask:0xf bank_mask:0xf
	v_mov_b32_dpp v89, v41 row_newbcast:15 row_mask:0xf bank_mask:0xf
	v_mov_b32_dpp v90, v42 row_newbcast:15 row_mask:0xf bank_mask:0xf
	v_mov_b32_dpp v91, v43 row_newbcast:15 row_mask:0xf bank_mask:0xf
	v_mov_b32_dpp v92, v44 row_newbcast:15 row_mask:0xf bank_mask:0xf
	v_mov_b32_dpp v93, v45 row_newbcast:15 row_mask:0xf bank_mask:0xf
	v_mov_b32_dpp v94, v46 row_newbcast:15 row_mask:0xf bank_mask:0xf
	v_mov_b32_dpp v95, v47 row_newbcast:15 row_mask:0xf bank_mask:0xf
	v_add_f32_e32 v40, v40, v170
	v_add_f32_e32 v44, v44, v171
	v_add_f32_e32 v41, v41, v172
	v_add_f32_e32 v45, v45, v173
	v_add_f32_e32 v42, v42, v174
	v_add_f32_e32 v46, v46, v175
	v_add_f32_e32 v43, v43, v176
	v_add_f32_e32 v47, v47, v177
	v_mul_f32_e32 v132, v40, v141
	v_mul_f32_e32 v40, v40, v140
	v_fma_f32 v40, -v44, v141, v40
	v_fma_f32 v44, v44, v140, v132
	v_mul_f32_e32 v133, v41, v145
	v_mul_f32_e32 v41, v41, v144
	v_fma_f32 v41, -v45, v145, v41
	v_fma_f32 v45, v45, v144, v133
	v_mul_f32_e32 v132, v42, v149
	v_mul_f32_e32 v42, v42, v148
	v_fma_f32 v42, -v46, v149, v42
	v_fma_f32 v46, v46, v148, v132
	v_mul_f32_e32 v133, v43, v153
	v_mul_f32_e32 v43, v43, v152
	v_fma_f32 v43, -v47, v153, v43
	v_fma_f32 v47, v47, v152, v133
	v_add_f32_e32 v88, v88, v170
	v_add_f32_e32 v92, v92, v171
	v_mul_f32_e32 v132, v92, v155
	v_mul_f32_e32 v171, v88, v155
	v_fma_f32 v170, v88, v154, -v132
	v_fma_f32 v171, v92, v154, v171
	v_add_f32_e32 v89, v89, v172
	v_add_f32_e32 v93, v93, v173
	v_mul_f32_e32 v133, v93, v159
	v_mul_f32_e32 v173, v89, v159
	v_fma_f32 v172, v89, v158, -v133
	v_fma_f32 v173, v93, v158, v173
	v_add_f32_e32 v90, v90, v174
	v_add_f32_e32 v94, v94, v175
	v_mul_f32_e32 v132, v94, v163
	v_mul_f32_e32 v175, v90, v163
	v_fma_f32 v174, v90, v162, -v132
	v_fma_f32 v175, v94, v162, v175
	v_add_f32_e32 v91, v91, v176
	v_add_f32_e32 v95, v95, v177
	v_mul_f32_e32 v133, v95, v167
	v_mul_f32_e32 v177, v91, v167
	v_fma_f32 v176, v91, v166, -v133
	v_fma_f32 v177, v95, v166, v177
	v_mul_f32_e32 v132, v48, v139
	v_mul_f32_e32 v48, v48, v138
	v_fma_f32 v48, -v52, v139, v48
	v_fma_f32 v52, v52, v138, v132
	v_mul_f32_e32 v133, v49, v143
	v_mul_f32_e32 v49, v49, v142
	v_fma_f32 v49, -v53, v143, v49
	v_fma_f32 v53, v53, v142, v133
	v_mul_f32_e32 v132, v50, v147
	v_mul_f32_e32 v50, v50, v146
	v_fma_f32 v50, -v54, v147, v50
	v_fma_f32 v54, v54, v146, v132
	v_mul_f32_e32 v133, v51, v151
	v_mul_f32_e32 v51, v51, v150
	v_fma_f32 v51, -v55, v151, v51
	v_fma_f32 v55, v55, v150, v133
	v_add_f32_dpp v48, v48, v48 row_shr:1 row_mask:0xf bank_mask:0xf bound_ctrl:1
	v_add_f32_dpp v49, v49, v49 row_shr:1 row_mask:0xf bank_mask:0xf bound_ctrl:1
	v_add_f32_dpp v50, v50, v50 row_shr:1 row_mask:0xf bank_mask:0xf bound_ctrl:1
	v_add_f32_dpp v51, v51, v51 row_shr:1 row_mask:0xf bank_mask:0xf bound_ctrl:1
	v_add_f32_dpp v52, v52, v52 row_shr:1 row_mask:0xf bank_mask:0xf bound_ctrl:1
	v_add_f32_dpp v53, v53, v53 row_shr:1 row_mask:0xf bank_mask:0xf bound_ctrl:1
	v_add_f32_dpp v54, v54, v54 row_shr:1 row_mask:0xf bank_mask:0xf bound_ctrl:1
	v_add_f32_dpp v55, v55, v55 row_shr:1 row_mask:0xf bank_mask:0xf bound_ctrl:1
	v_add_f32_dpp v48, v48, v48 row_shr:2 row_mask:0xf bank_mask:0xf bound_ctrl:1
	v_add_f32_dpp v49, v49, v49 row_shr:2 row_mask:0xf bank_mask:0xf bound_ctrl:1
	v_add_f32_dpp v50, v50, v50 row_shr:2 row_mask:0xf bank_mask:0xf bound_ctrl:1
	v_add_f32_dpp v51, v51, v51 row_shr:2 row_mask:0xf bank_mask:0xf bound_ctrl:1
	v_add_f32_dpp v52, v52, v52 row_shr:2 row_mask:0xf bank_mask:0xf bound_ctrl:1
	v_add_f32_dpp v53, v53, v53 row_shr:2 row_mask:0xf bank_mask:0xf bound_ctrl:1
	v_add_f32_dpp v54, v54, v54 row_shr:2 row_mask:0xf bank_mask:0xf bound_ctrl:1
	v_add_f32_dpp v55, v55, v55 row_shr:2 row_mask:0xf bank_mask:0xf bound_ctrl:1
	v_add_f32_dpp v48, v48, v48 row_shr:4 row_mask:0xf bank_mask:0xf bound_ctrl:1
	v_add_f32_dpp v49, v49, v49 row_shr:4 row_mask:0xf bank_mask:0xf bound_ctrl:1
	v_add_f32_dpp v50, v50, v50 row_shr:4 row_mask:0xf bank_mask:0xf bound_ctrl:1
	v_add_f32_dpp v51, v51, v51 row_shr:4 row_mask:0xf bank_mask:0xf bound_ctrl:1
	v_add_f32_dpp v52, v52, v52 row_shr:4 row_mask:0xf bank_mask:0xf bound_ctrl:1
	v_add_f32_dpp v53, v53, v53 row_shr:4 row_mask:0xf bank_mask:0xf bound_ctrl:1
	v_add_f32_dpp v54, v54, v54 row_shr:4 row_mask:0xf bank_mask:0xf bound_ctrl:1
	v_add_f32_dpp v55, v55, v55 row_shr:4 row_mask:0xf bank_mask:0xf bound_ctrl:1
	v_add_f32_dpp v48, v48, v48 row_shr:8 row_mask:0xf bank_mask:0xf bound_ctrl:1
	v_add_f32_dpp v49, v49, v49 row_shr:8 row_mask:0xf bank_mask:0xf bound_ctrl:1
	v_add_f32_dpp v50, v50, v50 row_shr:8 row_mask:0xf bank_mask:0xf bound_ctrl:1
	v_add_f32_dpp v51, v51, v51 row_shr:8 row_mask:0xf bank_mask:0xf bound_ctrl:1
	v_add_f32_dpp v52, v52, v52 row_shr:8 row_mask:0xf bank_mask:0xf bound_ctrl:1
	v_add_f32_dpp v53, v53, v53 row_shr:8 row_mask:0xf bank_mask:0xf bound_ctrl:1
	v_add_f32_dpp v54, v54, v54 row_shr:8 row_mask:0xf bank_mask:0xf bound_ctrl:1
	v_add_f32_dpp v55, v55, v55 row_shr:8 row_mask:0xf bank_mask:0xf bound_ctrl:1
	v_mov_b32_dpp v88, v48 row_newbcast:15 row_mask:0xf bank_mask:0xf
	v_mov_b32_dpp v89, v49 row_newbcast:15 row_mask:0xf bank_mask:0xf
	v_mov_b32_dpp v90, v50 row_newbcast:15 row_mask:0xf bank_mask:0xf
	v_mov_b32_dpp v91, v51 row_newbcast:15 row_mask:0xf bank_mask:0xf
	v_mov_b32_dpp v92, v52 row_newbcast:15 row_mask:0xf bank_mask:0xf
	v_mov_b32_dpp v93, v53 row_newbcast:15 row_mask:0xf bank_mask:0xf
	v_mov_b32_dpp v94, v54 row_newbcast:15 row_mask:0xf bank_mask:0xf
	v_mov_b32_dpp v95, v55 row_newbcast:15 row_mask:0xf bank_mask:0xf
	v_add_f32_e32 v48, v48, v170
	v_add_f32_e32 v52, v52, v171
	v_add_f32_e32 v49, v49, v172
	v_add_f32_e32 v53, v53, v173
	v_add_f32_e32 v50, v50, v174
	v_add_f32_e32 v54, v54, v175
	v_add_f32_e32 v51, v51, v176
	v_add_f32_e32 v55, v55, v177
	v_mul_f32_e32 v132, v48, v141
	v_mul_f32_e32 v48, v48, v140
	v_fma_f32 v48, -v52, v141, v48
	v_fma_f32 v52, v52, v140, v132
	v_mul_f32_e32 v133, v49, v145
	v_mul_f32_e32 v49, v49, v144
	v_fma_f32 v49, -v53, v145, v49
	v_fma_f32 v53, v53, v144, v133
	v_mul_f32_e32 v132, v50, v149
	v_mul_f32_e32 v50, v50, v148
	v_fma_f32 v50, -v54, v149, v50
	v_fma_f32 v54, v54, v148, v132
	v_mul_f32_e32 v133, v51, v153
	v_mul_f32_e32 v51, v51, v152
	v_fma_f32 v51, -v55, v153, v51
	v_fma_f32 v55, v55, v152, v133
	v_add_f32_e32 v88, v88, v170
	v_add_f32_e32 v92, v92, v171
	v_mul_f32_e32 v132, v92, v155
	v_mul_f32_e32 v171, v88, v155
	v_fma_f32 v170, v88, v154, -v132
	v_fma_f32 v171, v92, v154, v171
	v_add_f32_e32 v89, v89, v172
	v_add_f32_e32 v93, v93, v173
	v_mul_f32_e32 v133, v93, v159
	v_mul_f32_e32 v173, v89, v159
	v_fma_f32 v172, v89, v158, -v133
	v_fma_f32 v173, v93, v158, v173
	v_add_f32_e32 v90, v90, v174
	v_add_f32_e32 v94, v94, v175
	v_mul_f32_e32 v132, v94, v163
	v_mul_f32_e32 v175, v90, v163
	v_fma_f32 v174, v90, v162, -v132
	v_fma_f32 v175, v94, v162, v175
	v_add_f32_e32 v91, v91, v176
	v_add_f32_e32 v95, v95, v177
	v_mul_f32_e32 v133, v95, v167
	v_mul_f32_e32 v177, v91, v167
	v_fma_f32 v176, v91, v166, -v133
	v_fma_f32 v177, v95, v166, v177
	v_mul_f32_e32 v132, v56, v139
	v_mul_f32_e32 v56, v56, v138
	v_fma_f32 v56, -v60, v139, v56
	v_fma_f32 v60, v60, v138, v132
	v_mul_f32_e32 v133, v57, v143
	v_mul_f32_e32 v57, v57, v142
	v_fma_f32 v57, -v61, v143, v57
	v_fma_f32 v61, v61, v142, v133
	v_mul_f32_e32 v132, v58, v147
	v_mul_f32_e32 v58, v58, v146
	v_fma_f32 v58, -v62, v147, v58
	v_fma_f32 v62, v62, v146, v132
	v_mul_f32_e32 v133, v59, v151
	v_mul_f32_e32 v59, v59, v150
	v_fma_f32 v59, -v63, v151, v59
	v_fma_f32 v63, v63, v150, v133
	v_add_f32_dpp v56, v56, v56 row_shr:1 row_mask:0xf bank_mask:0xf bound_ctrl:1
	v_add_f32_dpp v57, v57, v57 row_shr:1 row_mask:0xf bank_mask:0xf bound_ctrl:1
	v_add_f32_dpp v58, v58, v58 row_shr:1 row_mask:0xf bank_mask:0xf bound_ctrl:1
	v_add_f32_dpp v59, v59, v59 row_shr:1 row_mask:0xf bank_mask:0xf bound_ctrl:1
	v_add_f32_dpp v60, v60, v60 row_shr:1 row_mask:0xf bank_mask:0xf bound_ctrl:1
	v_add_f32_dpp v61, v61, v61 row_shr:1 row_mask:0xf bank_mask:0xf bound_ctrl:1
	v_add_f32_dpp v62, v62, v62 row_shr:1 row_mask:0xf bank_mask:0xf bound_ctrl:1
	v_add_f32_dpp v63, v63, v63 row_shr:1 row_mask:0xf bank_mask:0xf bound_ctrl:1
	v_add_f32_dpp v56, v56, v56 row_shr:2 row_mask:0xf bank_mask:0xf bound_ctrl:1
	v_add_f32_dpp v57, v57, v57 row_shr:2 row_mask:0xf bank_mask:0xf bound_ctrl:1
	v_add_f32_dpp v58, v58, v58 row_shr:2 row_mask:0xf bank_mask:0xf bound_ctrl:1
	v_add_f32_dpp v59, v59, v59 row_shr:2 row_mask:0xf bank_mask:0xf bound_ctrl:1
	v_add_f32_dpp v60, v60, v60 row_shr:2 row_mask:0xf bank_mask:0xf bound_ctrl:1
	v_add_f32_dpp v61, v61, v61 row_shr:2 row_mask:0xf bank_mask:0xf bound_ctrl:1
	v_add_f32_dpp v62, v62, v62 row_shr:2 row_mask:0xf bank_mask:0xf bound_ctrl:1
	v_add_f32_dpp v63, v63, v63 row_shr:2 row_mask:0xf bank_mask:0xf bound_ctrl:1
	v_add_f32_dpp v56, v56, v56 row_shr:4 row_mask:0xf bank_mask:0xf bound_ctrl:1
	v_add_f32_dpp v57, v57, v57 row_shr:4 row_mask:0xf bank_mask:0xf bound_ctrl:1
	v_add_f32_dpp v58, v58, v58 row_shr:4 row_mask:0xf bank_mask:0xf bound_ctrl:1
	v_add_f32_dpp v59, v59, v59 row_shr:4 row_mask:0xf bank_mask:0xf bound_ctrl:1
	v_add_f32_dpp v60, v60, v60 row_shr:4 row_mask:0xf bank_mask:0xf bound_ctrl:1
	v_add_f32_dpp v61, v61, v61 row_shr:4 row_mask:0xf bank_mask:0xf bound_ctrl:1
	v_add_f32_dpp v62, v62, v62 row_shr:4 row_mask:0xf bank_mask:0xf bound_ctrl:1
	v_add_f32_dpp v63, v63, v63 row_shr:4 row_mask:0xf bank_mask:0xf bound_ctrl:1
	v_add_f32_dpp v56, v56, v56 row_shr:8 row_mask:0xf bank_mask:0xf bound_ctrl:1
	v_add_f32_dpp v57, v57, v57 row_shr:8 row_mask:0xf bank_mask:0xf bound_ctrl:1
	v_add_f32_dpp v58, v58, v58 row_shr:8 row_mask:0xf bank_mask:0xf bound_ctrl:1
	v_add_f32_dpp v59, v59, v59 row_shr:8 row_mask:0xf bank_mask:0xf bound_ctrl:1
	v_add_f32_dpp v60, v60, v60 row_shr:8 row_mask:0xf bank_mask:0xf bound_ctrl:1
	v_add_f32_dpp v61, v61, v61 row_shr:8 row_mask:0xf bank_mask:0xf bound_ctrl:1
	v_add_f32_dpp v62, v62, v62 row_shr:8 row_mask:0xf bank_mask:0xf bound_ctrl:1
	v_add_f32_dpp v63, v63, v63 row_shr:8 row_mask:0xf bank_mask:0xf bound_ctrl:1
	v_mov_b32_dpp v88, v56 row_newbcast:15 row_mask:0xf bank_mask:0xf
	v_mov_b32_dpp v89, v57 row_newbcast:15 row_mask:0xf bank_mask:0xf
	v_mov_b32_dpp v90, v58 row_newbcast:15 row_mask:0xf bank_mask:0xf
	v_mov_b32_dpp v91, v59 row_newbcast:15 row_mask:0xf bank_mask:0xf
	v_mov_b32_dpp v92, v60 row_newbcast:15 row_mask:0xf bank_mask:0xf
	v_mov_b32_dpp v93, v61 row_newbcast:15 row_mask:0xf bank_mask:0xf
	v_mov_b32_dpp v94, v62 row_newbcast:15 row_mask:0xf bank_mask:0xf
	v_mov_b32_dpp v95, v63 row_newbcast:15 row_mask:0xf bank_mask:0xf
	v_add_f32_e32 v56, v56, v170
	v_add_f32_e32 v60, v60, v171
	v_add_f32_e32 v57, v57, v172
	v_add_f32_e32 v61, v61, v173
	v_add_f32_e32 v58, v58, v174
	v_add_f32_e32 v62, v62, v175
	v_add_f32_e32 v59, v59, v176
	v_add_f32_e32 v63, v63, v177
	v_mul_f32_e32 v132, v56, v141
	v_mul_f32_e32 v56, v56, v140
	v_fma_f32 v56, -v60, v141, v56
	v_fma_f32 v60, v60, v140, v132
	v_mul_f32_e32 v133, v57, v145
	v_mul_f32_e32 v57, v57, v144
	v_fma_f32 v57, -v61, v145, v57
	v_fma_f32 v61, v61, v144, v133
	v_mul_f32_e32 v132, v58, v149
	v_mul_f32_e32 v58, v58, v148
	v_fma_f32 v58, -v62, v149, v58
	v_fma_f32 v62, v62, v148, v132
	v_mul_f32_e32 v133, v59, v153
	v_mul_f32_e32 v59, v59, v152
	v_fma_f32 v59, -v63, v153, v59
	v_fma_f32 v63, v63, v152, v133
	v_add_f32_e32 v88, v88, v170
	v_add_f32_e32 v92, v92, v171
	v_mul_f32_e32 v132, v92, v155
	v_mul_f32_e32 v171, v88, v155
	v_fma_f32 v170, v88, v154, -v132
	v_fma_f32 v171, v92, v154, v171
	v_add_f32_e32 v89, v89, v172
	v_add_f32_e32 v93, v93, v173
	v_mul_f32_e32 v133, v93, v159
	v_mul_f32_e32 v173, v89, v159
	v_fma_f32 v172, v89, v158, -v133
	v_fma_f32 v173, v93, v158, v173
	v_add_f32_e32 v90, v90, v174
	v_add_f32_e32 v94, v94, v175
	v_mul_f32_e32 v132, v94, v163
	v_mul_f32_e32 v175, v90, v163
	v_fma_f32 v174, v90, v162, -v132
	v_fma_f32 v175, v94, v162, v175
	v_add_f32_e32 v91, v91, v176
	v_add_f32_e32 v95, v95, v177
	v_mul_f32_e32 v133, v95, v167
	v_mul_f32_e32 v177, v91, v167
	v_fma_f32 v176, v91, v166, -v133
	v_fma_f32 v177, v95, v166, v177
	s_waitcnt vmcnt(12)
	v_cvt_pk_bf16_f32 v96, v32, v33
	v_cvt_pk_bf16_f32 v97, v34, v35
	v_cvt_pk_bf16_f32 v98, v36, v37
	v_cvt_pk_bf16_f32 v99, v38, v39
	s_nop 1
	v_mfma_f32_16x16x32_bf16 v[16:19], v[80:83], v[96:99], 0
	v_cvt_pk_bf16_f32 v96, v40, v41
	v_cvt_pk_bf16_f32 v97, v42, v43
	v_cvt_pk_bf16_f32 v98, v44, v45
	v_cvt_pk_bf16_f32 v99, v46, v47
	s_nop 1
	v_mfma_f32_16x16x32_bf16 v[20:23], v[80:83], v[96:99], 0
	v_cvt_pk_bf16_f32 v96, v48, v49
	v_cvt_pk_bf16_f32 v97, v50, v51
	v_cvt_pk_bf16_f32 v98, v52, v53
	v_cvt_pk_bf16_f32 v99, v54, v55
	s_nop 1
	v_mfma_f32_16x16x32_bf16 v[24:27], v[80:83], v[96:99], 0
	v_cvt_pk_bf16_f32 v96, v56, v57
	v_cvt_pk_bf16_f32 v97, v58, v59
	v_cvt_pk_bf16_f32 v98, v60, v61
	v_cvt_pk_bf16_f32 v99, v62, v63
	s_nop 1
	v_mfma_f32_16x16x32_bf16 v[28:31], v[80:83], v[96:99], 0
	s_waitcnt vmcnt(10)
	global_load_dwordx4 v[80:83], v134, s[38:39]
	s_add_u32 s38, s38, 0x400
	s_addc_u32 s39, s39, 0
	v_mfma_f32_16x16x32_bf16 v[32:35], v[64:67], v[0:3], 0
	v_mfma_f32_16x16x32_bf16 v[36:39], v[72:75], v[0:3], 0
	v_mfma_f32_16x16x32_bf16 v[40:43], v[64:67], v[4:7], 0
	v_mfma_f32_16x16x32_bf16 v[44:47], v[72:75], v[4:7], 0
	v_mfma_f32_16x16x32_bf16 v[48:51], v[64:67], v[8:11], 0
	v_mfma_f32_16x16x32_bf16 v[52:55], v[72:75], v[8:11], 0
	v_mfma_f32_16x16x32_bf16 v[56:59], v[64:67], v[12:15], 0
	v_mfma_f32_16x16x32_bf16 v[60:63], v[72:75], v[12:15], 0
	global_load_dwordx4 v[64:67], v134, s[20:21]
	global_load_dwordx4 v[72:75], v134, s[20:21] offset:1024
	s_add_u32 s20, s20, 0x800
	s_addc_u32 s21, s21, 0
	global_load_dwordx4 v[138:141], v134, s[42:43] offset:0
	global_load_dwordx4 v[142:145], v134, s[42:43] offset:1024
	global_load_dwordx4 v[146:149], v134, s[42:43] offset:2048
	global_load_dwordx4 v[150:153], v134, s[42:43] offset:3072
	global_load_dwordx4 v[154:157], v208, s[42:43] offset:0
	global_load_dwordx4 v[158:161], v208, s[42:43] offset:1024
	global_load_dwordx4 v[162:165], v208, s[42:43] offset:2048
	global_load_dwordx4 v[166:169], v208, s[42:43] offset:3072
	global_load_dwordx4 v[170:173], v206, s[44:45]
	global_load_dwordx4 v[174:177], v206, s[44:45] offset:16
	s_add_u32 s42, s42, 0x2000
	s_addc_u32 s43, s43, 0
	s_add_u32 s44, s44, 0x80
	s_addc_u32 s45, s45, 0
	s_waitcnt vmcnt(13)
	v_mul_f32_e32 v132, v179, v119
	v_mul_f32_e32 v133, v178, v119
	v_fma_f32 v178, v178, v118, -v132
	v_fma_f32 v179, v179, v118, v133
	v_mul_f32_e32 v132, v181, v123
	v_mul_f32_e32 v133, v180, v123
	v_fma_f32 v180, v180, v122, -v132
	v_fma_f32 v181, v181, v122, v133
	v_mul_f32_e32 v132, v183, v127
	v_mul_f32_e32 v133, v182, v127
	v_fma_f32 v182, v182, v126, -v132
	v_fma_f32 v183, v183, v126, v133
	v_mul_f32_e32 v132, v185, v131
	v_mul_f32_e32 v133, v184, v131
	v_fma_f32 v184, v184, v130, -v132
	v_fma_f32 v185, v185, v130, v133
	v_mul_f32_e32 v132, v32, v101
	v_mul_f32_e32 v32, v32, v100
	v_fma_f32 v32, -v36, v101, v32
	v_fma_f32 v36, v36, v100, v132
	v_mul_f32_e32 v133, v33, v105
	v_mul_f32_e32 v33, v33, v104
	v_fma_f32 v33, -v37, v105, v33
	v_fma_f32 v37, v37, v104, v133
	v_mul_f32_e32 v132, v34, v109
	v_mul_f32_e32 v34, v34, v108
	v_fma_f32 v34, -v38, v109, v34
	v_fma_f32 v38, v38, v108, v132
	v_mul_f32_e32 v133, v35, v113
	v_mul_f32_e32 v35, v35, v112
	v_fma_f32 v35, -v39, v113, v35
	v_fma_f32 v39, v39, v112, v133
	v_add_f32_dpp v32, v32, v32 row_shr:1 row_mask:0xf bank_mask:0xf bound_ctrl:1
	v_add_f32_dpp v33, v33, v33 row_shr:1 row_mask:0xf bank_mask:0xf bound_ctrl:1
	v_add_f32_dpp v34, v34, v34 row_shr:1 row_mask:0xf bank_mask:0xf bound_ctrl:1
	v_add_f32_dpp v35, v35, v35 row_shr:1 row_mask:0xf bank_mask:0xf bound_ctrl:1
	v_add_f32_dpp v36, v36, v36 row_shr:1 row_mask:0xf bank_mask:0xf bound_ctrl:1
	v_add_f32_dpp v37, v37, v37 row_shr:1 row_mask:0xf bank_mask:0xf bound_ctrl:1
	v_add_f32_dpp v38, v38, v38 row_shr:1 row_mask:0xf bank_mask:0xf bound_ctrl:1
	v_add_f32_dpp v39, v39, v39 row_shr:1 row_mask:0xf bank_mask:0xf bound_ctrl:1
	v_add_f32_dpp v32, v32, v32 row_shr:2 row_mask:0xf bank_mask:0xf bound_ctrl:1
	v_add_f32_dpp v33, v33, v33 row_shr:2 row_mask:0xf bank_mask:0xf bound_ctrl:1
	v_add_f32_dpp v34, v34, v34 row_shr:2 row_mask:0xf bank_mask:0xf bound_ctrl:1
	v_add_f32_dpp v35, v35, v35 row_shr:2 row_mask:0xf bank_mask:0xf bound_ctrl:1
	v_add_f32_dpp v36, v36, v36 row_shr:2 row_mask:0xf bank_mask:0xf bound_ctrl:1
	v_add_f32_dpp v37, v37, v37 row_shr:2 row_mask:0xf bank_mask:0xf bound_ctrl:1
	v_add_f32_dpp v38, v38, v38 row_shr:2 row_mask:0xf bank_mask:0xf bound_ctrl:1
	v_add_f32_dpp v39, v39, v39 row_shr:2 row_mask:0xf bank_mask:0xf bound_ctrl:1
	v_add_f32_dpp v32, v32, v32 row_shr:4 row_mask:0xf bank_mask:0xf bound_ctrl:1
	v_add_f32_dpp v33, v33, v33 row_shr:4 row_mask:0xf bank_mask:0xf bound_ctrl:1
	v_add_f32_dpp v34, v34, v34 row_shr:4 row_mask:0xf bank_mask:0xf bound_ctrl:1
	v_add_f32_dpp v35, v35, v35 row_shr:4 row_mask:0xf bank_mask:0xf bound_ctrl:1
	v_add_f32_dpp v36, v36, v36 row_shr:4 row_mask:0xf bank_mask:0xf bound_ctrl:1
	v_add_f32_dpp v37, v37, v37 row_shr:4 row_mask:0xf bank_mask:0xf bound_ctrl:1
	v_add_f32_dpp v38, v38, v38 row_shr:4 row_mask:0xf bank_mask:0xf bound_ctrl:1
	v_add_f32_dpp v39, v39, v39 row_shr:4 row_mask:0xf bank_mask:0xf bound_ctrl:1
	v_add_f32_dpp v32, v32, v32 row_shr:8 row_mask:0xf bank_mask:0xf bound_ctrl:1
	v_add_f32_dpp v33, v33, v33 row_shr:8 row_mask:0xf bank_mask:0xf bound_ctrl:1
	v_add_f32_dpp v34, v34, v34 row_shr:8 row_mask:0xf bank_mask:0xf bound_ctrl:1
	v_add_f32_dpp v35, v35, v35 row_shr:8 row_mask:0xf bank_mask:0xf bound_ctrl:1
	v_add_f32_dpp v36, v36, v36 row_shr:8 row_mask:0xf bank_mask:0xf bound_ctrl:1
	v_add_f32_dpp v37, v37, v37 row_shr:8 row_mask:0xf bank_mask:0xf bound_ctrl:1
	v_add_f32_dpp v38, v38, v38 row_shr:8 row_mask:0xf bank_mask:0xf bound_ctrl:1
	v_add_f32_dpp v39, v39, v39 row_shr:8 row_mask:0xf bank_mask:0xf bound_ctrl:1
	v_mov_b32_dpp v88, v32 row_newbcast:15 row_mask:0xf bank_mask:0xf
	v_mov_b32_dpp v89, v33 row_newbcast:15 row_mask:0xf bank_mask:0xf
	v_mov_b32_dpp v90, v34 row_newbcast:15 row_mask:0xf bank_mask:0xf
	v_mov_b32_dpp v91, v35 row_newbcast:15 row_mask:0xf bank_mask:0xf
	v_mov_b32_dpp v92, v36 row_newbcast:15 row_mask:0xf bank_mask:0xf
	v_mov_b32_dpp v93, v37 row_newbcast:15 row_mask:0xf bank_mask:0xf
	v_mov_b32_dpp v94, v38 row_newbcast:15 row_mask:0xf bank_mask:0xf
	v_mov_b32_dpp v95, v39 row_newbcast:15 row_mask:0xf bank_mask:0xf
	v_add_f32_e32 v32, v32, v178
	v_add_f32_e32 v36, v36, v179
	v_add_f32_e32 v33, v33, v180
	v_add_f32_e32 v37, v37, v181
	v_add_f32_e32 v34, v34, v182
	v_add_f32_e32 v38, v38, v183
	v_add_f32_e32 v35, v35, v184
	v_add_f32_e32 v39, v39, v185
	v_mul_f32_e32 v132, v32, v103
	v_mul_f32_e32 v32, v32, v102
	v_fma_f32 v32, -v36, v103, v32
	v_fma_f32 v36, v36, v102, v132
	v_mul_f32_e32 v133, v33, v107
	v_mul_f32_e32 v33, v33, v106
	v_fma_f32 v33, -v37, v107, v33
	v_fma_f32 v37, v37, v106, v133
	v_mul_f32_e32 v132, v34, v111
	v_mul_f32_e32 v34, v34, v110
	v_fma_f32 v34, -v38, v111, v34
	v_fma_f32 v38, v38, v110, v132
	v_mul_f32_e32 v133, v35, v115
	v_mul_f32_e32 v35, v35, v114
	v_fma_f32 v35, -v39, v115, v35
	v_fma_f32 v39, v39, v114, v133
	v_add_f32_e32 v88, v88, v178
	v_add_f32_e32 v92, v92, v179
	v_mul_f32_e32 v132, v92, v117
	v_mul_f32_e32 v179, v88, v117
	v_fma_f32 v178, v88, v116, -v132
	v_fma_f32 v179, v92, v116, v179
	v_add_f32_e32 v89, v89, v180
	v_add_f32_e32 v93, v93, v181
	v_mul_f32_e32 v133, v93, v121
	v_mul_f32_e32 v181, v89, v121
	v_fma_f32 v180, v89, v120, -v133
	v_fma_f32 v181, v93, v120, v181
	v_add_f32_e32 v90, v90, v182
	v_add_f32_e32 v94, v94, v183
	v_mul_f32_e32 v132, v94, v125
	v_mul_f32_e32 v183, v90, v125
	v_fma_f32 v182, v90, v124, -v132
	v_fma_f32 v183, v94, v124, v183
	v_add_f32_e32 v91, v91, v184
	v_add_f32_e32 v95, v95, v185
	v_mul_f32_e32 v133, v95, v129
	v_mul_f32_e32 v185, v91, v129
	v_fma_f32 v184, v91, v128, -v133
	v_fma_f32 v185, v95, v128, v185
	v_mul_f32_e32 v132, v40, v101
	v_mul_f32_e32 v40, v40, v100
	v_fma_f32 v40, -v44, v101, v40
	v_fma_f32 v44, v44, v100, v132
	v_mul_f32_e32 v133, v41, v105
	v_mul_f32_e32 v41, v41, v104
	v_fma_f32 v41, -v45, v105, v41
	v_fma_f32 v45, v45, v104, v133
	v_mul_f32_e32 v132, v42, v109
	v_mul_f32_e32 v42, v42, v108
	v_fma_f32 v42, -v46, v109, v42
	v_fma_f32 v46, v46, v108, v132
	v_mul_f32_e32 v133, v43, v113
	v_mul_f32_e32 v43, v43, v112
	v_fma_f32 v43, -v47, v113, v43
	v_fma_f32 v47, v47, v112, v133
	v_add_f32_dpp v40, v40, v40 row_shr:1 row_mask:0xf bank_mask:0xf bound_ctrl:1
	v_add_f32_dpp v41, v41, v41 row_shr:1 row_mask:0xf bank_mask:0xf bound_ctrl:1
	v_add_f32_dpp v42, v42, v42 row_shr:1 row_mask:0xf bank_mask:0xf bound_ctrl:1
	v_add_f32_dpp v43, v43, v43 row_shr:1 row_mask:0xf bank_mask:0xf bound_ctrl:1
	v_add_f32_dpp v44, v44, v44 row_shr:1 row_mask:0xf bank_mask:0xf bound_ctrl:1
	v_add_f32_dpp v45, v45, v45 row_shr:1 row_mask:0xf bank_mask:0xf bound_ctrl:1
	v_add_f32_dpp v46, v46, v46 row_shr:1 row_mask:0xf bank_mask:0xf bound_ctrl:1
	v_add_f32_dpp v47, v47, v47 row_shr:1 row_mask:0xf bank_mask:0xf bound_ctrl:1
	v_add_f32_dpp v40, v40, v40 row_shr:2 row_mask:0xf bank_mask:0xf bound_ctrl:1
	v_add_f32_dpp v41, v41, v41 row_shr:2 row_mask:0xf bank_mask:0xf bound_ctrl:1
	v_add_f32_dpp v42, v42, v42 row_shr:2 row_mask:0xf bank_mask:0xf bound_ctrl:1
	v_add_f32_dpp v43, v43, v43 row_shr:2 row_mask:0xf bank_mask:0xf bound_ctrl:1
	v_add_f32_dpp v44, v44, v44 row_shr:2 row_mask:0xf bank_mask:0xf bound_ctrl:1
	v_add_f32_dpp v45, v45, v45 row_shr:2 row_mask:0xf bank_mask:0xf bound_ctrl:1
	v_add_f32_dpp v46, v46, v46 row_shr:2 row_mask:0xf bank_mask:0xf bound_ctrl:1
	v_add_f32_dpp v47, v47, v47 row_shr:2 row_mask:0xf bank_mask:0xf bound_ctrl:1
	v_add_f32_dpp v40, v40, v40 row_shr:4 row_mask:0xf bank_mask:0xf bound_ctrl:1
	v_add_f32_dpp v41, v41, v41 row_shr:4 row_mask:0xf bank_mask:0xf bound_ctrl:1
	v_add_f32_dpp v42, v42, v42 row_shr:4 row_mask:0xf bank_mask:0xf bound_ctrl:1
	v_add_f32_dpp v43, v43, v43 row_shr:4 row_mask:0xf bank_mask:0xf bound_ctrl:1
	v_add_f32_dpp v44, v44, v44 row_shr:4 row_mask:0xf bank_mask:0xf bound_ctrl:1
	v_add_f32_dpp v45, v45, v45 row_shr:4 row_mask:0xf bank_mask:0xf bound_ctrl:1
	v_add_f32_dpp v46, v46, v46 row_shr:4 row_mask:0xf bank_mask:0xf bound_ctrl:1
	v_add_f32_dpp v47, v47, v47 row_shr:4 row_mask:0xf bank_mask:0xf bound_ctrl:1
	v_add_f32_dpp v40, v40, v40 row_shr:8 row_mask:0xf bank_mask:0xf bound_ctrl:1
	v_add_f32_dpp v41, v41, v41 row_shr:8 row_mask:0xf bank_mask:0xf bound_ctrl:1
	v_add_f32_dpp v42, v42, v42 row_shr:8 row_mask:0xf bank_mask:0xf bound_ctrl:1
	v_add_f32_dpp v43, v43, v43 row_shr:8 row_mask:0xf bank_mask:0xf bound_ctrl:1
	v_add_f32_dpp v44, v44, v44 row_shr:8 row_mask:0xf bank_mask:0xf bound_ctrl:1
	v_add_f32_dpp v45, v45, v45 row_shr:8 row_mask:0xf bank_mask:0xf bound_ctrl:1
	v_add_f32_dpp v46, v46, v46 row_shr:8 row_mask:0xf bank_mask:0xf bound_ctrl:1
	v_add_f32_dpp v47, v47, v47 row_shr:8 row_mask:0xf bank_mask:0xf bound_ctrl:1
	v_mov_b32_dpp v88, v40 row_newbcast:15 row_mask:0xf bank_mask:0xf
	v_mov_b32_dpp v89, v41 row_newbcast:15 row_mask:0xf bank_mask:0xf
	v_mov_b32_dpp v90, v42 row_newbcast:15 row_mask:0xf bank_mask:0xf
	v_mov_b32_dpp v91, v43 row_newbcast:15 row_mask:0xf bank_mask:0xf
	v_mov_b32_dpp v92, v44 row_newbcast:15 row_mask:0xf bank_mask:0xf
	v_mov_b32_dpp v93, v45 row_newbcast:15 row_mask:0xf bank_mask:0xf
	v_mov_b32_dpp v94, v46 row_newbcast:15 row_mask:0xf bank_mask:0xf
	v_mov_b32_dpp v95, v47 row_newbcast:15 row_mask:0xf bank_mask:0xf
	v_add_f32_e32 v40, v40, v178
	v_add_f32_e32 v44, v44, v179
	v_add_f32_e32 v41, v41, v180
	v_add_f32_e32 v45, v45, v181
	v_add_f32_e32 v42, v42, v182
	v_add_f32_e32 v46, v46, v183
	v_add_f32_e32 v43, v43, v184
	v_add_f32_e32 v47, v47, v185
	v_mul_f32_e32 v132, v40, v103
	v_mul_f32_e32 v40, v40, v102
	v_fma_f32 v40, -v44, v103, v40
	v_fma_f32 v44, v44, v102, v132
	v_mul_f32_e32 v133, v41, v107
	v_mul_f32_e32 v41, v41, v106
	v_fma_f32 v41, -v45, v107, v41
	v_fma_f32 v45, v45, v106, v133
	v_mul_f32_e32 v132, v42, v111
	v_mul_f32_e32 v42, v42, v110
	v_fma_f32 v42, -v46, v111, v42
	v_fma_f32 v46, v46, v110, v132
	v_mul_f32_e32 v133, v43, v115
	v_mul_f32_e32 v43, v43, v114
	v_fma_f32 v43, -v47, v115, v43
	v_fma_f32 v47, v47, v114, v133
	v_add_f32_e32 v88, v88, v178
	v_add_f32_e32 v92, v92, v179
	v_mul_f32_e32 v132, v92, v117
	v_mul_f32_e32 v179, v88, v117
	v_fma_f32 v178, v88, v116, -v132
	v_fma_f32 v179, v92, v116, v179
	v_add_f32_e32 v89, v89, v180
	v_add_f32_e32 v93, v93, v181
	v_mul_f32_e32 v133, v93, v121
	v_mul_f32_e32 v181, v89, v121
	v_fma_f32 v180, v89, v120, -v133
	v_fma_f32 v181, v93, v120, v181
	v_add_f32_e32 v90, v90, v182
	v_add_f32_e32 v94, v94, v183
	v_mul_f32_e32 v132, v94, v125
	v_mul_f32_e32 v183, v90, v125
	v_fma_f32 v182, v90, v124, -v132
	v_fma_f32 v183, v94, v124, v183
	v_add_f32_e32 v91, v91, v184
	v_add_f32_e32 v95, v95, v185
	v_mul_f32_e32 v133, v95, v129
	v_mul_f32_e32 v185, v91, v129
	v_fma_f32 v184, v91, v128, -v133
	v_fma_f32 v185, v95, v128, v185
	v_mul_f32_e32 v132, v48, v101
	v_mul_f32_e32 v48, v48, v100
	v_fma_f32 v48, -v52, v101, v48
	v_fma_f32 v52, v52, v100, v132
	v_mul_f32_e32 v133, v49, v105
	v_mul_f32_e32 v49, v49, v104
	v_fma_f32 v49, -v53, v105, v49
	v_fma_f32 v53, v53, v104, v133
	v_mul_f32_e32 v132, v50, v109
	v_mul_f32_e32 v50, v50, v108
	v_fma_f32 v50, -v54, v109, v50
	v_fma_f32 v54, v54, v108, v132
	v_mul_f32_e32 v133, v51, v113
	v_mul_f32_e32 v51, v51, v112
	v_fma_f32 v51, -v55, v113, v51
	v_fma_f32 v55, v55, v112, v133
	v_add_f32_dpp v48, v48, v48 row_shr:1 row_mask:0xf bank_mask:0xf bound_ctrl:1
	v_add_f32_dpp v49, v49, v49 row_shr:1 row_mask:0xf bank_mask:0xf bound_ctrl:1
	v_add_f32_dpp v50, v50, v50 row_shr:1 row_mask:0xf bank_mask:0xf bound_ctrl:1
	v_add_f32_dpp v51, v51, v51 row_shr:1 row_mask:0xf bank_mask:0xf bound_ctrl:1
	v_add_f32_dpp v52, v52, v52 row_shr:1 row_mask:0xf bank_mask:0xf bound_ctrl:1
	v_add_f32_dpp v53, v53, v53 row_shr:1 row_mask:0xf bank_mask:0xf bound_ctrl:1
	v_add_f32_dpp v54, v54, v54 row_shr:1 row_mask:0xf bank_mask:0xf bound_ctrl:1
	v_add_f32_dpp v55, v55, v55 row_shr:1 row_mask:0xf bank_mask:0xf bound_ctrl:1
	v_add_f32_dpp v48, v48, v48 row_shr:2 row_mask:0xf bank_mask:0xf bound_ctrl:1
	v_add_f32_dpp v49, v49, v49 row_shr:2 row_mask:0xf bank_mask:0xf bound_ctrl:1
	v_add_f32_dpp v50, v50, v50 row_shr:2 row_mask:0xf bank_mask:0xf bound_ctrl:1
	v_add_f32_dpp v51, v51, v51 row_shr:2 row_mask:0xf bank_mask:0xf bound_ctrl:1
	v_add_f32_dpp v52, v52, v52 row_shr:2 row_mask:0xf bank_mask:0xf bound_ctrl:1
	v_add_f32_dpp v53, v53, v53 row_shr:2 row_mask:0xf bank_mask:0xf bound_ctrl:1
	v_add_f32_dpp v54, v54, v54 row_shr:2 row_mask:0xf bank_mask:0xf bound_ctrl:1
	v_add_f32_dpp v55, v55, v55 row_shr:2 row_mask:0xf bank_mask:0xf bound_ctrl:1
	v_add_f32_dpp v48, v48, v48 row_shr:4 row_mask:0xf bank_mask:0xf bound_ctrl:1
	v_add_f32_dpp v49, v49, v49 row_shr:4 row_mask:0xf bank_mask:0xf bound_ctrl:1
	v_add_f32_dpp v50, v50, v50 row_shr:4 row_mask:0xf bank_mask:0xf bound_ctrl:1
	v_add_f32_dpp v51, v51, v51 row_shr:4 row_mask:0xf bank_mask:0xf bound_ctrl:1
	v_add_f32_dpp v52, v52, v52 row_shr:4 row_mask:0xf bank_mask:0xf bound_ctrl:1
	v_add_f32_dpp v53, v53, v53 row_shr:4 row_mask:0xf bank_mask:0xf bound_ctrl:1
	v_add_f32_dpp v54, v54, v54 row_shr:4 row_mask:0xf bank_mask:0xf bound_ctrl:1
	v_add_f32_dpp v55, v55, v55 row_shr:4 row_mask:0xf bank_mask:0xf bound_ctrl:1
	v_add_f32_dpp v48, v48, v48 row_shr:8 row_mask:0xf bank_mask:0xf bound_ctrl:1
	v_add_f32_dpp v49, v49, v49 row_shr:8 row_mask:0xf bank_mask:0xf bound_ctrl:1
	v_add_f32_dpp v50, v50, v50 row_shr:8 row_mask:0xf bank_mask:0xf bound_ctrl:1
	v_add_f32_dpp v51, v51, v51 row_shr:8 row_mask:0xf bank_mask:0xf bound_ctrl:1
	v_add_f32_dpp v52, v52, v52 row_shr:8 row_mask:0xf bank_mask:0xf bound_ctrl:1
	v_add_f32_dpp v53, v53, v53 row_shr:8 row_mask:0xf bank_mask:0xf bound_ctrl:1
	v_add_f32_dpp v54, v54, v54 row_shr:8 row_mask:0xf bank_mask:0xf bound_ctrl:1
	v_add_f32_dpp v55, v55, v55 row_shr:8 row_mask:0xf bank_mask:0xf bound_ctrl:1
	v_mov_b32_dpp v88, v48 row_newbcast:15 row_mask:0xf bank_mask:0xf
	v_mov_b32_dpp v89, v49 row_newbcast:15 row_mask:0xf bank_mask:0xf
	v_mov_b32_dpp v90, v50 row_newbcast:15 row_mask:0xf bank_mask:0xf
	v_mov_b32_dpp v91, v51 row_newbcast:15 row_mask:0xf bank_mask:0xf
	v_mov_b32_dpp v92, v52 row_newbcast:15 row_mask:0xf bank_mask:0xf
	v_mov_b32_dpp v93, v53 row_newbcast:15 row_mask:0xf bank_mask:0xf
	v_mov_b32_dpp v94, v54 row_newbcast:15 row_mask:0xf bank_mask:0xf
	v_mov_b32_dpp v95, v55 row_newbcast:15 row_mask:0xf bank_mask:0xf
	v_add_f32_e32 v48, v48, v178
	v_add_f32_e32 v52, v52, v179
	v_add_f32_e32 v49, v49, v180
	v_add_f32_e32 v53, v53, v181
	v_add_f32_e32 v50, v50, v182
	v_add_f32_e32 v54, v54, v183
	v_add_f32_e32 v51, v51, v184
	v_add_f32_e32 v55, v55, v185
	v_mul_f32_e32 v132, v48, v103
	v_mul_f32_e32 v48, v48, v102
	v_fma_f32 v48, -v52, v103, v48
	v_fma_f32 v52, v52, v102, v132
	v_mul_f32_e32 v133, v49, v107
	v_mul_f32_e32 v49, v49, v106
	v_fma_f32 v49, -v53, v107, v49
	v_fma_f32 v53, v53, v106, v133
	v_mul_f32_e32 v132, v50, v111
	v_mul_f32_e32 v50, v50, v110
	v_fma_f32 v50, -v54, v111, v50
	v_fma_f32 v54, v54, v110, v132
	v_mul_f32_e32 v133, v51, v115
	v_mul_f32_e32 v51, v51, v114
	v_fma_f32 v51, -v55, v115, v51
	v_fma_f32 v55, v55, v114, v133
	v_add_f32_e32 v88, v88, v178
	v_add_f32_e32 v92, v92, v179
	v_mul_f32_e32 v132, v92, v117
	v_mul_f32_e32 v179, v88, v117
	v_fma_f32 v178, v88, v116, -v132
	v_fma_f32 v179, v92, v116, v179
	v_add_f32_e32 v89, v89, v180
	v_add_f32_e32 v93, v93, v181
	v_mul_f32_e32 v133, v93, v121
	v_mul_f32_e32 v181, v89, v121
	v_fma_f32 v180, v89, v120, -v133
	v_fma_f32 v181, v93, v120, v181
	v_add_f32_e32 v90, v90, v182
	v_add_f32_e32 v94, v94, v183
	v_mul_f32_e32 v132, v94, v125
	v_mul_f32_e32 v183, v90, v125
	v_fma_f32 v182, v90, v124, -v132
	v_fma_f32 v183, v94, v124, v183
	v_add_f32_e32 v91, v91, v184
	v_add_f32_e32 v95, v95, v185
	v_mul_f32_e32 v133, v95, v129
	v_mul_f32_e32 v185, v91, v129
	v_fma_f32 v184, v91, v128, -v133
	v_fma_f32 v185, v95, v128, v185
	v_mul_f32_e32 v132, v56, v101
	v_mul_f32_e32 v56, v56, v100
	v_fma_f32 v56, -v60, v101, v56
	v_fma_f32 v60, v60, v100, v132
	v_mul_f32_e32 v133, v57, v105
	v_mul_f32_e32 v57, v57, v104
	v_fma_f32 v57, -v61, v105, v57
	v_fma_f32 v61, v61, v104, v133
	v_mul_f32_e32 v132, v58, v109
	v_mul_f32_e32 v58, v58, v108
	v_fma_f32 v58, -v62, v109, v58
	v_fma_f32 v62, v62, v108, v132
	v_mul_f32_e32 v133, v59, v113
	v_mul_f32_e32 v59, v59, v112
	v_fma_f32 v59, -v63, v113, v59
	v_fma_f32 v63, v63, v112, v133
	v_add_f32_dpp v56, v56, v56 row_shr:1 row_mask:0xf bank_mask:0xf bound_ctrl:1
	v_add_f32_dpp v57, v57, v57 row_shr:1 row_mask:0xf bank_mask:0xf bound_ctrl:1
	v_add_f32_dpp v58, v58, v58 row_shr:1 row_mask:0xf bank_mask:0xf bound_ctrl:1
	v_add_f32_dpp v59, v59, v59 row_shr:1 row_mask:0xf bank_mask:0xf bound_ctrl:1
	v_add_f32_dpp v60, v60, v60 row_shr:1 row_mask:0xf bank_mask:0xf bound_ctrl:1
	v_add_f32_dpp v61, v61, v61 row_shr:1 row_mask:0xf bank_mask:0xf bound_ctrl:1
	v_add_f32_dpp v62, v62, v62 row_shr:1 row_mask:0xf bank_mask:0xf bound_ctrl:1
	v_add_f32_dpp v63, v63, v63 row_shr:1 row_mask:0xf bank_mask:0xf bound_ctrl:1
	v_add_f32_dpp v56, v56, v56 row_shr:2 row_mask:0xf bank_mask:0xf bound_ctrl:1
	v_add_f32_dpp v57, v57, v57 row_shr:2 row_mask:0xf bank_mask:0xf bound_ctrl:1
	v_add_f32_dpp v58, v58, v58 row_shr:2 row_mask:0xf bank_mask:0xf bound_ctrl:1
	v_add_f32_dpp v59, v59, v59 row_shr:2 row_mask:0xf bank_mask:0xf bound_ctrl:1
	v_add_f32_dpp v60, v60, v60 row_shr:2 row_mask:0xf bank_mask:0xf bound_ctrl:1
	v_add_f32_dpp v61, v61, v61 row_shr:2 row_mask:0xf bank_mask:0xf bound_ctrl:1
	v_add_f32_dpp v62, v62, v62 row_shr:2 row_mask:0xf bank_mask:0xf bound_ctrl:1
	v_add_f32_dpp v63, v63, v63 row_shr:2 row_mask:0xf bank_mask:0xf bound_ctrl:1
	v_add_f32_dpp v56, v56, v56 row_shr:4 row_mask:0xf bank_mask:0xf bound_ctrl:1
	v_add_f32_dpp v57, v57, v57 row_shr:4 row_mask:0xf bank_mask:0xf bound_ctrl:1
	v_add_f32_dpp v58, v58, v58 row_shr:4 row_mask:0xf bank_mask:0xf bound_ctrl:1
	v_add_f32_dpp v59, v59, v59 row_shr:4 row_mask:0xf bank_mask:0xf bound_ctrl:1
	v_add_f32_dpp v60, v60, v60 row_shr:4 row_mask:0xf bank_mask:0xf bound_ctrl:1
	v_add_f32_dpp v61, v61, v61 row_shr:4 row_mask:0xf bank_mask:0xf bound_ctrl:1
	v_add_f32_dpp v62, v62, v62 row_shr:4 row_mask:0xf bank_mask:0xf bound_ctrl:1
	v_add_f32_dpp v63, v63, v63 row_shr:4 row_mask:0xf bank_mask:0xf bound_ctrl:1
	v_add_f32_dpp v56, v56, v56 row_shr:8 row_mask:0xf bank_mask:0xf bound_ctrl:1
	v_add_f32_dpp v57, v57, v57 row_shr:8 row_mask:0xf bank_mask:0xf bound_ctrl:1
	v_add_f32_dpp v58, v58, v58 row_shr:8 row_mask:0xf bank_mask:0xf bound_ctrl:1
	v_add_f32_dpp v59, v59, v59 row_shr:8 row_mask:0xf bank_mask:0xf bound_ctrl:1
	v_add_f32_dpp v60, v60, v60 row_shr:8 row_mask:0xf bank_mask:0xf bound_ctrl:1
	v_add_f32_dpp v61, v61, v61 row_shr:8 row_mask:0xf bank_mask:0xf bound_ctrl:1
	v_add_f32_dpp v62, v62, v62 row_shr:8 row_mask:0xf bank_mask:0xf bound_ctrl:1
	v_add_f32_dpp v63, v63, v63 row_shr:8 row_mask:0xf bank_mask:0xf bound_ctrl:1
	v_mov_b32_dpp v88, v56 row_newbcast:15 row_mask:0xf bank_mask:0xf
	v_mov_b32_dpp v89, v57 row_newbcast:15 row_mask:0xf bank_mask:0xf
	v_mov_b32_dpp v90, v58 row_newbcast:15 row_mask:0xf bank_mask:0xf
	v_mov_b32_dpp v91, v59 row_newbcast:15 row_mask:0xf bank_mask:0xf
	v_mov_b32_dpp v92, v60 row_newbcast:15 row_mask:0xf bank_mask:0xf
	v_mov_b32_dpp v93, v61 row_newbcast:15 row_mask:0xf bank_mask:0xf
	v_mov_b32_dpp v94, v62 row_newbcast:15 row_mask:0xf bank_mask:0xf
	v_mov_b32_dpp v95, v63 row_newbcast:15 row_mask:0xf bank_mask:0xf
	v_add_f32_e32 v56, v56, v178
	v_add_f32_e32 v60, v60, v179
	v_add_f32_e32 v57, v57, v180
	v_add_f32_e32 v61, v61, v181
	v_add_f32_e32 v58, v58, v182
	v_add_f32_e32 v62, v62, v183
	v_add_f32_e32 v59, v59, v184
	v_add_f32_e32 v63, v63, v185
	v_mul_f32_e32 v132, v56, v103
	v_mul_f32_e32 v56, v56, v102
	v_fma_f32 v56, -v60, v103, v56
	v_fma_f32 v60, v60, v102, v132
	v_mul_f32_e32 v133, v57, v107
	v_mul_f32_e32 v57, v57, v106
	v_fma_f32 v57, -v61, v107, v57
	v_fma_f32 v61, v61, v106, v133
	v_mul_f32_e32 v132, v58, v111
	v_mul_f32_e32 v58, v58, v110
	v_fma_f32 v58, -v62, v111, v58
	v_fma_f32 v62, v62, v110, v132
	v_mul_f32_e32 v133, v59, v115
	v_mul_f32_e32 v59, v59, v114
	v_fma_f32 v59, -v63, v115, v59
	v_fma_f32 v63, v63, v114, v133
	v_add_f32_e32 v88, v88, v178
	v_add_f32_e32 v92, v92, v179
	v_mul_f32_e32 v132, v92, v117
	v_mul_f32_e32 v179, v88, v117
	v_fma_f32 v178, v88, v116, -v132
	v_fma_f32 v179, v92, v116, v179
	v_add_f32_e32 v89, v89, v180
	v_add_f32_e32 v93, v93, v181
	v_mul_f32_e32 v133, v93, v121
	v_mul_f32_e32 v181, v89, v121
	v_fma_f32 v180, v89, v120, -v133
	v_fma_f32 v181, v93, v120, v181
	v_add_f32_e32 v90, v90, v182
	v_add_f32_e32 v94, v94, v183
	v_mul_f32_e32 v132, v94, v125
	v_mul_f32_e32 v183, v90, v125
	v_fma_f32 v182, v90, v124, -v132
	v_fma_f32 v183, v94, v124, v183
	v_add_f32_e32 v91, v91, v184
	v_add_f32_e32 v95, v95, v185
	v_mul_f32_e32 v133, v95, v129
	v_mul_f32_e32 v185, v91, v129
	v_fma_f32 v184, v91, v128, -v133
	v_fma_f32 v185, v95, v128, v185
	s_waitcnt vmcnt(12)
	v_cvt_pk_bf16_f32 v96, v32, v33
	v_cvt_pk_bf16_f32 v97, v34, v35
	v_cvt_pk_bf16_f32 v98, v36, v37
	v_cvt_pk_bf16_f32 v99, v38, v39
	s_nop 1
	v_mfma_f32_16x16x32_bf16 v[16:19], v[80:83], v[96:99], v[16:19]
	v_cvt_pk_bf16_f32 v96, v40, v41
	v_cvt_pk_bf16_f32 v97, v42, v43
	v_cvt_pk_bf16_f32 v98, v44, v45
	v_cvt_pk_bf16_f32 v99, v46, v47
	s_nop 1
	v_mfma_f32_16x16x32_bf16 v[20:23], v[80:83], v[96:99], v[20:23]
	v_cvt_pk_bf16_f32 v96, v48, v49
	v_cvt_pk_bf16_f32 v97, v50, v51
	v_cvt_pk_bf16_f32 v98, v52, v53
	v_cvt_pk_bf16_f32 v99, v54, v55
	s_nop 1
	v_mfma_f32_16x16x32_bf16 v[24:27], v[80:83], v[96:99], v[24:27]
	v_cvt_pk_bf16_f32 v96, v56, v57
	v_cvt_pk_bf16_f32 v97, v58, v59
	v_cvt_pk_bf16_f32 v98, v60, v61
	v_cvt_pk_bf16_f32 v99, v62, v63
	s_nop 1
	v_mfma_f32_16x16x32_bf16 v[28:31], v[80:83], v[96:99], v[28:31]
	s_waitcnt vmcnt(10)
	global_load_dwordx4 v[80:83], v134, s[38:39]
	s_add_u32 s38, s38, 0x400
	s_addc_u32 s39, s39, 0
	v_mfma_f32_16x16x32_bf16 v[32:35], v[64:67], v[0:3], 0
	v_mfma_f32_16x16x32_bf16 v[36:39], v[72:75], v[0:3], 0
	v_mfma_f32_16x16x32_bf16 v[40:43], v[64:67], v[4:7], 0
	v_mfma_f32_16x16x32_bf16 v[44:47], v[72:75], v[4:7], 0
	v_mfma_f32_16x16x32_bf16 v[48:51], v[64:67], v[8:11], 0
	v_mfma_f32_16x16x32_bf16 v[52:55], v[72:75], v[8:11], 0
	v_mfma_f32_16x16x32_bf16 v[56:59], v[64:67], v[12:15], 0
	v_mfma_f32_16x16x32_bf16 v[60:63], v[72:75], v[12:15], 0
	global_load_dwordx4 v[64:67], v134, s[20:21]
	global_load_dwordx4 v[72:75], v134, s[20:21] offset:1024
	global_load_dwordx4 v[100:103], v134, s[42:43] offset:0
	global_load_dwordx4 v[104:107], v134, s[42:43] offset:1024
	global_load_dwordx4 v[108:111], v134, s[42:43] offset:2048
	global_load_dwordx4 v[112:115], v134, s[42:43] offset:3072
	global_load_dwordx4 v[116:119], v208, s[42:43] offset:0
	global_load_dwordx4 v[120:123], v208, s[42:43] offset:1024
	global_load_dwordx4 v[124:127], v208, s[42:43] offset:2048
	global_load_dwordx4 v[128:131], v208, s[42:43] offset:3072
	global_load_dwordx4 v[178:181], v206, s[44:45]
	global_load_dwordx4 v[182:185], v206, s[44:45] offset:16
	s_waitcnt vmcnt(13)
	v_mul_f32_e32 v132, v171, v157
	v_mul_f32_e32 v133, v170, v157
	v_fma_f32 v170, v170, v156, -v132
	v_fma_f32 v171, v171, v156, v133
	v_mul_f32_e32 v132, v173, v161
	v_mul_f32_e32 v133, v172, v161
	v_fma_f32 v172, v172, v160, -v132
	v_fma_f32 v173, v173, v160, v133
	v_mul_f32_e32 v132, v175, v165
	v_mul_f32_e32 v133, v174, v165
	v_fma_f32 v174, v174, v164, -v132
	v_fma_f32 v175, v175, v164, v133
	v_mul_f32_e32 v132, v177, v169
	v_mul_f32_e32 v133, v176, v169
	v_fma_f32 v176, v176, v168, -v132
	v_fma_f32 v177, v177, v168, v133
	v_mul_f32_e32 v132, v32, v139
	v_mul_f32_e32 v32, v32, v138
	v_fma_f32 v32, -v36, v139, v32
	v_fma_f32 v36, v36, v138, v132
	v_mul_f32_e32 v133, v33, v143
	v_mul_f32_e32 v33, v33, v142
	v_fma_f32 v33, -v37, v143, v33
	v_fma_f32 v37, v37, v142, v133
	v_mul_f32_e32 v132, v34, v147
	v_mul_f32_e32 v34, v34, v146
	v_fma_f32 v34, -v38, v147, v34
	v_fma_f32 v38, v38, v146, v132
	v_mul_f32_e32 v133, v35, v151
	v_mul_f32_e32 v35, v35, v150
	v_fma_f32 v35, -v39, v151, v35
	v_fma_f32 v39, v39, v150, v133
	v_add_f32_dpp v32, v32, v32 row_shr:1 row_mask:0xf bank_mask:0xf bound_ctrl:1
	v_add_f32_dpp v33, v33, v33 row_shr:1 row_mask:0xf bank_mask:0xf bound_ctrl:1
	v_add_f32_dpp v34, v34, v34 row_shr:1 row_mask:0xf bank_mask:0xf bound_ctrl:1
	v_add_f32_dpp v35, v35, v35 row_shr:1 row_mask:0xf bank_mask:0xf bound_ctrl:1
	v_add_f32_dpp v36, v36, v36 row_shr:1 row_mask:0xf bank_mask:0xf bound_ctrl:1
	v_add_f32_dpp v37, v37, v37 row_shr:1 row_mask:0xf bank_mask:0xf bound_ctrl:1
	v_add_f32_dpp v38, v38, v38 row_shr:1 row_mask:0xf bank_mask:0xf bound_ctrl:1
	v_add_f32_dpp v39, v39, v39 row_shr:1 row_mask:0xf bank_mask:0xf bound_ctrl:1
	v_add_f32_dpp v32, v32, v32 row_shr:2 row_mask:0xf bank_mask:0xf bound_ctrl:1
	v_add_f32_dpp v33, v33, v33 row_shr:2 row_mask:0xf bank_mask:0xf bound_ctrl:1
	v_add_f32_dpp v34, v34, v34 row_shr:2 row_mask:0xf bank_mask:0xf bound_ctrl:1
	v_add_f32_dpp v35, v35, v35 row_shr:2 row_mask:0xf bank_mask:0xf bound_ctrl:1
	v_add_f32_dpp v36, v36, v36 row_shr:2 row_mask:0xf bank_mask:0xf bound_ctrl:1
	v_add_f32_dpp v37, v37, v37 row_shr:2 row_mask:0xf bank_mask:0xf bound_ctrl:1
	v_add_f32_dpp v38, v38, v38 row_shr:2 row_mask:0xf bank_mask:0xf bound_ctrl:1
	v_add_f32_dpp v39, v39, v39 row_shr:2 row_mask:0xf bank_mask:0xf bound_ctrl:1
	v_add_f32_dpp v32, v32, v32 row_shr:4 row_mask:0xf bank_mask:0xf bound_ctrl:1
	v_add_f32_dpp v33, v33, v33 row_shr:4 row_mask:0xf bank_mask:0xf bound_ctrl:1
	v_add_f32_dpp v34, v34, v34 row_shr:4 row_mask:0xf bank_mask:0xf bound_ctrl:1
	v_add_f32_dpp v35, v35, v35 row_shr:4 row_mask:0xf bank_mask:0xf bound_ctrl:1
	v_add_f32_dpp v36, v36, v36 row_shr:4 row_mask:0xf bank_mask:0xf bound_ctrl:1
	v_add_f32_dpp v37, v37, v37 row_shr:4 row_mask:0xf bank_mask:0xf bound_ctrl:1
	v_add_f32_dpp v38, v38, v38 row_shr:4 row_mask:0xf bank_mask:0xf bound_ctrl:1
	v_add_f32_dpp v39, v39, v39 row_shr:4 row_mask:0xf bank_mask:0xf bound_ctrl:1
	v_add_f32_dpp v32, v32, v32 row_shr:8 row_mask:0xf bank_mask:0xf bound_ctrl:1
	v_add_f32_dpp v33, v33, v33 row_shr:8 row_mask:0xf bank_mask:0xf bound_ctrl:1
	v_add_f32_dpp v34, v34, v34 row_shr:8 row_mask:0xf bank_mask:0xf bound_ctrl:1
	v_add_f32_dpp v35, v35, v35 row_shr:8 row_mask:0xf bank_mask:0xf bound_ctrl:1
	v_add_f32_dpp v36, v36, v36 row_shr:8 row_mask:0xf bank_mask:0xf bound_ctrl:1
	v_add_f32_dpp v37, v37, v37 row_shr:8 row_mask:0xf bank_mask:0xf bound_ctrl:1
	v_add_f32_dpp v38, v38, v38 row_shr:8 row_mask:0xf bank_mask:0xf bound_ctrl:1
	v_add_f32_dpp v39, v39, v39 row_shr:8 row_mask:0xf bank_mask:0xf bound_ctrl:1
	v_mov_b32_dpp v88, v32 row_newbcast:15 row_mask:0xf bank_mask:0xf
	v_mov_b32_dpp v89, v33 row_newbcast:15 row_mask:0xf bank_mask:0xf
	v_mov_b32_dpp v90, v34 row_newbcast:15 row_mask:0xf bank_mask:0xf
	v_mov_b32_dpp v91, v35 row_newbcast:15 row_mask:0xf bank_mask:0xf
	v_mov_b32_dpp v92, v36 row_newbcast:15 row_mask:0xf bank_mask:0xf
	v_mov_b32_dpp v93, v37 row_newbcast:15 row_mask:0xf bank_mask:0xf
	v_mov_b32_dpp v94, v38 row_newbcast:15 row_mask:0xf bank_mask:0xf
	v_mov_b32_dpp v95, v39 row_newbcast:15 row_mask:0xf bank_mask:0xf
	v_add_f32_e32 v32, v32, v170
	v_add_f32_e32 v36, v36, v171
	v_add_f32_e32 v33, v33, v172
	v_add_f32_e32 v37, v37, v173
	v_add_f32_e32 v34, v34, v174
	v_add_f32_e32 v38, v38, v175
	v_add_f32_e32 v35, v35, v176
	v_add_f32_e32 v39, v39, v177
	v_mul_f32_e32 v132, v32, v141
	v_mul_f32_e32 v32, v32, v140
	v_fma_f32 v32, -v36, v141, v32
	v_fma_f32 v36, v36, v140, v132
	v_mul_f32_e32 v133, v33, v145
	v_mul_f32_e32 v33, v33, v144
	v_fma_f32 v33, -v37, v145, v33
	v_fma_f32 v37, v37, v144, v133
	v_mul_f32_e32 v132, v34, v149
	v_mul_f32_e32 v34, v34, v148
	v_fma_f32 v34, -v38, v149, v34
	v_fma_f32 v38, v38, v148, v132
	v_mul_f32_e32 v133, v35, v153
	v_mul_f32_e32 v35, v35, v152
	v_fma_f32 v35, -v39, v153, v35
	v_fma_f32 v39, v39, v152, v133
	v_add_f32_e32 v88, v88, v170
	v_add_f32_e32 v92, v92, v171
	v_mul_f32_e32 v132, v92, v155
	v_mul_f32_e32 v171, v88, v155
	v_fma_f32 v170, v88, v154, -v132
	v_fma_f32 v171, v92, v154, v171
	v_add_f32_e32 v89, v89, v172
	v_add_f32_e32 v93, v93, v173
	v_mul_f32_e32 v133, v93, v159
	v_mul_f32_e32 v173, v89, v159
	v_fma_f32 v172, v89, v158, -v133
	v_fma_f32 v173, v93, v158, v173
	v_add_f32_e32 v90, v90, v174
	v_add_f32_e32 v94, v94, v175
	v_mul_f32_e32 v132, v94, v163
	v_mul_f32_e32 v175, v90, v163
	v_fma_f32 v174, v90, v162, -v132
	v_fma_f32 v175, v94, v162, v175
	v_add_f32_e32 v91, v91, v176
	v_add_f32_e32 v95, v95, v177
	v_mul_f32_e32 v133, v95, v167
	v_mul_f32_e32 v177, v91, v167
	v_fma_f32 v176, v91, v166, -v133
	v_fma_f32 v177, v95, v166, v177
	v_mul_f32_e32 v132, v40, v139
	v_mul_f32_e32 v40, v40, v138
	v_fma_f32 v40, -v44, v139, v40
	v_fma_f32 v44, v44, v138, v132
	v_mul_f32_e32 v133, v41, v143
	v_mul_f32_e32 v41, v41, v142
	v_fma_f32 v41, -v45, v143, v41
	v_fma_f32 v45, v45, v142, v133
	v_mul_f32_e32 v132, v42, v147
	v_mul_f32_e32 v42, v42, v146
	v_fma_f32 v42, -v46, v147, v42
	v_fma_f32 v46, v46, v146, v132
	v_mul_f32_e32 v133, v43, v151
	v_mul_f32_e32 v43, v43, v150
	v_fma_f32 v43, -v47, v151, v43
	v_fma_f32 v47, v47, v150, v133
	v_add_f32_dpp v40, v40, v40 row_shr:1 row_mask:0xf bank_mask:0xf bound_ctrl:1
	v_add_f32_dpp v41, v41, v41 row_shr:1 row_mask:0xf bank_mask:0xf bound_ctrl:1
	v_add_f32_dpp v42, v42, v42 row_shr:1 row_mask:0xf bank_mask:0xf bound_ctrl:1
	v_add_f32_dpp v43, v43, v43 row_shr:1 row_mask:0xf bank_mask:0xf bound_ctrl:1
	v_add_f32_dpp v44, v44, v44 row_shr:1 row_mask:0xf bank_mask:0xf bound_ctrl:1
	v_add_f32_dpp v45, v45, v45 row_shr:1 row_mask:0xf bank_mask:0xf bound_ctrl:1
	v_add_f32_dpp v46, v46, v46 row_shr:1 row_mask:0xf bank_mask:0xf bound_ctrl:1
	v_add_f32_dpp v47, v47, v47 row_shr:1 row_mask:0xf bank_mask:0xf bound_ctrl:1
	v_add_f32_dpp v40, v40, v40 row_shr:2 row_mask:0xf bank_mask:0xf bound_ctrl:1
	v_add_f32_dpp v41, v41, v41 row_shr:2 row_mask:0xf bank_mask:0xf bound_ctrl:1
	v_add_f32_dpp v42, v42, v42 row_shr:2 row_mask:0xf bank_mask:0xf bound_ctrl:1
	v_add_f32_dpp v43, v43, v43 row_shr:2 row_mask:0xf bank_mask:0xf bound_ctrl:1
	v_add_f32_dpp v44, v44, v44 row_shr:2 row_mask:0xf bank_mask:0xf bound_ctrl:1
	v_add_f32_dpp v45, v45, v45 row_shr:2 row_mask:0xf bank_mask:0xf bound_ctrl:1
	v_add_f32_dpp v46, v46, v46 row_shr:2 row_mask:0xf bank_mask:0xf bound_ctrl:1
	v_add_f32_dpp v47, v47, v47 row_shr:2 row_mask:0xf bank_mask:0xf bound_ctrl:1
	v_add_f32_dpp v40, v40, v40 row_shr:4 row_mask:0xf bank_mask:0xf bound_ctrl:1
	v_add_f32_dpp v41, v41, v41 row_shr:4 row_mask:0xf bank_mask:0xf bound_ctrl:1
	v_add_f32_dpp v42, v42, v42 row_shr:4 row_mask:0xf bank_mask:0xf bound_ctrl:1
	v_add_f32_dpp v43, v43, v43 row_shr:4 row_mask:0xf bank_mask:0xf bound_ctrl:1
	v_add_f32_dpp v44, v44, v44 row_shr:4 row_mask:0xf bank_mask:0xf bound_ctrl:1
	v_add_f32_dpp v45, v45, v45 row_shr:4 row_mask:0xf bank_mask:0xf bound_ctrl:1
	v_add_f32_dpp v46, v46, v46 row_shr:4 row_mask:0xf bank_mask:0xf bound_ctrl:1
	v_add_f32_dpp v47, v47, v47 row_shr:4 row_mask:0xf bank_mask:0xf bound_ctrl:1
	v_add_f32_dpp v40, v40, v40 row_shr:8 row_mask:0xf bank_mask:0xf bound_ctrl:1
	v_add_f32_dpp v41, v41, v41 row_shr:8 row_mask:0xf bank_mask:0xf bound_ctrl:1
	v_add_f32_dpp v42, v42, v42 row_shr:8 row_mask:0xf bank_mask:0xf bound_ctrl:1
	v_add_f32_dpp v43, v43, v43 row_shr:8 row_mask:0xf bank_mask:0xf bound_ctrl:1
	v_add_f32_dpp v44, v44, v44 row_shr:8 row_mask:0xf bank_mask:0xf bound_ctrl:1
	v_add_f32_dpp v45, v45, v45 row_shr:8 row_mask:0xf bank_mask:0xf bound_ctrl:1
	v_add_f32_dpp v46, v46, v46 row_shr:8 row_mask:0xf bank_mask:0xf bound_ctrl:1
	v_add_f32_dpp v47, v47, v47 row_shr:8 row_mask:0xf bank_mask:0xf bound_ctrl:1
	v_mov_b32_dpp v88, v40 row_newbcast:15 row_mask:0xf bank_mask:0xf
	v_mov_b32_dpp v89, v41 row_newbcast:15 row_mask:0xf bank_mask:0xf
	v_mov_b32_dpp v90, v42 row_newbcast:15 row_mask:0xf bank_mask:0xf
	v_mov_b32_dpp v91, v43 row_newbcast:15 row_mask:0xf bank_mask:0xf
	v_mov_b32_dpp v92, v44 row_newbcast:15 row_mask:0xf bank_mask:0xf
	v_mov_b32_dpp v93, v45 row_newbcast:15 row_mask:0xf bank_mask:0xf
	v_mov_b32_dpp v94, v46 row_newbcast:15 row_mask:0xf bank_mask:0xf
	v_mov_b32_dpp v95, v47 row_newbcast:15 row_mask:0xf bank_mask:0xf
	v_add_f32_e32 v40, v40, v170
	v_add_f32_e32 v44, v44, v171
	v_add_f32_e32 v41, v41, v172
	v_add_f32_e32 v45, v45, v173
	v_add_f32_e32 v42, v42, v174
	v_add_f32_e32 v46, v46, v175
	v_add_f32_e32 v43, v43, v176
	v_add_f32_e32 v47, v47, v177
	v_mul_f32_e32 v132, v40, v141
	v_mul_f32_e32 v40, v40, v140
	v_fma_f32 v40, -v44, v141, v40
	v_fma_f32 v44, v44, v140, v132
	v_mul_f32_e32 v133, v41, v145
	v_mul_f32_e32 v41, v41, v144
	v_fma_f32 v41, -v45, v145, v41
	v_fma_f32 v45, v45, v144, v133
	v_mul_f32_e32 v132, v42, v149
	v_mul_f32_e32 v42, v42, v148
	v_fma_f32 v42, -v46, v149, v42
	v_fma_f32 v46, v46, v148, v132
	v_mul_f32_e32 v133, v43, v153
	v_mul_f32_e32 v43, v43, v152
	v_fma_f32 v43, -v47, v153, v43
	v_fma_f32 v47, v47, v152, v133
	v_add_f32_e32 v88, v88, v170
	v_add_f32_e32 v92, v92, v171
	v_mul_f32_e32 v132, v92, v155
	v_mul_f32_e32 v171, v88, v155
	v_fma_f32 v170, v88, v154, -v132
	v_fma_f32 v171, v92, v154, v171
	v_add_f32_e32 v89, v89, v172
	v_add_f32_e32 v93, v93, v173
	v_mul_f32_e32 v133, v93, v159
	v_mul_f32_e32 v173, v89, v159
	v_fma_f32 v172, v89, v158, -v133
	v_fma_f32 v173, v93, v158, v173
	v_add_f32_e32 v90, v90, v174
	v_add_f32_e32 v94, v94, v175
	v_mul_f32_e32 v132, v94, v163
	v_mul_f32_e32 v175, v90, v163
	v_fma_f32 v174, v90, v162, -v132
	v_fma_f32 v175, v94, v162, v175
	v_add_f32_e32 v91, v91, v176
	v_add_f32_e32 v95, v95, v177
	v_mul_f32_e32 v133, v95, v167
	v_mul_f32_e32 v177, v91, v167
	v_fma_f32 v176, v91, v166, -v133
	v_fma_f32 v177, v95, v166, v177
	v_mul_f32_e32 v132, v48, v139
	v_mul_f32_e32 v48, v48, v138
	v_fma_f32 v48, -v52, v139, v48
	v_fma_f32 v52, v52, v138, v132
	v_mul_f32_e32 v133, v49, v143
	v_mul_f32_e32 v49, v49, v142
	v_fma_f32 v49, -v53, v143, v49
	v_fma_f32 v53, v53, v142, v133
	v_mul_f32_e32 v132, v50, v147
	v_mul_f32_e32 v50, v50, v146
	v_fma_f32 v50, -v54, v147, v50
	v_fma_f32 v54, v54, v146, v132
	v_mul_f32_e32 v133, v51, v151
	v_mul_f32_e32 v51, v51, v150
	v_fma_f32 v51, -v55, v151, v51
	v_fma_f32 v55, v55, v150, v133
	v_add_f32_dpp v48, v48, v48 row_shr:1 row_mask:0xf bank_mask:0xf bound_ctrl:1
	v_add_f32_dpp v49, v49, v49 row_shr:1 row_mask:0xf bank_mask:0xf bound_ctrl:1
	v_add_f32_dpp v50, v50, v50 row_shr:1 row_mask:0xf bank_mask:0xf bound_ctrl:1
	v_add_f32_dpp v51, v51, v51 row_shr:1 row_mask:0xf bank_mask:0xf bound_ctrl:1
	v_add_f32_dpp v52, v52, v52 row_shr:1 row_mask:0xf bank_mask:0xf bound_ctrl:1
	v_add_f32_dpp v53, v53, v53 row_shr:1 row_mask:0xf bank_mask:0xf bound_ctrl:1
	v_add_f32_dpp v54, v54, v54 row_shr:1 row_mask:0xf bank_mask:0xf bound_ctrl:1
	v_add_f32_dpp v55, v55, v55 row_shr:1 row_mask:0xf bank_mask:0xf bound_ctrl:1
	v_add_f32_dpp v48, v48, v48 row_shr:2 row_mask:0xf bank_mask:0xf bound_ctrl:1
	v_add_f32_dpp v49, v49, v49 row_shr:2 row_mask:0xf bank_mask:0xf bound_ctrl:1
	v_add_f32_dpp v50, v50, v50 row_shr:2 row_mask:0xf bank_mask:0xf bound_ctrl:1
	v_add_f32_dpp v51, v51, v51 row_shr:2 row_mask:0xf bank_mask:0xf bound_ctrl:1
	v_add_f32_dpp v52, v52, v52 row_shr:2 row_mask:0xf bank_mask:0xf bound_ctrl:1
	v_add_f32_dpp v53, v53, v53 row_shr:2 row_mask:0xf bank_mask:0xf bound_ctrl:1
	v_add_f32_dpp v54, v54, v54 row_shr:2 row_mask:0xf bank_mask:0xf bound_ctrl:1
	v_add_f32_dpp v55, v55, v55 row_shr:2 row_mask:0xf bank_mask:0xf bound_ctrl:1
	v_add_f32_dpp v48, v48, v48 row_shr:4 row_mask:0xf bank_mask:0xf bound_ctrl:1
	v_add_f32_dpp v49, v49, v49 row_shr:4 row_mask:0xf bank_mask:0xf bound_ctrl:1
	v_add_f32_dpp v50, v50, v50 row_shr:4 row_mask:0xf bank_mask:0xf bound_ctrl:1
	v_add_f32_dpp v51, v51, v51 row_shr:4 row_mask:0xf bank_mask:0xf bound_ctrl:1
	v_add_f32_dpp v52, v52, v52 row_shr:4 row_mask:0xf bank_mask:0xf bound_ctrl:1
	v_add_f32_dpp v53, v53, v53 row_shr:4 row_mask:0xf bank_mask:0xf bound_ctrl:1
	v_add_f32_dpp v54, v54, v54 row_shr:4 row_mask:0xf bank_mask:0xf bound_ctrl:1
	v_add_f32_dpp v55, v55, v55 row_shr:4 row_mask:0xf bank_mask:0xf bound_ctrl:1
	v_add_f32_dpp v48, v48, v48 row_shr:8 row_mask:0xf bank_mask:0xf bound_ctrl:1
	v_add_f32_dpp v49, v49, v49 row_shr:8 row_mask:0xf bank_mask:0xf bound_ctrl:1
	v_add_f32_dpp v50, v50, v50 row_shr:8 row_mask:0xf bank_mask:0xf bound_ctrl:1
	v_add_f32_dpp v51, v51, v51 row_shr:8 row_mask:0xf bank_mask:0xf bound_ctrl:1
	v_add_f32_dpp v52, v52, v52 row_shr:8 row_mask:0xf bank_mask:0xf bound_ctrl:1
	v_add_f32_dpp v53, v53, v53 row_shr:8 row_mask:0xf bank_mask:0xf bound_ctrl:1
	v_add_f32_dpp v54, v54, v54 row_shr:8 row_mask:0xf bank_mask:0xf bound_ctrl:1
	v_add_f32_dpp v55, v55, v55 row_shr:8 row_mask:0xf bank_mask:0xf bound_ctrl:1
	v_mov_b32_dpp v88, v48 row_newbcast:15 row_mask:0xf bank_mask:0xf
	v_mov_b32_dpp v89, v49 row_newbcast:15 row_mask:0xf bank_mask:0xf
	v_mov_b32_dpp v90, v50 row_newbcast:15 row_mask:0xf bank_mask:0xf
	v_mov_b32_dpp v91, v51 row_newbcast:15 row_mask:0xf bank_mask:0xf
	v_mov_b32_dpp v92, v52 row_newbcast:15 row_mask:0xf bank_mask:0xf
	v_mov_b32_dpp v93, v53 row_newbcast:15 row_mask:0xf bank_mask:0xf
	v_mov_b32_dpp v94, v54 row_newbcast:15 row_mask:0xf bank_mask:0xf
	v_mov_b32_dpp v95, v55 row_newbcast:15 row_mask:0xf bank_mask:0xf
	v_add_f32_e32 v48, v48, v170
	v_add_f32_e32 v52, v52, v171
	v_add_f32_e32 v49, v49, v172
	v_add_f32_e32 v53, v53, v173
	v_add_f32_e32 v50, v50, v174
	v_add_f32_e32 v54, v54, v175
	v_add_f32_e32 v51, v51, v176
	v_add_f32_e32 v55, v55, v177
	v_mul_f32_e32 v132, v48, v141
	v_mul_f32_e32 v48, v48, v140
	v_fma_f32 v48, -v52, v141, v48
	v_fma_f32 v52, v52, v140, v132
	v_mul_f32_e32 v133, v49, v145
	v_mul_f32_e32 v49, v49, v144
	v_fma_f32 v49, -v53, v145, v49
	v_fma_f32 v53, v53, v144, v133
	v_mul_f32_e32 v132, v50, v149
	v_mul_f32_e32 v50, v50, v148
	v_fma_f32 v50, -v54, v149, v50
	v_fma_f32 v54, v54, v148, v132
	v_mul_f32_e32 v133, v51, v153
	v_mul_f32_e32 v51, v51, v152
	v_fma_f32 v51, -v55, v153, v51
	v_fma_f32 v55, v55, v152, v133
	v_add_f32_e32 v88, v88, v170
	v_add_f32_e32 v92, v92, v171
	v_mul_f32_e32 v132, v92, v155
	v_mul_f32_e32 v171, v88, v155
	v_fma_f32 v170, v88, v154, -v132
	v_fma_f32 v171, v92, v154, v171
	v_add_f32_e32 v89, v89, v172
	v_add_f32_e32 v93, v93, v173
	v_mul_f32_e32 v133, v93, v159
	v_mul_f32_e32 v173, v89, v159
	v_fma_f32 v172, v89, v158, -v133
	v_fma_f32 v173, v93, v158, v173
	v_add_f32_e32 v90, v90, v174
	v_add_f32_e32 v94, v94, v175
	v_mul_f32_e32 v132, v94, v163
	v_mul_f32_e32 v175, v90, v163
	v_fma_f32 v174, v90, v162, -v132
	v_fma_f32 v175, v94, v162, v175
	v_add_f32_e32 v91, v91, v176
	v_add_f32_e32 v95, v95, v177
	v_mul_f32_e32 v133, v95, v167
	v_mul_f32_e32 v177, v91, v167
	v_fma_f32 v176, v91, v166, -v133
	v_fma_f32 v177, v95, v166, v177
	v_mul_f32_e32 v132, v56, v139
	v_mul_f32_e32 v56, v56, v138
	v_fma_f32 v56, -v60, v139, v56
	v_fma_f32 v60, v60, v138, v132
	v_mul_f32_e32 v133, v57, v143
	v_mul_f32_e32 v57, v57, v142
	v_fma_f32 v57, -v61, v143, v57
	v_fma_f32 v61, v61, v142, v133
	v_mul_f32_e32 v132, v58, v147
	v_mul_f32_e32 v58, v58, v146
	v_fma_f32 v58, -v62, v147, v58
	v_fma_f32 v62, v62, v146, v132
	v_mul_f32_e32 v133, v59, v151
	v_mul_f32_e32 v59, v59, v150
	v_fma_f32 v59, -v63, v151, v59
	v_fma_f32 v63, v63, v150, v133
	v_add_f32_dpp v56, v56, v56 row_shr:1 row_mask:0xf bank_mask:0xf bound_ctrl:1
	v_add_f32_dpp v57, v57, v57 row_shr:1 row_mask:0xf bank_mask:0xf bound_ctrl:1
	v_add_f32_dpp v58, v58, v58 row_shr:1 row_mask:0xf bank_mask:0xf bound_ctrl:1
	v_add_f32_dpp v59, v59, v59 row_shr:1 row_mask:0xf bank_mask:0xf bound_ctrl:1
	v_add_f32_dpp v60, v60, v60 row_shr:1 row_mask:0xf bank_mask:0xf bound_ctrl:1
	v_add_f32_dpp v61, v61, v61 row_shr:1 row_mask:0xf bank_mask:0xf bound_ctrl:1
	v_add_f32_dpp v62, v62, v62 row_shr:1 row_mask:0xf bank_mask:0xf bound_ctrl:1
	v_add_f32_dpp v63, v63, v63 row_shr:1 row_mask:0xf bank_mask:0xf bound_ctrl:1
	v_add_f32_dpp v56, v56, v56 row_shr:2 row_mask:0xf bank_mask:0xf bound_ctrl:1
	v_add_f32_dpp v57, v57, v57 row_shr:2 row_mask:0xf bank_mask:0xf bound_ctrl:1
	v_add_f32_dpp v58, v58, v58 row_shr:2 row_mask:0xf bank_mask:0xf bound_ctrl:1
	v_add_f32_dpp v59, v59, v59 row_shr:2 row_mask:0xf bank_mask:0xf bound_ctrl:1
	v_add_f32_dpp v60, v60, v60 row_shr:2 row_mask:0xf bank_mask:0xf bound_ctrl:1
	v_add_f32_dpp v61, v61, v61 row_shr:2 row_mask:0xf bank_mask:0xf bound_ctrl:1
	v_add_f32_dpp v62, v62, v62 row_shr:2 row_mask:0xf bank_mask:0xf bound_ctrl:1
	v_add_f32_dpp v63, v63, v63 row_shr:2 row_mask:0xf bank_mask:0xf bound_ctrl:1
	v_add_f32_dpp v56, v56, v56 row_shr:4 row_mask:0xf bank_mask:0xf bound_ctrl:1
	v_add_f32_dpp v57, v57, v57 row_shr:4 row_mask:0xf bank_mask:0xf bound_ctrl:1
	v_add_f32_dpp v58, v58, v58 row_shr:4 row_mask:0xf bank_mask:0xf bound_ctrl:1
	v_add_f32_dpp v59, v59, v59 row_shr:4 row_mask:0xf bank_mask:0xf bound_ctrl:1
	v_add_f32_dpp v60, v60, v60 row_shr:4 row_mask:0xf bank_mask:0xf bound_ctrl:1
	v_add_f32_dpp v61, v61, v61 row_shr:4 row_mask:0xf bank_mask:0xf bound_ctrl:1
	v_add_f32_dpp v62, v62, v62 row_shr:4 row_mask:0xf bank_mask:0xf bound_ctrl:1
	v_add_f32_dpp v63, v63, v63 row_shr:4 row_mask:0xf bank_mask:0xf bound_ctrl:1
	v_add_f32_dpp v56, v56, v56 row_shr:8 row_mask:0xf bank_mask:0xf bound_ctrl:1
	v_add_f32_dpp v57, v57, v57 row_shr:8 row_mask:0xf bank_mask:0xf bound_ctrl:1
	v_add_f32_dpp v58, v58, v58 row_shr:8 row_mask:0xf bank_mask:0xf bound_ctrl:1
	v_add_f32_dpp v59, v59, v59 row_shr:8 row_mask:0xf bank_mask:0xf bound_ctrl:1
	v_add_f32_dpp v60, v60, v60 row_shr:8 row_mask:0xf bank_mask:0xf bound_ctrl:1
	v_add_f32_dpp v61, v61, v61 row_shr:8 row_mask:0xf bank_mask:0xf bound_ctrl:1
	v_add_f32_dpp v62, v62, v62 row_shr:8 row_mask:0xf bank_mask:0xf bound_ctrl:1
	v_add_f32_dpp v63, v63, v63 row_shr:8 row_mask:0xf bank_mask:0xf bound_ctrl:1
	v_mov_b32_dpp v88, v56 row_newbcast:15 row_mask:0xf bank_mask:0xf
	v_mov_b32_dpp v89, v57 row_newbcast:15 row_mask:0xf bank_mask:0xf
	v_mov_b32_dpp v90, v58 row_newbcast:15 row_mask:0xf bank_mask:0xf
	v_mov_b32_dpp v91, v59 row_newbcast:15 row_mask:0xf bank_mask:0xf
	v_mov_b32_dpp v92, v60 row_newbcast:15 row_mask:0xf bank_mask:0xf
	v_mov_b32_dpp v93, v61 row_newbcast:15 row_mask:0xf bank_mask:0xf
	v_mov_b32_dpp v94, v62 row_newbcast:15 row_mask:0xf bank_mask:0xf
	v_mov_b32_dpp v95, v63 row_newbcast:15 row_mask:0xf bank_mask:0xf
	v_add_f32_e32 v56, v56, v170
	v_add_f32_e32 v60, v60, v171
	v_add_f32_e32 v57, v57, v172
	v_add_f32_e32 v61, v61, v173
	v_add_f32_e32 v58, v58, v174
	v_add_f32_e32 v62, v62, v175
	v_add_f32_e32 v59, v59, v176
	v_add_f32_e32 v63, v63, v177
	v_mul_f32_e32 v132, v56, v141
	v_mul_f32_e32 v56, v56, v140
	v_fma_f32 v56, -v60, v141, v56
	v_fma_f32 v60, v60, v140, v132
	v_mul_f32_e32 v133, v57, v145
	v_mul_f32_e32 v57, v57, v144
	v_fma_f32 v57, -v61, v145, v57
	v_fma_f32 v61, v61, v144, v133
	v_mul_f32_e32 v132, v58, v149
	v_mul_f32_e32 v58, v58, v148
	v_fma_f32 v58, -v62, v149, v58
	v_fma_f32 v62, v62, v148, v132
	v_mul_f32_e32 v133, v59, v153
	v_mul_f32_e32 v59, v59, v152
	v_fma_f32 v59, -v63, v153, v59
	v_fma_f32 v63, v63, v152, v133
	v_add_f32_e32 v88, v88, v170
	v_add_f32_e32 v92, v92, v171
	v_mul_f32_e32 v132, v92, v155
	v_mul_f32_e32 v171, v88, v155
	v_fma_f32 v170, v88, v154, -v132
	v_fma_f32 v171, v92, v154, v171
	v_add_f32_e32 v89, v89, v172
	v_add_f32_e32 v93, v93, v173
	v_mul_f32_e32 v133, v93, v159
	v_mul_f32_e32 v173, v89, v159
	v_fma_f32 v172, v89, v158, -v133
	v_fma_f32 v173, v93, v158, v173
	v_add_f32_e32 v90, v90, v174
	v_add_f32_e32 v94, v94, v175
	v_mul_f32_e32 v132, v94, v163
	v_mul_f32_e32 v175, v90, v163
	v_fma_f32 v174, v90, v162, -v132
	v_fma_f32 v175, v94, v162, v175
	v_add_f32_e32 v91, v91, v176
	v_add_f32_e32 v95, v95, v177
	v_mul_f32_e32 v133, v95, v167
	v_mul_f32_e32 v177, v91, v167
	v_fma_f32 v176, v91, v166, -v133
	v_fma_f32 v177, v95, v166, v177
	s_waitcnt vmcnt(12)
	v_cvt_pk_bf16_f32 v96, v32, v33
	v_cvt_pk_bf16_f32 v97, v34, v35
	v_cvt_pk_bf16_f32 v98, v36, v37
	v_cvt_pk_bf16_f32 v99, v38, v39
	s_nop 1
	v_mfma_f32_16x16x32_bf16 v[16:19], v[80:83], v[96:99], v[16:19]
	v_cvt_pk_bf16_f32 v96, v40, v41
	v_cvt_pk_bf16_f32 v97, v42, v43
	v_cvt_pk_bf16_f32 v98, v44, v45
	v_cvt_pk_bf16_f32 v99, v46, v47
	s_nop 1
	v_mfma_f32_16x16x32_bf16 v[20:23], v[80:83], v[96:99], v[20:23]
	v_cvt_pk_bf16_f32 v96, v48, v49
	v_cvt_pk_bf16_f32 v97, v50, v51
	v_cvt_pk_bf16_f32 v98, v52, v53
	v_cvt_pk_bf16_f32 v99, v54, v55
	s_nop 1
	v_mfma_f32_16x16x32_bf16 v[24:27], v[80:83], v[96:99], v[24:27]
	v_cvt_pk_bf16_f32 v96, v56, v57
	v_cvt_pk_bf16_f32 v97, v58, v59
	v_cvt_pk_bf16_f32 v98, v60, v61
	v_cvt_pk_bf16_f32 v99, v62, v63
	s_nop 1
	v_mfma_f32_16x16x32_bf16 v[28:31], v[80:83], v[96:99], v[28:31]
	s_waitcnt vmcnt(10)
	global_load_dwordx4 v[80:83], v134, s[38:39]
	v_mfma_f32_16x16x32_bf16 v[32:35], v[64:67], v[0:3], 0
	v_mfma_f32_16x16x32_bf16 v[36:39], v[72:75], v[0:3], 0
	v_mfma_f32_16x16x32_bf16 v[40:43], v[64:67], v[4:7], 0
	v_mfma_f32_16x16x32_bf16 v[44:47], v[72:75], v[4:7], 0
	v_mfma_f32_16x16x32_bf16 v[48:51], v[64:67], v[8:11], 0
	v_mfma_f32_16x16x32_bf16 v[52:55], v[72:75], v[8:11], 0
	v_mfma_f32_16x16x32_bf16 v[56:59], v[64:67], v[12:15], 0
	v_mfma_f32_16x16x32_bf16 v[60:63], v[72:75], v[12:15], 0
	v_readlane_b32 s10, v247, 28
	s_sub_i32 s11, 3, s8
	s_sub_i32 s17, 71, s8
	s_cmp_lt_u32 s8, 4
	s_cselect_b32 s11, s11, s17
	s_lshl_b32 s16, s10, 1
	s_add_i32 s16, s16, 1
	s_lshl_b32 s16, s16, 4
	s_add_i32 s16, s16, s7
	s_lshl_b32 s17, s6, 1
	s_add_i32 s17, s17, 1
	s_lshl_b32 s17, s17, 4
	s_add_i32 s17, s17, s7
	s_mul_i32 s17, s17, 68
	s_add_i32 s17, s17, s11
	s_lshl_b32 s17, s17, 6
	s_lshl_b32 s20, s16, 13
	s_add_u32 s20, s20, 0xfd00000
	s_add_u32 s20, s4, s20
	s_addc_u32 s21, s5, 0
	s_lshl_b32 s38, s16, 12
	s_add_u32 s38, s38, 0xfd80000
	s_add_u32 s38, s4, s38
	s_addc_u32 s39, s5, 0
	s_lshl_b32 s42, s16, 15
	s_add_u32 s42, s42, 0xf900000
	s_add_u32 s42, s4, s42
	s_addc_u32 s43, s5, 0
	s_lshl_b32 s44, s17, 3
	s_add_u32 s44, s44, 0x740000
	s_add_u32 s44, s4, s44
	s_addc_u32 s45, s5, 0
	global_load_dwordx4 v[64:67], v134, s[20:21]
	global_load_dwordx4 v[72:75], v134, s[20:21] offset:1024
	s_add_u32 s20, s20, 0x800
	s_addc_u32 s21, s21, 0
	global_load_dwordx4 v[138:141], v134, s[42:43] offset:0
	global_load_dwordx4 v[142:145], v134, s[42:43] offset:1024
	global_load_dwordx4 v[146:149], v134, s[42:43] offset:2048
	global_load_dwordx4 v[150:153], v134, s[42:43] offset:3072
	global_load_dwordx4 v[154:157], v208, s[42:43] offset:0
	global_load_dwordx4 v[158:161], v208, s[42:43] offset:1024
	global_load_dwordx4 v[162:165], v208, s[42:43] offset:2048
	global_load_dwordx4 v[166:169], v208, s[42:43] offset:3072
	global_load_dwordx4 v[170:173], v206, s[44:45]
	global_load_dwordx4 v[174:177], v206, s[44:45] offset:16
	s_add_u32 s42, s42, 0x2000
	s_addc_u32 s43, s43, 0
	s_add_u32 s44, s44, 0x80
	s_addc_u32 s45, s45, 0
	s_waitcnt vmcnt(13)
	v_mul_f32_e32 v132, v179, v119
	v_mul_f32_e32 v133, v178, v119
	v_fma_f32 v178, v178, v118, -v132
	v_fma_f32 v179, v179, v118, v133
	v_mul_f32_e32 v132, v181, v123
	v_mul_f32_e32 v133, v180, v123
	v_fma_f32 v180, v180, v122, -v132
	v_fma_f32 v181, v181, v122, v133
	v_mul_f32_e32 v132, v183, v127
	v_mul_f32_e32 v133, v182, v127
	v_fma_f32 v182, v182, v126, -v132
	v_fma_f32 v183, v183, v126, v133
	v_mul_f32_e32 v132, v185, v131
	v_mul_f32_e32 v133, v184, v131
	v_fma_f32 v184, v184, v130, -v132
	v_fma_f32 v185, v185, v130, v133
	v_mul_f32_e32 v132, v32, v101
	v_mul_f32_e32 v32, v32, v100
	v_fma_f32 v32, -v36, v101, v32
	v_fma_f32 v36, v36, v100, v132
	v_mul_f32_e32 v133, v33, v105
	v_mul_f32_e32 v33, v33, v104
	v_fma_f32 v33, -v37, v105, v33
	v_fma_f32 v37, v37, v104, v133
	v_mul_f32_e32 v132, v34, v109
	v_mul_f32_e32 v34, v34, v108
	v_fma_f32 v34, -v38, v109, v34
	v_fma_f32 v38, v38, v108, v132
	v_mul_f32_e32 v133, v35, v113
	v_mul_f32_e32 v35, v35, v112
	v_fma_f32 v35, -v39, v113, v35
	v_fma_f32 v39, v39, v112, v133
	v_add_f32_dpp v32, v32, v32 row_shr:1 row_mask:0xf bank_mask:0xf bound_ctrl:1
	v_add_f32_dpp v33, v33, v33 row_shr:1 row_mask:0xf bank_mask:0xf bound_ctrl:1
	v_add_f32_dpp v34, v34, v34 row_shr:1 row_mask:0xf bank_mask:0xf bound_ctrl:1
	v_add_f32_dpp v35, v35, v35 row_shr:1 row_mask:0xf bank_mask:0xf bound_ctrl:1
	v_add_f32_dpp v36, v36, v36 row_shr:1 row_mask:0xf bank_mask:0xf bound_ctrl:1
	v_add_f32_dpp v37, v37, v37 row_shr:1 row_mask:0xf bank_mask:0xf bound_ctrl:1
	v_add_f32_dpp v38, v38, v38 row_shr:1 row_mask:0xf bank_mask:0xf bound_ctrl:1
	v_add_f32_dpp v39, v39, v39 row_shr:1 row_mask:0xf bank_mask:0xf bound_ctrl:1
	v_add_f32_dpp v32, v32, v32 row_shr:2 row_mask:0xf bank_mask:0xf bound_ctrl:1
	v_add_f32_dpp v33, v33, v33 row_shr:2 row_mask:0xf bank_mask:0xf bound_ctrl:1
	v_add_f32_dpp v34, v34, v34 row_shr:2 row_mask:0xf bank_mask:0xf bound_ctrl:1
	v_add_f32_dpp v35, v35, v35 row_shr:2 row_mask:0xf bank_mask:0xf bound_ctrl:1
	v_add_f32_dpp v36, v36, v36 row_shr:2 row_mask:0xf bank_mask:0xf bound_ctrl:1
	v_add_f32_dpp v37, v37, v37 row_shr:2 row_mask:0xf bank_mask:0xf bound_ctrl:1
	v_add_f32_dpp v38, v38, v38 row_shr:2 row_mask:0xf bank_mask:0xf bound_ctrl:1
	v_add_f32_dpp v39, v39, v39 row_shr:2 row_mask:0xf bank_mask:0xf bound_ctrl:1
	v_add_f32_dpp v32, v32, v32 row_shr:4 row_mask:0xf bank_mask:0xf bound_ctrl:1
	v_add_f32_dpp v33, v33, v33 row_shr:4 row_mask:0xf bank_mask:0xf bound_ctrl:1
	v_add_f32_dpp v34, v34, v34 row_shr:4 row_mask:0xf bank_mask:0xf bound_ctrl:1
	v_add_f32_dpp v35, v35, v35 row_shr:4 row_mask:0xf bank_mask:0xf bound_ctrl:1
	v_add_f32_dpp v36, v36, v36 row_shr:4 row_mask:0xf bank_mask:0xf bound_ctrl:1
	v_add_f32_dpp v37, v37, v37 row_shr:4 row_mask:0xf bank_mask:0xf bound_ctrl:1
	v_add_f32_dpp v38, v38, v38 row_shr:4 row_mask:0xf bank_mask:0xf bound_ctrl:1
	v_add_f32_dpp v39, v39, v39 row_shr:4 row_mask:0xf bank_mask:0xf bound_ctrl:1
	v_add_f32_dpp v32, v32, v32 row_shr:8 row_mask:0xf bank_mask:0xf bound_ctrl:1
	v_add_f32_dpp v33, v33, v33 row_shr:8 row_mask:0xf bank_mask:0xf bound_ctrl:1
	v_add_f32_dpp v34, v34, v34 row_shr:8 row_mask:0xf bank_mask:0xf bound_ctrl:1
	v_add_f32_dpp v35, v35, v35 row_shr:8 row_mask:0xf bank_mask:0xf bound_ctrl:1
	v_add_f32_dpp v36, v36, v36 row_shr:8 row_mask:0xf bank_mask:0xf bound_ctrl:1
	v_add_f32_dpp v37, v37, v37 row_shr:8 row_mask:0xf bank_mask:0xf bound_ctrl:1
	v_add_f32_dpp v38, v38, v38 row_shr:8 row_mask:0xf bank_mask:0xf bound_ctrl:1
	v_add_f32_dpp v39, v39, v39 row_shr:8 row_mask:0xf bank_mask:0xf bound_ctrl:1
	v_mov_b32_dpp v88, v32 row_newbcast:15 row_mask:0xf bank_mask:0xf
	v_mov_b32_dpp v89, v33 row_newbcast:15 row_mask:0xf bank_mask:0xf
	v_mov_b32_dpp v90, v34 row_newbcast:15 row_mask:0xf bank_mask:0xf
	v_mov_b32_dpp v91, v35 row_newbcast:15 row_mask:0xf bank_mask:0xf
	v_mov_b32_dpp v92, v36 row_newbcast:15 row_mask:0xf bank_mask:0xf
	v_mov_b32_dpp v93, v37 row_newbcast:15 row_mask:0xf bank_mask:0xf
	v_mov_b32_dpp v94, v38 row_newbcast:15 row_mask:0xf bank_mask:0xf
	v_mov_b32_dpp v95, v39 row_newbcast:15 row_mask:0xf bank_mask:0xf
	v_add_f32_e32 v32, v32, v178
	v_add_f32_e32 v36, v36, v179
	v_add_f32_e32 v33, v33, v180
	v_add_f32_e32 v37, v37, v181
	v_add_f32_e32 v34, v34, v182
	v_add_f32_e32 v38, v38, v183
	v_add_f32_e32 v35, v35, v184
	v_add_f32_e32 v39, v39, v185
	v_mul_f32_e32 v132, v32, v103
	v_mul_f32_e32 v32, v32, v102
	v_fma_f32 v32, -v36, v103, v32
	v_fma_f32 v36, v36, v102, v132
	v_mul_f32_e32 v133, v33, v107
	v_mul_f32_e32 v33, v33, v106
	v_fma_f32 v33, -v37, v107, v33
	v_fma_f32 v37, v37, v106, v133
	v_mul_f32_e32 v132, v34, v111
	v_mul_f32_e32 v34, v34, v110
	v_fma_f32 v34, -v38, v111, v34
	v_fma_f32 v38, v38, v110, v132
	v_mul_f32_e32 v133, v35, v115
	v_mul_f32_e32 v35, v35, v114
	v_fma_f32 v35, -v39, v115, v35
	v_fma_f32 v39, v39, v114, v133
	v_add_f32_e32 v88, v88, v178
	v_add_f32_e32 v92, v92, v179
	v_mul_f32_e32 v132, v92, v117
	v_mul_f32_e32 v179, v88, v117
	v_fma_f32 v178, v88, v116, -v132
	v_fma_f32 v179, v92, v116, v179
	v_add_f32_e32 v89, v89, v180
	v_add_f32_e32 v93, v93, v181
	v_mul_f32_e32 v133, v93, v121
	v_mul_f32_e32 v181, v89, v121
	v_fma_f32 v180, v89, v120, -v133
	v_fma_f32 v181, v93, v120, v181
	v_add_f32_e32 v90, v90, v182
	v_add_f32_e32 v94, v94, v183
	v_mul_f32_e32 v132, v94, v125
	v_mul_f32_e32 v183, v90, v125
	v_fma_f32 v182, v90, v124, -v132
	v_fma_f32 v183, v94, v124, v183
	v_add_f32_e32 v91, v91, v184
	v_add_f32_e32 v95, v95, v185
	v_mul_f32_e32 v133, v95, v129
	v_mul_f32_e32 v185, v91, v129
	v_fma_f32 v184, v91, v128, -v133
	v_fma_f32 v185, v95, v128, v185
	v_mul_f32_e32 v132, v40, v101
	v_mul_f32_e32 v40, v40, v100
	v_fma_f32 v40, -v44, v101, v40
	v_fma_f32 v44, v44, v100, v132
	v_mul_f32_e32 v133, v41, v105
	v_mul_f32_e32 v41, v41, v104
	v_fma_f32 v41, -v45, v105, v41
	v_fma_f32 v45, v45, v104, v133
	v_mul_f32_e32 v132, v42, v109
	v_mul_f32_e32 v42, v42, v108
	v_fma_f32 v42, -v46, v109, v42
	v_fma_f32 v46, v46, v108, v132
	v_mul_f32_e32 v133, v43, v113
	v_mul_f32_e32 v43, v43, v112
	v_fma_f32 v43, -v47, v113, v43
	v_fma_f32 v47, v47, v112, v133
	v_add_f32_dpp v40, v40, v40 row_shr:1 row_mask:0xf bank_mask:0xf bound_ctrl:1
	v_add_f32_dpp v41, v41, v41 row_shr:1 row_mask:0xf bank_mask:0xf bound_ctrl:1
	v_add_f32_dpp v42, v42, v42 row_shr:1 row_mask:0xf bank_mask:0xf bound_ctrl:1
	v_add_f32_dpp v43, v43, v43 row_shr:1 row_mask:0xf bank_mask:0xf bound_ctrl:1
	v_add_f32_dpp v44, v44, v44 row_shr:1 row_mask:0xf bank_mask:0xf bound_ctrl:1
	v_add_f32_dpp v45, v45, v45 row_shr:1 row_mask:0xf bank_mask:0xf bound_ctrl:1
	v_add_f32_dpp v46, v46, v46 row_shr:1 row_mask:0xf bank_mask:0xf bound_ctrl:1
	v_add_f32_dpp v47, v47, v47 row_shr:1 row_mask:0xf bank_mask:0xf bound_ctrl:1
	v_add_f32_dpp v40, v40, v40 row_shr:2 row_mask:0xf bank_mask:0xf bound_ctrl:1
	v_add_f32_dpp v41, v41, v41 row_shr:2 row_mask:0xf bank_mask:0xf bound_ctrl:1
	v_add_f32_dpp v42, v42, v42 row_shr:2 row_mask:0xf bank_mask:0xf bound_ctrl:1
	v_add_f32_dpp v43, v43, v43 row_shr:2 row_mask:0xf bank_mask:0xf bound_ctrl:1
	v_add_f32_dpp v44, v44, v44 row_shr:2 row_mask:0xf bank_mask:0xf bound_ctrl:1
	v_add_f32_dpp v45, v45, v45 row_shr:2 row_mask:0xf bank_mask:0xf bound_ctrl:1
	v_add_f32_dpp v46, v46, v46 row_shr:2 row_mask:0xf bank_mask:0xf bound_ctrl:1
	v_add_f32_dpp v47, v47, v47 row_shr:2 row_mask:0xf bank_mask:0xf bound_ctrl:1
	v_add_f32_dpp v40, v40, v40 row_shr:4 row_mask:0xf bank_mask:0xf bound_ctrl:1
	v_add_f32_dpp v41, v41, v41 row_shr:4 row_mask:0xf bank_mask:0xf bound_ctrl:1
	v_add_f32_dpp v42, v42, v42 row_shr:4 row_mask:0xf bank_mask:0xf bound_ctrl:1
	v_add_f32_dpp v43, v43, v43 row_shr:4 row_mask:0xf bank_mask:0xf bound_ctrl:1
	v_add_f32_dpp v44, v44, v44 row_shr:4 row_mask:0xf bank_mask:0xf bound_ctrl:1
	v_add_f32_dpp v45, v45, v45 row_shr:4 row_mask:0xf bank_mask:0xf bound_ctrl:1
	v_add_f32_dpp v46, v46, v46 row_shr:4 row_mask:0xf bank_mask:0xf bound_ctrl:1
	v_add_f32_dpp v47, v47, v47 row_shr:4 row_mask:0xf bank_mask:0xf bound_ctrl:1
	v_add_f32_dpp v40, v40, v40 row_shr:8 row_mask:0xf bank_mask:0xf bound_ctrl:1
	v_add_f32_dpp v41, v41, v41 row_shr:8 row_mask:0xf bank_mask:0xf bound_ctrl:1
	v_add_f32_dpp v42, v42, v42 row_shr:8 row_mask:0xf bank_mask:0xf bound_ctrl:1
	v_add_f32_dpp v43, v43, v43 row_shr:8 row_mask:0xf bank_mask:0xf bound_ctrl:1
	v_add_f32_dpp v44, v44, v44 row_shr:8 row_mask:0xf bank_mask:0xf bound_ctrl:1
	v_add_f32_dpp v45, v45, v45 row_shr:8 row_mask:0xf bank_mask:0xf bound_ctrl:1
	v_add_f32_dpp v46, v46, v46 row_shr:8 row_mask:0xf bank_mask:0xf bound_ctrl:1
	v_add_f32_dpp v47, v47, v47 row_shr:8 row_mask:0xf bank_mask:0xf bound_ctrl:1
	v_mov_b32_dpp v88, v40 row_newbcast:15 row_mask:0xf bank_mask:0xf
	v_mov_b32_dpp v89, v41 row_newbcast:15 row_mask:0xf bank_mask:0xf
	v_mov_b32_dpp v90, v42 row_newbcast:15 row_mask:0xf bank_mask:0xf
	v_mov_b32_dpp v91, v43 row_newbcast:15 row_mask:0xf bank_mask:0xf
	v_mov_b32_dpp v92, v44 row_newbcast:15 row_mask:0xf bank_mask:0xf
	v_mov_b32_dpp v93, v45 row_newbcast:15 row_mask:0xf bank_mask:0xf
	v_mov_b32_dpp v94, v46 row_newbcast:15 row_mask:0xf bank_mask:0xf
	v_mov_b32_dpp v95, v47 row_newbcast:15 row_mask:0xf bank_mask:0xf
	v_add_f32_e32 v40, v40, v178
	v_add_f32_e32 v44, v44, v179
	v_add_f32_e32 v41, v41, v180
	v_add_f32_e32 v45, v45, v181
	v_add_f32_e32 v42, v42, v182
	v_add_f32_e32 v46, v46, v183
	v_add_f32_e32 v43, v43, v184
	v_add_f32_e32 v47, v47, v185
	v_mul_f32_e32 v132, v40, v103
	v_mul_f32_e32 v40, v40, v102
	v_fma_f32 v40, -v44, v103, v40
	v_fma_f32 v44, v44, v102, v132
	v_mul_f32_e32 v133, v41, v107
	v_mul_f32_e32 v41, v41, v106
	v_fma_f32 v41, -v45, v107, v41
	v_fma_f32 v45, v45, v106, v133
	v_mul_f32_e32 v132, v42, v111
	v_mul_f32_e32 v42, v42, v110
	v_fma_f32 v42, -v46, v111, v42
	v_fma_f32 v46, v46, v110, v132
	v_mul_f32_e32 v133, v43, v115
	v_mul_f32_e32 v43, v43, v114
	v_fma_f32 v43, -v47, v115, v43
	v_fma_f32 v47, v47, v114, v133
	v_add_f32_e32 v88, v88, v178
	v_add_f32_e32 v92, v92, v179
	v_mul_f32_e32 v132, v92, v117
	v_mul_f32_e32 v179, v88, v117
	v_fma_f32 v178, v88, v116, -v132
	v_fma_f32 v179, v92, v116, v179
	v_add_f32_e32 v89, v89, v180
	v_add_f32_e32 v93, v93, v181
	v_mul_f32_e32 v133, v93, v121
	v_mul_f32_e32 v181, v89, v121
	v_fma_f32 v180, v89, v120, -v133
	v_fma_f32 v181, v93, v120, v181
	v_add_f32_e32 v90, v90, v182
	v_add_f32_e32 v94, v94, v183
	v_mul_f32_e32 v132, v94, v125
	v_mul_f32_e32 v183, v90, v125
	v_fma_f32 v182, v90, v124, -v132
	v_fma_f32 v183, v94, v124, v183
	v_add_f32_e32 v91, v91, v184
	v_add_f32_e32 v95, v95, v185
	v_mul_f32_e32 v133, v95, v129
	v_mul_f32_e32 v185, v91, v129
	v_fma_f32 v184, v91, v128, -v133
	v_fma_f32 v185, v95, v128, v185
	v_mul_f32_e32 v132, v48, v101
	v_mul_f32_e32 v48, v48, v100
	v_fma_f32 v48, -v52, v101, v48
	v_fma_f32 v52, v52, v100, v132
	v_mul_f32_e32 v133, v49, v105
	v_mul_f32_e32 v49, v49, v104
	v_fma_f32 v49, -v53, v105, v49
	v_fma_f32 v53, v53, v104, v133
	v_mul_f32_e32 v132, v50, v109
	v_mul_f32_e32 v50, v50, v108
	v_fma_f32 v50, -v54, v109, v50
	v_fma_f32 v54, v54, v108, v132
	v_mul_f32_e32 v133, v51, v113
	v_mul_f32_e32 v51, v51, v112
	v_fma_f32 v51, -v55, v113, v51
	v_fma_f32 v55, v55, v112, v133
	v_add_f32_dpp v48, v48, v48 row_shr:1 row_mask:0xf bank_mask:0xf bound_ctrl:1
	v_add_f32_dpp v49, v49, v49 row_shr:1 row_mask:0xf bank_mask:0xf bound_ctrl:1
	v_add_f32_dpp v50, v50, v50 row_shr:1 row_mask:0xf bank_mask:0xf bound_ctrl:1
	v_add_f32_dpp v51, v51, v51 row_shr:1 row_mask:0xf bank_mask:0xf bound_ctrl:1
	v_add_f32_dpp v52, v52, v52 row_shr:1 row_mask:0xf bank_mask:0xf bound_ctrl:1
	v_add_f32_dpp v53, v53, v53 row_shr:1 row_mask:0xf bank_mask:0xf bound_ctrl:1
	v_add_f32_dpp v54, v54, v54 row_shr:1 row_mask:0xf bank_mask:0xf bound_ctrl:1
	v_add_f32_dpp v55, v55, v55 row_shr:1 row_mask:0xf bank_mask:0xf bound_ctrl:1
	v_add_f32_dpp v48, v48, v48 row_shr:2 row_mask:0xf bank_mask:0xf bound_ctrl:1
	v_add_f32_dpp v49, v49, v49 row_shr:2 row_mask:0xf bank_mask:0xf bound_ctrl:1
	v_add_f32_dpp v50, v50, v50 row_shr:2 row_mask:0xf bank_mask:0xf bound_ctrl:1
	v_add_f32_dpp v51, v51, v51 row_shr:2 row_mask:0xf bank_mask:0xf bound_ctrl:1
	v_add_f32_dpp v52, v52, v52 row_shr:2 row_mask:0xf bank_mask:0xf bound_ctrl:1
	v_add_f32_dpp v53, v53, v53 row_shr:2 row_mask:0xf bank_mask:0xf bound_ctrl:1
	v_add_f32_dpp v54, v54, v54 row_shr:2 row_mask:0xf bank_mask:0xf bound_ctrl:1
	v_add_f32_dpp v55, v55, v55 row_shr:2 row_mask:0xf bank_mask:0xf bound_ctrl:1
	v_add_f32_dpp v48, v48, v48 row_shr:4 row_mask:0xf bank_mask:0xf bound_ctrl:1
	v_add_f32_dpp v49, v49, v49 row_shr:4 row_mask:0xf bank_mask:0xf bound_ctrl:1
	v_add_f32_dpp v50, v50, v50 row_shr:4 row_mask:0xf bank_mask:0xf bound_ctrl:1
	v_add_f32_dpp v51, v51, v51 row_shr:4 row_mask:0xf bank_mask:0xf bound_ctrl:1
	v_add_f32_dpp v52, v52, v52 row_shr:4 row_mask:0xf bank_mask:0xf bound_ctrl:1
	v_add_f32_dpp v53, v53, v53 row_shr:4 row_mask:0xf bank_mask:0xf bound_ctrl:1
	v_add_f32_dpp v54, v54, v54 row_shr:4 row_mask:0xf bank_mask:0xf bound_ctrl:1
	v_add_f32_dpp v55, v55, v55 row_shr:4 row_mask:0xf bank_mask:0xf bound_ctrl:1
	v_add_f32_dpp v48, v48, v48 row_shr:8 row_mask:0xf bank_mask:0xf bound_ctrl:1
	v_add_f32_dpp v49, v49, v49 row_shr:8 row_mask:0xf bank_mask:0xf bound_ctrl:1
	v_add_f32_dpp v50, v50, v50 row_shr:8 row_mask:0xf bank_mask:0xf bound_ctrl:1
	v_add_f32_dpp v51, v51, v51 row_shr:8 row_mask:0xf bank_mask:0xf bound_ctrl:1
	v_add_f32_dpp v52, v52, v52 row_shr:8 row_mask:0xf bank_mask:0xf bound_ctrl:1
	v_add_f32_dpp v53, v53, v53 row_shr:8 row_mask:0xf bank_mask:0xf bound_ctrl:1
	v_add_f32_dpp v54, v54, v54 row_shr:8 row_mask:0xf bank_mask:0xf bound_ctrl:1
	v_add_f32_dpp v55, v55, v55 row_shr:8 row_mask:0xf bank_mask:0xf bound_ctrl:1
	v_mov_b32_dpp v88, v48 row_newbcast:15 row_mask:0xf bank_mask:0xf
	v_mov_b32_dpp v89, v49 row_newbcast:15 row_mask:0xf bank_mask:0xf
	v_mov_b32_dpp v90, v50 row_newbcast:15 row_mask:0xf bank_mask:0xf
	v_mov_b32_dpp v91, v51 row_newbcast:15 row_mask:0xf bank_mask:0xf
	v_mov_b32_dpp v92, v52 row_newbcast:15 row_mask:0xf bank_mask:0xf
	v_mov_b32_dpp v93, v53 row_newbcast:15 row_mask:0xf bank_mask:0xf
	v_mov_b32_dpp v94, v54 row_newbcast:15 row_mask:0xf bank_mask:0xf
	v_mov_b32_dpp v95, v55 row_newbcast:15 row_mask:0xf bank_mask:0xf
	v_add_f32_e32 v48, v48, v178
	v_add_f32_e32 v52, v52, v179
	v_add_f32_e32 v49, v49, v180
	v_add_f32_e32 v53, v53, v181
	v_add_f32_e32 v50, v50, v182
	v_add_f32_e32 v54, v54, v183
	v_add_f32_e32 v51, v51, v184
	v_add_f32_e32 v55, v55, v185
	v_mul_f32_e32 v132, v48, v103
	v_mul_f32_e32 v48, v48, v102
	v_fma_f32 v48, -v52, v103, v48
	v_fma_f32 v52, v52, v102, v132
	v_mul_f32_e32 v133, v49, v107
	v_mul_f32_e32 v49, v49, v106
	v_fma_f32 v49, -v53, v107, v49
	v_fma_f32 v53, v53, v106, v133
	v_mul_f32_e32 v132, v50, v111
	v_mul_f32_e32 v50, v50, v110
	v_fma_f32 v50, -v54, v111, v50
	v_fma_f32 v54, v54, v110, v132
	v_mul_f32_e32 v133, v51, v115
	v_mul_f32_e32 v51, v51, v114
	v_fma_f32 v51, -v55, v115, v51
	v_fma_f32 v55, v55, v114, v133
	v_add_f32_e32 v88, v88, v178
	v_add_f32_e32 v92, v92, v179
	v_mul_f32_e32 v132, v92, v117
	v_mul_f32_e32 v179, v88, v117
	v_fma_f32 v178, v88, v116, -v132
	v_fma_f32 v179, v92, v116, v179
	v_add_f32_e32 v89, v89, v180
	v_add_f32_e32 v93, v93, v181
	v_mul_f32_e32 v133, v93, v121
	v_mul_f32_e32 v181, v89, v121
	v_fma_f32 v180, v89, v120, -v133
	v_fma_f32 v181, v93, v120, v181
	v_add_f32_e32 v90, v90, v182
	v_add_f32_e32 v94, v94, v183
	v_mul_f32_e32 v132, v94, v125
	v_mul_f32_e32 v183, v90, v125
	v_fma_f32 v182, v90, v124, -v132
	v_fma_f32 v183, v94, v124, v183
	v_add_f32_e32 v91, v91, v184
	v_add_f32_e32 v95, v95, v185
	v_mul_f32_e32 v133, v95, v129
	v_mul_f32_e32 v185, v91, v129
	v_fma_f32 v184, v91, v128, -v133
	v_fma_f32 v185, v95, v128, v185
	v_mul_f32_e32 v132, v56, v101
	v_mul_f32_e32 v56, v56, v100
	v_fma_f32 v56, -v60, v101, v56
	v_fma_f32 v60, v60, v100, v132
	v_mul_f32_e32 v133, v57, v105
	v_mul_f32_e32 v57, v57, v104
	v_fma_f32 v57, -v61, v105, v57
	v_fma_f32 v61, v61, v104, v133
	v_mul_f32_e32 v132, v58, v109
	v_mul_f32_e32 v58, v58, v108
	v_fma_f32 v58, -v62, v109, v58
	v_fma_f32 v62, v62, v108, v132
	v_mul_f32_e32 v133, v59, v113
	v_mul_f32_e32 v59, v59, v112
	v_fma_f32 v59, -v63, v113, v59
	v_fma_f32 v63, v63, v112, v133
	v_add_f32_dpp v56, v56, v56 row_shr:1 row_mask:0xf bank_mask:0xf bound_ctrl:1
	v_add_f32_dpp v57, v57, v57 row_shr:1 row_mask:0xf bank_mask:0xf bound_ctrl:1
	v_add_f32_dpp v58, v58, v58 row_shr:1 row_mask:0xf bank_mask:0xf bound_ctrl:1
	v_add_f32_dpp v59, v59, v59 row_shr:1 row_mask:0xf bank_mask:0xf bound_ctrl:1
	v_add_f32_dpp v60, v60, v60 row_shr:1 row_mask:0xf bank_mask:0xf bound_ctrl:1
	v_add_f32_dpp v61, v61, v61 row_shr:1 row_mask:0xf bank_mask:0xf bound_ctrl:1
	v_add_f32_dpp v62, v62, v62 row_shr:1 row_mask:0xf bank_mask:0xf bound_ctrl:1
	v_add_f32_dpp v63, v63, v63 row_shr:1 row_mask:0xf bank_mask:0xf bound_ctrl:1
	v_add_f32_dpp v56, v56, v56 row_shr:2 row_mask:0xf bank_mask:0xf bound_ctrl:1
	v_add_f32_dpp v57, v57, v57 row_shr:2 row_mask:0xf bank_mask:0xf bound_ctrl:1
	v_add_f32_dpp v58, v58, v58 row_shr:2 row_mask:0xf bank_mask:0xf bound_ctrl:1
	v_add_f32_dpp v59, v59, v59 row_shr:2 row_mask:0xf bank_mask:0xf bound_ctrl:1
	v_add_f32_dpp v60, v60, v60 row_shr:2 row_mask:0xf bank_mask:0xf bound_ctrl:1
	v_add_f32_dpp v61, v61, v61 row_shr:2 row_mask:0xf bank_mask:0xf bound_ctrl:1
	v_add_f32_dpp v62, v62, v62 row_shr:2 row_mask:0xf bank_mask:0xf bound_ctrl:1
	v_add_f32_dpp v63, v63, v63 row_shr:2 row_mask:0xf bank_mask:0xf bound_ctrl:1
	v_add_f32_dpp v56, v56, v56 row_shr:4 row_mask:0xf bank_mask:0xf bound_ctrl:1
	v_add_f32_dpp v57, v57, v57 row_shr:4 row_mask:0xf bank_mask:0xf bound_ctrl:1
	v_add_f32_dpp v58, v58, v58 row_shr:4 row_mask:0xf bank_mask:0xf bound_ctrl:1
	v_add_f32_dpp v59, v59, v59 row_shr:4 row_mask:0xf bank_mask:0xf bound_ctrl:1
	v_add_f32_dpp v60, v60, v60 row_shr:4 row_mask:0xf bank_mask:0xf bound_ctrl:1
	v_add_f32_dpp v61, v61, v61 row_shr:4 row_mask:0xf bank_mask:0xf bound_ctrl:1
	v_add_f32_dpp v62, v62, v62 row_shr:4 row_mask:0xf bank_mask:0xf bound_ctrl:1
	v_add_f32_dpp v63, v63, v63 row_shr:4 row_mask:0xf bank_mask:0xf bound_ctrl:1
	v_add_f32_dpp v56, v56, v56 row_shr:8 row_mask:0xf bank_mask:0xf bound_ctrl:1
	v_add_f32_dpp v57, v57, v57 row_shr:8 row_mask:0xf bank_mask:0xf bound_ctrl:1
	v_add_f32_dpp v58, v58, v58 row_shr:8 row_mask:0xf bank_mask:0xf bound_ctrl:1
	v_add_f32_dpp v59, v59, v59 row_shr:8 row_mask:0xf bank_mask:0xf bound_ctrl:1
	v_add_f32_dpp v60, v60, v60 row_shr:8 row_mask:0xf bank_mask:0xf bound_ctrl:1
	v_add_f32_dpp v61, v61, v61 row_shr:8 row_mask:0xf bank_mask:0xf bound_ctrl:1
	v_add_f32_dpp v62, v62, v62 row_shr:8 row_mask:0xf bank_mask:0xf bound_ctrl:1
	v_add_f32_dpp v63, v63, v63 row_shr:8 row_mask:0xf bank_mask:0xf bound_ctrl:1
	v_mov_b32_dpp v88, v56 row_newbcast:15 row_mask:0xf bank_mask:0xf
	v_mov_b32_dpp v89, v57 row_newbcast:15 row_mask:0xf bank_mask:0xf
	v_mov_b32_dpp v90, v58 row_newbcast:15 row_mask:0xf bank_mask:0xf
	v_mov_b32_dpp v91, v59 row_newbcast:15 row_mask:0xf bank_mask:0xf
	v_mov_b32_dpp v92, v60 row_newbcast:15 row_mask:0xf bank_mask:0xf
	v_mov_b32_dpp v93, v61 row_newbcast:15 row_mask:0xf bank_mask:0xf
	v_mov_b32_dpp v94, v62 row_newbcast:15 row_mask:0xf bank_mask:0xf
	v_mov_b32_dpp v95, v63 row_newbcast:15 row_mask:0xf bank_mask:0xf
	v_add_f32_e32 v56, v56, v178
	v_add_f32_e32 v60, v60, v179
	v_add_f32_e32 v57, v57, v180
	v_add_f32_e32 v61, v61, v181
	v_add_f32_e32 v58, v58, v182
	v_add_f32_e32 v62, v62, v183
	v_add_f32_e32 v59, v59, v184
	v_add_f32_e32 v63, v63, v185
	v_mul_f32_e32 v132, v56, v103
	v_mul_f32_e32 v56, v56, v102
	v_fma_f32 v56, -v60, v103, v56
	v_fma_f32 v60, v60, v102, v132
	v_mul_f32_e32 v133, v57, v107
	v_mul_f32_e32 v57, v57, v106
	v_fma_f32 v57, -v61, v107, v57
	v_fma_f32 v61, v61, v106, v133
	v_mul_f32_e32 v132, v58, v111
	v_mul_f32_e32 v58, v58, v110
	v_fma_f32 v58, -v62, v111, v58
	v_fma_f32 v62, v62, v110, v132
	v_mul_f32_e32 v133, v59, v115
	v_mul_f32_e32 v59, v59, v114
	v_fma_f32 v59, -v63, v115, v59
	v_fma_f32 v63, v63, v114, v133
	v_add_f32_e32 v88, v88, v178
	v_add_f32_e32 v92, v92, v179
	v_mul_f32_e32 v132, v92, v117
	v_mul_f32_e32 v179, v88, v117
	v_fma_f32 v178, v88, v116, -v132
	v_fma_f32 v179, v92, v116, v179
	v_add_f32_e32 v89, v89, v180
	v_add_f32_e32 v93, v93, v181
	v_mul_f32_e32 v133, v93, v121
	v_mul_f32_e32 v181, v89, v121
	v_fma_f32 v180, v89, v120, -v133
	v_fma_f32 v181, v93, v120, v181
	v_add_f32_e32 v90, v90, v182
	v_add_f32_e32 v94, v94, v183
	v_mul_f32_e32 v132, v94, v125
	v_mul_f32_e32 v183, v90, v125
	v_fma_f32 v182, v90, v124, -v132
	v_fma_f32 v183, v94, v124, v183
	v_add_f32_e32 v91, v91, v184
	v_add_f32_e32 v95, v95, v185
	v_mul_f32_e32 v133, v95, v129
	v_mul_f32_e32 v185, v91, v129
	v_fma_f32 v184, v91, v128, -v133
	v_fma_f32 v185, v95, v128, v185
	s_waitcnt vmcnt(12)
	v_cvt_pk_bf16_f32 v96, v32, v33
	v_cvt_pk_bf16_f32 v97, v34, v35
	v_cvt_pk_bf16_f32 v98, v36, v37
	v_cvt_pk_bf16_f32 v99, v38, v39
	s_nop 1
	v_mfma_f32_16x16x32_bf16 v[16:19], v[80:83], v[96:99], v[16:19]
	v_cvt_pk_bf16_f32 v96, v40, v41
	v_cvt_pk_bf16_f32 v97, v42, v43
	v_cvt_pk_bf16_f32 v98, v44, v45
	v_cvt_pk_bf16_f32 v99, v46, v47
	s_nop 1
	v_mfma_f32_16x16x32_bf16 v[20:23], v[80:83], v[96:99], v[20:23]
	v_cvt_pk_bf16_f32 v96, v48, v49
	v_cvt_pk_bf16_f32 v97, v50, v51
	v_cvt_pk_bf16_f32 v98, v52, v53
	v_cvt_pk_bf16_f32 v99, v54, v55
	s_nop 1
	v_mfma_f32_16x16x32_bf16 v[24:27], v[80:83], v[96:99], v[24:27]
	v_cvt_pk_bf16_f32 v96, v56, v57
	v_cvt_pk_bf16_f32 v97, v58, v59
	v_cvt_pk_bf16_f32 v98, v60, v61
	v_cvt_pk_bf16_f32 v99, v62, v63
	s_nop 1
	v_mfma_f32_16x16x32_bf16 v[28:31], v[80:83], v[96:99], v[28:31]
	s_waitcnt vmcnt(10)
	global_load_dwordx4 v[80:83], v134, s[38:39]
	s_add_u32 s38, s38, 0x400
	s_addc_u32 s39, s39, 0
	v_mfma_f32_16x16x32_bf16 v[32:35], v[64:67], v[0:3], 0
	v_mfma_f32_16x16x32_bf16 v[36:39], v[72:75], v[0:3], 0
	v_mfma_f32_16x16x32_bf16 v[40:43], v[64:67], v[4:7], 0
	v_mfma_f32_16x16x32_bf16 v[44:47], v[72:75], v[4:7], 0
	v_mfma_f32_16x16x32_bf16 v[48:51], v[64:67], v[8:11], 0
	v_mfma_f32_16x16x32_bf16 v[52:55], v[72:75], v[8:11], 0
	v_mfma_f32_16x16x32_bf16 v[56:59], v[64:67], v[12:15], 0
	v_mfma_f32_16x16x32_bf16 v[60:63], v[72:75], v[12:15], 0
	global_load_dwordx4 v[64:67], v134, s[20:21]
	global_load_dwordx4 v[72:75], v134, s[20:21] offset:1024
	s_add_u32 s20, s20, 0x800
	s_addc_u32 s21, s21, 0
	global_load_dwordx4 v[100:103], v134, s[42:43] offset:0
	global_load_dwordx4 v[104:107], v134, s[42:43] offset:1024
	global_load_dwordx4 v[108:111], v134, s[42:43] offset:2048
	global_load_dwordx4 v[112:115], v134, s[42:43] offset:3072
	global_load_dwordx4 v[116:119], v208, s[42:43] offset:0
	global_load_dwordx4 v[120:123], v208, s[42:43] offset:1024
	global_load_dwordx4 v[124:127], v208, s[42:43] offset:2048
	global_load_dwordx4 v[128:131], v208, s[42:43] offset:3072
	global_load_dwordx4 v[178:181], v206, s[44:45]
	global_load_dwordx4 v[182:185], v206, s[44:45] offset:16
	s_add_u32 s42, s42, 0x2000
	s_addc_u32 s43, s43, 0
	s_add_u32 s44, s44, 0x80
	s_addc_u32 s45, s45, 0
	s_waitcnt vmcnt(13)
	v_mul_f32_e32 v132, v171, v157
	v_mul_f32_e32 v133, v170, v157
	v_fma_f32 v170, v170, v156, -v132
	v_fma_f32 v171, v171, v156, v133
	v_mul_f32_e32 v132, v173, v161
	v_mul_f32_e32 v133, v172, v161
	v_fma_f32 v172, v172, v160, -v132
	v_fma_f32 v173, v173, v160, v133
	v_mul_f32_e32 v132, v175, v165
	v_mul_f32_e32 v133, v174, v165
	v_fma_f32 v174, v174, v164, -v132
	v_fma_f32 v175, v175, v164, v133
	v_mul_f32_e32 v132, v177, v169
	v_mul_f32_e32 v133, v176, v169
	v_fma_f32 v176, v176, v168, -v132
	v_fma_f32 v177, v177, v168, v133
	v_mul_f32_e32 v132, v56, v139
	v_mul_f32_e32 v56, v56, v138
	v_fma_f32 v56, -v60, v139, v56
	v_fma_f32 v60, v60, v138, v132
	v_mul_f32_e32 v133, v57, v143
	v_mul_f32_e32 v57, v57, v142
	v_fma_f32 v57, -v61, v143, v57
	v_fma_f32 v61, v61, v142, v133
	v_mul_f32_e32 v132, v58, v147
	v_mul_f32_e32 v58, v58, v146
	v_fma_f32 v58, -v62, v147, v58
	v_fma_f32 v62, v62, v146, v132
	v_mul_f32_e32 v133, v59, v151
	v_mul_f32_e32 v59, v59, v150
	v_fma_f32 v59, -v63, v151, v59
	v_fma_f32 v63, v63, v150, v133
	v_add_f32_dpp v56, v56, v56 row_shl:1 row_mask:0xf bank_mask:0xf bound_ctrl:1
	v_add_f32_dpp v57, v57, v57 row_shl:1 row_mask:0xf bank_mask:0xf bound_ctrl:1
	v_add_f32_dpp v58, v58, v58 row_shl:1 row_mask:0xf bank_mask:0xf bound_ctrl:1
	v_add_f32_dpp v59, v59, v59 row_shl:1 row_mask:0xf bank_mask:0xf bound_ctrl:1
	v_add_f32_dpp v60, v60, v60 row_shl:1 row_mask:0xf bank_mask:0xf bound_ctrl:1
	v_add_f32_dpp v61, v61, v61 row_shl:1 row_mask:0xf bank_mask:0xf bound_ctrl:1
	v_add_f32_dpp v62, v62, v62 row_shl:1 row_mask:0xf bank_mask:0xf bound_ctrl:1
	v_add_f32_dpp v63, v63, v63 row_shl:1 row_mask:0xf bank_mask:0xf bound_ctrl:1
	v_add_f32_dpp v56, v56, v56 row_shl:2 row_mask:0xf bank_mask:0xf bound_ctrl:1
	v_add_f32_dpp v57, v57, v57 row_shl:2 row_mask:0xf bank_mask:0xf bound_ctrl:1
	v_add_f32_dpp v58, v58, v58 row_shl:2 row_mask:0xf bank_mask:0xf bound_ctrl:1
	v_add_f32_dpp v59, v59, v59 row_shl:2 row_mask:0xf bank_mask:0xf bound_ctrl:1
	v_add_f32_dpp v60, v60, v60 row_shl:2 row_mask:0xf bank_mask:0xf bound_ctrl:1
	v_add_f32_dpp v61, v61, v61 row_shl:2 row_mask:0xf bank_mask:0xf bound_ctrl:1
	v_add_f32_dpp v62, v62, v62 row_shl:2 row_mask:0xf bank_mask:0xf bound_ctrl:1
	v_add_f32_dpp v63, v63, v63 row_shl:2 row_mask:0xf bank_mask:0xf bound_ctrl:1
	v_add_f32_dpp v56, v56, v56 row_shl:4 row_mask:0xf bank_mask:0xf bound_ctrl:1
	v_add_f32_dpp v57, v57, v57 row_shl:4 row_mask:0xf bank_mask:0xf bound_ctrl:1
	v_add_f32_dpp v58, v58, v58 row_shl:4 row_mask:0xf bank_mask:0xf bound_ctrl:1
	v_add_f32_dpp v59, v59, v59 row_shl:4 row_mask:0xf bank_mask:0xf bound_ctrl:1
	v_add_f32_dpp v60, v60, v60 row_shl:4 row_mask:0xf bank_mask:0xf bound_ctrl:1
	v_add_f32_dpp v61, v61, v61 row_shl:4 row_mask:0xf bank_mask:0xf bound_ctrl:1
	v_add_f32_dpp v62, v62, v62 row_shl:4 row_mask:0xf bank_mask:0xf bound_ctrl:1
	v_add_f32_dpp v63, v63, v63 row_shl:4 row_mask:0xf bank_mask:0xf bound_ctrl:1
	v_add_f32_dpp v56, v56, v56 row_shl:8 row_mask:0xf bank_mask:0xf bound_ctrl:1
	v_add_f32_dpp v57, v57, v57 row_shl:8 row_mask:0xf bank_mask:0xf bound_ctrl:1
	v_add_f32_dpp v58, v58, v58 row_shl:8 row_mask:0xf bank_mask:0xf bound_ctrl:1
	v_add_f32_dpp v59, v59, v59 row_shl:8 row_mask:0xf bank_mask:0xf bound_ctrl:1
	v_add_f32_dpp v60, v60, v60 row_shl:8 row_mask:0xf bank_mask:0xf bound_ctrl:1
	v_add_f32_dpp v61, v61, v61 row_shl:8 row_mask:0xf bank_mask:0xf bound_ctrl:1
	v_add_f32_dpp v62, v62, v62 row_shl:8 row_mask:0xf bank_mask:0xf bound_ctrl:1
	v_add_f32_dpp v63, v63, v63 row_shl:8 row_mask:0xf bank_mask:0xf bound_ctrl:1
	v_mov_b32_dpp v88, v56 row_newbcast:0 row_mask:0xf bank_mask:0xf
	v_mov_b32_dpp v89, v57 row_newbcast:0 row_mask:0xf bank_mask:0xf
	v_mov_b32_dpp v90, v58 row_newbcast:0 row_mask:0xf bank_mask:0xf
	v_mov_b32_dpp v91, v59 row_newbcast:0 row_mask:0xf bank_mask:0xf
	v_mov_b32_dpp v92, v60 row_newbcast:0 row_mask:0xf bank_mask:0xf
	v_mov_b32_dpp v93, v61 row_newbcast:0 row_mask:0xf bank_mask:0xf
	v_mov_b32_dpp v94, v62 row_newbcast:0 row_mask:0xf bank_mask:0xf
	v_mov_b32_dpp v95, v63 row_newbcast:0 row_mask:0xf bank_mask:0xf
	v_add_f32_e32 v56, v56, v170
	v_add_f32_e32 v60, v60, v171
	v_add_f32_e32 v57, v57, v172
	v_add_f32_e32 v61, v61, v173
	v_add_f32_e32 v58, v58, v174
	v_add_f32_e32 v62, v62, v175
	v_add_f32_e32 v59, v59, v176
	v_add_f32_e32 v63, v63, v177
	v_mul_f32_e32 v132, v56, v141
	v_mul_f32_e32 v56, v56, v140
	v_fma_f32 v56, -v60, v141, v56
	v_fma_f32 v60, v60, v140, v132
	v_mul_f32_e32 v133, v57, v145
	v_mul_f32_e32 v57, v57, v144
	v_fma_f32 v57, -v61, v145, v57
	v_fma_f32 v61, v61, v144, v133
	v_mul_f32_e32 v132, v58, v149
	v_mul_f32_e32 v58, v58, v148
	v_fma_f32 v58, -v62, v149, v58
	v_fma_f32 v62, v62, v148, v132
	v_mul_f32_e32 v133, v59, v153
	v_mul_f32_e32 v59, v59, v152
	v_fma_f32 v59, -v63, v153, v59
	v_fma_f32 v63, v63, v152, v133
	v_add_f32_e32 v88, v88, v170
	v_add_f32_e32 v92, v92, v171
	v_mul_f32_e32 v132, v92, v155
	v_mul_f32_e32 v171, v88, v155
	v_fma_f32 v170, v88, v154, -v132
	v_fma_f32 v171, v92, v154, v171
	v_add_f32_e32 v89, v89, v172
	v_add_f32_e32 v93, v93, v173
	v_mul_f32_e32 v133, v93, v159
	v_mul_f32_e32 v173, v89, v159
	v_fma_f32 v172, v89, v158, -v133
	v_fma_f32 v173, v93, v158, v173
	v_add_f32_e32 v90, v90, v174
	v_add_f32_e32 v94, v94, v175
	v_mul_f32_e32 v132, v94, v163
	v_mul_f32_e32 v175, v90, v163
	v_fma_f32 v174, v90, v162, -v132
	v_fma_f32 v175, v94, v162, v175
	v_add_f32_e32 v91, v91, v176
	v_add_f32_e32 v95, v95, v177
	v_mul_f32_e32 v133, v95, v167
	v_mul_f32_e32 v177, v91, v167
	v_fma_f32 v176, v91, v166, -v133
	v_fma_f32 v177, v95, v166, v177
	v_mul_f32_e32 v132, v48, v139
	v_mul_f32_e32 v48, v48, v138
	v_fma_f32 v48, -v52, v139, v48
	v_fma_f32 v52, v52, v138, v132
	v_mul_f32_e32 v133, v49, v143
	v_mul_f32_e32 v49, v49, v142
	v_fma_f32 v49, -v53, v143, v49
	v_fma_f32 v53, v53, v142, v133
	v_mul_f32_e32 v132, v50, v147
	v_mul_f32_e32 v50, v50, v146
	v_fma_f32 v50, -v54, v147, v50
	v_fma_f32 v54, v54, v146, v132
	v_mul_f32_e32 v133, v51, v151
	v_mul_f32_e32 v51, v51, v150
	v_fma_f32 v51, -v55, v151, v51
	v_fma_f32 v55, v55, v150, v133
	v_add_f32_dpp v48, v48, v48 row_shl:1 row_mask:0xf bank_mask:0xf bound_ctrl:1
	v_add_f32_dpp v49, v49, v49 row_shl:1 row_mask:0xf bank_mask:0xf bound_ctrl:1
	v_add_f32_dpp v50, v50, v50 row_shl:1 row_mask:0xf bank_mask:0xf bound_ctrl:1
	v_add_f32_dpp v51, v51, v51 row_shl:1 row_mask:0xf bank_mask:0xf bound_ctrl:1
	v_add_f32_dpp v52, v52, v52 row_shl:1 row_mask:0xf bank_mask:0xf bound_ctrl:1
	v_add_f32_dpp v53, v53, v53 row_shl:1 row_mask:0xf bank_mask:0xf bound_ctrl:1
	v_add_f32_dpp v54, v54, v54 row_shl:1 row_mask:0xf bank_mask:0xf bound_ctrl:1
	v_add_f32_dpp v55, v55, v55 row_shl:1 row_mask:0xf bank_mask:0xf bound_ctrl:1
	v_add_f32_dpp v48, v48, v48 row_shl:2 row_mask:0xf bank_mask:0xf bound_ctrl:1
	v_add_f32_dpp v49, v49, v49 row_shl:2 row_mask:0xf bank_mask:0xf bound_ctrl:1
	v_add_f32_dpp v50, v50, v50 row_shl:2 row_mask:0xf bank_mask:0xf bound_ctrl:1
	v_add_f32_dpp v51, v51, v51 row_shl:2 row_mask:0xf bank_mask:0xf bound_ctrl:1
	v_add_f32_dpp v52, v52, v52 row_shl:2 row_mask:0xf bank_mask:0xf bound_ctrl:1
	v_add_f32_dpp v53, v53, v53 row_shl:2 row_mask:0xf bank_mask:0xf bound_ctrl:1
	v_add_f32_dpp v54, v54, v54 row_shl:2 row_mask:0xf bank_mask:0xf bound_ctrl:1
	v_add_f32_dpp v55, v55, v55 row_shl:2 row_mask:0xf bank_mask:0xf bound_ctrl:1
	v_add_f32_dpp v48, v48, v48 row_shl:4 row_mask:0xf bank_mask:0xf bound_ctrl:1
	v_add_f32_dpp v49, v49, v49 row_shl:4 row_mask:0xf bank_mask:0xf bound_ctrl:1
	v_add_f32_dpp v50, v50, v50 row_shl:4 row_mask:0xf bank_mask:0xf bound_ctrl:1
	v_add_f32_dpp v51, v51, v51 row_shl:4 row_mask:0xf bank_mask:0xf bound_ctrl:1
	v_add_f32_dpp v52, v52, v52 row_shl:4 row_mask:0xf bank_mask:0xf bound_ctrl:1
	v_add_f32_dpp v53, v53, v53 row_shl:4 row_mask:0xf bank_mask:0xf bound_ctrl:1
	v_add_f32_dpp v54, v54, v54 row_shl:4 row_mask:0xf bank_mask:0xf bound_ctrl:1
	v_add_f32_dpp v55, v55, v55 row_shl:4 row_mask:0xf bank_mask:0xf bound_ctrl:1
	v_add_f32_dpp v48, v48, v48 row_shl:8 row_mask:0xf bank_mask:0xf bound_ctrl:1
	v_add_f32_dpp v49, v49, v49 row_shl:8 row_mask:0xf bank_mask:0xf bound_ctrl:1
	v_add_f32_dpp v50, v50, v50 row_shl:8 row_mask:0xf bank_mask:0xf bound_ctrl:1
	v_add_f32_dpp v51, v51, v51 row_shl:8 row_mask:0xf bank_mask:0xf bound_ctrl:1
	v_add_f32_dpp v52, v52, v52 row_shl:8 row_mask:0xf bank_mask:0xf bound_ctrl:1
	v_add_f32_dpp v53, v53, v53 row_shl:8 row_mask:0xf bank_mask:0xf bound_ctrl:1
	v_add_f32_dpp v54, v54, v54 row_shl:8 row_mask:0xf bank_mask:0xf bound_ctrl:1
	v_add_f32_dpp v55, v55, v55 row_shl:8 row_mask:0xf bank_mask:0xf bound_ctrl:1
	v_mov_b32_dpp v88, v48 row_newbcast:0 row_mask:0xf bank_mask:0xf
	v_mov_b32_dpp v89, v49 row_newbcast:0 row_mask:0xf bank_mask:0xf
	v_mov_b32_dpp v90, v50 row_newbcast:0 row_mask:0xf bank_mask:0xf
	v_mov_b32_dpp v91, v51 row_newbcast:0 row_mask:0xf bank_mask:0xf
	v_mov_b32_dpp v92, v52 row_newbcast:0 row_mask:0xf bank_mask:0xf
	v_mov_b32_dpp v93, v53 row_newbcast:0 row_mask:0xf bank_mask:0xf
	v_mov_b32_dpp v94, v54 row_newbcast:0 row_mask:0xf bank_mask:0xf
	v_mov_b32_dpp v95, v55 row_newbcast:0 row_mask:0xf bank_mask:0xf
	v_add_f32_e32 v48, v48, v170
	v_add_f32_e32 v52, v52, v171
	v_add_f32_e32 v49, v49, v172
	v_add_f32_e32 v53, v53, v173
	v_add_f32_e32 v50, v50, v174
	v_add_f32_e32 v54, v54, v175
	v_add_f32_e32 v51, v51, v176
	v_add_f32_e32 v55, v55, v177
	v_mul_f32_e32 v132, v48, v141
	v_mul_f32_e32 v48, v48, v140
	v_fma_f32 v48, -v52, v141, v48
	v_fma_f32 v52, v52, v140, v132
	v_mul_f32_e32 v133, v49, v145
	v_mul_f32_e32 v49, v49, v144
	v_fma_f32 v49, -v53, v145, v49
	v_fma_f32 v53, v53, v144, v133
	v_mul_f32_e32 v132, v50, v149
	v_mul_f32_e32 v50, v50, v148
	v_fma_f32 v50, -v54, v149, v50
	v_fma_f32 v54, v54, v148, v132
	v_mul_f32_e32 v133, v51, v153
	v_mul_f32_e32 v51, v51, v152
	v_fma_f32 v51, -v55, v153, v51
	v_fma_f32 v55, v55, v152, v133
	v_add_f32_e32 v88, v88, v170
	v_add_f32_e32 v92, v92, v171
	v_mul_f32_e32 v132, v92, v155
	v_mul_f32_e32 v171, v88, v155
	v_fma_f32 v170, v88, v154, -v132
	v_fma_f32 v171, v92, v154, v171
	v_add_f32_e32 v89, v89, v172
	v_add_f32_e32 v93, v93, v173
	v_mul_f32_e32 v133, v93, v159
	v_mul_f32_e32 v173, v89, v159
	v_fma_f32 v172, v89, v158, -v133
	v_fma_f32 v173, v93, v158, v173
	v_add_f32_e32 v90, v90, v174
	v_add_f32_e32 v94, v94, v175
	v_mul_f32_e32 v132, v94, v163
	v_mul_f32_e32 v175, v90, v163
	v_fma_f32 v174, v90, v162, -v132
	v_fma_f32 v175, v94, v162, v175
	v_add_f32_e32 v91, v91, v176
	v_add_f32_e32 v95, v95, v177
	v_mul_f32_e32 v133, v95, v167
	v_mul_f32_e32 v177, v91, v167
	v_fma_f32 v176, v91, v166, -v133
	v_fma_f32 v177, v95, v166, v177
	v_mul_f32_e32 v132, v40, v139
	v_mul_f32_e32 v40, v40, v138
	v_fma_f32 v40, -v44, v139, v40
	v_fma_f32 v44, v44, v138, v132
	v_mul_f32_e32 v133, v41, v143
	v_mul_f32_e32 v41, v41, v142
	v_fma_f32 v41, -v45, v143, v41
	v_fma_f32 v45, v45, v142, v133
	v_mul_f32_e32 v132, v42, v147
	v_mul_f32_e32 v42, v42, v146
	v_fma_f32 v42, -v46, v147, v42
	v_fma_f32 v46, v46, v146, v132
	v_mul_f32_e32 v133, v43, v151
	v_mul_f32_e32 v43, v43, v150
	v_fma_f32 v43, -v47, v151, v43
	v_fma_f32 v47, v47, v150, v133
	v_add_f32_dpp v40, v40, v40 row_shl:1 row_mask:0xf bank_mask:0xf bound_ctrl:1
	v_add_f32_dpp v41, v41, v41 row_shl:1 row_mask:0xf bank_mask:0xf bound_ctrl:1
	v_add_f32_dpp v42, v42, v42 row_shl:1 row_mask:0xf bank_mask:0xf bound_ctrl:1
	v_add_f32_dpp v43, v43, v43 row_shl:1 row_mask:0xf bank_mask:0xf bound_ctrl:1
	v_add_f32_dpp v44, v44, v44 row_shl:1 row_mask:0xf bank_mask:0xf bound_ctrl:1
	v_add_f32_dpp v45, v45, v45 row_shl:1 row_mask:0xf bank_mask:0xf bound_ctrl:1
	v_add_f32_dpp v46, v46, v46 row_shl:1 row_mask:0xf bank_mask:0xf bound_ctrl:1
	v_add_f32_dpp v47, v47, v47 row_shl:1 row_mask:0xf bank_mask:0xf bound_ctrl:1
	v_add_f32_dpp v40, v40, v40 row_shl:2 row_mask:0xf bank_mask:0xf bound_ctrl:1
	v_add_f32_dpp v41, v41, v41 row_shl:2 row_mask:0xf bank_mask:0xf bound_ctrl:1
	v_add_f32_dpp v42, v42, v42 row_shl:2 row_mask:0xf bank_mask:0xf bound_ctrl:1
	v_add_f32_dpp v43, v43, v43 row_shl:2 row_mask:0xf bank_mask:0xf bound_ctrl:1
	v_add_f32_dpp v44, v44, v44 row_shl:2 row_mask:0xf bank_mask:0xf bound_ctrl:1
	v_add_f32_dpp v45, v45, v45 row_shl:2 row_mask:0xf bank_mask:0xf bound_ctrl:1
	v_add_f32_dpp v46, v46, v46 row_shl:2 row_mask:0xf bank_mask:0xf bound_ctrl:1
	v_add_f32_dpp v47, v47, v47 row_shl:2 row_mask:0xf bank_mask:0xf bound_ctrl:1
	v_add_f32_dpp v40, v40, v40 row_shl:4 row_mask:0xf bank_mask:0xf bound_ctrl:1
	v_add_f32_dpp v41, v41, v41 row_shl:4 row_mask:0xf bank_mask:0xf bound_ctrl:1
	v_add_f32_dpp v42, v42, v42 row_shl:4 row_mask:0xf bank_mask:0xf bound_ctrl:1
	v_add_f32_dpp v43, v43, v43 row_shl:4 row_mask:0xf bank_mask:0xf bound_ctrl:1
	v_add_f32_dpp v44, v44, v44 row_shl:4 row_mask:0xf bank_mask:0xf bound_ctrl:1
	v_add_f32_dpp v45, v45, v45 row_shl:4 row_mask:0xf bank_mask:0xf bound_ctrl:1
	v_add_f32_dpp v46, v46, v46 row_shl:4 row_mask:0xf bank_mask:0xf bound_ctrl:1
	v_add_f32_dpp v47, v47, v47 row_shl:4 row_mask:0xf bank_mask:0xf bound_ctrl:1
	v_add_f32_dpp v40, v40, v40 row_shl:8 row_mask:0xf bank_mask:0xf bound_ctrl:1
	v_add_f32_dpp v41, v41, v41 row_shl:8 row_mask:0xf bank_mask:0xf bound_ctrl:1
	v_add_f32_dpp v42, v42, v42 row_shl:8 row_mask:0xf bank_mask:0xf bound_ctrl:1
	v_add_f32_dpp v43, v43, v43 row_shl:8 row_mask:0xf bank_mask:0xf bound_ctrl:1
	v_add_f32_dpp v44, v44, v44 row_shl:8 row_mask:0xf bank_mask:0xf bound_ctrl:1
	v_add_f32_dpp v45, v45, v45 row_shl:8 row_mask:0xf bank_mask:0xf bound_ctrl:1
	v_add_f32_dpp v46, v46, v46 row_shl:8 row_mask:0xf bank_mask:0xf bound_ctrl:1
	v_add_f32_dpp v47, v47, v47 row_shl:8 row_mask:0xf bank_mask:0xf bound_ctrl:1
	v_mov_b32_dpp v88, v40 row_newbcast:0 row_mask:0xf bank_mask:0xf
	v_mov_b32_dpp v89, v41 row_newbcast:0 row_mask:0xf bank_mask:0xf
	v_mov_b32_dpp v90, v42 row_newbcast:0 row_mask:0xf bank_mask:0xf
	v_mov_b32_dpp v91, v43 row_newbcast:0 row_mask:0xf bank_mask:0xf
	v_mov_b32_dpp v92, v44 row_newbcast:0 row_mask:0xf bank_mask:0xf
	v_mov_b32_dpp v93, v45 row_newbcast:0 row_mask:0xf bank_mask:0xf
	v_mov_b32_dpp v94, v46 row_newbcast:0 row_mask:0xf bank_mask:0xf
	v_mov_b32_dpp v95, v47 row_newbcast:0 row_mask:0xf bank_mask:0xf
	v_add_f32_e32 v40, v40, v170
	v_add_f32_e32 v44, v44, v171
	v_add_f32_e32 v41, v41, v172
	v_add_f32_e32 v45, v45, v173
	v_add_f32_e32 v42, v42, v174
	v_add_f32_e32 v46, v46, v175
	v_add_f32_e32 v43, v43, v176
	v_add_f32_e32 v47, v47, v177
	v_mul_f32_e32 v132, v40, v141
	v_mul_f32_e32 v40, v40, v140
	v_fma_f32 v40, -v44, v141, v40
	v_fma_f32 v44, v44, v140, v132
	v_mul_f32_e32 v133, v41, v145
	v_mul_f32_e32 v41, v41, v144
	v_fma_f32 v41, -v45, v145, v41
	v_fma_f32 v45, v45, v144, v133
	v_mul_f32_e32 v132, v42, v149
	v_mul_f32_e32 v42, v42, v148
	v_fma_f32 v42, -v46, v149, v42
	v_fma_f32 v46, v46, v148, v132
	v_mul_f32_e32 v133, v43, v153
	v_mul_f32_e32 v43, v43, v152
	v_fma_f32 v43, -v47, v153, v43
	v_fma_f32 v47, v47, v152, v133
	v_add_f32_e32 v88, v88, v170
	v_add_f32_e32 v92, v92, v171
	v_mul_f32_e32 v132, v92, v155
	v_mul_f32_e32 v171, v88, v155
	v_fma_f32 v170, v88, v154, -v132
	v_fma_f32 v171, v92, v154, v171
	v_add_f32_e32 v89, v89, v172
	v_add_f32_e32 v93, v93, v173
	v_mul_f32_e32 v133, v93, v159
	v_mul_f32_e32 v173, v89, v159
	v_fma_f32 v172, v89, v158, -v133
	v_fma_f32 v173, v93, v158, v173
	v_add_f32_e32 v90, v90, v174
	v_add_f32_e32 v94, v94, v175
	v_mul_f32_e32 v132, v94, v163
	v_mul_f32_e32 v175, v90, v163
	v_fma_f32 v174, v90, v162, -v132
	v_fma_f32 v175, v94, v162, v175
	v_add_f32_e32 v91, v91, v176
	v_add_f32_e32 v95, v95, v177
	v_mul_f32_e32 v133, v95, v167
	v_mul_f32_e32 v177, v91, v167
	v_fma_f32 v176, v91, v166, -v133
	v_fma_f32 v177, v95, v166, v177
	v_mul_f32_e32 v132, v32, v139
	v_mul_f32_e32 v32, v32, v138
	v_fma_f32 v32, -v36, v139, v32
	v_fma_f32 v36, v36, v138, v132
	v_mul_f32_e32 v133, v33, v143
	v_mul_f32_e32 v33, v33, v142
	v_fma_f32 v33, -v37, v143, v33
	v_fma_f32 v37, v37, v142, v133
	v_mul_f32_e32 v132, v34, v147
	v_mul_f32_e32 v34, v34, v146
	v_fma_f32 v34, -v38, v147, v34
	v_fma_f32 v38, v38, v146, v132
	v_mul_f32_e32 v133, v35, v151
	v_mul_f32_e32 v35, v35, v150
	v_fma_f32 v35, -v39, v151, v35
	v_fma_f32 v39, v39, v150, v133
	v_add_f32_dpp v32, v32, v32 row_shl:1 row_mask:0xf bank_mask:0xf bound_ctrl:1
	v_add_f32_dpp v33, v33, v33 row_shl:1 row_mask:0xf bank_mask:0xf bound_ctrl:1
	v_add_f32_dpp v34, v34, v34 row_shl:1 row_mask:0xf bank_mask:0xf bound_ctrl:1
	v_add_f32_dpp v35, v35, v35 row_shl:1 row_mask:0xf bank_mask:0xf bound_ctrl:1
	v_add_f32_dpp v36, v36, v36 row_shl:1 row_mask:0xf bank_mask:0xf bound_ctrl:1
	v_add_f32_dpp v37, v37, v37 row_shl:1 row_mask:0xf bank_mask:0xf bound_ctrl:1
	v_add_f32_dpp v38, v38, v38 row_shl:1 row_mask:0xf bank_mask:0xf bound_ctrl:1
	v_add_f32_dpp v39, v39, v39 row_shl:1 row_mask:0xf bank_mask:0xf bound_ctrl:1
	v_add_f32_dpp v32, v32, v32 row_shl:2 row_mask:0xf bank_mask:0xf bound_ctrl:1
	v_add_f32_dpp v33, v33, v33 row_shl:2 row_mask:0xf bank_mask:0xf bound_ctrl:1
	v_add_f32_dpp v34, v34, v34 row_shl:2 row_mask:0xf bank_mask:0xf bound_ctrl:1
	v_add_f32_dpp v35, v35, v35 row_shl:2 row_mask:0xf bank_mask:0xf bound_ctrl:1
	v_add_f32_dpp v36, v36, v36 row_shl:2 row_mask:0xf bank_mask:0xf bound_ctrl:1
	v_add_f32_dpp v37, v37, v37 row_shl:2 row_mask:0xf bank_mask:0xf bound_ctrl:1
	v_add_f32_dpp v38, v38, v38 row_shl:2 row_mask:0xf bank_mask:0xf bound_ctrl:1
	v_add_f32_dpp v39, v39, v39 row_shl:2 row_mask:0xf bank_mask:0xf bound_ctrl:1
	v_add_f32_dpp v32, v32, v32 row_shl:4 row_mask:0xf bank_mask:0xf bound_ctrl:1
	v_add_f32_dpp v33, v33, v33 row_shl:4 row_mask:0xf bank_mask:0xf bound_ctrl:1
	v_add_f32_dpp v34, v34, v34 row_shl:4 row_mask:0xf bank_mask:0xf bound_ctrl:1
	v_add_f32_dpp v35, v35, v35 row_shl:4 row_mask:0xf bank_mask:0xf bound_ctrl:1
	v_add_f32_dpp v36, v36, v36 row_shl:4 row_mask:0xf bank_mask:0xf bound_ctrl:1
	v_add_f32_dpp v37, v37, v37 row_shl:4 row_mask:0xf bank_mask:0xf bound_ctrl:1
	v_add_f32_dpp v38, v38, v38 row_shl:4 row_mask:0xf bank_mask:0xf bound_ctrl:1
	v_add_f32_dpp v39, v39, v39 row_shl:4 row_mask:0xf bank_mask:0xf bound_ctrl:1
	v_add_f32_dpp v32, v32, v32 row_shl:8 row_mask:0xf bank_mask:0xf bound_ctrl:1
	v_add_f32_dpp v33, v33, v33 row_shl:8 row_mask:0xf bank_mask:0xf bound_ctrl:1
	v_add_f32_dpp v34, v34, v34 row_shl:8 row_mask:0xf bank_mask:0xf bound_ctrl:1
	v_add_f32_dpp v35, v35, v35 row_shl:8 row_mask:0xf bank_mask:0xf bound_ctrl:1
	v_add_f32_dpp v36, v36, v36 row_shl:8 row_mask:0xf bank_mask:0xf bound_ctrl:1
	v_add_f32_dpp v37, v37, v37 row_shl:8 row_mask:0xf bank_mask:0xf bound_ctrl:1
	v_add_f32_dpp v38, v38, v38 row_shl:8 row_mask:0xf bank_mask:0xf bound_ctrl:1
	v_add_f32_dpp v39, v39, v39 row_shl:8 row_mask:0xf bank_mask:0xf bound_ctrl:1
	v_mov_b32_dpp v88, v32 row_newbcast:0 row_mask:0xf bank_mask:0xf
	v_mov_b32_dpp v89, v33 row_newbcast:0 row_mask:0xf bank_mask:0xf
	v_mov_b32_dpp v90, v34 row_newbcast:0 row_mask:0xf bank_mask:0xf
	v_mov_b32_dpp v91, v35 row_newbcast:0 row_mask:0xf bank_mask:0xf
	v_mov_b32_dpp v92, v36 row_newbcast:0 row_mask:0xf bank_mask:0xf
	v_mov_b32_dpp v93, v37 row_newbcast:0 row_mask:0xf bank_mask:0xf
	v_mov_b32_dpp v94, v38 row_newbcast:0 row_mask:0xf bank_mask:0xf
	v_mov_b32_dpp v95, v39 row_newbcast:0 row_mask:0xf bank_mask:0xf
	v_add_f32_e32 v32, v32, v170
	v_add_f32_e32 v36, v36, v171
	v_add_f32_e32 v33, v33, v172
	v_add_f32_e32 v37, v37, v173
	v_add_f32_e32 v34, v34, v174
	v_add_f32_e32 v38, v38, v175
	v_add_f32_e32 v35, v35, v176
	v_add_f32_e32 v39, v39, v177
	v_mul_f32_e32 v132, v32, v141
	v_mul_f32_e32 v32, v32, v140
	v_fma_f32 v32, -v36, v141, v32
	v_fma_f32 v36, v36, v140, v132
	v_mul_f32_e32 v133, v33, v145
	v_mul_f32_e32 v33, v33, v144
	v_fma_f32 v33, -v37, v145, v33
	v_fma_f32 v37, v37, v144, v133
	v_mul_f32_e32 v132, v34, v149
	v_mul_f32_e32 v34, v34, v148
	v_fma_f32 v34, -v38, v149, v34
	v_fma_f32 v38, v38, v148, v132
	v_mul_f32_e32 v133, v35, v153
	v_mul_f32_e32 v35, v35, v152
	v_fma_f32 v35, -v39, v153, v35
	v_fma_f32 v39, v39, v152, v133
	v_add_f32_e32 v88, v88, v170
	v_add_f32_e32 v92, v92, v171
	v_mul_f32_e32 v132, v92, v155
	v_mul_f32_e32 v171, v88, v155
	v_fma_f32 v170, v88, v154, -v132
	v_fma_f32 v171, v92, v154, v171
	v_add_f32_e32 v89, v89, v172
	v_add_f32_e32 v93, v93, v173
	v_mul_f32_e32 v133, v93, v159
	v_mul_f32_e32 v173, v89, v159
	v_fma_f32 v172, v89, v158, -v133
	v_fma_f32 v173, v93, v158, v173
	v_add_f32_e32 v90, v90, v174
	v_add_f32_e32 v94, v94, v175
	v_mul_f32_e32 v132, v94, v163
	v_mul_f32_e32 v175, v90, v163
	v_fma_f32 v174, v90, v162, -v132
	v_fma_f32 v175, v94, v162, v175
	v_add_f32_e32 v91, v91, v176
	v_add_f32_e32 v95, v95, v177
	v_mul_f32_e32 v133, v95, v167
	v_mul_f32_e32 v177, v91, v167
	v_fma_f32 v176, v91, v166, -v133
	v_fma_f32 v177, v95, v166, v177
	s_waitcnt vmcnt(12)
	v_cvt_pk_bf16_f32 v96, v32, v33
	v_cvt_pk_bf16_f32 v97, v34, v35
	v_cvt_pk_bf16_f32 v98, v36, v37
	v_cvt_pk_bf16_f32 v99, v38, v39
	s_nop 1
	v_mfma_f32_16x16x32_bf16 v[16:19], v[80:83], v[96:99], v[16:19]
	v_cvt_pk_bf16_f32 v96, v40, v41
	v_cvt_pk_bf16_f32 v97, v42, v43
	v_cvt_pk_bf16_f32 v98, v44, v45
	v_cvt_pk_bf16_f32 v99, v46, v47
	s_nop 1
	v_mfma_f32_16x16x32_bf16 v[20:23], v[80:83], v[96:99], v[20:23]
	v_cvt_pk_bf16_f32 v96, v48, v49
	v_cvt_pk_bf16_f32 v97, v50, v51
	v_cvt_pk_bf16_f32 v98, v52, v53
	v_cvt_pk_bf16_f32 v99, v54, v55
	s_nop 1
	v_mfma_f32_16x16x32_bf16 v[24:27], v[80:83], v[96:99], v[24:27]
	v_cvt_pk_bf16_f32 v96, v56, v57
	v_cvt_pk_bf16_f32 v97, v58, v59
	v_cvt_pk_bf16_f32 v98, v60, v61
	v_cvt_pk_bf16_f32 v99, v62, v63
	s_nop 1
	v_mfma_f32_16x16x32_bf16 v[28:31], v[80:83], v[96:99], v[28:31]
	s_waitcnt vmcnt(10)
	global_load_dwordx4 v[80:83], v134, s[38:39]
	s_add_u32 s38, s38, 0x400
	s_addc_u32 s39, s39, 0
	v_mfma_f32_16x16x32_bf16 v[32:35], v[64:67], v[0:3], 0
	v_mfma_f32_16x16x32_bf16 v[36:39], v[72:75], v[0:3], 0
	v_mfma_f32_16x16x32_bf16 v[40:43], v[64:67], v[4:7], 0
	v_mfma_f32_16x16x32_bf16 v[44:47], v[72:75], v[4:7], 0
	v_mfma_f32_16x16x32_bf16 v[48:51], v[64:67], v[8:11], 0
	v_mfma_f32_16x16x32_bf16 v[52:55], v[72:75], v[8:11], 0
	v_mfma_f32_16x16x32_bf16 v[56:59], v[64:67], v[12:15], 0
	v_mfma_f32_16x16x32_bf16 v[60:63], v[72:75], v[12:15], 0
	global_load_dwordx4 v[64:67], v134, s[20:21]
	global_load_dwordx4 v[72:75], v134, s[20:21] offset:1024
	s_add_u32 s20, s20, 0x800
	s_addc_u32 s21, s21, 0
	global_load_dwordx4 v[138:141], v134, s[42:43] offset:0
	global_load_dwordx4 v[142:145], v134, s[42:43] offset:1024
	global_load_dwordx4 v[146:149], v134, s[42:43] offset:2048
	global_load_dwordx4 v[150:153], v134, s[42:43] offset:3072
	global_load_dwordx4 v[154:157], v208, s[42:43] offset:0
	global_load_dwordx4 v[158:161], v208, s[42:43] offset:1024
	global_load_dwordx4 v[162:165], v208, s[42:43] offset:2048
	global_load_dwordx4 v[166:169], v208, s[42:43] offset:3072
	global_load_dwordx4 v[170:173], v206, s[44:45]
	global_load_dwordx4 v[174:177], v206, s[44:45] offset:16
	s_add_u32 s42, s42, 0x2000
	s_addc_u32 s43, s43, 0
	s_add_u32 s44, s44, 0x80
	s_addc_u32 s45, s45, 0
	s_waitcnt vmcnt(13)
	v_mul_f32_e32 v132, v179, v119
	v_mul_f32_e32 v133, v178, v119
	v_fma_f32 v178, v178, v118, -v132
	v_fma_f32 v179, v179, v118, v133
	v_mul_f32_e32 v132, v181, v123
	v_mul_f32_e32 v133, v180, v123
	v_fma_f32 v180, v180, v122, -v132
	v_fma_f32 v181, v181, v122, v133
	v_mul_f32_e32 v132, v183, v127
	v_mul_f32_e32 v133, v182, v127
	v_fma_f32 v182, v182, v126, -v132
	v_fma_f32 v183, v183, v126, v133
	v_mul_f32_e32 v132, v185, v131
	v_mul_f32_e32 v133, v184, v131
	v_fma_f32 v184, v184, v130, -v132
	v_fma_f32 v185, v185, v130, v133
	v_mul_f32_e32 v132, v56, v101
	v_mul_f32_e32 v56, v56, v100
	v_fma_f32 v56, -v60, v101, v56
	v_fma_f32 v60, v60, v100, v132
	v_mul_f32_e32 v133, v57, v105
	v_mul_f32_e32 v57, v57, v104
	v_fma_f32 v57, -v61, v105, v57
	v_fma_f32 v61, v61, v104, v133
	v_mul_f32_e32 v132, v58, v109
	v_mul_f32_e32 v58, v58, v108
	v_fma_f32 v58, -v62, v109, v58
	v_fma_f32 v62, v62, v108, v132
	v_mul_f32_e32 v133, v59, v113
	v_mul_f32_e32 v59, v59, v112
	v_fma_f32 v59, -v63, v113, v59
	v_fma_f32 v63, v63, v112, v133
	v_add_f32_dpp v56, v56, v56 row_shl:1 row_mask:0xf bank_mask:0xf bound_ctrl:1
	v_add_f32_dpp v57, v57, v57 row_shl:1 row_mask:0xf bank_mask:0xf bound_ctrl:1
	v_add_f32_dpp v58, v58, v58 row_shl:1 row_mask:0xf bank_mask:0xf bound_ctrl:1
	v_add_f32_dpp v59, v59, v59 row_shl:1 row_mask:0xf bank_mask:0xf bound_ctrl:1
	v_add_f32_dpp v60, v60, v60 row_shl:1 row_mask:0xf bank_mask:0xf bound_ctrl:1
	v_add_f32_dpp v61, v61, v61 row_shl:1 row_mask:0xf bank_mask:0xf bound_ctrl:1
	v_add_f32_dpp v62, v62, v62 row_shl:1 row_mask:0xf bank_mask:0xf bound_ctrl:1
	v_add_f32_dpp v63, v63, v63 row_shl:1 row_mask:0xf bank_mask:0xf bound_ctrl:1
	v_add_f32_dpp v56, v56, v56 row_shl:2 row_mask:0xf bank_mask:0xf bound_ctrl:1
	v_add_f32_dpp v57, v57, v57 row_shl:2 row_mask:0xf bank_mask:0xf bound_ctrl:1
	v_add_f32_dpp v58, v58, v58 row_shl:2 row_mask:0xf bank_mask:0xf bound_ctrl:1
	v_add_f32_dpp v59, v59, v59 row_shl:2 row_mask:0xf bank_mask:0xf bound_ctrl:1
	v_add_f32_dpp v60, v60, v60 row_shl:2 row_mask:0xf bank_mask:0xf bound_ctrl:1
	v_add_f32_dpp v61, v61, v61 row_shl:2 row_mask:0xf bank_mask:0xf bound_ctrl:1
	v_add_f32_dpp v62, v62, v62 row_shl:2 row_mask:0xf bank_mask:0xf bound_ctrl:1
	v_add_f32_dpp v63, v63, v63 row_shl:2 row_mask:0xf bank_mask:0xf bound_ctrl:1
	v_add_f32_dpp v56, v56, v56 row_shl:4 row_mask:0xf bank_mask:0xf bound_ctrl:1
	v_add_f32_dpp v57, v57, v57 row_shl:4 row_mask:0xf bank_mask:0xf bound_ctrl:1
	v_add_f32_dpp v58, v58, v58 row_shl:4 row_mask:0xf bank_mask:0xf bound_ctrl:1
	v_add_f32_dpp v59, v59, v59 row_shl:4 row_mask:0xf bank_mask:0xf bound_ctrl:1
	v_add_f32_dpp v60, v60, v60 row_shl:4 row_mask:0xf bank_mask:0xf bound_ctrl:1
	v_add_f32_dpp v61, v61, v61 row_shl:4 row_mask:0xf bank_mask:0xf bound_ctrl:1
	v_add_f32_dpp v62, v62, v62 row_shl:4 row_mask:0xf bank_mask:0xf bound_ctrl:1
	v_add_f32_dpp v63, v63, v63 row_shl:4 row_mask:0xf bank_mask:0xf bound_ctrl:1
	v_add_f32_dpp v56, v56, v56 row_shl:8 row_mask:0xf bank_mask:0xf bound_ctrl:1
	v_add_f32_dpp v57, v57, v57 row_shl:8 row_mask:0xf bank_mask:0xf bound_ctrl:1
	v_add_f32_dpp v58, v58, v58 row_shl:8 row_mask:0xf bank_mask:0xf bound_ctrl:1
	v_add_f32_dpp v59, v59, v59 row_shl:8 row_mask:0xf bank_mask:0xf bound_ctrl:1
	v_add_f32_dpp v60, v60, v60 row_shl:8 row_mask:0xf bank_mask:0xf bound_ctrl:1
	v_add_f32_dpp v61, v61, v61 row_shl:8 row_mask:0xf bank_mask:0xf bound_ctrl:1
	v_add_f32_dpp v62, v62, v62 row_shl:8 row_mask:0xf bank_mask:0xf bound_ctrl:1
	v_add_f32_dpp v63, v63, v63 row_shl:8 row_mask:0xf bank_mask:0xf bound_ctrl:1
	v_mov_b32_dpp v88, v56 row_newbcast:0 row_mask:0xf bank_mask:0xf
	v_mov_b32_dpp v89, v57 row_newbcast:0 row_mask:0xf bank_mask:0xf
	v_mov_b32_dpp v90, v58 row_newbcast:0 row_mask:0xf bank_mask:0xf
	v_mov_b32_dpp v91, v59 row_newbcast:0 row_mask:0xf bank_mask:0xf
	v_mov_b32_dpp v92, v60 row_newbcast:0 row_mask:0xf bank_mask:0xf
	v_mov_b32_dpp v93, v61 row_newbcast:0 row_mask:0xf bank_mask:0xf
	v_mov_b32_dpp v94, v62 row_newbcast:0 row_mask:0xf bank_mask:0xf
	v_mov_b32_dpp v95, v63 row_newbcast:0 row_mask:0xf bank_mask:0xf
	v_add_f32_e32 v56, v56, v178
	v_add_f32_e32 v60, v60, v179
	v_add_f32_e32 v57, v57, v180
	v_add_f32_e32 v61, v61, v181
	v_add_f32_e32 v58, v58, v182
	v_add_f32_e32 v62, v62, v183
	v_add_f32_e32 v59, v59, v184
	v_add_f32_e32 v63, v63, v185
	v_mul_f32_e32 v132, v56, v103
	v_mul_f32_e32 v56, v56, v102
	v_fma_f32 v56, -v60, v103, v56
	v_fma_f32 v60, v60, v102, v132
	v_mul_f32_e32 v133, v57, v107
	v_mul_f32_e32 v57, v57, v106
	v_fma_f32 v57, -v61, v107, v57
	v_fma_f32 v61, v61, v106, v133
	v_mul_f32_e32 v132, v58, v111
	v_mul_f32_e32 v58, v58, v110
	v_fma_f32 v58, -v62, v111, v58
	v_fma_f32 v62, v62, v110, v132
	v_mul_f32_e32 v133, v59, v115
	v_mul_f32_e32 v59, v59, v114
	v_fma_f32 v59, -v63, v115, v59
	v_fma_f32 v63, v63, v114, v133
	v_add_f32_e32 v88, v88, v178
	v_add_f32_e32 v92, v92, v179
	v_mul_f32_e32 v132, v92, v117
	v_mul_f32_e32 v179, v88, v117
	v_fma_f32 v178, v88, v116, -v132
	v_fma_f32 v179, v92, v116, v179
	v_add_f32_e32 v89, v89, v180
	v_add_f32_e32 v93, v93, v181
	v_mul_f32_e32 v133, v93, v121
	v_mul_f32_e32 v181, v89, v121
	v_fma_f32 v180, v89, v120, -v133
	v_fma_f32 v181, v93, v120, v181
	v_add_f32_e32 v90, v90, v182
	v_add_f32_e32 v94, v94, v183
	v_mul_f32_e32 v132, v94, v125
	v_mul_f32_e32 v183, v90, v125
	v_fma_f32 v182, v90, v124, -v132
	v_fma_f32 v183, v94, v124, v183
	v_add_f32_e32 v91, v91, v184
	v_add_f32_e32 v95, v95, v185
	v_mul_f32_e32 v133, v95, v129
	v_mul_f32_e32 v185, v91, v129
	v_fma_f32 v184, v91, v128, -v133
	v_fma_f32 v185, v95, v128, v185
	v_mul_f32_e32 v132, v48, v101
	v_mul_f32_e32 v48, v48, v100
	v_fma_f32 v48, -v52, v101, v48
	v_fma_f32 v52, v52, v100, v132
	v_mul_f32_e32 v133, v49, v105
	v_mul_f32_e32 v49, v49, v104
	v_fma_f32 v49, -v53, v105, v49
	v_fma_f32 v53, v53, v104, v133
	v_mul_f32_e32 v132, v50, v109
	v_mul_f32_e32 v50, v50, v108
	v_fma_f32 v50, -v54, v109, v50
	v_fma_f32 v54, v54, v108, v132
	v_mul_f32_e32 v133, v51, v113
	v_mul_f32_e32 v51, v51, v112
	v_fma_f32 v51, -v55, v113, v51
	v_fma_f32 v55, v55, v112, v133
	v_add_f32_dpp v48, v48, v48 row_shl:1 row_mask:0xf bank_mask:0xf bound_ctrl:1
	v_add_f32_dpp v49, v49, v49 row_shl:1 row_mask:0xf bank_mask:0xf bound_ctrl:1
	v_add_f32_dpp v50, v50, v50 row_shl:1 row_mask:0xf bank_mask:0xf bound_ctrl:1
	v_add_f32_dpp v51, v51, v51 row_shl:1 row_mask:0xf bank_mask:0xf bound_ctrl:1
	v_add_f32_dpp v52, v52, v52 row_shl:1 row_mask:0xf bank_mask:0xf bound_ctrl:1
	v_add_f32_dpp v53, v53, v53 row_shl:1 row_mask:0xf bank_mask:0xf bound_ctrl:1
	v_add_f32_dpp v54, v54, v54 row_shl:1 row_mask:0xf bank_mask:0xf bound_ctrl:1
	v_add_f32_dpp v55, v55, v55 row_shl:1 row_mask:0xf bank_mask:0xf bound_ctrl:1
	v_add_f32_dpp v48, v48, v48 row_shl:2 row_mask:0xf bank_mask:0xf bound_ctrl:1
	v_add_f32_dpp v49, v49, v49 row_shl:2 row_mask:0xf bank_mask:0xf bound_ctrl:1
	v_add_f32_dpp v50, v50, v50 row_shl:2 row_mask:0xf bank_mask:0xf bound_ctrl:1
	v_add_f32_dpp v51, v51, v51 row_shl:2 row_mask:0xf bank_mask:0xf bound_ctrl:1
	v_add_f32_dpp v52, v52, v52 row_shl:2 row_mask:0xf bank_mask:0xf bound_ctrl:1
	v_add_f32_dpp v53, v53, v53 row_shl:2 row_mask:0xf bank_mask:0xf bound_ctrl:1
	v_add_f32_dpp v54, v54, v54 row_shl:2 row_mask:0xf bank_mask:0xf bound_ctrl:1
	v_add_f32_dpp v55, v55, v55 row_shl:2 row_mask:0xf bank_mask:0xf bound_ctrl:1
	v_add_f32_dpp v48, v48, v48 row_shl:4 row_mask:0xf bank_mask:0xf bound_ctrl:1
	v_add_f32_dpp v49, v49, v49 row_shl:4 row_mask:0xf bank_mask:0xf bound_ctrl:1
	v_add_f32_dpp v50, v50, v50 row_shl:4 row_mask:0xf bank_mask:0xf bound_ctrl:1
	v_add_f32_dpp v51, v51, v51 row_shl:4 row_mask:0xf bank_mask:0xf bound_ctrl:1
	v_add_f32_dpp v52, v52, v52 row_shl:4 row_mask:0xf bank_mask:0xf bound_ctrl:1
	v_add_f32_dpp v53, v53, v53 row_shl:4 row_mask:0xf bank_mask:0xf bound_ctrl:1
	v_add_f32_dpp v54, v54, v54 row_shl:4 row_mask:0xf bank_mask:0xf bound_ctrl:1
	v_add_f32_dpp v55, v55, v55 row_shl:4 row_mask:0xf bank_mask:0xf bound_ctrl:1
	v_add_f32_dpp v48, v48, v48 row_shl:8 row_mask:0xf bank_mask:0xf bound_ctrl:1
	v_add_f32_dpp v49, v49, v49 row_shl:8 row_mask:0xf bank_mask:0xf bound_ctrl:1
	v_add_f32_dpp v50, v50, v50 row_shl:8 row_mask:0xf bank_mask:0xf bound_ctrl:1
	v_add_f32_dpp v51, v51, v51 row_shl:8 row_mask:0xf bank_mask:0xf bound_ctrl:1
	v_add_f32_dpp v52, v52, v52 row_shl:8 row_mask:0xf bank_mask:0xf bound_ctrl:1
	v_add_f32_dpp v53, v53, v53 row_shl:8 row_mask:0xf bank_mask:0xf bound_ctrl:1
	v_add_f32_dpp v54, v54, v54 row_shl:8 row_mask:0xf bank_mask:0xf bound_ctrl:1
	v_add_f32_dpp v55, v55, v55 row_shl:8 row_mask:0xf bank_mask:0xf bound_ctrl:1
	v_mov_b32_dpp v88, v48 row_newbcast:0 row_mask:0xf bank_mask:0xf
	v_mov_b32_dpp v89, v49 row_newbcast:0 row_mask:0xf bank_mask:0xf
	v_mov_b32_dpp v90, v50 row_newbcast:0 row_mask:0xf bank_mask:0xf
	v_mov_b32_dpp v91, v51 row_newbcast:0 row_mask:0xf bank_mask:0xf
	v_mov_b32_dpp v92, v52 row_newbcast:0 row_mask:0xf bank_mask:0xf
	v_mov_b32_dpp v93, v53 row_newbcast:0 row_mask:0xf bank_mask:0xf
	v_mov_b32_dpp v94, v54 row_newbcast:0 row_mask:0xf bank_mask:0xf
	v_mov_b32_dpp v95, v55 row_newbcast:0 row_mask:0xf bank_mask:0xf
	v_add_f32_e32 v48, v48, v178
	v_add_f32_e32 v52, v52, v179
	v_add_f32_e32 v49, v49, v180
	v_add_f32_e32 v53, v53, v181
	v_add_f32_e32 v50, v50, v182
	v_add_f32_e32 v54, v54, v183
	v_add_f32_e32 v51, v51, v184
	v_add_f32_e32 v55, v55, v185
	v_mul_f32_e32 v132, v48, v103
	v_mul_f32_e32 v48, v48, v102
	v_fma_f32 v48, -v52, v103, v48
	v_fma_f32 v52, v52, v102, v132
	v_mul_f32_e32 v133, v49, v107
	v_mul_f32_e32 v49, v49, v106
	v_fma_f32 v49, -v53, v107, v49
	v_fma_f32 v53, v53, v106, v133
	v_mul_f32_e32 v132, v50, v111
	v_mul_f32_e32 v50, v50, v110
	v_fma_f32 v50, -v54, v111, v50
	v_fma_f32 v54, v54, v110, v132
	v_mul_f32_e32 v133, v51, v115
	v_mul_f32_e32 v51, v51, v114
	v_fma_f32 v51, -v55, v115, v51
	v_fma_f32 v55, v55, v114, v133
	v_add_f32_e32 v88, v88, v178
	v_add_f32_e32 v92, v92, v179
	v_mul_f32_e32 v132, v92, v117
	v_mul_f32_e32 v179, v88, v117
	v_fma_f32 v178, v88, v116, -v132
	v_fma_f32 v179, v92, v116, v179
	v_add_f32_e32 v89, v89, v180
	v_add_f32_e32 v93, v93, v181
	v_mul_f32_e32 v133, v93, v121
	v_mul_f32_e32 v181, v89, v121
	v_fma_f32 v180, v89, v120, -v133
	v_fma_f32 v181, v93, v120, v181
	v_add_f32_e32 v90, v90, v182
	v_add_f32_e32 v94, v94, v183
	v_mul_f32_e32 v132, v94, v125
	v_mul_f32_e32 v183, v90, v125
	v_fma_f32 v182, v90, v124, -v132
	v_fma_f32 v183, v94, v124, v183
	v_add_f32_e32 v91, v91, v184
	v_add_f32_e32 v95, v95, v185
	v_mul_f32_e32 v133, v95, v129
	v_mul_f32_e32 v185, v91, v129
	v_fma_f32 v184, v91, v128, -v133
	v_fma_f32 v185, v95, v128, v185
	v_mul_f32_e32 v132, v40, v101
	v_mul_f32_e32 v40, v40, v100
	v_fma_f32 v40, -v44, v101, v40
	v_fma_f32 v44, v44, v100, v132
	v_mul_f32_e32 v133, v41, v105
	v_mul_f32_e32 v41, v41, v104
	v_fma_f32 v41, -v45, v105, v41
	v_fma_f32 v45, v45, v104, v133
	v_mul_f32_e32 v132, v42, v109
	v_mul_f32_e32 v42, v42, v108
	v_fma_f32 v42, -v46, v109, v42
	v_fma_f32 v46, v46, v108, v132
	v_mul_f32_e32 v133, v43, v113
	v_mul_f32_e32 v43, v43, v112
	v_fma_f32 v43, -v47, v113, v43
	v_fma_f32 v47, v47, v112, v133
	v_add_f32_dpp v40, v40, v40 row_shl:1 row_mask:0xf bank_mask:0xf bound_ctrl:1
	v_add_f32_dpp v41, v41, v41 row_shl:1 row_mask:0xf bank_mask:0xf bound_ctrl:1
	v_add_f32_dpp v42, v42, v42 row_shl:1 row_mask:0xf bank_mask:0xf bound_ctrl:1
	v_add_f32_dpp v43, v43, v43 row_shl:1 row_mask:0xf bank_mask:0xf bound_ctrl:1
	v_add_f32_dpp v44, v44, v44 row_shl:1 row_mask:0xf bank_mask:0xf bound_ctrl:1
	v_add_f32_dpp v45, v45, v45 row_shl:1 row_mask:0xf bank_mask:0xf bound_ctrl:1
	v_add_f32_dpp v46, v46, v46 row_shl:1 row_mask:0xf bank_mask:0xf bound_ctrl:1
	v_add_f32_dpp v47, v47, v47 row_shl:1 row_mask:0xf bank_mask:0xf bound_ctrl:1
	v_add_f32_dpp v40, v40, v40 row_shl:2 row_mask:0xf bank_mask:0xf bound_ctrl:1
	v_add_f32_dpp v41, v41, v41 row_shl:2 row_mask:0xf bank_mask:0xf bound_ctrl:1
	v_add_f32_dpp v42, v42, v42 row_shl:2 row_mask:0xf bank_mask:0xf bound_ctrl:1
	v_add_f32_dpp v43, v43, v43 row_shl:2 row_mask:0xf bank_mask:0xf bound_ctrl:1
	v_add_f32_dpp v44, v44, v44 row_shl:2 row_mask:0xf bank_mask:0xf bound_ctrl:1
	v_add_f32_dpp v45, v45, v45 row_shl:2 row_mask:0xf bank_mask:0xf bound_ctrl:1
	v_add_f32_dpp v46, v46, v46 row_shl:2 row_mask:0xf bank_mask:0xf bound_ctrl:1
	v_add_f32_dpp v47, v47, v47 row_shl:2 row_mask:0xf bank_mask:0xf bound_ctrl:1
	v_add_f32_dpp v40, v40, v40 row_shl:4 row_mask:0xf bank_mask:0xf bound_ctrl:1
	v_add_f32_dpp v41, v41, v41 row_shl:4 row_mask:0xf bank_mask:0xf bound_ctrl:1
	v_add_f32_dpp v42, v42, v42 row_shl:4 row_mask:0xf bank_mask:0xf bound_ctrl:1
	v_add_f32_dpp v43, v43, v43 row_shl:4 row_mask:0xf bank_mask:0xf bound_ctrl:1
	v_add_f32_dpp v44, v44, v44 row_shl:4 row_mask:0xf bank_mask:0xf bound_ctrl:1
	v_add_f32_dpp v45, v45, v45 row_shl:4 row_mask:0xf bank_mask:0xf bound_ctrl:1
	v_add_f32_dpp v46, v46, v46 row_shl:4 row_mask:0xf bank_mask:0xf bound_ctrl:1
	v_add_f32_dpp v47, v47, v47 row_shl:4 row_mask:0xf bank_mask:0xf bound_ctrl:1
	v_add_f32_dpp v40, v40, v40 row_shl:8 row_mask:0xf bank_mask:0xf bound_ctrl:1
	v_add_f32_dpp v41, v41, v41 row_shl:8 row_mask:0xf bank_mask:0xf bound_ctrl:1
	v_add_f32_dpp v42, v42, v42 row_shl:8 row_mask:0xf bank_mask:0xf bound_ctrl:1
	v_add_f32_dpp v43, v43, v43 row_shl:8 row_mask:0xf bank_mask:0xf bound_ctrl:1
	v_add_f32_dpp v44, v44, v44 row_shl:8 row_mask:0xf bank_mask:0xf bound_ctrl:1
	v_add_f32_dpp v45, v45, v45 row_shl:8 row_mask:0xf bank_mask:0xf bound_ctrl:1
	v_add_f32_dpp v46, v46, v46 row_shl:8 row_mask:0xf bank_mask:0xf bound_ctrl:1
	v_add_f32_dpp v47, v47, v47 row_shl:8 row_mask:0xf bank_mask:0xf bound_ctrl:1
	v_mov_b32_dpp v88, v40 row_newbcast:0 row_mask:0xf bank_mask:0xf
	v_mov_b32_dpp v89, v41 row_newbcast:0 row_mask:0xf bank_mask:0xf
	v_mov_b32_dpp v90, v42 row_newbcast:0 row_mask:0xf bank_mask:0xf
	v_mov_b32_dpp v91, v43 row_newbcast:0 row_mask:0xf bank_mask:0xf
	v_mov_b32_dpp v92, v44 row_newbcast:0 row_mask:0xf bank_mask:0xf
	v_mov_b32_dpp v93, v45 row_newbcast:0 row_mask:0xf bank_mask:0xf
	v_mov_b32_dpp v94, v46 row_newbcast:0 row_mask:0xf bank_mask:0xf
	v_mov_b32_dpp v95, v47 row_newbcast:0 row_mask:0xf bank_mask:0xf
	v_add_f32_e32 v40, v40, v178
	v_add_f32_e32 v44, v44, v179
	v_add_f32_e32 v41, v41, v180
	v_add_f32_e32 v45, v45, v181
	v_add_f32_e32 v42, v42, v182
	v_add_f32_e32 v46, v46, v183
	v_add_f32_e32 v43, v43, v184
	v_add_f32_e32 v47, v47, v185
	v_mul_f32_e32 v132, v40, v103
	v_mul_f32_e32 v40, v40, v102
	v_fma_f32 v40, -v44, v103, v40
	v_fma_f32 v44, v44, v102, v132
	v_mul_f32_e32 v133, v41, v107
	v_mul_f32_e32 v41, v41, v106
	v_fma_f32 v41, -v45, v107, v41
	v_fma_f32 v45, v45, v106, v133
	v_mul_f32_e32 v132, v42, v111
	v_mul_f32_e32 v42, v42, v110
	v_fma_f32 v42, -v46, v111, v42
	v_fma_f32 v46, v46, v110, v132
	v_mul_f32_e32 v133, v43, v115
	v_mul_f32_e32 v43, v43, v114
	v_fma_f32 v43, -v47, v115, v43
	v_fma_f32 v47, v47, v114, v133
	v_add_f32_e32 v88, v88, v178
	v_add_f32_e32 v92, v92, v179
	v_mul_f32_e32 v132, v92, v117
	v_mul_f32_e32 v179, v88, v117
	v_fma_f32 v178, v88, v116, -v132
	v_fma_f32 v179, v92, v116, v179
	v_add_f32_e32 v89, v89, v180
	v_add_f32_e32 v93, v93, v181
	v_mul_f32_e32 v133, v93, v121
	v_mul_f32_e32 v181, v89, v121
	v_fma_f32 v180, v89, v120, -v133
	v_fma_f32 v181, v93, v120, v181
	v_add_f32_e32 v90, v90, v182
	v_add_f32_e32 v94, v94, v183
	v_mul_f32_e32 v132, v94, v125
	v_mul_f32_e32 v183, v90, v125
	v_fma_f32 v182, v90, v124, -v132
	v_fma_f32 v183, v94, v124, v183
	v_add_f32_e32 v91, v91, v184
	v_add_f32_e32 v95, v95, v185
	v_mul_f32_e32 v133, v95, v129
	v_mul_f32_e32 v185, v91, v129
	v_fma_f32 v184, v91, v128, -v133
	v_fma_f32 v185, v95, v128, v185
	v_mul_f32_e32 v132, v32, v101
	v_mul_f32_e32 v32, v32, v100
	v_fma_f32 v32, -v36, v101, v32
	v_fma_f32 v36, v36, v100, v132
	v_mul_f32_e32 v133, v33, v105
	v_mul_f32_e32 v33, v33, v104
	v_fma_f32 v33, -v37, v105, v33
	v_fma_f32 v37, v37, v104, v133
	v_mul_f32_e32 v132, v34, v109
	v_mul_f32_e32 v34, v34, v108
	v_fma_f32 v34, -v38, v109, v34
	v_fma_f32 v38, v38, v108, v132
	v_mul_f32_e32 v133, v35, v113
	v_mul_f32_e32 v35, v35, v112
	v_fma_f32 v35, -v39, v113, v35
	v_fma_f32 v39, v39, v112, v133
	v_add_f32_dpp v32, v32, v32 row_shl:1 row_mask:0xf bank_mask:0xf bound_ctrl:1
	v_add_f32_dpp v33, v33, v33 row_shl:1 row_mask:0xf bank_mask:0xf bound_ctrl:1
	v_add_f32_dpp v34, v34, v34 row_shl:1 row_mask:0xf bank_mask:0xf bound_ctrl:1
	v_add_f32_dpp v35, v35, v35 row_shl:1 row_mask:0xf bank_mask:0xf bound_ctrl:1
	v_add_f32_dpp v36, v36, v36 row_shl:1 row_mask:0xf bank_mask:0xf bound_ctrl:1
	v_add_f32_dpp v37, v37, v37 row_shl:1 row_mask:0xf bank_mask:0xf bound_ctrl:1
	v_add_f32_dpp v38, v38, v38 row_shl:1 row_mask:0xf bank_mask:0xf bound_ctrl:1
	v_add_f32_dpp v39, v39, v39 row_shl:1 row_mask:0xf bank_mask:0xf bound_ctrl:1
	v_add_f32_dpp v32, v32, v32 row_shl:2 row_mask:0xf bank_mask:0xf bound_ctrl:1
	v_add_f32_dpp v33, v33, v33 row_shl:2 row_mask:0xf bank_mask:0xf bound_ctrl:1
	v_add_f32_dpp v34, v34, v34 row_shl:2 row_mask:0xf bank_mask:0xf bound_ctrl:1
	v_add_f32_dpp v35, v35, v35 row_shl:2 row_mask:0xf bank_mask:0xf bound_ctrl:1
	v_add_f32_dpp v36, v36, v36 row_shl:2 row_mask:0xf bank_mask:0xf bound_ctrl:1
	v_add_f32_dpp v37, v37, v37 row_shl:2 row_mask:0xf bank_mask:0xf bound_ctrl:1
	v_add_f32_dpp v38, v38, v38 row_shl:2 row_mask:0xf bank_mask:0xf bound_ctrl:1
	v_add_f32_dpp v39, v39, v39 row_shl:2 row_mask:0xf bank_mask:0xf bound_ctrl:1
	v_add_f32_dpp v32, v32, v32 row_shl:4 row_mask:0xf bank_mask:0xf bound_ctrl:1
	v_add_f32_dpp v33, v33, v33 row_shl:4 row_mask:0xf bank_mask:0xf bound_ctrl:1
	v_add_f32_dpp v34, v34, v34 row_shl:4 row_mask:0xf bank_mask:0xf bound_ctrl:1
	v_add_f32_dpp v35, v35, v35 row_shl:4 row_mask:0xf bank_mask:0xf bound_ctrl:1
	v_add_f32_dpp v36, v36, v36 row_shl:4 row_mask:0xf bank_mask:0xf bound_ctrl:1
	v_add_f32_dpp v37, v37, v37 row_shl:4 row_mask:0xf bank_mask:0xf bound_ctrl:1
	v_add_f32_dpp v38, v38, v38 row_shl:4 row_mask:0xf bank_mask:0xf bound_ctrl:1
	v_add_f32_dpp v39, v39, v39 row_shl:4 row_mask:0xf bank_mask:0xf bound_ctrl:1
	v_add_f32_dpp v32, v32, v32 row_shl:8 row_mask:0xf bank_mask:0xf bound_ctrl:1
	v_add_f32_dpp v33, v33, v33 row_shl:8 row_mask:0xf bank_mask:0xf bound_ctrl:1
	v_add_f32_dpp v34, v34, v34 row_shl:8 row_mask:0xf bank_mask:0xf bound_ctrl:1
	v_add_f32_dpp v35, v35, v35 row_shl:8 row_mask:0xf bank_mask:0xf bound_ctrl:1
	v_add_f32_dpp v36, v36, v36 row_shl:8 row_mask:0xf bank_mask:0xf bound_ctrl:1
	v_add_f32_dpp v37, v37, v37 row_shl:8 row_mask:0xf bank_mask:0xf bound_ctrl:1
	v_add_f32_dpp v38, v38, v38 row_shl:8 row_mask:0xf bank_mask:0xf bound_ctrl:1
	v_add_f32_dpp v39, v39, v39 row_shl:8 row_mask:0xf bank_mask:0xf bound_ctrl:1
	v_mov_b32_dpp v88, v32 row_newbcast:0 row_mask:0xf bank_mask:0xf
	v_mov_b32_dpp v89, v33 row_newbcast:0 row_mask:0xf bank_mask:0xf
	v_mov_b32_dpp v90, v34 row_newbcast:0 row_mask:0xf bank_mask:0xf
	v_mov_b32_dpp v91, v35 row_newbcast:0 row_mask:0xf bank_mask:0xf
	v_mov_b32_dpp v92, v36 row_newbcast:0 row_mask:0xf bank_mask:0xf
	v_mov_b32_dpp v93, v37 row_newbcast:0 row_mask:0xf bank_mask:0xf
	v_mov_b32_dpp v94, v38 row_newbcast:0 row_mask:0xf bank_mask:0xf
	v_mov_b32_dpp v95, v39 row_newbcast:0 row_mask:0xf bank_mask:0xf
	v_add_f32_e32 v32, v32, v178
	v_add_f32_e32 v36, v36, v179
	v_add_f32_e32 v33, v33, v180
	v_add_f32_e32 v37, v37, v181
	v_add_f32_e32 v34, v34, v182
	v_add_f32_e32 v38, v38, v183
	v_add_f32_e32 v35, v35, v184
	v_add_f32_e32 v39, v39, v185
	v_mul_f32_e32 v132, v32, v103
	v_mul_f32_e32 v32, v32, v102
	v_fma_f32 v32, -v36, v103, v32
	v_fma_f32 v36, v36, v102, v132
	v_mul_f32_e32 v133, v33, v107
	v_mul_f32_e32 v33, v33, v106
	v_fma_f32 v33, -v37, v107, v33
	v_fma_f32 v37, v37, v106, v133
	v_mul_f32_e32 v132, v34, v111
	v_mul_f32_e32 v34, v34, v110
	v_fma_f32 v34, -v38, v111, v34
	v_fma_f32 v38, v38, v110, v132
	v_mul_f32_e32 v133, v35, v115
	v_mul_f32_e32 v35, v35, v114
	v_fma_f32 v35, -v39, v115, v35
	v_fma_f32 v39, v39, v114, v133
	v_add_f32_e32 v88, v88, v178
	v_add_f32_e32 v92, v92, v179
	v_mul_f32_e32 v132, v92, v117
	v_mul_f32_e32 v179, v88, v117
	v_fma_f32 v178, v88, v116, -v132
	v_fma_f32 v179, v92, v116, v179
	v_add_f32_e32 v89, v89, v180
	v_add_f32_e32 v93, v93, v181
	v_mul_f32_e32 v133, v93, v121
	v_mul_f32_e32 v181, v89, v121
	v_fma_f32 v180, v89, v120, -v133
	v_fma_f32 v181, v93, v120, v181
	v_add_f32_e32 v90, v90, v182
	v_add_f32_e32 v94, v94, v183
	v_mul_f32_e32 v132, v94, v125
	v_mul_f32_e32 v183, v90, v125
	v_fma_f32 v182, v90, v124, -v132
	v_fma_f32 v183, v94, v124, v183
	v_add_f32_e32 v91, v91, v184
	v_add_f32_e32 v95, v95, v185
	v_mul_f32_e32 v133, v95, v129
	v_mul_f32_e32 v185, v91, v129
	v_fma_f32 v184, v91, v128, -v133
	v_fma_f32 v185, v95, v128, v185
	s_waitcnt vmcnt(12)
	v_cvt_pk_bf16_f32 v96, v32, v33
	v_cvt_pk_bf16_f32 v97, v34, v35
	v_cvt_pk_bf16_f32 v98, v36, v37
	v_cvt_pk_bf16_f32 v99, v38, v39
	s_nop 1
	v_mfma_f32_16x16x32_bf16 v[16:19], v[80:83], v[96:99], v[16:19]
	v_cvt_pk_bf16_f32 v96, v40, v41
	v_cvt_pk_bf16_f32 v97, v42, v43
	v_cvt_pk_bf16_f32 v98, v44, v45
	v_cvt_pk_bf16_f32 v99, v46, v47
	s_nop 1
	v_mfma_f32_16x16x32_bf16 v[20:23], v[80:83], v[96:99], v[20:23]
	v_cvt_pk_bf16_f32 v96, v48, v49
	v_cvt_pk_bf16_f32 v97, v50, v51
	v_cvt_pk_bf16_f32 v98, v52, v53
	v_cvt_pk_bf16_f32 v99, v54, v55
	s_nop 1
	v_mfma_f32_16x16x32_bf16 v[24:27], v[80:83], v[96:99], v[24:27]
	v_cvt_pk_bf16_f32 v96, v56, v57
	v_cvt_pk_bf16_f32 v97, v58, v59
	v_cvt_pk_bf16_f32 v98, v60, v61
	v_cvt_pk_bf16_f32 v99, v62, v63
	s_nop 1
	v_mfma_f32_16x16x32_bf16 v[28:31], v[80:83], v[96:99], v[28:31]
	s_waitcnt vmcnt(10)
	global_load_dwordx4 v[80:83], v134, s[38:39]
	s_add_u32 s38, s38, 0x400
	s_addc_u32 s39, s39, 0
	v_mfma_f32_16x16x32_bf16 v[32:35], v[64:67], v[0:3], 0
	v_mfma_f32_16x16x32_bf16 v[36:39], v[72:75], v[0:3], 0
	v_mfma_f32_16x16x32_bf16 v[40:43], v[64:67], v[4:7], 0
	v_mfma_f32_16x16x32_bf16 v[44:47], v[72:75], v[4:7], 0
	v_mfma_f32_16x16x32_bf16 v[48:51], v[64:67], v[8:11], 0
	v_mfma_f32_16x16x32_bf16 v[52:55], v[72:75], v[8:11], 0
	v_mfma_f32_16x16x32_bf16 v[56:59], v[64:67], v[12:15], 0
	v_mfma_f32_16x16x32_bf16 v[60:63], v[72:75], v[12:15], 0
	global_load_dwordx4 v[64:67], v134, s[20:21]
	global_load_dwordx4 v[72:75], v134, s[20:21] offset:1024
	global_load_dwordx4 v[100:103], v134, s[42:43] offset:0
	global_load_dwordx4 v[104:107], v134, s[42:43] offset:1024
	global_load_dwordx4 v[108:111], v134, s[42:43] offset:2048
	global_load_dwordx4 v[112:115], v134, s[42:43] offset:3072
	global_load_dwordx4 v[116:119], v208, s[42:43] offset:0
	global_load_dwordx4 v[120:123], v208, s[42:43] offset:1024
	global_load_dwordx4 v[124:127], v208, s[42:43] offset:2048
	global_load_dwordx4 v[128:131], v208, s[42:43] offset:3072
	global_load_dwordx4 v[178:181], v206, s[44:45]
	global_load_dwordx4 v[182:185], v206, s[44:45] offset:16
	s_waitcnt vmcnt(13)
	v_mul_f32_e32 v132, v171, v157
	v_mul_f32_e32 v133, v170, v157
	v_fma_f32 v170, v170, v156, -v132
	v_fma_f32 v171, v171, v156, v133
	v_mul_f32_e32 v132, v173, v161
	v_mul_f32_e32 v133, v172, v161
	v_fma_f32 v172, v172, v160, -v132
	v_fma_f32 v173, v173, v160, v133
	v_mul_f32_e32 v132, v175, v165
	v_mul_f32_e32 v133, v174, v165
	v_fma_f32 v174, v174, v164, -v132
	v_fma_f32 v175, v175, v164, v133
	v_mul_f32_e32 v132, v177, v169
	v_mul_f32_e32 v133, v176, v169
	v_fma_f32 v176, v176, v168, -v132
	v_fma_f32 v177, v177, v168, v133
	v_mul_f32_e32 v132, v56, v139
	v_mul_f32_e32 v56, v56, v138
	v_fma_f32 v56, -v60, v139, v56
	v_fma_f32 v60, v60, v138, v132
	v_mul_f32_e32 v133, v57, v143
	v_mul_f32_e32 v57, v57, v142
	v_fma_f32 v57, -v61, v143, v57
	v_fma_f32 v61, v61, v142, v133
	v_mul_f32_e32 v132, v58, v147
	v_mul_f32_e32 v58, v58, v146
	v_fma_f32 v58, -v62, v147, v58
	v_fma_f32 v62, v62, v146, v132
	v_mul_f32_e32 v133, v59, v151
	v_mul_f32_e32 v59, v59, v150
	v_fma_f32 v59, -v63, v151, v59
	v_fma_f32 v63, v63, v150, v133
	v_add_f32_dpp v56, v56, v56 row_shl:1 row_mask:0xf bank_mask:0xf bound_ctrl:1
	v_add_f32_dpp v57, v57, v57 row_shl:1 row_mask:0xf bank_mask:0xf bound_ctrl:1
	v_add_f32_dpp v58, v58, v58 row_shl:1 row_mask:0xf bank_mask:0xf bound_ctrl:1
	v_add_f32_dpp v59, v59, v59 row_shl:1 row_mask:0xf bank_mask:0xf bound_ctrl:1
	v_add_f32_dpp v60, v60, v60 row_shl:1 row_mask:0xf bank_mask:0xf bound_ctrl:1
	v_add_f32_dpp v61, v61, v61 row_shl:1 row_mask:0xf bank_mask:0xf bound_ctrl:1
	v_add_f32_dpp v62, v62, v62 row_shl:1 row_mask:0xf bank_mask:0xf bound_ctrl:1
	v_add_f32_dpp v63, v63, v63 row_shl:1 row_mask:0xf bank_mask:0xf bound_ctrl:1
	v_add_f32_dpp v56, v56, v56 row_shl:2 row_mask:0xf bank_mask:0xf bound_ctrl:1
	v_add_f32_dpp v57, v57, v57 row_shl:2 row_mask:0xf bank_mask:0xf bound_ctrl:1
	v_add_f32_dpp v58, v58, v58 row_shl:2 row_mask:0xf bank_mask:0xf bound_ctrl:1
	v_add_f32_dpp v59, v59, v59 row_shl:2 row_mask:0xf bank_mask:0xf bound_ctrl:1
	v_add_f32_dpp v60, v60, v60 row_shl:2 row_mask:0xf bank_mask:0xf bound_ctrl:1
	v_add_f32_dpp v61, v61, v61 row_shl:2 row_mask:0xf bank_mask:0xf bound_ctrl:1
	v_add_f32_dpp v62, v62, v62 row_shl:2 row_mask:0xf bank_mask:0xf bound_ctrl:1
	v_add_f32_dpp v63, v63, v63 row_shl:2 row_mask:0xf bank_mask:0xf bound_ctrl:1
	v_add_f32_dpp v56, v56, v56 row_shl:4 row_mask:0xf bank_mask:0xf bound_ctrl:1
	v_add_f32_dpp v57, v57, v57 row_shl:4 row_mask:0xf bank_mask:0xf bound_ctrl:1
	v_add_f32_dpp v58, v58, v58 row_shl:4 row_mask:0xf bank_mask:0xf bound_ctrl:1
	v_add_f32_dpp v59, v59, v59 row_shl:4 row_mask:0xf bank_mask:0xf bound_ctrl:1
	v_add_f32_dpp v60, v60, v60 row_shl:4 row_mask:0xf bank_mask:0xf bound_ctrl:1
	v_add_f32_dpp v61, v61, v61 row_shl:4 row_mask:0xf bank_mask:0xf bound_ctrl:1
	v_add_f32_dpp v62, v62, v62 row_shl:4 row_mask:0xf bank_mask:0xf bound_ctrl:1
	v_add_f32_dpp v63, v63, v63 row_shl:4 row_mask:0xf bank_mask:0xf bound_ctrl:1
	v_add_f32_dpp v56, v56, v56 row_shl:8 row_mask:0xf bank_mask:0xf bound_ctrl:1
	v_add_f32_dpp v57, v57, v57 row_shl:8 row_mask:0xf bank_mask:0xf bound_ctrl:1
	v_add_f32_dpp v58, v58, v58 row_shl:8 row_mask:0xf bank_mask:0xf bound_ctrl:1
	v_add_f32_dpp v59, v59, v59 row_shl:8 row_mask:0xf bank_mask:0xf bound_ctrl:1
	v_add_f32_dpp v60, v60, v60 row_shl:8 row_mask:0xf bank_mask:0xf bound_ctrl:1
	v_add_f32_dpp v61, v61, v61 row_shl:8 row_mask:0xf bank_mask:0xf bound_ctrl:1
	v_add_f32_dpp v62, v62, v62 row_shl:8 row_mask:0xf bank_mask:0xf bound_ctrl:1
	v_add_f32_dpp v63, v63, v63 row_shl:8 row_mask:0xf bank_mask:0xf bound_ctrl:1
	v_mov_b32_dpp v88, v56 row_newbcast:0 row_mask:0xf bank_mask:0xf
	v_mov_b32_dpp v89, v57 row_newbcast:0 row_mask:0xf bank_mask:0xf
	v_mov_b32_dpp v90, v58 row_newbcast:0 row_mask:0xf bank_mask:0xf
	v_mov_b32_dpp v91, v59 row_newbcast:0 row_mask:0xf bank_mask:0xf
	v_mov_b32_dpp v92, v60 row_newbcast:0 row_mask:0xf bank_mask:0xf
	v_mov_b32_dpp v93, v61 row_newbcast:0 row_mask:0xf bank_mask:0xf
	v_mov_b32_dpp v94, v62 row_newbcast:0 row_mask:0xf bank_mask:0xf
	v_mov_b32_dpp v95, v63 row_newbcast:0 row_mask:0xf bank_mask:0xf
	v_add_f32_e32 v56, v56, v170
	v_add_f32_e32 v60, v60, v171
	v_add_f32_e32 v57, v57, v172
	v_add_f32_e32 v61, v61, v173
	v_add_f32_e32 v58, v58, v174
	v_add_f32_e32 v62, v62, v175
	v_add_f32_e32 v59, v59, v176
	v_add_f32_e32 v63, v63, v177
	v_mul_f32_e32 v132, v56, v141
	v_mul_f32_e32 v56, v56, v140
	v_fma_f32 v56, -v60, v141, v56
	v_fma_f32 v60, v60, v140, v132
	v_mul_f32_e32 v133, v57, v145
	v_mul_f32_e32 v57, v57, v144
	v_fma_f32 v57, -v61, v145, v57
	v_fma_f32 v61, v61, v144, v133
	v_mul_f32_e32 v132, v58, v149
	v_mul_f32_e32 v58, v58, v148
	v_fma_f32 v58, -v62, v149, v58
	v_fma_f32 v62, v62, v148, v132
	v_mul_f32_e32 v133, v59, v153
	v_mul_f32_e32 v59, v59, v152
	v_fma_f32 v59, -v63, v153, v59
	v_fma_f32 v63, v63, v152, v133
	v_add_f32_e32 v88, v88, v170
	v_add_f32_e32 v92, v92, v171
	v_mul_f32_e32 v132, v92, v155
	v_mul_f32_e32 v171, v88, v155
	v_fma_f32 v170, v88, v154, -v132
	v_fma_f32 v171, v92, v154, v171
	v_add_f32_e32 v89, v89, v172
	v_add_f32_e32 v93, v93, v173
	v_mul_f32_e32 v133, v93, v159
	v_mul_f32_e32 v173, v89, v159
	v_fma_f32 v172, v89, v158, -v133
	v_fma_f32 v173, v93, v158, v173
	v_add_f32_e32 v90, v90, v174
	v_add_f32_e32 v94, v94, v175
	v_mul_f32_e32 v132, v94, v163
	v_mul_f32_e32 v175, v90, v163
	v_fma_f32 v174, v90, v162, -v132
	v_fma_f32 v175, v94, v162, v175
	v_add_f32_e32 v91, v91, v176
	v_add_f32_e32 v95, v95, v177
	v_mul_f32_e32 v133, v95, v167
	v_mul_f32_e32 v177, v91, v167
	v_fma_f32 v176, v91, v166, -v133
	v_fma_f32 v177, v95, v166, v177
	v_mul_f32_e32 v132, v48, v139
	v_mul_f32_e32 v48, v48, v138
	v_fma_f32 v48, -v52, v139, v48
	v_fma_f32 v52, v52, v138, v132
	v_mul_f32_e32 v133, v49, v143
	v_mul_f32_e32 v49, v49, v142
	v_fma_f32 v49, -v53, v143, v49
	v_fma_f32 v53, v53, v142, v133
	v_mul_f32_e32 v132, v50, v147
	v_mul_f32_e32 v50, v50, v146
	v_fma_f32 v50, -v54, v147, v50
	v_fma_f32 v54, v54, v146, v132
	v_mul_f32_e32 v133, v51, v151
	v_mul_f32_e32 v51, v51, v150
	v_fma_f32 v51, -v55, v151, v51
	v_fma_f32 v55, v55, v150, v133
	v_add_f32_dpp v48, v48, v48 row_shl:1 row_mask:0xf bank_mask:0xf bound_ctrl:1
	v_add_f32_dpp v49, v49, v49 row_shl:1 row_mask:0xf bank_mask:0xf bound_ctrl:1
	v_add_f32_dpp v50, v50, v50 row_shl:1 row_mask:0xf bank_mask:0xf bound_ctrl:1
	v_add_f32_dpp v51, v51, v51 row_shl:1 row_mask:0xf bank_mask:0xf bound_ctrl:1
	v_add_f32_dpp v52, v52, v52 row_shl:1 row_mask:0xf bank_mask:0xf bound_ctrl:1
	v_add_f32_dpp v53, v53, v53 row_shl:1 row_mask:0xf bank_mask:0xf bound_ctrl:1
	v_add_f32_dpp v54, v54, v54 row_shl:1 row_mask:0xf bank_mask:0xf bound_ctrl:1
	v_add_f32_dpp v55, v55, v55 row_shl:1 row_mask:0xf bank_mask:0xf bound_ctrl:1
	v_add_f32_dpp v48, v48, v48 row_shl:2 row_mask:0xf bank_mask:0xf bound_ctrl:1
	v_add_f32_dpp v49, v49, v49 row_shl:2 row_mask:0xf bank_mask:0xf bound_ctrl:1
	v_add_f32_dpp v50, v50, v50 row_shl:2 row_mask:0xf bank_mask:0xf bound_ctrl:1
	v_add_f32_dpp v51, v51, v51 row_shl:2 row_mask:0xf bank_mask:0xf bound_ctrl:1
	v_add_f32_dpp v52, v52, v52 row_shl:2 row_mask:0xf bank_mask:0xf bound_ctrl:1
	v_add_f32_dpp v53, v53, v53 row_shl:2 row_mask:0xf bank_mask:0xf bound_ctrl:1
	v_add_f32_dpp v54, v54, v54 row_shl:2 row_mask:0xf bank_mask:0xf bound_ctrl:1
	v_add_f32_dpp v55, v55, v55 row_shl:2 row_mask:0xf bank_mask:0xf bound_ctrl:1
	v_add_f32_dpp v48, v48, v48 row_shl:4 row_mask:0xf bank_mask:0xf bound_ctrl:1
	v_add_f32_dpp v49, v49, v49 row_shl:4 row_mask:0xf bank_mask:0xf bound_ctrl:1
	v_add_f32_dpp v50, v50, v50 row_shl:4 row_mask:0xf bank_mask:0xf bound_ctrl:1
	v_add_f32_dpp v51, v51, v51 row_shl:4 row_mask:0xf bank_mask:0xf bound_ctrl:1
	v_add_f32_dpp v52, v52, v52 row_shl:4 row_mask:0xf bank_mask:0xf bound_ctrl:1
	v_add_f32_dpp v53, v53, v53 row_shl:4 row_mask:0xf bank_mask:0xf bound_ctrl:1
	v_add_f32_dpp v54, v54, v54 row_shl:4 row_mask:0xf bank_mask:0xf bound_ctrl:1
	v_add_f32_dpp v55, v55, v55 row_shl:4 row_mask:0xf bank_mask:0xf bound_ctrl:1
	v_add_f32_dpp v48, v48, v48 row_shl:8 row_mask:0xf bank_mask:0xf bound_ctrl:1
	v_add_f32_dpp v49, v49, v49 row_shl:8 row_mask:0xf bank_mask:0xf bound_ctrl:1
	v_add_f32_dpp v50, v50, v50 row_shl:8 row_mask:0xf bank_mask:0xf bound_ctrl:1
	v_add_f32_dpp v51, v51, v51 row_shl:8 row_mask:0xf bank_mask:0xf bound_ctrl:1
	v_add_f32_dpp v52, v52, v52 row_shl:8 row_mask:0xf bank_mask:0xf bound_ctrl:1
	v_add_f32_dpp v53, v53, v53 row_shl:8 row_mask:0xf bank_mask:0xf bound_ctrl:1
	v_add_f32_dpp v54, v54, v54 row_shl:8 row_mask:0xf bank_mask:0xf bound_ctrl:1
	v_add_f32_dpp v55, v55, v55 row_shl:8 row_mask:0xf bank_mask:0xf bound_ctrl:1
	v_mov_b32_dpp v88, v48 row_newbcast:0 row_mask:0xf bank_mask:0xf
	v_mov_b32_dpp v89, v49 row_newbcast:0 row_mask:0xf bank_mask:0xf
	v_mov_b32_dpp v90, v50 row_newbcast:0 row_mask:0xf bank_mask:0xf
	v_mov_b32_dpp v91, v51 row_newbcast:0 row_mask:0xf bank_mask:0xf
	v_mov_b32_dpp v92, v52 row_newbcast:0 row_mask:0xf bank_mask:0xf
	v_mov_b32_dpp v93, v53 row_newbcast:0 row_mask:0xf bank_mask:0xf
	v_mov_b32_dpp v94, v54 row_newbcast:0 row_mask:0xf bank_mask:0xf
	v_mov_b32_dpp v95, v55 row_newbcast:0 row_mask:0xf bank_mask:0xf
	v_add_f32_e32 v48, v48, v170
	v_add_f32_e32 v52, v52, v171
	v_add_f32_e32 v49, v49, v172
	v_add_f32_e32 v53, v53, v173
	v_add_f32_e32 v50, v50, v174
	v_add_f32_e32 v54, v54, v175
	v_add_f32_e32 v51, v51, v176
	v_add_f32_e32 v55, v55, v177
	v_mul_f32_e32 v132, v48, v141
	v_mul_f32_e32 v48, v48, v140
	v_fma_f32 v48, -v52, v141, v48
	v_fma_f32 v52, v52, v140, v132
	v_mul_f32_e32 v133, v49, v145
	v_mul_f32_e32 v49, v49, v144
	v_fma_f32 v49, -v53, v145, v49
	v_fma_f32 v53, v53, v144, v133
	v_mul_f32_e32 v132, v50, v149
	v_mul_f32_e32 v50, v50, v148
	v_fma_f32 v50, -v54, v149, v50
	v_fma_f32 v54, v54, v148, v132
	v_mul_f32_e32 v133, v51, v153
	v_mul_f32_e32 v51, v51, v152
	v_fma_f32 v51, -v55, v153, v51
	v_fma_f32 v55, v55, v152, v133
	v_add_f32_e32 v88, v88, v170
	v_add_f32_e32 v92, v92, v171
	v_mul_f32_e32 v132, v92, v155
	v_mul_f32_e32 v171, v88, v155
	v_fma_f32 v170, v88, v154, -v132
	v_fma_f32 v171, v92, v154, v171
	v_add_f32_e32 v89, v89, v172
	v_add_f32_e32 v93, v93, v173
	v_mul_f32_e32 v133, v93, v159
	v_mul_f32_e32 v173, v89, v159
	v_fma_f32 v172, v89, v158, -v133
	v_fma_f32 v173, v93, v158, v173
	v_add_f32_e32 v90, v90, v174
	v_add_f32_e32 v94, v94, v175
	v_mul_f32_e32 v132, v94, v163
	v_mul_f32_e32 v175, v90, v163
	v_fma_f32 v174, v90, v162, -v132
	v_fma_f32 v175, v94, v162, v175
	v_add_f32_e32 v91, v91, v176
	v_add_f32_e32 v95, v95, v177
	v_mul_f32_e32 v133, v95, v167
	v_mul_f32_e32 v177, v91, v167
	v_fma_f32 v176, v91, v166, -v133
	v_fma_f32 v177, v95, v166, v177
	v_mul_f32_e32 v132, v40, v139
	v_mul_f32_e32 v40, v40, v138
	v_fma_f32 v40, -v44, v139, v40
	v_fma_f32 v44, v44, v138, v132
	v_mul_f32_e32 v133, v41, v143
	v_mul_f32_e32 v41, v41, v142
	v_fma_f32 v41, -v45, v143, v41
	v_fma_f32 v45, v45, v142, v133
	v_mul_f32_e32 v132, v42, v147
	v_mul_f32_e32 v42, v42, v146
	v_fma_f32 v42, -v46, v147, v42
	v_fma_f32 v46, v46, v146, v132
	v_mul_f32_e32 v133, v43, v151
	v_mul_f32_e32 v43, v43, v150
	v_fma_f32 v43, -v47, v151, v43
	v_fma_f32 v47, v47, v150, v133
	v_add_f32_dpp v40, v40, v40 row_shl:1 row_mask:0xf bank_mask:0xf bound_ctrl:1
	v_add_f32_dpp v41, v41, v41 row_shl:1 row_mask:0xf bank_mask:0xf bound_ctrl:1
	v_add_f32_dpp v42, v42, v42 row_shl:1 row_mask:0xf bank_mask:0xf bound_ctrl:1
	v_add_f32_dpp v43, v43, v43 row_shl:1 row_mask:0xf bank_mask:0xf bound_ctrl:1
	v_add_f32_dpp v44, v44, v44 row_shl:1 row_mask:0xf bank_mask:0xf bound_ctrl:1
	v_add_f32_dpp v45, v45, v45 row_shl:1 row_mask:0xf bank_mask:0xf bound_ctrl:1
	v_add_f32_dpp v46, v46, v46 row_shl:1 row_mask:0xf bank_mask:0xf bound_ctrl:1
	v_add_f32_dpp v47, v47, v47 row_shl:1 row_mask:0xf bank_mask:0xf bound_ctrl:1
	v_add_f32_dpp v40, v40, v40 row_shl:2 row_mask:0xf bank_mask:0xf bound_ctrl:1
	v_add_f32_dpp v41, v41, v41 row_shl:2 row_mask:0xf bank_mask:0xf bound_ctrl:1
	v_add_f32_dpp v42, v42, v42 row_shl:2 row_mask:0xf bank_mask:0xf bound_ctrl:1
	v_add_f32_dpp v43, v43, v43 row_shl:2 row_mask:0xf bank_mask:0xf bound_ctrl:1
	v_add_f32_dpp v44, v44, v44 row_shl:2 row_mask:0xf bank_mask:0xf bound_ctrl:1
	v_add_f32_dpp v45, v45, v45 row_shl:2 row_mask:0xf bank_mask:0xf bound_ctrl:1
	v_add_f32_dpp v46, v46, v46 row_shl:2 row_mask:0xf bank_mask:0xf bound_ctrl:1
	v_add_f32_dpp v47, v47, v47 row_shl:2 row_mask:0xf bank_mask:0xf bound_ctrl:1
	v_add_f32_dpp v40, v40, v40 row_shl:4 row_mask:0xf bank_mask:0xf bound_ctrl:1
	v_add_f32_dpp v41, v41, v41 row_shl:4 row_mask:0xf bank_mask:0xf bound_ctrl:1
	v_add_f32_dpp v42, v42, v42 row_shl:4 row_mask:0xf bank_mask:0xf bound_ctrl:1
	v_add_f32_dpp v43, v43, v43 row_shl:4 row_mask:0xf bank_mask:0xf bound_ctrl:1
	v_add_f32_dpp v44, v44, v44 row_shl:4 row_mask:0xf bank_mask:0xf bound_ctrl:1
	v_add_f32_dpp v45, v45, v45 row_shl:4 row_mask:0xf bank_mask:0xf bound_ctrl:1
	v_add_f32_dpp v46, v46, v46 row_shl:4 row_mask:0xf bank_mask:0xf bound_ctrl:1
	v_add_f32_dpp v47, v47, v47 row_shl:4 row_mask:0xf bank_mask:0xf bound_ctrl:1
	v_add_f32_dpp v40, v40, v40 row_shl:8 row_mask:0xf bank_mask:0xf bound_ctrl:1
	v_add_f32_dpp v41, v41, v41 row_shl:8 row_mask:0xf bank_mask:0xf bound_ctrl:1
	v_add_f32_dpp v42, v42, v42 row_shl:8 row_mask:0xf bank_mask:0xf bound_ctrl:1
	v_add_f32_dpp v43, v43, v43 row_shl:8 row_mask:0xf bank_mask:0xf bound_ctrl:1
	v_add_f32_dpp v44, v44, v44 row_shl:8 row_mask:0xf bank_mask:0xf bound_ctrl:1
	v_add_f32_dpp v45, v45, v45 row_shl:8 row_mask:0xf bank_mask:0xf bound_ctrl:1
	v_add_f32_dpp v46, v46, v46 row_shl:8 row_mask:0xf bank_mask:0xf bound_ctrl:1
	v_add_f32_dpp v47, v47, v47 row_shl:8 row_mask:0xf bank_mask:0xf bound_ctrl:1
	v_mov_b32_dpp v88, v40 row_newbcast:0 row_mask:0xf bank_mask:0xf
	v_mov_b32_dpp v89, v41 row_newbcast:0 row_mask:0xf bank_mask:0xf
	v_mov_b32_dpp v90, v42 row_newbcast:0 row_mask:0xf bank_mask:0xf
	v_mov_b32_dpp v91, v43 row_newbcast:0 row_mask:0xf bank_mask:0xf
	v_mov_b32_dpp v92, v44 row_newbcast:0 row_mask:0xf bank_mask:0xf
	v_mov_b32_dpp v93, v45 row_newbcast:0 row_mask:0xf bank_mask:0xf
	v_mov_b32_dpp v94, v46 row_newbcast:0 row_mask:0xf bank_mask:0xf
	v_mov_b32_dpp v95, v47 row_newbcast:0 row_mask:0xf bank_mask:0xf
	v_add_f32_e32 v40, v40, v170
	v_add_f32_e32 v44, v44, v171
	v_add_f32_e32 v41, v41, v172
	v_add_f32_e32 v45, v45, v173
	v_add_f32_e32 v42, v42, v174
	v_add_f32_e32 v46, v46, v175
	v_add_f32_e32 v43, v43, v176
	v_add_f32_e32 v47, v47, v177
	v_mul_f32_e32 v132, v40, v141
	v_mul_f32_e32 v40, v40, v140
	v_fma_f32 v40, -v44, v141, v40
	v_fma_f32 v44, v44, v140, v132
	v_mul_f32_e32 v133, v41, v145
	v_mul_f32_e32 v41, v41, v144
	v_fma_f32 v41, -v45, v145, v41
	v_fma_f32 v45, v45, v144, v133
	v_mul_f32_e32 v132, v42, v149
	v_mul_f32_e32 v42, v42, v148
	v_fma_f32 v42, -v46, v149, v42
	v_fma_f32 v46, v46, v148, v132
	v_mul_f32_e32 v133, v43, v153
	v_mul_f32_e32 v43, v43, v152
	v_fma_f32 v43, -v47, v153, v43
	v_fma_f32 v47, v47, v152, v133
	v_add_f32_e32 v88, v88, v170
	v_add_f32_e32 v92, v92, v171
	v_mul_f32_e32 v132, v92, v155
	v_mul_f32_e32 v171, v88, v155
	v_fma_f32 v170, v88, v154, -v132
	v_fma_f32 v171, v92, v154, v171
	v_add_f32_e32 v89, v89, v172
	v_add_f32_e32 v93, v93, v173
	v_mul_f32_e32 v133, v93, v159
	v_mul_f32_e32 v173, v89, v159
	v_fma_f32 v172, v89, v158, -v133
	v_fma_f32 v173, v93, v158, v173
	v_add_f32_e32 v90, v90, v174
	v_add_f32_e32 v94, v94, v175
	v_mul_f32_e32 v132, v94, v163
	v_mul_f32_e32 v175, v90, v163
	v_fma_f32 v174, v90, v162, -v132
	v_fma_f32 v175, v94, v162, v175
	v_add_f32_e32 v91, v91, v176
	v_add_f32_e32 v95, v95, v177
	v_mul_f32_e32 v133, v95, v167
	v_mul_f32_e32 v177, v91, v167
	v_fma_f32 v176, v91, v166, -v133
	v_fma_f32 v177, v95, v166, v177
	v_mul_f32_e32 v132, v32, v139
	v_mul_f32_e32 v32, v32, v138
	v_fma_f32 v32, -v36, v139, v32
	v_fma_f32 v36, v36, v138, v132
	v_mul_f32_e32 v133, v33, v143
	v_mul_f32_e32 v33, v33, v142
	v_fma_f32 v33, -v37, v143, v33
	v_fma_f32 v37, v37, v142, v133
	v_mul_f32_e32 v132, v34, v147
	v_mul_f32_e32 v34, v34, v146
	v_fma_f32 v34, -v38, v147, v34
	v_fma_f32 v38, v38, v146, v132
	v_mul_f32_e32 v133, v35, v151
	v_mul_f32_e32 v35, v35, v150
	v_fma_f32 v35, -v39, v151, v35
	v_fma_f32 v39, v39, v150, v133
	v_add_f32_dpp v32, v32, v32 row_shl:1 row_mask:0xf bank_mask:0xf bound_ctrl:1
	v_add_f32_dpp v33, v33, v33 row_shl:1 row_mask:0xf bank_mask:0xf bound_ctrl:1
	v_add_f32_dpp v34, v34, v34 row_shl:1 row_mask:0xf bank_mask:0xf bound_ctrl:1
	v_add_f32_dpp v35, v35, v35 row_shl:1 row_mask:0xf bank_mask:0xf bound_ctrl:1
	v_add_f32_dpp v36, v36, v36 row_shl:1 row_mask:0xf bank_mask:0xf bound_ctrl:1
	v_add_f32_dpp v37, v37, v37 row_shl:1 row_mask:0xf bank_mask:0xf bound_ctrl:1
	v_add_f32_dpp v38, v38, v38 row_shl:1 row_mask:0xf bank_mask:0xf bound_ctrl:1
	v_add_f32_dpp v39, v39, v39 row_shl:1 row_mask:0xf bank_mask:0xf bound_ctrl:1
	v_add_f32_dpp v32, v32, v32 row_shl:2 row_mask:0xf bank_mask:0xf bound_ctrl:1
	v_add_f32_dpp v33, v33, v33 row_shl:2 row_mask:0xf bank_mask:0xf bound_ctrl:1
	v_add_f32_dpp v34, v34, v34 row_shl:2 row_mask:0xf bank_mask:0xf bound_ctrl:1
	v_add_f32_dpp v35, v35, v35 row_shl:2 row_mask:0xf bank_mask:0xf bound_ctrl:1
	v_add_f32_dpp v36, v36, v36 row_shl:2 row_mask:0xf bank_mask:0xf bound_ctrl:1
	v_add_f32_dpp v37, v37, v37 row_shl:2 row_mask:0xf bank_mask:0xf bound_ctrl:1
	v_add_f32_dpp v38, v38, v38 row_shl:2 row_mask:0xf bank_mask:0xf bound_ctrl:1
	v_add_f32_dpp v39, v39, v39 row_shl:2 row_mask:0xf bank_mask:0xf bound_ctrl:1
	v_add_f32_dpp v32, v32, v32 row_shl:4 row_mask:0xf bank_mask:0xf bound_ctrl:1
	v_add_f32_dpp v33, v33, v33 row_shl:4 row_mask:0xf bank_mask:0xf bound_ctrl:1
	v_add_f32_dpp v34, v34, v34 row_shl:4 row_mask:0xf bank_mask:0xf bound_ctrl:1
	v_add_f32_dpp v35, v35, v35 row_shl:4 row_mask:0xf bank_mask:0xf bound_ctrl:1
	v_add_f32_dpp v36, v36, v36 row_shl:4 row_mask:0xf bank_mask:0xf bound_ctrl:1
	v_add_f32_dpp v37, v37, v37 row_shl:4 row_mask:0xf bank_mask:0xf bound_ctrl:1
	v_add_f32_dpp v38, v38, v38 row_shl:4 row_mask:0xf bank_mask:0xf bound_ctrl:1
	v_add_f32_dpp v39, v39, v39 row_shl:4 row_mask:0xf bank_mask:0xf bound_ctrl:1
	v_add_f32_dpp v32, v32, v32 row_shl:8 row_mask:0xf bank_mask:0xf bound_ctrl:1
	v_add_f32_dpp v33, v33, v33 row_shl:8 row_mask:0xf bank_mask:0xf bound_ctrl:1
	v_add_f32_dpp v34, v34, v34 row_shl:8 row_mask:0xf bank_mask:0xf bound_ctrl:1
	v_add_f32_dpp v35, v35, v35 row_shl:8 row_mask:0xf bank_mask:0xf bound_ctrl:1
	v_add_f32_dpp v36, v36, v36 row_shl:8 row_mask:0xf bank_mask:0xf bound_ctrl:1
	v_add_f32_dpp v37, v37, v37 row_shl:8 row_mask:0xf bank_mask:0xf bound_ctrl:1
	v_add_f32_dpp v38, v38, v38 row_shl:8 row_mask:0xf bank_mask:0xf bound_ctrl:1
	v_add_f32_dpp v39, v39, v39 row_shl:8 row_mask:0xf bank_mask:0xf bound_ctrl:1
	v_mov_b32_dpp v88, v32 row_newbcast:0 row_mask:0xf bank_mask:0xf
	v_mov_b32_dpp v89, v33 row_newbcast:0 row_mask:0xf bank_mask:0xf
	v_mov_b32_dpp v90, v34 row_newbcast:0 row_mask:0xf bank_mask:0xf
	v_mov_b32_dpp v91, v35 row_newbcast:0 row_mask:0xf bank_mask:0xf
	v_mov_b32_dpp v92, v36 row_newbcast:0 row_mask:0xf bank_mask:0xf
	v_mov_b32_dpp v93, v37 row_newbcast:0 row_mask:0xf bank_mask:0xf
	v_mov_b32_dpp v94, v38 row_newbcast:0 row_mask:0xf bank_mask:0xf
	v_mov_b32_dpp v95, v39 row_newbcast:0 row_mask:0xf bank_mask:0xf
	v_add_f32_e32 v32, v32, v170
	v_add_f32_e32 v36, v36, v171
	v_add_f32_e32 v33, v33, v172
	v_add_f32_e32 v37, v37, v173
	v_add_f32_e32 v34, v34, v174
	v_add_f32_e32 v38, v38, v175
	v_add_f32_e32 v35, v35, v176
	v_add_f32_e32 v39, v39, v177
	v_mul_f32_e32 v132, v32, v141
	v_mul_f32_e32 v32, v32, v140
	v_fma_f32 v32, -v36, v141, v32
	v_fma_f32 v36, v36, v140, v132
	v_mul_f32_e32 v133, v33, v145
	v_mul_f32_e32 v33, v33, v144
	v_fma_f32 v33, -v37, v145, v33
	v_fma_f32 v37, v37, v144, v133
	v_mul_f32_e32 v132, v34, v149
	v_mul_f32_e32 v34, v34, v148
	v_fma_f32 v34, -v38, v149, v34
	v_fma_f32 v38, v38, v148, v132
	v_mul_f32_e32 v133, v35, v153
	v_mul_f32_e32 v35, v35, v152
	v_fma_f32 v35, -v39, v153, v35
	v_fma_f32 v39, v39, v152, v133
	v_add_f32_e32 v88, v88, v170
	v_add_f32_e32 v92, v92, v171
	v_mul_f32_e32 v132, v92, v155
	v_mul_f32_e32 v171, v88, v155
	v_fma_f32 v170, v88, v154, -v132
	v_fma_f32 v171, v92, v154, v171
	v_add_f32_e32 v89, v89, v172
	v_add_f32_e32 v93, v93, v173
	v_mul_f32_e32 v133, v93, v159
	v_mul_f32_e32 v173, v89, v159
	v_fma_f32 v172, v89, v158, -v133
	v_fma_f32 v173, v93, v158, v173
	v_add_f32_e32 v90, v90, v174
	v_add_f32_e32 v94, v94, v175
	v_mul_f32_e32 v132, v94, v163
	v_mul_f32_e32 v175, v90, v163
	v_fma_f32 v174, v90, v162, -v132
	v_fma_f32 v175, v94, v162, v175
	v_add_f32_e32 v91, v91, v176
	v_add_f32_e32 v95, v95, v177
	v_mul_f32_e32 v133, v95, v167
	v_mul_f32_e32 v177, v91, v167
	v_fma_f32 v176, v91, v166, -v133
	v_fma_f32 v177, v95, v166, v177
	s_waitcnt vmcnt(12)
	v_cvt_pk_bf16_f32 v96, v32, v33
	v_cvt_pk_bf16_f32 v97, v34, v35
	v_cvt_pk_bf16_f32 v98, v36, v37
	v_cvt_pk_bf16_f32 v99, v38, v39
	s_nop 1
	v_mfma_f32_16x16x32_bf16 v[16:19], v[80:83], v[96:99], v[16:19]
	v_cvt_pk_bf16_f32 v96, v40, v41
	v_cvt_pk_bf16_f32 v97, v42, v43
	v_cvt_pk_bf16_f32 v98, v44, v45
	v_cvt_pk_bf16_f32 v99, v46, v47
	s_nop 1
	v_mfma_f32_16x16x32_bf16 v[20:23], v[80:83], v[96:99], v[20:23]
	v_cvt_pk_bf16_f32 v96, v48, v49
	v_cvt_pk_bf16_f32 v97, v50, v51
	v_cvt_pk_bf16_f32 v98, v52, v53
	v_cvt_pk_bf16_f32 v99, v54, v55
	s_nop 1
	v_mfma_f32_16x16x32_bf16 v[24:27], v[80:83], v[96:99], v[24:27]
	v_cvt_pk_bf16_f32 v96, v56, v57
	v_cvt_pk_bf16_f32 v97, v58, v59
	v_cvt_pk_bf16_f32 v98, v60, v61
	v_cvt_pk_bf16_f32 v99, v62, v63
	s_nop 1
	v_mfma_f32_16x16x32_bf16 v[28:31], v[80:83], v[96:99], v[28:31]
	s_waitcnt vmcnt(10)
	global_load_dwordx4 v[80:83], v134, s[38:39]
	v_mfma_f32_16x16x32_bf16 v[32:35], v[64:67], v[0:3], 0
	v_mfma_f32_16x16x32_bf16 v[36:39], v[72:75], v[0:3], 0
	v_mfma_f32_16x16x32_bf16 v[40:43], v[64:67], v[4:7], 0
	v_mfma_f32_16x16x32_bf16 v[44:47], v[72:75], v[4:7], 0
	v_mfma_f32_16x16x32_bf16 v[48:51], v[64:67], v[8:11], 0
	v_mfma_f32_16x16x32_bf16 v[52:55], v[72:75], v[8:11], 0
	v_mfma_f32_16x16x32_bf16 v[56:59], v[64:67], v[12:15], 0
	v_mfma_f32_16x16x32_bf16 v[60:63], v[72:75], v[12:15], 0
	s_waitcnt vmcnt(1)
	v_mul_f32_e32 v132, v179, v119
	v_mul_f32_e32 v133, v178, v119
	v_fma_f32 v178, v178, v118, -v132
	v_fma_f32 v179, v179, v118, v133
	v_mul_f32_e32 v132, v181, v123
	v_mul_f32_e32 v133, v180, v123
	v_fma_f32 v180, v180, v122, -v132
	v_fma_f32 v181, v181, v122, v133
	v_mul_f32_e32 v132, v183, v127
	v_mul_f32_e32 v133, v182, v127
	v_fma_f32 v182, v182, v126, -v132
	v_fma_f32 v183, v183, v126, v133
	v_mul_f32_e32 v132, v185, v131
	v_mul_f32_e32 v133, v184, v131
	v_fma_f32 v184, v184, v130, -v132
	v_fma_f32 v185, v185, v130, v133
	v_mul_f32_e32 v132, v56, v101
	v_mul_f32_e32 v56, v56, v100
	v_fma_f32 v56, -v60, v101, v56
	v_fma_f32 v60, v60, v100, v132
	v_mul_f32_e32 v133, v57, v105
	v_mul_f32_e32 v57, v57, v104
	v_fma_f32 v57, -v61, v105, v57
	v_fma_f32 v61, v61, v104, v133
	v_mul_f32_e32 v132, v58, v109
	v_mul_f32_e32 v58, v58, v108
	v_fma_f32 v58, -v62, v109, v58
	v_fma_f32 v62, v62, v108, v132
	v_mul_f32_e32 v133, v59, v113
	v_mul_f32_e32 v59, v59, v112
	v_fma_f32 v59, -v63, v113, v59
	v_fma_f32 v63, v63, v112, v133
	v_add_f32_dpp v56, v56, v56 row_shl:1 row_mask:0xf bank_mask:0xf bound_ctrl:1
	v_add_f32_dpp v57, v57, v57 row_shl:1 row_mask:0xf bank_mask:0xf bound_ctrl:1
	v_add_f32_dpp v58, v58, v58 row_shl:1 row_mask:0xf bank_mask:0xf bound_ctrl:1
	v_add_f32_dpp v59, v59, v59 row_shl:1 row_mask:0xf bank_mask:0xf bound_ctrl:1
	v_add_f32_dpp v60, v60, v60 row_shl:1 row_mask:0xf bank_mask:0xf bound_ctrl:1
	v_add_f32_dpp v61, v61, v61 row_shl:1 row_mask:0xf bank_mask:0xf bound_ctrl:1
	v_add_f32_dpp v62, v62, v62 row_shl:1 row_mask:0xf bank_mask:0xf bound_ctrl:1
	v_add_f32_dpp v63, v63, v63 row_shl:1 row_mask:0xf bank_mask:0xf bound_ctrl:1
	v_add_f32_dpp v56, v56, v56 row_shl:2 row_mask:0xf bank_mask:0xf bound_ctrl:1
	v_add_f32_dpp v57, v57, v57 row_shl:2 row_mask:0xf bank_mask:0xf bound_ctrl:1
	v_add_f32_dpp v58, v58, v58 row_shl:2 row_mask:0xf bank_mask:0xf bound_ctrl:1
	v_add_f32_dpp v59, v59, v59 row_shl:2 row_mask:0xf bank_mask:0xf bound_ctrl:1
	v_add_f32_dpp v60, v60, v60 row_shl:2 row_mask:0xf bank_mask:0xf bound_ctrl:1
	v_add_f32_dpp v61, v61, v61 row_shl:2 row_mask:0xf bank_mask:0xf bound_ctrl:1
	v_add_f32_dpp v62, v62, v62 row_shl:2 row_mask:0xf bank_mask:0xf bound_ctrl:1
	v_add_f32_dpp v63, v63, v63 row_shl:2 row_mask:0xf bank_mask:0xf bound_ctrl:1
	v_add_f32_dpp v56, v56, v56 row_shl:4 row_mask:0xf bank_mask:0xf bound_ctrl:1
	v_add_f32_dpp v57, v57, v57 row_shl:4 row_mask:0xf bank_mask:0xf bound_ctrl:1
	v_add_f32_dpp v58, v58, v58 row_shl:4 row_mask:0xf bank_mask:0xf bound_ctrl:1
	v_add_f32_dpp v59, v59, v59 row_shl:4 row_mask:0xf bank_mask:0xf bound_ctrl:1
	v_add_f32_dpp v60, v60, v60 row_shl:4 row_mask:0xf bank_mask:0xf bound_ctrl:1
	v_add_f32_dpp v61, v61, v61 row_shl:4 row_mask:0xf bank_mask:0xf bound_ctrl:1
	v_add_f32_dpp v62, v62, v62 row_shl:4 row_mask:0xf bank_mask:0xf bound_ctrl:1
	v_add_f32_dpp v63, v63, v63 row_shl:4 row_mask:0xf bank_mask:0xf bound_ctrl:1
	v_add_f32_dpp v56, v56, v56 row_shl:8 row_mask:0xf bank_mask:0xf bound_ctrl:1
	v_add_f32_dpp v57, v57, v57 row_shl:8 row_mask:0xf bank_mask:0xf bound_ctrl:1
	v_add_f32_dpp v58, v58, v58 row_shl:8 row_mask:0xf bank_mask:0xf bound_ctrl:1
	v_add_f32_dpp v59, v59, v59 row_shl:8 row_mask:0xf bank_mask:0xf bound_ctrl:1
	v_add_f32_dpp v60, v60, v60 row_shl:8 row_mask:0xf bank_mask:0xf bound_ctrl:1
	v_add_f32_dpp v61, v61, v61 row_shl:8 row_mask:0xf bank_mask:0xf bound_ctrl:1
	v_add_f32_dpp v62, v62, v62 row_shl:8 row_mask:0xf bank_mask:0xf bound_ctrl:1
	v_add_f32_dpp v63, v63, v63 row_shl:8 row_mask:0xf bank_mask:0xf bound_ctrl:1
	v_mov_b32_dpp v88, v56 row_newbcast:0 row_mask:0xf bank_mask:0xf
	v_mov_b32_dpp v89, v57 row_newbcast:0 row_mask:0xf bank_mask:0xf
	v_mov_b32_dpp v90, v58 row_newbcast:0 row_mask:0xf bank_mask:0xf
	v_mov_b32_dpp v91, v59 row_newbcast:0 row_mask:0xf bank_mask:0xf
	v_mov_b32_dpp v92, v60 row_newbcast:0 row_mask:0xf bank_mask:0xf
	v_mov_b32_dpp v93, v61 row_newbcast:0 row_mask:0xf bank_mask:0xf
	v_mov_b32_dpp v94, v62 row_newbcast:0 row_mask:0xf bank_mask:0xf
	v_mov_b32_dpp v95, v63 row_newbcast:0 row_mask:0xf bank_mask:0xf
	v_add_f32_e32 v56, v56, v178
	v_add_f32_e32 v60, v60, v179
	v_add_f32_e32 v57, v57, v180
	v_add_f32_e32 v61, v61, v181
	v_add_f32_e32 v58, v58, v182
	v_add_f32_e32 v62, v62, v183
	v_add_f32_e32 v59, v59, v184
	v_add_f32_e32 v63, v63, v185
	v_mul_f32_e32 v132, v56, v103
	v_mul_f32_e32 v56, v56, v102
	v_fma_f32 v56, -v60, v103, v56
	v_fma_f32 v60, v60, v102, v132
	v_mul_f32_e32 v133, v57, v107
	v_mul_f32_e32 v57, v57, v106
	v_fma_f32 v57, -v61, v107, v57
	v_fma_f32 v61, v61, v106, v133
	v_mul_f32_e32 v132, v58, v111
	v_mul_f32_e32 v58, v58, v110
	v_fma_f32 v58, -v62, v111, v58
	v_fma_f32 v62, v62, v110, v132
	v_mul_f32_e32 v133, v59, v115
	v_mul_f32_e32 v59, v59, v114
	v_fma_f32 v59, -v63, v115, v59
	v_fma_f32 v63, v63, v114, v133
	v_add_f32_e32 v88, v88, v178
	v_add_f32_e32 v92, v92, v179
	v_mul_f32_e32 v132, v92, v117
	v_mul_f32_e32 v179, v88, v117
	v_fma_f32 v178, v88, v116, -v132
	v_fma_f32 v179, v92, v116, v179
	v_add_f32_e32 v89, v89, v180
	v_add_f32_e32 v93, v93, v181
	v_mul_f32_e32 v133, v93, v121
	v_mul_f32_e32 v181, v89, v121
	v_fma_f32 v180, v89, v120, -v133
	v_fma_f32 v181, v93, v120, v181
	v_add_f32_e32 v90, v90, v182
	v_add_f32_e32 v94, v94, v183
	v_mul_f32_e32 v132, v94, v125
	v_mul_f32_e32 v183, v90, v125
	v_fma_f32 v182, v90, v124, -v132
	v_fma_f32 v183, v94, v124, v183
	v_add_f32_e32 v91, v91, v184
	v_add_f32_e32 v95, v95, v185
	v_mul_f32_e32 v133, v95, v129
	v_mul_f32_e32 v185, v91, v129
	v_fma_f32 v184, v91, v128, -v133
	v_fma_f32 v185, v95, v128, v185
	v_mul_f32_e32 v132, v48, v101
	v_mul_f32_e32 v48, v48, v100
	v_fma_f32 v48, -v52, v101, v48
	v_fma_f32 v52, v52, v100, v132
	v_mul_f32_e32 v133, v49, v105
	v_mul_f32_e32 v49, v49, v104
	v_fma_f32 v49, -v53, v105, v49
	v_fma_f32 v53, v53, v104, v133
	v_mul_f32_e32 v132, v50, v109
	v_mul_f32_e32 v50, v50, v108
	v_fma_f32 v50, -v54, v109, v50
	v_fma_f32 v54, v54, v108, v132
	v_mul_f32_e32 v133, v51, v113
	v_mul_f32_e32 v51, v51, v112
	v_fma_f32 v51, -v55, v113, v51
	v_fma_f32 v55, v55, v112, v133
	v_add_f32_dpp v48, v48, v48 row_shl:1 row_mask:0xf bank_mask:0xf bound_ctrl:1
	v_add_f32_dpp v49, v49, v49 row_shl:1 row_mask:0xf bank_mask:0xf bound_ctrl:1
	v_add_f32_dpp v50, v50, v50 row_shl:1 row_mask:0xf bank_mask:0xf bound_ctrl:1
	v_add_f32_dpp v51, v51, v51 row_shl:1 row_mask:0xf bank_mask:0xf bound_ctrl:1
	v_add_f32_dpp v52, v52, v52 row_shl:1 row_mask:0xf bank_mask:0xf bound_ctrl:1
	v_add_f32_dpp v53, v53, v53 row_shl:1 row_mask:0xf bank_mask:0xf bound_ctrl:1
	v_add_f32_dpp v54, v54, v54 row_shl:1 row_mask:0xf bank_mask:0xf bound_ctrl:1
	v_add_f32_dpp v55, v55, v55 row_shl:1 row_mask:0xf bank_mask:0xf bound_ctrl:1
	v_add_f32_dpp v48, v48, v48 row_shl:2 row_mask:0xf bank_mask:0xf bound_ctrl:1
	v_add_f32_dpp v49, v49, v49 row_shl:2 row_mask:0xf bank_mask:0xf bound_ctrl:1
	v_add_f32_dpp v50, v50, v50 row_shl:2 row_mask:0xf bank_mask:0xf bound_ctrl:1
	v_add_f32_dpp v51, v51, v51 row_shl:2 row_mask:0xf bank_mask:0xf bound_ctrl:1
	v_add_f32_dpp v52, v52, v52 row_shl:2 row_mask:0xf bank_mask:0xf bound_ctrl:1
	v_add_f32_dpp v53, v53, v53 row_shl:2 row_mask:0xf bank_mask:0xf bound_ctrl:1
	v_add_f32_dpp v54, v54, v54 row_shl:2 row_mask:0xf bank_mask:0xf bound_ctrl:1
	v_add_f32_dpp v55, v55, v55 row_shl:2 row_mask:0xf bank_mask:0xf bound_ctrl:1
	v_add_f32_dpp v48, v48, v48 row_shl:4 row_mask:0xf bank_mask:0xf bound_ctrl:1
	v_add_f32_dpp v49, v49, v49 row_shl:4 row_mask:0xf bank_mask:0xf bound_ctrl:1
	v_add_f32_dpp v50, v50, v50 row_shl:4 row_mask:0xf bank_mask:0xf bound_ctrl:1
	v_add_f32_dpp v51, v51, v51 row_shl:4 row_mask:0xf bank_mask:0xf bound_ctrl:1
	v_add_f32_dpp v52, v52, v52 row_shl:4 row_mask:0xf bank_mask:0xf bound_ctrl:1
	v_add_f32_dpp v53, v53, v53 row_shl:4 row_mask:0xf bank_mask:0xf bound_ctrl:1
	v_add_f32_dpp v54, v54, v54 row_shl:4 row_mask:0xf bank_mask:0xf bound_ctrl:1
	v_add_f32_dpp v55, v55, v55 row_shl:4 row_mask:0xf bank_mask:0xf bound_ctrl:1
	v_add_f32_dpp v48, v48, v48 row_shl:8 row_mask:0xf bank_mask:0xf bound_ctrl:1
	v_add_f32_dpp v49, v49, v49 row_shl:8 row_mask:0xf bank_mask:0xf bound_ctrl:1
	v_add_f32_dpp v50, v50, v50 row_shl:8 row_mask:0xf bank_mask:0xf bound_ctrl:1
	v_add_f32_dpp v51, v51, v51 row_shl:8 row_mask:0xf bank_mask:0xf bound_ctrl:1
	v_add_f32_dpp v52, v52, v52 row_shl:8 row_mask:0xf bank_mask:0xf bound_ctrl:1
	v_add_f32_dpp v53, v53, v53 row_shl:8 row_mask:0xf bank_mask:0xf bound_ctrl:1
	v_add_f32_dpp v54, v54, v54 row_shl:8 row_mask:0xf bank_mask:0xf bound_ctrl:1
	v_add_f32_dpp v55, v55, v55 row_shl:8 row_mask:0xf bank_mask:0xf bound_ctrl:1
	v_mov_b32_dpp v88, v48 row_newbcast:0 row_mask:0xf bank_mask:0xf
	v_mov_b32_dpp v89, v49 row_newbcast:0 row_mask:0xf bank_mask:0xf
	v_mov_b32_dpp v90, v50 row_newbcast:0 row_mask:0xf bank_mask:0xf
	v_mov_b32_dpp v91, v51 row_newbcast:0 row_mask:0xf bank_mask:0xf
	v_mov_b32_dpp v92, v52 row_newbcast:0 row_mask:0xf bank_mask:0xf
	v_mov_b32_dpp v93, v53 row_newbcast:0 row_mask:0xf bank_mask:0xf
	v_mov_b32_dpp v94, v54 row_newbcast:0 row_mask:0xf bank_mask:0xf
	v_mov_b32_dpp v95, v55 row_newbcast:0 row_mask:0xf bank_mask:0xf
	v_add_f32_e32 v48, v48, v178
	v_add_f32_e32 v52, v52, v179
	v_add_f32_e32 v49, v49, v180
	v_add_f32_e32 v53, v53, v181
	v_add_f32_e32 v50, v50, v182
	v_add_f32_e32 v54, v54, v183
	v_add_f32_e32 v51, v51, v184
	v_add_f32_e32 v55, v55, v185
	v_mul_f32_e32 v132, v48, v103
	v_mul_f32_e32 v48, v48, v102
	v_fma_f32 v48, -v52, v103, v48
	v_fma_f32 v52, v52, v102, v132
	v_mul_f32_e32 v133, v49, v107
	v_mul_f32_e32 v49, v49, v106
	v_fma_f32 v49, -v53, v107, v49
	v_fma_f32 v53, v53, v106, v133
	v_mul_f32_e32 v132, v50, v111
	v_mul_f32_e32 v50, v50, v110
	v_fma_f32 v50, -v54, v111, v50
	v_fma_f32 v54, v54, v110, v132
	v_mul_f32_e32 v133, v51, v115
	v_mul_f32_e32 v51, v51, v114
	v_fma_f32 v51, -v55, v115, v51
	v_fma_f32 v55, v55, v114, v133
	v_add_f32_e32 v88, v88, v178
	v_add_f32_e32 v92, v92, v179
	v_mul_f32_e32 v132, v92, v117
	v_mul_f32_e32 v179, v88, v117
	v_fma_f32 v178, v88, v116, -v132
	v_fma_f32 v179, v92, v116, v179
	v_add_f32_e32 v89, v89, v180
	v_add_f32_e32 v93, v93, v181
	v_mul_f32_e32 v133, v93, v121
	v_mul_f32_e32 v181, v89, v121
	v_fma_f32 v180, v89, v120, -v133
	v_fma_f32 v181, v93, v120, v181
	v_add_f32_e32 v90, v90, v182
	v_add_f32_e32 v94, v94, v183
	v_mul_f32_e32 v132, v94, v125
	v_mul_f32_e32 v183, v90, v125
	v_fma_f32 v182, v90, v124, -v132
	v_fma_f32 v183, v94, v124, v183
	v_add_f32_e32 v91, v91, v184
	v_add_f32_e32 v95, v95, v185
	v_mul_f32_e32 v133, v95, v129
	v_mul_f32_e32 v185, v91, v129
	v_fma_f32 v184, v91, v128, -v133
	v_fma_f32 v185, v95, v128, v185
	v_mul_f32_e32 v132, v40, v101
	v_mul_f32_e32 v40, v40, v100
	v_fma_f32 v40, -v44, v101, v40
	v_fma_f32 v44, v44, v100, v132
	v_mul_f32_e32 v133, v41, v105
	v_mul_f32_e32 v41, v41, v104
	v_fma_f32 v41, -v45, v105, v41
	v_fma_f32 v45, v45, v104, v133
	v_mul_f32_e32 v132, v42, v109
	v_mul_f32_e32 v42, v42, v108
	v_fma_f32 v42, -v46, v109, v42
	v_fma_f32 v46, v46, v108, v132
	v_mul_f32_e32 v133, v43, v113
	v_mul_f32_e32 v43, v43, v112
	v_fma_f32 v43, -v47, v113, v43
	v_fma_f32 v47, v47, v112, v133
	v_add_f32_dpp v40, v40, v40 row_shl:1 row_mask:0xf bank_mask:0xf bound_ctrl:1
	v_add_f32_dpp v41, v41, v41 row_shl:1 row_mask:0xf bank_mask:0xf bound_ctrl:1
	v_add_f32_dpp v42, v42, v42 row_shl:1 row_mask:0xf bank_mask:0xf bound_ctrl:1
	v_add_f32_dpp v43, v43, v43 row_shl:1 row_mask:0xf bank_mask:0xf bound_ctrl:1
	v_add_f32_dpp v44, v44, v44 row_shl:1 row_mask:0xf bank_mask:0xf bound_ctrl:1
	v_add_f32_dpp v45, v45, v45 row_shl:1 row_mask:0xf bank_mask:0xf bound_ctrl:1
	v_add_f32_dpp v46, v46, v46 row_shl:1 row_mask:0xf bank_mask:0xf bound_ctrl:1
	v_add_f32_dpp v47, v47, v47 row_shl:1 row_mask:0xf bank_mask:0xf bound_ctrl:1
	v_add_f32_dpp v40, v40, v40 row_shl:2 row_mask:0xf bank_mask:0xf bound_ctrl:1
	v_add_f32_dpp v41, v41, v41 row_shl:2 row_mask:0xf bank_mask:0xf bound_ctrl:1
	v_add_f32_dpp v42, v42, v42 row_shl:2 row_mask:0xf bank_mask:0xf bound_ctrl:1
	v_add_f32_dpp v43, v43, v43 row_shl:2 row_mask:0xf bank_mask:0xf bound_ctrl:1
	v_add_f32_dpp v44, v44, v44 row_shl:2 row_mask:0xf bank_mask:0xf bound_ctrl:1
	v_add_f32_dpp v45, v45, v45 row_shl:2 row_mask:0xf bank_mask:0xf bound_ctrl:1
	v_add_f32_dpp v46, v46, v46 row_shl:2 row_mask:0xf bank_mask:0xf bound_ctrl:1
	v_add_f32_dpp v47, v47, v47 row_shl:2 row_mask:0xf bank_mask:0xf bound_ctrl:1
	v_add_f32_dpp v40, v40, v40 row_shl:4 row_mask:0xf bank_mask:0xf bound_ctrl:1
	v_add_f32_dpp v41, v41, v41 row_shl:4 row_mask:0xf bank_mask:0xf bound_ctrl:1
	v_add_f32_dpp v42, v42, v42 row_shl:4 row_mask:0xf bank_mask:0xf bound_ctrl:1
	v_add_f32_dpp v43, v43, v43 row_shl:4 row_mask:0xf bank_mask:0xf bound_ctrl:1
	v_add_f32_dpp v44, v44, v44 row_shl:4 row_mask:0xf bank_mask:0xf bound_ctrl:1
	v_add_f32_dpp v45, v45, v45 row_shl:4 row_mask:0xf bank_mask:0xf bound_ctrl:1
	v_add_f32_dpp v46, v46, v46 row_shl:4 row_mask:0xf bank_mask:0xf bound_ctrl:1
	v_add_f32_dpp v47, v47, v47 row_shl:4 row_mask:0xf bank_mask:0xf bound_ctrl:1
	v_add_f32_dpp v40, v40, v40 row_shl:8 row_mask:0xf bank_mask:0xf bound_ctrl:1
	v_add_f32_dpp v41, v41, v41 row_shl:8 row_mask:0xf bank_mask:0xf bound_ctrl:1
	v_add_f32_dpp v42, v42, v42 row_shl:8 row_mask:0xf bank_mask:0xf bound_ctrl:1
	v_add_f32_dpp v43, v43, v43 row_shl:8 row_mask:0xf bank_mask:0xf bound_ctrl:1
	v_add_f32_dpp v44, v44, v44 row_shl:8 row_mask:0xf bank_mask:0xf bound_ctrl:1
	v_add_f32_dpp v45, v45, v45 row_shl:8 row_mask:0xf bank_mask:0xf bound_ctrl:1
	v_add_f32_dpp v46, v46, v46 row_shl:8 row_mask:0xf bank_mask:0xf bound_ctrl:1
	v_add_f32_dpp v47, v47, v47 row_shl:8 row_mask:0xf bank_mask:0xf bound_ctrl:1
	v_mov_b32_dpp v88, v40 row_newbcast:0 row_mask:0xf bank_mask:0xf
	v_mov_b32_dpp v89, v41 row_newbcast:0 row_mask:0xf bank_mask:0xf
	v_mov_b32_dpp v90, v42 row_newbcast:0 row_mask:0xf bank_mask:0xf
	v_mov_b32_dpp v91, v43 row_newbcast:0 row_mask:0xf bank_mask:0xf
	v_mov_b32_dpp v92, v44 row_newbcast:0 row_mask:0xf bank_mask:0xf
	v_mov_b32_dpp v93, v45 row_newbcast:0 row_mask:0xf bank_mask:0xf
	v_mov_b32_dpp v94, v46 row_newbcast:0 row_mask:0xf bank_mask:0xf
	v_mov_b32_dpp v95, v47 row_newbcast:0 row_mask:0xf bank_mask:0xf
	v_add_f32_e32 v40, v40, v178
	v_add_f32_e32 v44, v44, v179
	v_add_f32_e32 v41, v41, v180
	v_add_f32_e32 v45, v45, v181
	v_add_f32_e32 v42, v42, v182
	v_add_f32_e32 v46, v46, v183
	v_add_f32_e32 v43, v43, v184
	v_add_f32_e32 v47, v47, v185
	v_mul_f32_e32 v132, v40, v103
	v_mul_f32_e32 v40, v40, v102
	v_fma_f32 v40, -v44, v103, v40
	v_fma_f32 v44, v44, v102, v132
	v_mul_f32_e32 v133, v41, v107
	v_mul_f32_e32 v41, v41, v106
	v_fma_f32 v41, -v45, v107, v41
	v_fma_f32 v45, v45, v106, v133
	v_mul_f32_e32 v132, v42, v111
	v_mul_f32_e32 v42, v42, v110
	v_fma_f32 v42, -v46, v111, v42
	v_fma_f32 v46, v46, v110, v132
	v_mul_f32_e32 v133, v43, v115
	v_mul_f32_e32 v43, v43, v114
	v_fma_f32 v43, -v47, v115, v43
	v_fma_f32 v47, v47, v114, v133
	v_add_f32_e32 v88, v88, v178
	v_add_f32_e32 v92, v92, v179
	v_mul_f32_e32 v132, v92, v117
	v_mul_f32_e32 v179, v88, v117
	v_fma_f32 v178, v88, v116, -v132
	v_fma_f32 v179, v92, v116, v179
	v_add_f32_e32 v89, v89, v180
	v_add_f32_e32 v93, v93, v181
	v_mul_f32_e32 v133, v93, v121
	v_mul_f32_e32 v181, v89, v121
	v_fma_f32 v180, v89, v120, -v133
	v_fma_f32 v181, v93, v120, v181
	v_add_f32_e32 v90, v90, v182
	v_add_f32_e32 v94, v94, v183
	v_mul_f32_e32 v132, v94, v125
	v_mul_f32_e32 v183, v90, v125
	v_fma_f32 v182, v90, v124, -v132
	v_fma_f32 v183, v94, v124, v183
	v_add_f32_e32 v91, v91, v184
	v_add_f32_e32 v95, v95, v185
	v_mul_f32_e32 v133, v95, v129
	v_mul_f32_e32 v185, v91, v129
	v_fma_f32 v184, v91, v128, -v133
	v_fma_f32 v185, v95, v128, v185
	v_mul_f32_e32 v132, v32, v101
	v_mul_f32_e32 v32, v32, v100
	v_fma_f32 v32, -v36, v101, v32
	v_fma_f32 v36, v36, v100, v132
	v_mul_f32_e32 v133, v33, v105
	v_mul_f32_e32 v33, v33, v104
	v_fma_f32 v33, -v37, v105, v33
	v_fma_f32 v37, v37, v104, v133
	v_mul_f32_e32 v132, v34, v109
	v_mul_f32_e32 v34, v34, v108
	v_fma_f32 v34, -v38, v109, v34
	v_fma_f32 v38, v38, v108, v132
	v_mul_f32_e32 v133, v35, v113
	v_mul_f32_e32 v35, v35, v112
	v_fma_f32 v35, -v39, v113, v35
	v_fma_f32 v39, v39, v112, v133
	v_add_f32_dpp v32, v32, v32 row_shl:1 row_mask:0xf bank_mask:0xf bound_ctrl:1
	v_add_f32_dpp v33, v33, v33 row_shl:1 row_mask:0xf bank_mask:0xf bound_ctrl:1
	v_add_f32_dpp v34, v34, v34 row_shl:1 row_mask:0xf bank_mask:0xf bound_ctrl:1
	v_add_f32_dpp v35, v35, v35 row_shl:1 row_mask:0xf bank_mask:0xf bound_ctrl:1
	v_add_f32_dpp v36, v36, v36 row_shl:1 row_mask:0xf bank_mask:0xf bound_ctrl:1
	v_add_f32_dpp v37, v37, v37 row_shl:1 row_mask:0xf bank_mask:0xf bound_ctrl:1
	v_add_f32_dpp v38, v38, v38 row_shl:1 row_mask:0xf bank_mask:0xf bound_ctrl:1
	v_add_f32_dpp v39, v39, v39 row_shl:1 row_mask:0xf bank_mask:0xf bound_ctrl:1
	v_add_f32_dpp v32, v32, v32 row_shl:2 row_mask:0xf bank_mask:0xf bound_ctrl:1
	v_add_f32_dpp v33, v33, v33 row_shl:2 row_mask:0xf bank_mask:0xf bound_ctrl:1
	v_add_f32_dpp v34, v34, v34 row_shl:2 row_mask:0xf bank_mask:0xf bound_ctrl:1
	v_add_f32_dpp v35, v35, v35 row_shl:2 row_mask:0xf bank_mask:0xf bound_ctrl:1
	v_add_f32_dpp v36, v36, v36 row_shl:2 row_mask:0xf bank_mask:0xf bound_ctrl:1
	v_add_f32_dpp v37, v37, v37 row_shl:2 row_mask:0xf bank_mask:0xf bound_ctrl:1
	v_add_f32_dpp v38, v38, v38 row_shl:2 row_mask:0xf bank_mask:0xf bound_ctrl:1
	v_add_f32_dpp v39, v39, v39 row_shl:2 row_mask:0xf bank_mask:0xf bound_ctrl:1
	v_add_f32_dpp v32, v32, v32 row_shl:4 row_mask:0xf bank_mask:0xf bound_ctrl:1
	v_add_f32_dpp v33, v33, v33 row_shl:4 row_mask:0xf bank_mask:0xf bound_ctrl:1
	v_add_f32_dpp v34, v34, v34 row_shl:4 row_mask:0xf bank_mask:0xf bound_ctrl:1
	v_add_f32_dpp v35, v35, v35 row_shl:4 row_mask:0xf bank_mask:0xf bound_ctrl:1
	v_add_f32_dpp v36, v36, v36 row_shl:4 row_mask:0xf bank_mask:0xf bound_ctrl:1
	v_add_f32_dpp v37, v37, v37 row_shl:4 row_mask:0xf bank_mask:0xf bound_ctrl:1
	v_add_f32_dpp v38, v38, v38 row_shl:4 row_mask:0xf bank_mask:0xf bound_ctrl:1
	v_add_f32_dpp v39, v39, v39 row_shl:4 row_mask:0xf bank_mask:0xf bound_ctrl:1
	v_add_f32_dpp v32, v32, v32 row_shl:8 row_mask:0xf bank_mask:0xf bound_ctrl:1
	v_add_f32_dpp v33, v33, v33 row_shl:8 row_mask:0xf bank_mask:0xf bound_ctrl:1
	v_add_f32_dpp v34, v34, v34 row_shl:8 row_mask:0xf bank_mask:0xf bound_ctrl:1
	v_add_f32_dpp v35, v35, v35 row_shl:8 row_mask:0xf bank_mask:0xf bound_ctrl:1
	v_add_f32_dpp v36, v36, v36 row_shl:8 row_mask:0xf bank_mask:0xf bound_ctrl:1
	v_add_f32_dpp v37, v37, v37 row_shl:8 row_mask:0xf bank_mask:0xf bound_ctrl:1
	v_add_f32_dpp v38, v38, v38 row_shl:8 row_mask:0xf bank_mask:0xf bound_ctrl:1
	v_add_f32_dpp v39, v39, v39 row_shl:8 row_mask:0xf bank_mask:0xf bound_ctrl:1
	v_mov_b32_dpp v88, v32 row_newbcast:0 row_mask:0xf bank_mask:0xf
	v_mov_b32_dpp v89, v33 row_newbcast:0 row_mask:0xf bank_mask:0xf
	v_mov_b32_dpp v90, v34 row_newbcast:0 row_mask:0xf bank_mask:0xf
	v_mov_b32_dpp v91, v35 row_newbcast:0 row_mask:0xf bank_mask:0xf
	v_mov_b32_dpp v92, v36 row_newbcast:0 row_mask:0xf bank_mask:0xf
	v_mov_b32_dpp v93, v37 row_newbcast:0 row_mask:0xf bank_mask:0xf
	v_mov_b32_dpp v94, v38 row_newbcast:0 row_mask:0xf bank_mask:0xf
	v_mov_b32_dpp v95, v39 row_newbcast:0 row_mask:0xf bank_mask:0xf
	v_add_f32_e32 v32, v32, v178
	v_add_f32_e32 v36, v36, v179
	v_add_f32_e32 v33, v33, v180
	v_add_f32_e32 v37, v37, v181
	v_add_f32_e32 v34, v34, v182
	v_add_f32_e32 v38, v38, v183
	v_add_f32_e32 v35, v35, v184
	v_add_f32_e32 v39, v39, v185
	v_mul_f32_e32 v132, v32, v103
	v_mul_f32_e32 v32, v32, v102
	v_fma_f32 v32, -v36, v103, v32
	v_fma_f32 v36, v36, v102, v132
	v_mul_f32_e32 v133, v33, v107
	v_mul_f32_e32 v33, v33, v106
	v_fma_f32 v33, -v37, v107, v33
	v_fma_f32 v37, v37, v106, v133
	v_mul_f32_e32 v132, v34, v111
	v_mul_f32_e32 v34, v34, v110
	v_fma_f32 v34, -v38, v111, v34
	v_fma_f32 v38, v38, v110, v132
	v_mul_f32_e32 v133, v35, v115
	v_mul_f32_e32 v35, v35, v114
	v_fma_f32 v35, -v39, v115, v35
	v_fma_f32 v39, v39, v114, v133
	v_add_f32_e32 v88, v88, v178
	v_add_f32_e32 v92, v92, v179
	v_mul_f32_e32 v132, v92, v117
	v_mul_f32_e32 v179, v88, v117
	v_fma_f32 v178, v88, v116, -v132
	v_fma_f32 v179, v92, v116, v179
	v_add_f32_e32 v89, v89, v180
	v_add_f32_e32 v93, v93, v181
	v_mul_f32_e32 v133, v93, v121
	v_mul_f32_e32 v181, v89, v121
	v_fma_f32 v180, v89, v120, -v133
	v_fma_f32 v181, v93, v120, v181
	v_add_f32_e32 v90, v90, v182
	v_add_f32_e32 v94, v94, v183
	v_mul_f32_e32 v132, v94, v125
	v_mul_f32_e32 v183, v90, v125
	v_fma_f32 v182, v90, v124, -v132
	v_fma_f32 v183, v94, v124, v183
	v_add_f32_e32 v91, v91, v184
	v_add_f32_e32 v95, v95, v185
	v_mul_f32_e32 v133, v95, v129
	v_mul_f32_e32 v185, v91, v129
	v_fma_f32 v184, v91, v128, -v133
	v_fma_f32 v185, v95, v128, v185
	s_waitcnt vmcnt(0)
	v_cvt_pk_bf16_f32 v96, v32, v33
	v_cvt_pk_bf16_f32 v97, v34, v35
	v_cvt_pk_bf16_f32 v98, v36, v37
	v_cvt_pk_bf16_f32 v99, v38, v39
	s_nop 1
	v_mfma_f32_16x16x32_bf16 v[16:19], v[80:83], v[96:99], v[16:19]
	v_cvt_pk_bf16_f32 v96, v40, v41
	v_cvt_pk_bf16_f32 v97, v42, v43
	v_cvt_pk_bf16_f32 v98, v44, v45
	v_cvt_pk_bf16_f32 v99, v46, v47
	s_nop 1
	v_mfma_f32_16x16x32_bf16 v[20:23], v[80:83], v[96:99], v[20:23]
	v_cvt_pk_bf16_f32 v96, v48, v49
	v_cvt_pk_bf16_f32 v97, v50, v51
	v_cvt_pk_bf16_f32 v98, v52, v53
	v_cvt_pk_bf16_f32 v99, v54, v55
	s_nop 1
	v_mfma_f32_16x16x32_bf16 v[24:27], v[80:83], v[96:99], v[24:27]
	v_cvt_pk_bf16_f32 v96, v56, v57
	v_cvt_pk_bf16_f32 v97, v58, v59
	v_cvt_pk_bf16_f32 v98, v60, v61
	v_cvt_pk_bf16_f32 v99, v62, v63
	s_nop 1
	v_mfma_f32_16x16x32_bf16 v[28:31], v[80:83], v[96:99], v[28:31]
	v_and_b32_e32 v100, 15, v205
	v_lshrrev_b32_e32 v101, 4, v205
	v_mul_u32_u24_e32 v102, 0xe00, v100
	v_lshl_add_u32 v102, v101, 3, v102
	v_lshlrev_b32_e32 v103, 9, v100
	v_lshl_add_u32 v103, v101, 3, v103
	v_lshlrev_b32_e32 v104, 4, v101
	s_mul_i32 s18, s9, 0xe00
	s_lshl_b32 s19, s7, 5
	s_add_i32 s18, s18, s19
	s_add_u32 s18, s18, 0x5e00c00
	s_add_u32 s18, s4, s18
	s_addc_u32 s19, s5, 0
	global_load_dwordx2 v[108:109], v102, s[18:19]
	s_add_u32 s18, s18, 0xe000
	s_addc_u32 s19, s19, 0
	global_load_dwordx2 v[110:111], v102, s[18:19]
	s_add_u32 s18, s18, 0xe000
	s_addc_u32 s19, s19, 0
	global_load_dwordx2 v[112:113], v102, s[18:19]
	s_add_u32 s18, s18, 0xe000
	s_addc_u32 s19, s19, 0
	global_load_dwordx2 v[114:115], v102, s[18:19]
	v_readlane_b32 s10, v247, 28
	s_lshl_b32 s10, s10, 10
	s_lshl_b32 s11, s7, 6
	s_add_i32 s10, s10, s11
	s_add_u32 s10, s10, 0x21fb20
	s_add_u32 s20, s4, s10
	s_addc_u32 s21, s5, 0
	global_load_dwordx4 v[116:119], v104, s[20:21]
	s_lshl_b32 s10, s9, 9
	s_add_i32 s10, s10, s11
	s_lshr_b32 s11, s11, 1
	s_sub_i32 s10, s10, s11
	s_add_u32 s10, s10, 0xc500000
	s_add_u32 s22, s4, s10
	s_addc_u32 s23, s5, 0
	s_waitcnt vmcnt(0)
	s_nop 4
	v_lshlrev_b32_e32 v120, 16, v108
	v_and_b32_e32 v121, 0xffff0000, v108
	v_lshlrev_b32_e32 v122, 16, v109
	v_and_b32_e32 v123, 0xffff0000, v109
	v_fmac_f32_e32 v16, v116, v120
	v_fmac_f32_e32 v17, v117, v121
	v_fmac_f32_e32 v18, v118, v122
	v_fmac_f32_e32 v19, v119, v123
	v_cvt_pk_bf16_f32 v124, v16, v17
	v_cvt_pk_bf16_f32 v125, v18, v19
	global_store_dwordx2 v103, v[124:125], s[22:23] offset:0
	s_add_u32 s22, s22, 0x2000
	s_addc_u32 s23, s23, 0
	v_lshlrev_b32_e32 v120, 16, v110
	v_and_b32_e32 v121, 0xffff0000, v110
	v_lshlrev_b32_e32 v122, 16, v111
	v_and_b32_e32 v123, 0xffff0000, v111
	v_fmac_f32_e32 v20, v116, v120
	v_fmac_f32_e32 v21, v117, v121
	v_fmac_f32_e32 v22, v118, v122
	v_fmac_f32_e32 v23, v119, v123
	v_cvt_pk_bf16_f32 v124, v20, v21
	v_cvt_pk_bf16_f32 v125, v22, v23
	global_store_dwordx2 v103, v[124:125], s[22:23] offset:0
	s_add_u32 s22, s22, 0x2000
	s_addc_u32 s23, s23, 0
	v_lshlrev_b32_e32 v120, 16, v112
	v_and_b32_e32 v121, 0xffff0000, v112
	v_lshlrev_b32_e32 v122, 16, v113
	v_and_b32_e32 v123, 0xffff0000, v113
	v_fmac_f32_e32 v24, v116, v120
	v_fmac_f32_e32 v25, v117, v121
	v_fmac_f32_e32 v26, v118, v122
	v_fmac_f32_e32 v27, v119, v123
	v_cvt_pk_bf16_f32 v124, v24, v25
	v_cvt_pk_bf16_f32 v125, v26, v27
	global_store_dwordx2 v103, v[124:125], s[22:23] offset:0
	s_add_u32 s22, s22, 0x2000
	s_addc_u32 s23, s23, 0
	v_lshlrev_b32_e32 v120, 16, v114
	v_and_b32_e32 v121, 0xffff0000, v114
	v_lshlrev_b32_e32 v122, 16, v115
	v_and_b32_e32 v123, 0xffff0000, v115
	v_fmac_f32_e32 v28, v116, v120
	v_fmac_f32_e32 v29, v117, v121
	v_fmac_f32_e32 v30, v118, v122
	v_fmac_f32_e32 v31, v119, v123
	v_cvt_pk_bf16_f32 v124, v28, v29
	v_cvt_pk_bf16_f32 v125, v30, v31
	global_store_dwordx2 v103, v[124:125], s[22:23] offset:0
	s_cmp_eq_u32 s37, 1
	s_cbranch_scc1 .Lss3_done
	s_add_i32 s36, s36, s30
	s_branch .Lss3_top

.LBB0_612:
	v_readlane_b32 s78, v247, 22
	s_bitcmp0_b32 s94, 0
	v_readlane_b32 s79, v247, 23
	v_readlane_b32 s24, v247, 28
	v_readlane_b32 s25, v244, 30
	v_readlane_b32 s26, v244, 31
	v_readlane_b32 s27, v245, 40
	s_cbranch_scc1 .LBB0_620
	v_readlane_b32 s0, v246, 3
	v_readlane_b32 s1, v246, 4
	s_andn2_b64 vcc, exec, s[0:1]
	s_cbranch_vccnz .LBB0_620
	v_readlane_b32 s0, v245, 21
	s_nop 0
	s_sub_u32 s0, s0, 0x400
	s_cbranch_scc1 .Lstab_end
	s_and_b32 s1, s0, 7
	s_cmp_lg_u32 s1, 0
	s_cbranch_scc1 .Lstab_end
	s_lshr_b32 s0, s0, 3
	s_lshr_b32 s1, s0, 2
	s_and_b32 s6, s0, 3
	s_lshl_b32 s7, s24, 5
	s_add_i32 s7, s7, s1
	s_bfe_u32 s8, s1, 0x10004
	s_mul_i32 s9, s8, 15
	v_and_b32_e32 v0, 15, v205
	v_lshrrev_b32_e32 v1, 4, v205
	v_xor_b32_e32 v2, s9, v0
	v_and_b32_e32 v3, 1, v2
	v_cmp_ne_u32_e64 s[10:11], 0, v3
	v_and_b32_e32 v3, 2, v2
	v_cmp_ne_u32_e64 s[12:13], 0, v3
	v_and_b32_e32 v3, 4, v2
	v_cmp_ne_u32_e64 s[14:15], 0, v3
	v_and_b32_e32 v3, 8, v2
	v_cmp_ne_u32_e64 s[16:17], 0, v3
	s_lshl_b32 s18, s7, 6
	s_lshl_b32 s19, s6, 4
	s_add_i32 s18, s18, s19
	s_lshl_b32 s18, s18, 2
	s_add_u32 s18, s18, 0x117a20
	s_add_u32 s20, s4, s18
	s_addc_u32 s21, s5, 0
	s_add_u32 s22, s20, 0x4000
	s_addc_u32 s23, s21, 0
	v_lshlrev_b32_e32 v3, 4, v1
	global_load_dwordx4 v[4:7], v3, s[20:21]
	global_load_dwordx4 v[8:11], v3, s[22:23]
	s_lshl_b32 s19, s7, 2
	s_add_u32 s19, s19, 0x11fa20
	s_add_u32 s0, s4, s19
	s_addc_u32 s1, s5, 0
	global_load_dword v12, v137, s[0:1]
	s_lshl_b32 s18, s7, 2
	s_add_i32 s18, s18, s6
	s_lshl_b32 s19, s18, 13
	s_add_u32 s19, s19, 0xf900000
	s_add_u32 s20, s4, s19
	s_addc_u32 s21, s5, 0
	s_lshl_b32 s19, s18, 12
	s_add_u32 s19, s19, 0xfc00000
	s_add_u32 s22, s4, s19
	s_addc_u32 s23, s5, 0
	v_lshlrev_b32_e32 v13, 4, v205
	v_lshlrev_b32_e32 v14, 4, v205
	v_add_u32_e32 v44, 0x1000, v13
	s_waitcnt vmcnt(0)
	v_mul_f32_e32 v12, 0x3fb8aa3b, v12
	v_exp_f32_e32 v12, v12
	s_nop 0
	v_mul_f32_e32 v15, v12, v4
	v_mul_f32_e32 v16, 0x3fb8aa3b, v15
	v_mul_f32_e32 v17, 0xbfb8aa3b, v15
	v_exp_f32_e32 v16, v16
	v_exp_f32_e32 v17, v17
	v_mul_f32_e32 v18, v12, v8
	v_mul_f32_e32 v19, 0.15915494, v18
	v_rndne_f32_e32 v19, v19
	v_fma_f32 v18, v18, 0.15915494, -v19
	v_cos_f32_e32 v19, v18
	v_sin_f32_e32 v20, v18
	s_nop 0
	v_mul_f32_e32 v22, v16, v19
	v_mul_f32_e32 v23, v16, v20
	v_mul_f32_e32 v24, v17, v19
	v_mul_f32_e64 v25, -v17, v20
	v_add_f32_e32 v26, -1.0, v22
	v_mul_f32_e32 v27, v8, v8
	v_fmac_f32_e32 v27, v4, v4
	v_rcp_f32_e32 v27, v27
	v_mul_f32_e32 v28, v26, v4
	v_fmac_f32_e32 v28, v23, v8
	v_mul_f32_e32 v29, v23, v4
	v_fma_f32 v29, -v26, v8, v29
	v_mul_f32_e32 v28, v28, v27
	v_mul_f32_e32 v29, v29, v27
	v_mul_f32_e32 v42, v23, v23
	v_mul_f32_e32 v43, v22, v23
	v_fma_f32 v30, v22, v22, -v42
	v_add_f32_e32 v31, v43, v43
	v_mul_f32_e32 v42, v31, v31
	v_mul_f32_e32 v43, v30, v31
	v_fma_f32 v32, v30, v30, -v42
	v_add_f32_e32 v33, v43, v43
	v_mul_f32_e32 v42, v33, v33
	v_mul_f32_e32 v43, v32, v33
	v_fma_f32 v34, v32, v32, -v42
	v_add_f32_e32 v35, v43, v43
	v_mul_f32_e32 v42, v35, v35
	v_mul_f32_e32 v43, v34, v35
	v_fma_f32 v36, v34, v34, -v42
	v_add_f32_e32 v37, v43, v43
	v_mov_b32_e32 v38, 1.0
	v_mov_b32_e32 v39, 0
	v_mov_b32_e32 v40, 1.0
	v_mov_b32_e32 v41, 0
	v_mul_f32_e32 v15, v39, v23
	v_fma_f32 v42, v38, v22, -v15
	v_mul_f32_e32 v15, v38, v23
	v_fma_f32 v43, v39, v22, v15
	v_cndmask_b32_e64 v38, v38, v42, s[10:11]
	v_cndmask_b32_e64 v39, v39, v43, s[10:11]
	v_mul_f32_e32 v15, v41, v23
	v_fma_f32 v42, v40, v22, -v15
	v_mul_f32_e32 v15, v40, v23
	v_fma_f32 v43, v41, v22, v15
	v_cndmask_b32_e64 v40, v42, v40, s[10:11]
	v_cndmask_b32_e64 v41, v43, v41, s[10:11]
	v_mul_f32_e32 v15, v39, v31
	v_fma_f32 v42, v38, v30, -v15
	v_mul_f32_e32 v15, v38, v31
	v_fma_f32 v43, v39, v30, v15
	v_cndmask_b32_e64 v38, v38, v42, s[12:13]
	v_cndmask_b32_e64 v39, v39, v43, s[12:13]
	v_mul_f32_e32 v15, v41, v31
	v_fma_f32 v42, v40, v30, -v15
	v_mul_f32_e32 v15, v40, v31
	v_fma_f32 v43, v41, v30, v15
	v_cndmask_b32_e64 v40, v42, v40, s[12:13]
	v_cndmask_b32_e64 v41, v43, v41, s[12:13]
	v_mul_f32_e32 v15, v39, v33
	v_fma_f32 v42, v38, v32, -v15
	v_mul_f32_e32 v15, v38, v33
	v_fma_f32 v43, v39, v32, v15
	v_cndmask_b32_e64 v38, v38, v42, s[14:15]
	v_cndmask_b32_e64 v39, v39, v43, s[14:15]
	v_mul_f32_e32 v15, v41, v33
	v_fma_f32 v42, v40, v32, -v15
	v_mul_f32_e32 v15, v40, v33
	v_fma_f32 v43, v41, v32, v15
	v_cndmask_b32_e64 v40, v42, v40, s[14:15]
	v_cndmask_b32_e64 v41, v43, v41, s[14:15]
	v_mul_f32_e32 v15, v39, v35
	v_fma_f32 v42, v38, v34, -v15
	v_mul_f32_e32 v15, v38, v35
	v_fma_f32 v43, v39, v34, v15
	v_cndmask_b32_e64 v38, v38, v42, s[16:17]
	v_cndmask_b32_e64 v39, v39, v43, s[16:17]
	v_mul_f32_e32 v15, v41, v35
	v_fma_f32 v42, v40, v34, -v15
	v_mul_f32_e32 v15, v40, v35
	v_fma_f32 v43, v41, v34, v15
	v_cndmask_b32_e64 v40, v42, v40, s[16:17]
	v_cndmask_b32_e64 v41, v43, v41, s[16:17]
	v_mul_f32_e32 v42, v25, v25
	v_mul_f32_e32 v43, v24, v25
	v_fma_f32 v30, v24, v24, -v42
	v_add_f32_e32 v31, v43, v43
	v_mul_f32_e32 v42, v31, v31
	v_mul_f32_e32 v43, v30, v31
	v_fma_f32 v32, v30, v30, -v42
	v_add_f32_e32 v33, v43, v43
	v_mul_f32_e32 v42, v33, v33
	v_mul_f32_e32 v43, v32, v33
	v_fma_f32 v34, v32, v32, -v42
	v_add_f32_e32 v35, v43, v43
	v_mov_b32_e32 v16, 1.0
	v_mov_b32_e32 v17, 0
	v_mul_f32_e32 v15, v17, v25
	v_fma_f32 v42, v16, v24, -v15
	v_mul_f32_e32 v15, v16, v25
	v_fma_f32 v43, v17, v24, v15
	v_cndmask_b32_e64 v16, v16, v42, s[10:11]
	v_cndmask_b32_e64 v17, v17, v43, s[10:11]
	v_mul_f32_e32 v15, v17, v31
	v_fma_f32 v42, v16, v30, -v15
	v_mul_f32_e32 v15, v16, v31
	v_fma_f32 v43, v17, v30, v15
	v_cndmask_b32_e64 v16, v16, v42, s[12:13]
	v_cndmask_b32_e64 v17, v17, v43, s[12:13]
	v_mul_f32_e32 v15, v17, v33
	v_fma_f32 v42, v16, v32, -v15
	v_mul_f32_e32 v15, v16, v33
	v_fma_f32 v43, v17, v32, v15
	v_cndmask_b32_e64 v16, v16, v42, s[14:15]
	v_cndmask_b32_e64 v17, v17, v43, s[14:15]
	v_mul_f32_e32 v15, v17, v35
	v_fma_f32 v42, v16, v34, -v15
	v_mul_f32_e32 v15, v16, v35
	v_fma_f32 v43, v17, v34, v15
	v_cndmask_b32_e64 v16, v16, v42, s[16:17]
	v_cndmask_b32_e64 v17, v17, v43, s[16:17]
	v_mul_f32_e32 v15, v29, v17
	v_fma_f32 v18, v28, v16, -v15
	v_mul_f32_e32 v15, v28, v17
	v_fma_f32 v19, v29, v16, v15
	v_mul_f32_e32 v15, v29, v41
	v_fma_f32 v20, v28, v40, -v15
	v_mul_f32_e32 v15, v28, v41
	v_fma_f32 v21, v29, v40, v15
	global_store_dwordx2 v13, v[18:19], s[20:21] offset:0
	global_store_dwordx2 v13, v[38:39], s[20:21] offset:8
	global_store_dwordx2 v44, v[36:37], s[20:21] offset:0
	global_store_dwordx2 v44, v[22:23], s[20:21] offset:8
	global_store_dwordx2 v14, v[20:21], s[22:23] offset:0
	global_store_dwordx2 v14, v[36:37], s[22:23] offset:8
	s_nop 1
	v_mul_f32_e32 v15, v12, v5
	v_mul_f32_e32 v16, 0x3fb8aa3b, v15
	v_mul_f32_e32 v17, 0xbfb8aa3b, v15
	v_exp_f32_e32 v16, v16
	v_exp_f32_e32 v17, v17
	v_mul_f32_e32 v18, v12, v9
	v_mul_f32_e32 v19, 0.15915494, v18
	v_rndne_f32_e32 v19, v19
	v_fma_f32 v18, v18, 0.15915494, -v19
	v_cos_f32_e32 v19, v18
	v_sin_f32_e32 v20, v18
	s_nop 0
	v_mul_f32_e32 v22, v16, v19
	v_mul_f32_e32 v23, v16, v20
	v_mul_f32_e32 v24, v17, v19
	v_mul_f32_e64 v25, -v17, v20
	v_add_f32_e32 v26, -1.0, v22
	v_mul_f32_e32 v27, v9, v9
	v_fmac_f32_e32 v27, v5, v5
	v_rcp_f32_e32 v27, v27
	v_mul_f32_e32 v28, v26, v5
	v_fmac_f32_e32 v28, v23, v9
	v_mul_f32_e32 v29, v23, v5
	v_fma_f32 v29, -v26, v9, v29
	v_mul_f32_e32 v28, v28, v27
	v_mul_f32_e32 v29, v29, v27
	v_mul_f32_e32 v42, v23, v23
	v_mul_f32_e32 v43, v22, v23
	v_fma_f32 v30, v22, v22, -v42
	v_add_f32_e32 v31, v43, v43
	v_mul_f32_e32 v42, v31, v31
	v_mul_f32_e32 v43, v30, v31
	v_fma_f32 v32, v30, v30, -v42
	v_add_f32_e32 v33, v43, v43
	v_mul_f32_e32 v42, v33, v33
	v_mul_f32_e32 v43, v32, v33
	v_fma_f32 v34, v32, v32, -v42
	v_add_f32_e32 v35, v43, v43
	v_mul_f32_e32 v42, v35, v35
	v_mul_f32_e32 v43, v34, v35
	v_fma_f32 v36, v34, v34, -v42
	v_add_f32_e32 v37, v43, v43
	v_mov_b32_e32 v38, 1.0
	v_mov_b32_e32 v39, 0
	v_mov_b32_e32 v40, 1.0
	v_mov_b32_e32 v41, 0
	v_mul_f32_e32 v15, v39, v23
	v_fma_f32 v42, v38, v22, -v15
	v_mul_f32_e32 v15, v38, v23
	v_fma_f32 v43, v39, v22, v15
	v_cndmask_b32_e64 v38, v38, v42, s[10:11]
	v_cndmask_b32_e64 v39, v39, v43, s[10:11]
	v_mul_f32_e32 v15, v41, v23
	v_fma_f32 v42, v40, v22, -v15
	v_mul_f32_e32 v15, v40, v23
	v_fma_f32 v43, v41, v22, v15
	v_cndmask_b32_e64 v40, v42, v40, s[10:11]
	v_cndmask_b32_e64 v41, v43, v41, s[10:11]
	v_mul_f32_e32 v15, v39, v31
	v_fma_f32 v42, v38, v30, -v15
	v_mul_f32_e32 v15, v38, v31
	v_fma_f32 v43, v39, v30, v15
	v_cndmask_b32_e64 v38, v38, v42, s[12:13]
	v_cndmask_b32_e64 v39, v39, v43, s[12:13]
	v_mul_f32_e32 v15, v41, v31
	v_fma_f32 v42, v40, v30, -v15
	v_mul_f32_e32 v15, v40, v31
	v_fma_f32 v43, v41, v30, v15
	v_cndmask_b32_e64 v40, v42, v40, s[12:13]
	v_cndmask_b32_e64 v41, v43, v41, s[12:13]
	v_mul_f32_e32 v15, v39, v33
	v_fma_f32 v42, v38, v32, -v15
	v_mul_f32_e32 v15, v38, v33
	v_fma_f32 v43, v39, v32, v15
	v_cndmask_b32_e64 v38, v38, v42, s[14:15]
	v_cndmask_b32_e64 v39, v39, v43, s[14:15]
	v_mul_f32_e32 v15, v41, v33
	v_fma_f32 v42, v40, v32, -v15
	v_mul_f32_e32 v15, v40, v33
	v_fma_f32 v43, v41, v32, v15
	v_cndmask_b32_e64 v40, v42, v40, s[14:15]
	v_cndmask_b32_e64 v41, v43, v41, s[14:15]
	v_mul_f32_e32 v15, v39, v35
	v_fma_f32 v42, v38, v34, -v15
	v_mul_f32_e32 v15, v38, v35
	v_fma_f32 v43, v39, v34, v15
	v_cndmask_b32_e64 v38, v38, v42, s[16:17]
	v_cndmask_b32_e64 v39, v39, v43, s[16:17]
	v_mul_f32_e32 v15, v41, v35
	v_fma_f32 v42, v40, v34, -v15
	v_mul_f32_e32 v15, v40, v35
	v_fma_f32 v43, v41, v34, v15
	v_cndmask_b32_e64 v40, v42, v40, s[16:17]
	v_cndmask_b32_e64 v41, v43, v41, s[16:17]
	v_mul_f32_e32 v42, v25, v25
	v_mul_f32_e32 v43, v24, v25
	v_fma_f32 v30, v24, v24, -v42
	v_add_f32_e32 v31, v43, v43
	v_mul_f32_e32 v42, v31, v31
	v_mul_f32_e32 v43, v30, v31
	v_fma_f32 v32, v30, v30, -v42
	v_add_f32_e32 v33, v43, v43
	v_mul_f32_e32 v42, v33, v33
	v_mul_f32_e32 v43, v32, v33
	v_fma_f32 v34, v32, v32, -v42
	v_add_f32_e32 v35, v43, v43
	v_mov_b32_e32 v16, 1.0
	v_mov_b32_e32 v17, 0
	v_mul_f32_e32 v15, v17, v25
	v_fma_f32 v42, v16, v24, -v15
	v_mul_f32_e32 v15, v16, v25
	v_fma_f32 v43, v17, v24, v15
	v_cndmask_b32_e64 v16, v16, v42, s[10:11]
	v_cndmask_b32_e64 v17, v17, v43, s[10:11]
	v_mul_f32_e32 v15, v17, v31
	v_fma_f32 v42, v16, v30, -v15
	v_mul_f32_e32 v15, v16, v31
	v_fma_f32 v43, v17, v30, v15
	v_cndmask_b32_e64 v16, v16, v42, s[12:13]
	v_cndmask_b32_e64 v17, v17, v43, s[12:13]
	v_mul_f32_e32 v15, v17, v33
	v_fma_f32 v42, v16, v32, -v15
	v_mul_f32_e32 v15, v16, v33
	v_fma_f32 v43, v17, v32, v15
	v_cndmask_b32_e64 v16, v16, v42, s[14:15]
	v_cndmask_b32_e64 v17, v17, v43, s[14:15]
	v_mul_f32_e32 v15, v17, v35
	v_fma_f32 v42, v16, v34, -v15
	v_mul_f32_e32 v15, v16, v35
	v_fma_f32 v43, v17, v34, v15
	v_cndmask_b32_e64 v16, v16, v42, s[16:17]
	v_cndmask_b32_e64 v17, v17, v43, s[16:17]
	v_mul_f32_e32 v15, v29, v17
	v_fma_f32 v18, v28, v16, -v15
	v_mul_f32_e32 v15, v28, v17
	v_fma_f32 v19, v29, v16, v15
	v_mul_f32_e32 v15, v29, v41
	v_fma_f32 v20, v28, v40, -v15
	v_mul_f32_e32 v15, v28, v41
	v_fma_f32 v21, v29, v40, v15
	global_store_dwordx2 v13, v[18:19], s[20:21] offset:1024
	global_store_dwordx2 v13, v[38:39], s[20:21] offset:1032
	global_store_dwordx2 v44, v[36:37], s[20:21] offset:1024
	global_store_dwordx2 v44, v[22:23], s[20:21] offset:1032
	global_store_dwordx2 v14, v[20:21], s[22:23] offset:1024
	global_store_dwordx2 v14, v[36:37], s[22:23] offset:1032
	s_nop 1
	v_mul_f32_e32 v15, v12, v6
	v_mul_f32_e32 v16, 0x3fb8aa3b, v15
	v_mul_f32_e32 v17, 0xbfb8aa3b, v15
	v_exp_f32_e32 v16, v16
	v_exp_f32_e32 v17, v17
	v_mul_f32_e32 v18, v12, v10
	v_mul_f32_e32 v19, 0.15915494, v18
	v_rndne_f32_e32 v19, v19
	v_fma_f32 v18, v18, 0.15915494, -v19
	v_cos_f32_e32 v19, v18
	v_sin_f32_e32 v20, v18
	s_nop 0
	v_mul_f32_e32 v22, v16, v19
	v_mul_f32_e32 v23, v16, v20
	v_mul_f32_e32 v24, v17, v19
	v_mul_f32_e64 v25, -v17, v20
	v_add_f32_e32 v26, -1.0, v22
	v_mul_f32_e32 v27, v10, v10
	v_fmac_f32_e32 v27, v6, v6
	v_rcp_f32_e32 v27, v27
	v_mul_f32_e32 v28, v26, v6
	v_fmac_f32_e32 v28, v23, v10
	v_mul_f32_e32 v29, v23, v6
	v_fma_f32 v29, -v26, v10, v29
	v_mul_f32_e32 v28, v28, v27
	v_mul_f32_e32 v29, v29, v27
	v_mul_f32_e32 v42, v23, v23
	v_mul_f32_e32 v43, v22, v23
	v_fma_f32 v30, v22, v22, -v42
	v_add_f32_e32 v31, v43, v43
	v_mul_f32_e32 v42, v31, v31
	v_mul_f32_e32 v43, v30, v31
	v_fma_f32 v32, v30, v30, -v42
	v_add_f32_e32 v33, v43, v43
	v_mul_f32_e32 v42, v33, v33
	v_mul_f32_e32 v43, v32, v33
	v_fma_f32 v34, v32, v32, -v42
	v_add_f32_e32 v35, v43, v43
	v_mul_f32_e32 v42, v35, v35
	v_mul_f32_e32 v43, v34, v35
	v_fma_f32 v36, v34, v34, -v42
	v_add_f32_e32 v37, v43, v43
	v_mov_b32_e32 v38, 1.0
	v_mov_b32_e32 v39, 0
	v_mov_b32_e32 v40, 1.0
	v_mov_b32_e32 v41, 0
	v_mul_f32_e32 v15, v39, v23
	v_fma_f32 v42, v38, v22, -v15
	v_mul_f32_e32 v15, v38, v23
	v_fma_f32 v43, v39, v22, v15
	v_cndmask_b32_e64 v38, v38, v42, s[10:11]
	v_cndmask_b32_e64 v39, v39, v43, s[10:11]
	v_mul_f32_e32 v15, v41, v23
	v_fma_f32 v42, v40, v22, -v15
	v_mul_f32_e32 v15, v40, v23
	v_fma_f32 v43, v41, v22, v15
	v_cndmask_b32_e64 v40, v42, v40, s[10:11]
	v_cndmask_b32_e64 v41, v43, v41, s[10:11]
	v_mul_f32_e32 v15, v39, v31
	v_fma_f32 v42, v38, v30, -v15
	v_mul_f32_e32 v15, v38, v31
	v_fma_f32 v43, v39, v30, v15
	v_cndmask_b32_e64 v38, v38, v42, s[12:13]
	v_cndmask_b32_e64 v39, v39, v43, s[12:13]
	v_mul_f32_e32 v15, v41, v31
	v_fma_f32 v42, v40, v30, -v15
	v_mul_f32_e32 v15, v40, v31
	v_fma_f32 v43, v41, v30, v15
	v_cndmask_b32_e64 v40, v42, v40, s[12:13]
	v_cndmask_b32_e64 v41, v43, v41, s[12:13]
	v_mul_f32_e32 v15, v39, v33
	v_fma_f32 v42, v38, v32, -v15
	v_mul_f32_e32 v15, v38, v33
	v_fma_f32 v43, v39, v32, v15
	v_cndmask_b32_e64 v38, v38, v42, s[14:15]
	v_cndmask_b32_e64 v39, v39, v43, s[14:15]
	v_mul_f32_e32 v15, v41, v33
	v_fma_f32 v42, v40, v32, -v15
	v_mul_f32_e32 v15, v40, v33
	v_fma_f32 v43, v41, v32, v15
	v_cndmask_b32_e64 v40, v42, v40, s[14:15]
	v_cndmask_b32_e64 v41, v43, v41, s[14:15]
	v_mul_f32_e32 v15, v39, v35
	v_fma_f32 v42, v38, v34, -v15
	v_mul_f32_e32 v15, v38, v35
	v_fma_f32 v43, v39, v34, v15
	v_cndmask_b32_e64 v38, v38, v42, s[16:17]
	v_cndmask_b32_e64 v39, v39, v43, s[16:17]
	v_mul_f32_e32 v15, v41, v35
	v_fma_f32 v42, v40, v34, -v15
	v_mul_f32_e32 v15, v40, v35
	v_fma_f32 v43, v41, v34, v15
	v_cndmask_b32_e64 v40, v42, v40, s[16:17]
	v_cndmask_b32_e64 v41, v43, v41, s[16:17]
	v_mul_f32_e32 v42, v25, v25
	v_mul_f32_e32 v43, v24, v25
	v_fma_f32 v30, v24, v24, -v42
	v_add_f32_e32 v31, v43, v43
	v_mul_f32_e32 v42, v31, v31
	v_mul_f32_e32 v43, v30, v31
	v_fma_f32 v32, v30, v30, -v42
	v_add_f32_e32 v33, v43, v43
	v_mul_f32_e32 v42, v33, v33
	v_mul_f32_e32 v43, v32, v33
	v_fma_f32 v34, v32, v32, -v42
	v_add_f32_e32 v35, v43, v43
	v_mov_b32_e32 v16, 1.0
	v_mov_b32_e32 v17, 0
	v_mul_f32_e32 v15, v17, v25
	v_fma_f32 v42, v16, v24, -v15
	v_mul_f32_e32 v15, v16, v25
	v_fma_f32 v43, v17, v24, v15
	v_cndmask_b32_e64 v16, v16, v42, s[10:11]
	v_cndmask_b32_e64 v17, v17, v43, s[10:11]
	v_mul_f32_e32 v15, v17, v31
	v_fma_f32 v42, v16, v30, -v15
	v_mul_f32_e32 v15, v16, v31
	v_fma_f32 v43, v17, v30, v15
	v_cndmask_b32_e64 v16, v16, v42, s[12:13]
	v_cndmask_b32_e64 v17, v17, v43, s[12:13]
	v_mul_f32_e32 v15, v17, v33
	v_fma_f32 v42, v16, v32, -v15
	v_mul_f32_e32 v15, v16, v33
	v_fma_f32 v43, v17, v32, v15
	v_cndmask_b32_e64 v16, v16, v42, s[14:15]
	v_cndmask_b32_e64 v17, v17, v43, s[14:15]
	v_mul_f32_e32 v15, v17, v35
	v_fma_f32 v42, v16, v34, -v15
	v_mul_f32_e32 v15, v16, v35
	v_fma_f32 v43, v17, v34, v15
	v_cndmask_b32_e64 v16, v16, v42, s[16:17]
	v_cndmask_b32_e64 v17, v17, v43, s[16:17]
	v_mul_f32_e32 v15, v29, v17
	v_fma_f32 v18, v28, v16, -v15
	v_mul_f32_e32 v15, v28, v17
	v_fma_f32 v19, v29, v16, v15
	v_mul_f32_e32 v15, v29, v41
	v_fma_f32 v20, v28, v40, -v15
	v_mul_f32_e32 v15, v28, v41
	v_fma_f32 v21, v29, v40, v15
	global_store_dwordx2 v13, v[18:19], s[20:21] offset:2048
	global_store_dwordx2 v13, v[38:39], s[20:21] offset:2056
	global_store_dwordx2 v44, v[36:37], s[20:21] offset:2048
	global_store_dwordx2 v44, v[22:23], s[20:21] offset:2056
	global_store_dwordx2 v14, v[20:21], s[22:23] offset:2048
	global_store_dwordx2 v14, v[36:37], s[22:23] offset:2056
	s_nop 1
	v_mul_f32_e32 v15, v12, v7
	v_mul_f32_e32 v16, 0x3fb8aa3b, v15
	v_mul_f32_e32 v17, 0xbfb8aa3b, v15
	v_exp_f32_e32 v16, v16
	v_exp_f32_e32 v17, v17
	v_mul_f32_e32 v18, v12, v11
	v_mul_f32_e32 v19, 0.15915494, v18
	v_rndne_f32_e32 v19, v19
	v_fma_f32 v18, v18, 0.15915494, -v19
	v_cos_f32_e32 v19, v18
	v_sin_f32_e32 v20, v18
	s_nop 0
	v_mul_f32_e32 v22, v16, v19
	v_mul_f32_e32 v23, v16, v20
	v_mul_f32_e32 v24, v17, v19
	v_mul_f32_e64 v25, -v17, v20
	v_add_f32_e32 v26, -1.0, v22
	v_mul_f32_e32 v27, v11, v11
	v_fmac_f32_e32 v27, v7, v7
	v_rcp_f32_e32 v27, v27
	v_mul_f32_e32 v28, v26, v7
	v_fmac_f32_e32 v28, v23, v11
	v_mul_f32_e32 v29, v23, v7
	v_fma_f32 v29, -v26, v11, v29
	v_mul_f32_e32 v28, v28, v27
	v_mul_f32_e32 v29, v29, v27
	v_mul_f32_e32 v42, v23, v23
	v_mul_f32_e32 v43, v22, v23
	v_fma_f32 v30, v22, v22, -v42
	v_add_f32_e32 v31, v43, v43
	v_mul_f32_e32 v42, v31, v31
	v_mul_f32_e32 v43, v30, v31
	v_fma_f32 v32, v30, v30, -v42
	v_add_f32_e32 v33, v43, v43
	v_mul_f32_e32 v42, v33, v33
	v_mul_f32_e32 v43, v32, v33
	v_fma_f32 v34, v32, v32, -v42
	v_add_f32_e32 v35, v43, v43
	v_mul_f32_e32 v42, v35, v35
	v_mul_f32_e32 v43, v34, v35
	v_fma_f32 v36, v34, v34, -v42
	v_add_f32_e32 v37, v43, v43
	v_mov_b32_e32 v38, 1.0
	v_mov_b32_e32 v39, 0
	v_mov_b32_e32 v40, 1.0
	v_mov_b32_e32 v41, 0
	v_mul_f32_e32 v15, v39, v23
	v_fma_f32 v42, v38, v22, -v15
	v_mul_f32_e32 v15, v38, v23
	v_fma_f32 v43, v39, v22, v15
	v_cndmask_b32_e64 v38, v38, v42, s[10:11]
	v_cndmask_b32_e64 v39, v39, v43, s[10:11]
	v_mul_f32_e32 v15, v41, v23
	v_fma_f32 v42, v40, v22, -v15
	v_mul_f32_e32 v15, v40, v23
	v_fma_f32 v43, v41, v22, v15
	v_cndmask_b32_e64 v40, v42, v40, s[10:11]
	v_cndmask_b32_e64 v41, v43, v41, s[10:11]
	v_mul_f32_e32 v15, v39, v31
	v_fma_f32 v42, v38, v30, -v15
	v_mul_f32_e32 v15, v38, v31
	v_fma_f32 v43, v39, v30, v15
	v_cndmask_b32_e64 v38, v38, v42, s[12:13]
	v_cndmask_b32_e64 v39, v39, v43, s[12:13]
	v_mul_f32_e32 v15, v41, v31
	v_fma_f32 v42, v40, v30, -v15
	v_mul_f32_e32 v15, v40, v31
	v_fma_f32 v43, v41, v30, v15
	v_cndmask_b32_e64 v40, v42, v40, s[12:13]
	v_cndmask_b32_e64 v41, v43, v41, s[12:13]
	v_mul_f32_e32 v15, v39, v33
	v_fma_f32 v42, v38, v32, -v15
	v_mul_f32_e32 v15, v38, v33
	v_fma_f32 v43, v39, v32, v15
	v_cndmask_b32_e64 v38, v38, v42, s[14:15]
	v_cndmask_b32_e64 v39, v39, v43, s[14:15]
	v_mul_f32_e32 v15, v41, v33
	v_fma_f32 v42, v40, v32, -v15
	v_mul_f32_e32 v15, v40, v33
	v_fma_f32 v43, v41, v32, v15
	v_cndmask_b32_e64 v40, v42, v40, s[14:15]
	v_cndmask_b32_e64 v41, v43, v41, s[14:15]
	v_mul_f32_e32 v15, v39, v35
	v_fma_f32 v42, v38, v34, -v15
	v_mul_f32_e32 v15, v38, v35
	v_fma_f32 v43, v39, v34, v15
	v_cndmask_b32_e64 v38, v38, v42, s[16:17]
	v_cndmask_b32_e64 v39, v39, v43, s[16:17]
	v_mul_f32_e32 v15, v41, v35
	v_fma_f32 v42, v40, v34, -v15
	v_mul_f32_e32 v15, v40, v35
	v_fma_f32 v43, v41, v34, v15
	v_cndmask_b32_e64 v40, v42, v40, s[16:17]
	v_cndmask_b32_e64 v41, v43, v41, s[16:17]
	v_mul_f32_e32 v42, v25, v25
	v_mul_f32_e32 v43, v24, v25
	v_fma_f32 v30, v24, v24, -v42
	v_add_f32_e32 v31, v43, v43
	v_mul_f32_e32 v42, v31, v31
	v_mul_f32_e32 v43, v30, v31
	v_fma_f32 v32, v30, v30, -v42
	v_add_f32_e32 v33, v43, v43
	v_mul_f32_e32 v42, v33, v33
	v_mul_f32_e32 v43, v32, v33
	v_fma_f32 v34, v32, v32, -v42
	v_add_f32_e32 v35, v43, v43
	v_mov_b32_e32 v16, 1.0
	v_mov_b32_e32 v17, 0
	v_mul_f32_e32 v15, v17, v25
	v_fma_f32 v42, v16, v24, -v15
	v_mul_f32_e32 v15, v16, v25
	v_fma_f32 v43, v17, v24, v15
	v_cndmask_b32_e64 v16, v16, v42, s[10:11]
	v_cndmask_b32_e64 v17, v17, v43, s[10:11]
	v_mul_f32_e32 v15, v17, v31
	v_fma_f32 v42, v16, v30, -v15
	v_mul_f32_e32 v15, v16, v31
	v_fma_f32 v43, v17, v30, v15
	v_cndmask_b32_e64 v16, v16, v42, s[12:13]
	v_cndmask_b32_e64 v17, v17, v43, s[12:13]
	v_mul_f32_e32 v15, v17, v33
	v_fma_f32 v42, v16, v32, -v15
	v_mul_f32_e32 v15, v16, v33
	v_fma_f32 v43, v17, v32, v15
	v_cndmask_b32_e64 v16, v16, v42, s[14:15]
	v_cndmask_b32_e64 v17, v17, v43, s[14:15]
	v_mul_f32_e32 v15, v17, v35
	v_fma_f32 v42, v16, v34, -v15
	v_mul_f32_e32 v15, v16, v35
	v_fma_f32 v43, v17, v34, v15
	v_cndmask_b32_e64 v16, v16, v42, s[16:17]
	v_cndmask_b32_e64 v17, v17, v43, s[16:17]
	v_mul_f32_e32 v15, v29, v17
	v_fma_f32 v18, v28, v16, -v15
	v_mul_f32_e32 v15, v28, v17
	v_fma_f32 v19, v29, v16, v15
	v_mul_f32_e32 v15, v29, v41
	v_fma_f32 v20, v28, v40, -v15
	v_mul_f32_e32 v15, v28, v41
	v_fma_f32 v21, v29, v40, v15
	global_store_dwordx2 v13, v[18:19], s[20:21] offset:3072
	global_store_dwordx2 v13, v[38:39], s[20:21] offset:3080
	global_store_dwordx2 v44, v[36:37], s[20:21] offset:3072
	global_store_dwordx2 v44, v[22:23], s[20:21] offset:3080
	global_store_dwordx2 v14, v[20:21], s[22:23] offset:3072
	global_store_dwordx2 v14, v[36:37], s[22:23] offset:3080
	s_nop 1
	s_lshl_b32 s0, s7, 2
	s_add_i32 s0, s0, s6
	s_lshl_b32 s8, s7, 12
	s_lshl_b32 s9, s6, 10
	s_add_i32 s8, s8, s9
	s_add_u32 s8, s8, 0x11fb20
	s_add_u32 s8, s4, s8
	s_addc_u32 s9, s5, 0
	s_add_u32 s10, s8, 0x40000
	s_addc_u32 s11, s9, 0
	s_lshl_b32 s12, s7, 12
	s_lshl_b32 s13, s6, 6
	s_add_i32 s12, s12, s13
	s_add_u32 s12, s12, 0x19fb20
	s_add_u32 s12, s4, s12
	s_addc_u32 s13, s5, 0
	s_add_u32 s14, s12, 0x40000
	s_addc_u32 s15, s13, 0
	s_lshl_b32 s16, s0, 11
	s_add_u32 s16, s16, 0xfd00000
	s_add_u32 s16, s4, s16
	s_addc_u32 s17, s5, 0
	s_lshl_b32 s18, s0, 10
	s_add_u32 s18, s18, 0xfd80000
	s_add_u32 s18, s4, s18
	s_addc_u32 s19, s5, 0
	v_mov_b32_e32 v0, 0
	v_mov_b32_e32 v1, 0
	v_mov_b32_e32 v2, 0
	v_mov_b32_e32 v3, 0
	v_mov_b32_e32 v4, 0
	v_mov_b32_e32 v5, 0
	v_mov_b32_e32 v6, 0
	v_mov_b32_e32 v7, 0
	v_mov_b32_e32 v8, 0
	v_mov_b32_e32 v9, 0
	v_mov_b32_e32 v10, 0
	v_mov_b32_e32 v11, 0
	v_mov_b32_e32 v12, 0
	v_mov_b32_e32 v13, 0
	v_mov_b32_e32 v14, 0
	v_mov_b32_e32 v15, 0
	v_and_b32_e32 v24, 15, v205
	v_lshrrev_b32_e32 v26, 4, v205
	v_lshlrev_b32_e32 v25, 8, v24
	v_lshl_add_u32 v25, v26, 4, v25
	v_lshlrev_b32_e32 v24, 6, v24
	v_and_b32_e32 v26, 16, v205
	v_lshl_add_u32 v24, v26, 1, v24
	s_mov_b32 exec_hi, 0
	global_load_dwordx4 v[0:3], v24, s[8:9]
	global_load_dwordx4 v[4:7], v24, s[8:9] offset:16
	global_load_dwordx4 v[8:11], v24, s[10:11]
	global_load_dwordx4 v[12:15], v24, s[10:11] offset:16
	s_mov_b64 exec, -1
	global_load_dwordx4 v[16:19], v25, s[12:13]
	global_load_dwordx4 v[20:23], v25, s[14:15]
	s_waitcnt vmcnt(2)
	v_cvt_pk_bf16_f32 v0, v0, v1
	v_cvt_pk_bf16_f32 v1, v2, v3
	v_cvt_pk_bf16_f32 v2, v4, v5
	v_cvt_pk_bf16_f32 v3, v6, v7
	v_cvt_pk_bf16_f32 v8, v8, v9
	v_cvt_pk_bf16_f32 v9, v10, v11
	v_cvt_pk_bf16_f32 v10, v12, v13
	v_cvt_pk_bf16_f32 v11, v14, v15
	v_lshlrev_b32_e32 v27, 4, v205
	global_store_dwordx4 v27, v[0:3], s[16:17]
	global_store_dwordx4 v27, v[8:11], s[16:17] offset:1024
	s_waitcnt vmcnt(0)
	v_cvt_pk_bf16_f32 v16, v16, v17
	v_cvt_pk_bf16_f32 v17, v18, v19
	v_cvt_pk_bf16_f32 v18, -v20, -v21
	v_cvt_pk_bf16_f32 v19, -v22, -v23
	global_store_dwordx4 v27, v[16:19], s[18:19]
	s_nop 1
